# grid-size guard for barrier hooks; attention row-halves / SGU row blocks balanced across SIMD partner waves
# speedup vs baseline: 1.0021x; 1.0021x over previous
;     unsigned char* ws = a.ws;
;     int base = 0;
; #pragma unroll 1
;     for (int mi = 0; mi < 7 * DEPTH; ++mi) {
;         if (!((mask >> mi) & 1u)) continue;
; __global__ void __launch_bounds__(NTHREADS, 2) mk_fwd(Args args) {
;     ...
;     if (KON(0) && IN(0)) { const int vcu = (G % 8 == 0) ? (blk % 8) * (G / 8) + blk / 8 : blk; p0_prologue(args, vcu * NWAVES + wave, G * NWAVES, lane, 0x000Fu | 0x0010u | 0x0800u, true, 0x0810u, 0, 10); }
.LBB0_11:
	s_lshl_b32 s48, 1, s43
	s_cmpk_eq_u32 s3, 0x100
	s_cselect_b32 s4, 0xf, 0x81f
	s_and_b32 s4, s48, s4
	s_cmp_eq_u32 s4, 0
	s_cbranch_scc1 .LBB0_10
	s_cmp_gt_u32 s43, 6
	s_cselect_b64 s[18:19], -1, 0
	s_and_b64 s[4:5], s[18:19], exec
	s_cselect_b32 s49, -7, 0
	s_add_i32 s49, s49, s43
	s_mov_b64 s[24:25], -1
	s_mov_b64 s[22:23], 0
	s_cmp_lt_i32 s49, 3
	s_mov_b64 s[20:21], 0
	s_cbranch_scc0 .LBB0_31
	s_movk_i32 s47, 0x800
	s_and_b64 vcc, exec, s[24:25]
	s_cbranch_vccnz .LBB0_43

.LBB0_132:
	s_or_b64 exec, exec, s[4:5]
	s_cmpk_lg_u32 s3, 0x100
	s_cbranch_scc1 .Lcv_skip_0
	v_readfirstlane_b32 vcc_lo, v204
	s_nop 3
	s_lshr_b32 vcc_lo, vcc_lo, 6
	s_cmp_eq_u32 vcc_lo, 0
	s_cbranch_scc1 .Lcv_skip_0
	s_lshr_b32 m0, s85, 5
	v_subrev_u32_e32 v106, 64, v204
	v_mov_b32_e32 v107, m0
	v_lshlrev_b32_e32 v107, 8, v107
	v_mov_b32_e32 v108, v106
	v_lshrrev_b32_e32 v109, 3, v108
	v_add_u32_e32 v109, v109, v107
	v_mul_u32_u24_e32 v109, 0x1000, v109
	v_and_b32_e32 v108, 7, v108
	v_lshl_add_u32 v109, v108, 6, v109
	v_add_u32_e32 v108, 448, v106
	v_lshrrev_b32_e32 v110, 3, v108
	v_add_u32_e32 v110, v110, v107
	v_mul_u32_u24_e32 v110, 0x1000, v110
	v_and_b32_e32 v108, 7, v108
	v_lshl_add_u32 v110, v108, 6, v110
	v_add_u32_e32 v108, 896, v106
	v_lshrrev_b32_e32 v111, 3, v108
	v_add_u32_e32 v111, v111, v107
	v_mul_u32_u24_e32 v111, 0x1000, v111
	v_and_b32_e32 v108, 7, v108
	v_lshl_add_u32 v111, v108, 6, v111
	v_add_u32_e32 v108, 1344, v106
	v_lshrrev_b32_e32 v112, 3, v108
	v_add_u32_e32 v112, v112, v107
	v_mul_u32_u24_e32 v112, 0x1000, v112
	v_and_b32_e32 v108, 7, v108
	v_lshl_add_u32 v112, v108, 6, v112
	v_add_u32_e32 v108, 1792, v106
	v_and_b32_e32 v108, 0x7ff, v108
	v_lshrrev_b32_e32 v113, 3, v108
	v_add_u32_e32 v113, v113, v107
	v_mul_u32_u24_e32 v113, 0x1000, v113
	v_and_b32_e32 v108, 7, v108
	v_lshl_add_u32 v113, v108, 6, v113
	v_readlane_b32 vcc_lo, v250, 36
	v_readlane_b32 vcc_hi, v250, 37
	s_nop 3
	s_add_u32 vcc_lo, vcc_lo, 0x1c0000
	s_addc_u32 vcc_hi, vcc_hi, 0
	global_load_dword v120, v109, vcc
	global_load_dword v121, v110, vcc
	global_load_dword v122, v111, vcc
	global_load_dword v123, v112, vcc
	global_load_dword v124, v113, vcc

; __device__ __forceinline__ unsigned cvt_pk_bf16(float lo, float hi) { unsigned r; asm volatile("v_cvt_pk_bf16_f32 %0, %1, %2" : "=v"(r) : "v"(lo), "v"(hi)); return r; }
; __device__ __forceinline__ void st16_wt(void* p, u32x4 v) { asm volatile("global_store_dwordx4 %0, %1, off sc1\n\ts_nop 1" :: "v"(p), "v"(v) : "memory"); }
; __device__ __forceinline__ void tr_item(const float* __restrict__ W, int K, int N, bf16_t* WT, const float* __restrict__ kscale, int rowmode, int item, int lane) {
;     const int nblk = N >> 5, kb = item / nblk, nb = item - kb * nblk;
;     const int c = lane >> 3, q = lane & 7, k0 = kb * 64 + c * 8, n0 = nb * 32 + q * 4;
;     f32x4 v[8];
; #pragma unroll
;     for (int i = 0; i < 8; ++i) v[i] = __builtin_nontemporal_load((const f32x4*)(W + (size_t)(k0 + i) * N + n0));
;     if (kscale) { const f32x4 s0 = *(const f32x4*)(kscale + k0), s1 = *(const f32x4*)(kscale + k0 + 4);
; #pragma unroll
;         for (int i = 0; i < 4; ++i) { v[i] = v[i] * s0[i]; v[4 + i] = v[4 + i] * s1[i]; } }
;     int drow;
;     if (rowmode == 0) drow = n0;
;     else if (rowmode == 3) { const int g = n0 - pg8::C_GA; drow = g < 0 ? n0 : pg8::C_GA + (((g & 2047) >> 7) << 8) + ((g >> 11) << 7) + (g & 127); }
;     else drow = ((n0 >> 7) << 8) + (n0 & 127) + (rowmode == 2 ? 128 : 0);
; #pragma unroll
;     for (int e = 0; e < 4; ++e) { u32x4 o; o.x = cvt_pk_bf16(v[0][e], v[1][e]); o.y = cvt_pk_bf16(v[2][e], v[3][e]); o.z = cvt_pk_bf16(v[4][e], v[5][e]); o.w = cvt_pk_bf16(v[6][e], v[7][e]);
;         pg8::st16_wt(WT + (size_t)(drow + e) * K + k0, o); }
.LBB0_310:
	s_or_b64 exec, exec, s[6:7]
	s_cmpk_lg_u32 s3, 0x100
	s_cbranch_scc1 .Lcv_skip_1
	v_readfirstlane_b32 vcc_lo, v204
	s_nop 3
	s_lshr_b32 vcc_lo, vcc_lo, 6
	s_cmp_eq_u32 vcc_lo, 0
	s_cbranch_scc1 .Lcv_skip_1
	s_cmp_lg_u32 s64, 0
	s_cbranch_scc1 .Lcv_pfwait_1
	v_and_b32_e32 v106, 63, v204
	v_lshrrev_b32_e32 v107, 3, v106
	v_and_b32_e32 v108, 7, v106
	v_readfirstlane_b32 vcc_lo, v204
	s_nop 3
	s_lshr_b32 vcc_lo, vcc_lo, 6
	s_mul_i32 vcc_hi, s85, 7
	s_add_i32 vcc_lo, vcc_lo, vcc_hi
	s_add_i32 vcc_lo, vcc_lo, -1
	s_add_i32 vcc_lo, vcc_lo, 0
	s_sub_u32 vcc_lo, vcc_lo, 0
	v_mov_b32_e32 v113, vcc_lo
	v_mul_u32_u24_e32 v109, 0x5d18, v113
	v_lshrrev_b32_e32 v109, 22, v109
	v_mul_u32_u24_e32 v110, 0xb0, v109
	v_sub_u32_e32 v110, v113, v110
	v_lshlrev_b32_e32 v109, 6, v109
	v_lshl_add_u32 v109, v107, 3, v109
	v_lshlrev_b32_e32 v110, 5, v110
	v_lshl_add_u32 v110, v108, 2, v110
	v_mul_u32_u24_e32 v111, 0x5800, v109
	v_lshl_add_u32 v111, v110, 2, v111
	v_lshrrev_b32_e32 v112, 7, v110
	v_lshlrev_b32_e32 v112, 8, v112
	v_and_b32_e32 v113, 0x7f, v110
	v_add_u32_e32 v112, v112, v113
	v_lshlrev_b32_e32 v112, 12, v112
	v_lshl_add_u32 v112, v109, 1, v112
	v_lshlrev_b32_e32 v113, 2, v109
	v_readlane_b32 vcc_lo, v250, 28
	v_readlane_b32 vcc_hi, v250, 29
	s_nop 4
	global_load_dwordx4 v[98:101], v113, vcc
	global_load_dwordx4 v[102:105], v113, vcc offset:16
	v_readlane_b32 vcc_lo, v250, 30
	v_readlane_b32 vcc_hi, v250, 31
	s_nop 4
	global_load_dwordx4 v[66:69], v111, vcc nt
	v_add_u32_e32 v111, 0x5800, v111
	global_load_dwordx4 v[70:73], v111, vcc nt
	v_add_u32_e32 v111, 0x5800, v111
	global_load_dwordx4 v[74:77], v111, vcc nt
	v_add_u32_e32 v111, 0x5800, v111
	global_load_dwordx4 v[78:81], v111, vcc nt
	v_add_u32_e32 v111, 0x5800, v111
	global_load_dwordx4 v[82:85], v111, vcc nt
	v_add_u32_e32 v111, 0x5800, v111
	global_load_dwordx4 v[86:89], v111, vcc nt
	v_add_u32_e32 v111, 0x5800, v111
	global_load_dwordx4 v[90:93], v111, vcc nt
	v_add_u32_e32 v111, 0x5800, v111
	global_load_dwordx4 v[94:97], v111, vcc nt
	v_readlane_b32 vcc_lo, v250, 36
	v_readlane_b32 vcc_hi, v250, 37
	s_nop 3
	s_add_u32 vcc_lo, vcc_lo, 0x5dc0000
	s_addc_u32 vcc_hi, vcc_hi, 0
	s_waitcnt vmcnt(0)
	v_mul_f32_e32 v66, v66, v98
	v_mul_f32_e32 v67, v67, v98
	v_mul_f32_e32 v68, v68, v98
	v_mul_f32_e32 v69, v69, v98
	v_mul_f32_e32 v70, v70, v99
	v_mul_f32_e32 v71, v71, v99
	v_mul_f32_e32 v72, v72, v99
	v_mul_f32_e32 v73, v73, v99
	v_mul_f32_e32 v74, v74, v100
	v_mul_f32_e32 v75, v75, v100
	v_mul_f32_e32 v76, v76, v100
	v_mul_f32_e32 v77, v77, v100
	v_mul_f32_e32 v78, v78, v101
	v_mul_f32_e32 v79, v79, v101
	v_mul_f32_e32 v80, v80, v101
	v_mul_f32_e32 v81, v81, v101
	v_mul_f32_e32 v82, v82, v102
	v_mul_f32_e32 v83, v83, v102
	v_mul_f32_e32 v84, v84, v102
	v_mul_f32_e32 v85, v85, v102
	v_mul_f32_e32 v86, v86, v103
	v_mul_f32_e32 v87, v87, v103
	v_mul_f32_e32 v88, v88, v103
	v_mul_f32_e32 v89, v89, v103
	v_mul_f32_e32 v90, v90, v104
	v_mul_f32_e32 v91, v91, v104
	v_mul_f32_e32 v92, v92, v104
	v_mul_f32_e32 v93, v93, v104
	v_mul_f32_e32 v94, v94, v105
	v_mul_f32_e32 v95, v95, v105
	v_mul_f32_e32 v96, v96, v105
	v_mul_f32_e32 v97, v97, v105
	v_cvt_pk_bf16_f32 v114, v66, v70
	v_cvt_pk_bf16_f32 v115, v74, v78
	v_cvt_pk_bf16_f32 v116, v82, v86
	v_cvt_pk_bf16_f32 v117, v90, v94
	v_cvt_pk_bf16_f32 v118, v67, v71
	v_cvt_pk_bf16_f32 v119, v75, v79
	v_cvt_pk_bf16_f32 v120, v83, v87
	v_cvt_pk_bf16_f32 v121, v91, v95
	v_cvt_pk_bf16_f32 v122, v68, v72
	v_cvt_pk_bf16_f32 v123, v76, v80
	v_cvt_pk_bf16_f32 v124, v84, v88
	v_cvt_pk_bf16_f32 v125, v92, v96
	v_cvt_pk_bf16_f32 v126, v69, v73
	v_cvt_pk_bf16_f32 v127, v77, v81
	v_cvt_pk_bf16_f32 v128, v85, v89
	v_cvt_pk_bf16_f32 v129, v93, v97
	global_store_dwordx4 v112, v[114:117], vcc sc1
	v_add_u32_e32 v112, 0x1000, v112
	global_store_dwordx4 v112, v[118:121], vcc sc1
	v_add_u32_e32 v112, 0x1000, v112
	global_store_dwordx4 v112, v[122:125], vcc sc1
	v_add_u32_e32 v112, 0x1000, v112
	global_store_dwordx4 v112, v[126:129], vcc sc1

; #define LAS __attribute__((address_space(3)))
; __device__ __forceinline__ void p2_block(LAS unsigned char* lds, const bf16_t* __restrict__ PROJ, bf16_t* __restrict__ ATT, bf16_t* __restrict__ SGU, const float* __restrict__ qn, const float* __restrict__ kn, ...
;     ...
;     const int b = item >> 6, n = (item >> 2) & 15, kvh = item & 3;
;     const int lane = tid & 63, w = __builtin_amdgcn_readfirstlane(tid >> 6), fr = lane & 15, fq = lane >> 4;
;     LAS unsigned char* KS = lds; LAS unsigned char* VT = lds + KS_BYTES;
;     const int g = w >> 1, rbase = (w & 1) * 64, hq = kvh * 4 + g;
;     const int kk = tid >> 1, h = tid & 1, s = n * 128 - 128 + kk, sc = s < 0 ? 0 : s;
;     const bf16_t* rowp = PROJ + (size_t)(b * pg8::SEQ + sc) * pg8::IN_W;
;     const bf16_t* kp = rowp + pg8::C_K + kvh * 64 + 16 * h;
;     const u32x4 ka = *(const u32x4*)kp, kb = *(const u32x4*)(kp + 8), kc = *(const u32x4*)(kp + 32), kd = *(const u32x4*)(kp + 40);
;     const bf16_t* vp = rowp + pg8::C_V + kvh * 64 + 32 * h;
;     u32x4 vv[4];
; #pragma unroll
;     for (int c4 = 0; c4 < 4; ++c4) vv[c4] = *(const u32x4*)(vp + 8 * c4);
;     const int sp_ = tid >> 2, q4 = tid & 3;
;     u32x4 sv[2][4];
;     const bf16_t* svsrc = PROJ + ((size_t)b * pg8::SEQ + n * 128 + sp_) * pg8::IN_W + pg8::C_VS + (2 * kvh) * 128 + 32 * q4;
; #pragma unroll
;     for (int c4 = 0; c4 < 4; ++c4) sv[0][c4] = *(const u32x4*)(svsrc + 8 * c4);
;     u32x4 qa[4], qb[4];
; #pragma unroll
;     for (int c = 0; c < 2; ++c) { const bf16_t* qp = PROJ + ((size_t)b * pg8::SEQ + n * 128 + rbase + 16 * c + fr) * pg8::IN_W + hq * 64 + 8 * fq; qa[c] = *(const u32x4*)qp; qb[c] = *(const u32x4*)(qp + 32); }
.LBB0_330:
	s_bfe_u32 s27, s2, 0x40002
	v_mov_b32_e32 v160, v204
	s_lshl_b32 s17, s27, 7
	s_add_i32 s4, s17, 0xffffff80
	v_ashrrev_i32_e32 v167, 1, v160
	v_add_u32_e32 v22, s4, v167
	s_ashr_i32 s6, s2, 6
	v_max_i32_e32 v66, 0, v22
	s_and_b32 s73, s2, 3
	v_lshl_add_u32 v0, s6, 11, v66
	s_waitcnt lgkmcnt(0)
	v_mov_b64_e32 v[2:3], s[10:11]
	v_and_b32_e32 v166, 1, v160
	v_mad_i64_i32 v[4:5], s[24:25], v0, s83, v[2:3]
	s_lshl_b32 s4, s73, 7
	v_lshl_add_u64 v[4:5], v[4:5], 0, s[4:5]
	v_lshlrev_b32_e32 v0, 5, v166
	v_lshl_add_u64 v[6:7], v[4:5], 0, v[0:1]
	global_load_dwordx4 v[50:53], v[6:7], off offset:2048
	global_load_dwordx4 v[58:61], v[6:7], off offset:2064
	global_load_dwordx4 v[54:57], v[6:7], off offset:2112
	global_load_dwordx4 v[62:65], v[6:7], off offset:2128
	v_readfirstlane_b32 s16, v160
	s_ashr_i32 s77, s16, 7
	s_lshl_b32 s7, s73, 2
	s_add_i32 s42, s77, s7
	s_ashr_i32 s7, s6, 31
	v_lshlrev_b32_e32 v74, 6, v166
	v_mov_b32_e32 v75, v1
	v_ashrrev_i32_e32 v136, 2, v160
	s_lshl_b64 s[48:49], s[6:7], 11
	v_lshl_add_u64 v[4:5], v[4:5], 0, v[74:75]
	s_or_b32 s24, s48, s17
	s_mov_b32 s25, s49
	v_ashrrev_i32_e32 v137, 31, v136
	s_waitcnt lgkmcnt(0)
	v_mov_b64_e32 v[144:145], v[4:5]
	s_nop 0
	s_nop 0
	s_nop 0
	v_lshl_add_u64 v[4:5], s[24:25], 0, v[136:137]
	v_mad_u64_u32 v[2:3], s[6:7], v4, s83, v[2:3]
	v_lshlrev_b32_e32 v4, 5, v160
	v_mad_i32_i24 v3, v5, s83, v3
	s_lshl_b32 s4, s73, 9
	v_and_b32_e32 v165, 0x60, v4
	v_lshl_add_u64 v[2:3], v[2:3], 0, s[4:5]
	v_lshlrev_b32_e32 v4, 1, v165
	v_mov_b32_e32 v5, v1
	v_lshl_add_u64 v[2:3], v[2:3], 0, v[4:5]
	s_mov_b64 s[6:7], 0x1400
	v_lshl_add_u64 v[138:139], v[2:3], 0, s[6:7]
	s_lshl_b32 s6, s42, 6
	s_ashr_i32 s7, s6, 31
	s_and_b32 s26, s16, 64
	s_lshl_b64 s[6:7], s[6:7], 1
	v_bfe_u32 v162, v160, 4, 2
	s_add_u32 s28, s10, s6
	s_movk_i32 s4, 0x1000
	v_and_b32_e32 v137, 15, v160
	s_addc_u32 s29, s11, s7
	v_lshlrev_b32_e32 v132, 4, v162
	v_mov_b32_e32 v133, v1
	v_and_b32_e32 v68, 64, v211
	v_add_co_u32_e32 v2, vcc, s4, v2
	v_or_b32_e32 v161, s26, v137
	v_lshl_add_u64 v[134:135], s[28:29], 0, v[132:133]
	v_xor_b32_e32 v67, 1, v211
	v_add_u32_e32 v133, 64, v68
	v_addc_co_u32_e32 v3, vcc, 0, v3, vcc
	v_or_b32_e32 v163, s24, v161
	v_cmp_lt_i32_e64 s[40:41], v67, v133
	v_cmp_gt_i32_e32 vcc, 0, v22
	v_mad_u64_u32 v[22:23], s[28:29], v163, s83, v[134:135]
	v_cndmask_b32_e64 v67, v211, v67, s[40:41]
	v_mad_i32_i24 v23, s49, v212, v23
	v_lshlrev_b32_e32 v164, 2, v67
	v_lshlrev_b32_e32 v66, 5, v66
	v_mov_b32_e32 v67, v1
	v_readlane_b32 s44, v250, 36
	v_readlane_b32 s46, v250, 38
	s_nop 0
	s_nop 0
	s_nop 0
	s_nop 0
	s_nop 0
	v_or_b32_e32 v22, 16, v163
	v_lshlrev_b64 v[66:67], 2, v[66:67]
	v_readlane_b32 s45, v250, 37
	v_readlane_b32 s47, v250, 39
	v_mad_u64_u32 v[26:27], s[28:29], v22, s83, v[134:135]
	v_lshl_add_u64 v[68:69], s[44:45], 0, v[66:67]
	v_lshl_add_u64 v[66:67], s[46:47], 0, v[66:67]
	v_mad_i32_i24 v27, s49, v212, v27
	v_lshl_add_u64 v[86:87], v[68:69], 0, v[74:75]
	v_lshl_add_u64 v[126:127], v[66:67], 0, v[74:75]
	s_nop 0
	s_nop 0
	global_load_dwordx4 v[66:69], v74, s[0:1] offset:48
	global_load_dwordx4 v[78:81], v74, s[0:1] offset:32
	global_load_dwordx4 v[94:97], v74, s[0:1] offset:16
	global_load_dwordx4 v[106:109], v74, s[0:1]
	global_load_dwordx4 v[70:73], v74, s[0:1] offset:176
	global_load_dwordx4 v[82:85], v74, s[0:1] offset:160
	global_load_dwordx4 v[98:101], v74, s[0:1] offset:144
	global_load_dwordx4 v[110:113], v74, s[0:1] offset:128
	s_nop 0
	global_load_dwordx4 v[74:77], v[86:87], off offset:48
	global_load_dwordx4 v[90:93], v[86:87], off offset:32
	global_load_dwordx4 v[102:105], v[86:87], off offset:16
	global_load_dwordx4 v[114:117], v[86:87], off
	s_nop 0
	global_load_dwordx4 v[86:89], v[126:127], off offset:48
	global_load_dwordx4 v[118:121], v[126:127], off offset:32
	global_load_dwordx4 v[122:125], v[126:127], off offset:16
	s_nop 0
	global_load_dwordx4 v[126:129], v[126:127], off
	v_cndmask_b32_e64 v180, 1.0, 0, vcc
	s_lshl_b32 s4, s73, 10
	global_load_dwordx4 v[46:49], v[2:3], off offset:1024
	global_load_dwordx4 v[34:37], v[138:139], off offset:48
	global_load_dwordx4 v[38:41], v[138:139], off offset:32
	global_load_dwordx4 v[42:45], v[138:139], off offset:16
	global_load_dwordx4 v[18:21], v[144:145], off offset:2560
	global_load_dwordx4 v[14:17], v[144:145], off offset:2576
	global_load_dwordx4 v[10:13], v[144:145], off offset:2592
	global_load_dwordx4 v[6:9], v[144:145], off offset:2608
	s_waitcnt vmcnt(8)
; __device__ __forceinline__ void unpack8(const u32x4 w, float* f) { f[0] = bf_lo(w.x); f[1] = bf_hi(w.x); f[2] = bf_lo(w.y); f[3] = bf_hi(w.y); f[4] = bf_lo(w.z); f[5] = bf_hi(w.z); f[6] = bf_lo(w.w); f[7] = bf_hi(w.w); }
; __device__ __forceinline__ void p2_block(LAS unsigned char* lds, const bf16_t* __restrict__ PROJ, bf16_t* __restrict__ ATT, bf16_t* __restrict__ SGU, const float* __restrict__ qn, const float* __restrict__ kn, ...
;     ...
;         const float valid = s < 0 ? 0.f : 1.f;
;         float x1[16], x2[16]; unpack8(ka, x1); unpack8(kb, x1 + 8); unpack8(kc, x2); unpack8(kd, x2 + 8);
;         float ss = 0.f;
; #pragma unroll
;         for (int j = 0; j < 16; ++j) ss += x1[j] * x1[j] + x2[j] * x2[j];
;         ss += __shfl_xor(ss, 1);
;         const float rinv = rsqrtf(ss * (1.0f / 64.0f) + pg8::EPS) * valid;
;         const float* cp = COS + sc * 32 + 16 * h; const float* sp = SIN + sc * 32 + 16 * h;
;         float o1[16], o2[16];
; #pragma unroll
;         for (int j = 0; j < 16; ++j) { const float a1 = x1[j] * rinv * kn[16 * h + j], a2 = x2[j] * rinv * kn[32 + 16 * h + j], c = cp[j], sn = sp[j]; o1[j] = a1 * c - a2 * sn; o2[j] = a2 * c + a1 * sn; }
	v_lshlrev_b32_e32 v226, 16, v51
	v_lshlrev_b32_e32 v142, 16, v61
	v_and_b32_e32 v140, 0xffff0000, v61
	v_lshlrev_b32_e32 v143, 16, v65
	v_and_b32_e32 v141, 0xffff0000, v65
	v_mov_b32_e32 v150, v141
	v_mov_b32_e32 v151, v143
	v_mov_b32_e32 v148, v140
	v_mov_b32_e32 v149, v142
	v_pk_mul_f32 v[150:151], v[150:151], v[150:151]
	v_and_b32_e32 v61, 0xffff0000, v64
	v_pk_fma_f32 v[182:183], v[148:149], v[148:149], v[150:151]
	v_lshlrev_b32_e32 v149, 16, v64
	v_lshlrev_b32_e32 v148, 16, v60
	v_and_b32_e32 v60, 0xffff0000, v60
	v_mov_b32_e32 v154, v61
	v_mov_b32_e32 v155, v149
	v_mov_b32_e32 v64, v60
	v_mov_b32_e32 v65, v148
	v_pk_mul_f32 v[154:155], v[154:155], v[154:155]
	v_and_b32_e32 v201, 0xffff0000, v57
	v_pk_fma_f32 v[184:185], v[64:65], v[64:65], v[154:155]
	v_lshlrev_b32_e32 v155, 16, v63
	v_and_b32_e32 v65, 0xffff0000, v63
	v_lshlrev_b32_e32 v154, 16, v59
	v_and_b32_e32 v64, 0xffff0000, v59
	v_mov_b32_e32 v188, v65
	v_mov_b32_e32 v189, v155
	v_mov_b32_e32 v186, v64
	v_mov_b32_e32 v187, v154
	v_pk_mul_f32 v[188:189], v[188:189], v[188:189]
	v_and_b32_e32 v59, 0xffff0000, v62
	v_pk_fma_f32 v[186:187], v[186:187], v[186:187], v[188:189]
	v_lshlrev_b32_e32 v189, 16, v62
	v_lshlrev_b32_e32 v188, 16, v58
	v_and_b32_e32 v58, 0xffff0000, v58
	v_mov_b32_e32 v194, v59
	v_mov_b32_e32 v195, v189
	v_mov_b32_e32 v62, v58
	v_mov_b32_e32 v63, v188
	v_pk_mul_f32 v[194:195], v[194:195], v[194:195]
	v_and_b32_e32 v234, 0xffff0000, v51
	v_pk_fma_f32 v[62:63], v[62:63], v[62:63], v[194:195]
	v_lshlrev_b32_e32 v195, 16, v57
	v_lshlrev_b32_e32 v239, 16, v54
	v_lshlrev_b32_e32 v238, 16, v50
	v_and_b32_e32 v51, 0xffff0000, v54
	v_and_b32_e32 v50, 0xffff0000, v50
	v_lshlrev_b32_e32 v194, 16, v53
	v_and_b32_e32 v200, 0xffff0000, v53
	v_mov_b32_e32 v218, v201
	v_mov_b32_e32 v219, v195
	v_lshlrev_b32_e32 v227, 16, v55
	v_and_b32_e32 v235, 0xffff0000, v55
	v_pk_mul_f32 v[240:241], v[238:239], v[238:239]
	v_pk_mul_f32 v[54:55], v[50:51], v[50:51]
	v_mov_b32_e32 v202, v200
	v_mov_b32_e32 v203, v194
	v_pk_mul_f32 v[218:219], v[218:219], v[218:219]
	v_pk_mul_f32 v[228:229], v[226:227], v[226:227]
	v_add_f32_e32 v54, v54, v55
	v_add_f32_e32 v55, v240, v241
	v_pk_fma_f32 v[202:203], v[202:203], v[202:203], v[218:219]
	v_lshlrev_b32_e32 v219, 16, v56
	v_lshlrev_b32_e32 v218, 16, v52
	v_pk_mul_f32 v[236:237], v[234:235], v[234:235]
	v_add_f32_e32 v54, v55, v54
	v_add_f32_e32 v55, v228, v229
	v_mov_b32_e32 v150, v66
	v_pk_mul_f32 v[220:221], v[218:219], v[218:219]
	v_and_b32_e32 v53, 0xffff0000, v56
	v_and_b32_e32 v52, 0xffff0000, v52
	v_add_f32_e32 v66, v236, v237
	v_add_f32_e32 v54, v55, v54
	v_pk_mul_f32 v[56:57], v[52:53], v[52:53]
	v_add_f32_e32 v54, v66, v54
	v_add_f32_e32 v55, v220, v221
	v_add_f32_e32 v54, v55, v54
	v_add_f32_e32 v55, v56, v57
	v_add_f32_e32 v54, v55, v54
	v_add_f32_e32 v54, v203, v54
	v_add_f32_e32 v54, v202, v54
	v_add_f32_e32 v54, v63, v54
	v_add_f32_e32 v54, v62, v54
	v_add_f32_e32 v54, v187, v54
	v_add_f32_e32 v54, v186, v54
	v_add_f32_e32 v54, v185, v54
	v_add_f32_e32 v54, v184, v54
	v_add_f32_e32 v54, v183, v54
	v_add_f32_e32 v54, v182, v54
	s_nop 1
	v_mov_b32_dpp v55, v54 quad_perm:[1,0,3,2] row_mask:0xf bank_mask:0xf
	v_mov_b32_e32 v242, v106
	v_mov_b32_e32 v243, v110
	v_mov_b32_e32 v244, v114
	v_mov_b32_e32 v245, v126
	s_waitcnt lgkmcnt(0)
	v_add_f32_e32 v54, v54, v55
	v_fmamk_f32 v54, v54, 0x3c800000, v209
	v_cmp_gt_f32_e64 s[40:41], s82, v54
	v_mul_f32_e32 v55, 0x4b800000, v54
	v_mov_b32_e32 v110, v107
	v_cndmask_b32_e64 v54, v54, v55, s[40:41]
	v_rsq_f32_e32 v54, v54
	v_mov_b32_e32 v230, v108
	v_mov_b32_e32 v231, v112
	v_mov_b32_e32 v232, v116
	v_mul_f32_e32 v55, 0x45800000, v54
	v_cndmask_b32_e64 v54, v54, v55, s[40:41]
	v_mul_f32_e32 v54, v180, v54
	v_pk_mul_f32 v[56:57], v[54:55], v[238:239] op_sel_hi:[0,1]
	v_pk_mul_f32 v[56:57], v[242:243], v[56:57]
	v_mov_b32_e32 v233, v128
	v_pk_mul_f32 v[62:63], v[244:245], v[56:57]
	v_mov_b32_e32 v144, v68
	v_sub_f32_e32 v55, v62, v63
	v_mov_b32_e32 v62, v126
	v_mov_b32_e32 v63, v114
	v_pk_mul_f32 v[50:51], v[54:55], v[50:51] op_sel_hi:[0,1]
	v_pk_mul_f32 v[56:57], v[62:63], v[56:57]
	v_pk_mul_f32 v[50:51], v[110:111], v[50:51]
	v_mov_b32_e32 v126, v115
	v_mov_b32_e32 v114, v127
	v_add_f32_e32 v62, v57, v56
	v_pk_mul_f32 v[56:57], v[126:127], v[50:51]
	v_pk_mul_f32 v[50:51], v[114:115], v[50:51]
	v_sub_f32_e32 v63, v56, v57
	v_add_f32_e32 v66, v51, v50
	v_pk_mul_f32 v[50:51], v[54:55], v[226:227] op_sel_hi:[0,1]
	v_pk_mul_f32 v[50:51], v[230:231], v[50:51]
	v_mov_b32_e32 v190, v78
	v_pk_mul_f32 v[56:57], v[232:233], v[50:51]
	v_mov_b32_e32 v112, v109
	v_sub_f32_e32 v68, v56, v57
	v_mov_b32_e32 v56, v128
	v_mov_b32_e32 v57, v116
	v_pk_mul_f32 v[50:51], v[56:57], v[50:51]
	v_mov_b32_e32 v128, v117
	v_add_f32_e32 v78, v51, v50
	v_pk_mul_f32 v[50:51], v[54:55], v[234:235] op_sel_hi:[0,1]
	v_pk_mul_f32 v[50:51], v[112:113], v[50:51]
	v_mov_b32_e32 v116, v129
	v_pk_mul_f32 v[56:57], v[128:129], v[50:51]
	v_pk_mul_f32 v[50:51], v[116:117], v[50:51]
	v_mov_b32_e32 v222, v94
	v_mov_b32_e32 v223, v98
	v_add_f32_e32 v94, v51, v50
	v_pk_mul_f32 v[50:51], v[54:55], v[218:219] op_sel_hi:[0,1]
	v_mov_b32_e32 v224, v102
	v_mov_b32_e32 v225, v122
	v_pk_mul_f32 v[50:51], v[50:51], v[222:223]
	v_mov_b32_e32 v156, v80
	v_sub_f32_e32 v80, v56, v57
	v_pk_mul_f32 v[56:57], v[50:51], v[224:225]
	v_mov_b32_e32 v196, v96
	v_sub_f32_e32 v96, v56, v57
	v_mov_b32_e32 v56, v122
	v_mov_b32_e32 v57, v102
	v_pk_mul_f32 v[50:51], v[50:51], v[56:57]
	v_mov_b32_e32 v98, v95
	v_add_f32_e32 v106, v51, v50
	v_pk_mul_f32 v[50:51], v[54:55], v[52:53] op_sel_hi:[0,1]
	v_pk_mul_f32 v[50:51], v[50:51], v[98:99]
	v_mov_b32_e32 v122, v103
; __device__ __forceinline__ unsigned cvt_pk_bf16(float lo, float hi) { unsigned r; asm volatile("v_cvt_pk_bf16_f32 %0, %1, %2" : "=v"(r) : "v"(lo), "v"(hi)); return r; }
; #define LAS __attribute__((address_space(3)))
; __device__ __forceinline__ void p2_block(LAS unsigned char* lds, const bf16_t* __restrict__ PROJ, bf16_t* __restrict__ ATT, bf16_t* __restrict__ SGU, const float* __restrict__ qn, const float* __restrict__ kn, ...
;     ...
;         float o1[16], o2[16];
; #pragma unroll
;         for (int j = 0; j < 16; ++j) { const float a1 = x1[j] * rinv * kn[16 * h + j], a2 = x2[j] * rinv * kn[32 + 16 * h + j], c = cp[j], sn = sp[j]; o1[j] = a1 * c - a2 * sn; o2[j] = a2 * c + a1 * sn; }
;         LAS unsigned char* kdst = KS + kk * KS_STRIDE + 32 * h;
;         u32x4 w0, w1;
;         w0.x = cvt_pk_bf16(o1[0], o1[1]); w0.y = cvt_pk_bf16(o1[2], o1[3]); w0.z = cvt_pk_bf16(o1[4], o1[5]); w0.w = cvt_pk_bf16(o1[6], o1[7]);
;         w1.x = cvt_pk_bf16(o1[8], o1[9]); w1.y = cvt_pk_bf16(o1[10], o1[11]); w1.z = cvt_pk_bf16(o1[12], o1[13]); w1.w = cvt_pk_bf16(o1[14], o1[15]);
;         *(LAS u32x4*)kdst = w0; *(LAS u32x4*)(kdst + 16) = w1;
;         w0.x = cvt_pk_bf16(o2[0], o2[1]); w0.y = cvt_pk_bf16(o2[2], o2[3]); w0.z = cvt_pk_bf16(o2[4], o2[5]); w0.w = cvt_pk_bf16(o2[6], o2[7]);
;         w1.x = cvt_pk_bf16(o2[8], o2[9]); w1.y = cvt_pk_bf16(o2[10], o2[11]); w1.z = cvt_pk_bf16(o2[12], o2[13]); w1.w = cvt_pk_bf16(o2[14], o2[15]);
;     ...
;         const float* gp = lng + gg * 128 + 32 * q4; const float* bp = lnb + gg * 128 + 32 * q4;
	v_mov_b32_e32 v102, v123
	v_pk_mul_f32 v[52:53], v[50:51], v[122:123]
	v_pk_mul_f32 v[50:51], v[50:51], v[102:103]
	v_mov_b32_e32 v197, v100
	v_add_f32_e32 v95, v51, v50
	v_pk_mul_f32 v[50:51], v[54:55], v[194:195] op_sel_hi:[0,1]
	v_mov_b32_e32 v198, v104
	v_mov_b32_e32 v199, v124
	v_pk_mul_f32 v[50:51], v[50:51], v[196:197]
	v_sub_f32_e32 v56, v52, v53
	v_pk_mul_f32 v[52:53], v[50:51], v[198:199]
	v_mov_b32_e32 v100, v97
	v_sub_f32_e32 v57, v52, v53
	v_mov_b32_e32 v52, v124
	v_mov_b32_e32 v53, v104
	v_pk_mul_f32 v[50:51], v[50:51], v[52:53]
	v_mov_b32_e32 v124, v105
	v_add_f32_e32 v98, v51, v50
	v_pk_mul_f32 v[50:51], v[54:55], v[200:201] op_sel_hi:[0,1]
	v_pk_mul_f32 v[50:51], v[50:51], v[100:101]
	v_mov_b32_e32 v104, v125
	v_pk_mul_f32 v[52:53], v[50:51], v[124:125]
	v_pk_mul_f32 v[50:51], v[50:51], v[104:105]
	v_mov_b32_e32 v191, v82
	v_add_f32_e32 v99, v51, v50
	v_pk_mul_f32 v[50:51], v[54:55], v[188:189] op_sel_hi:[0,1]
	v_mov_b32_e32 v192, v90
	v_mov_b32_e32 v193, v118
	v_pk_mul_f32 v[50:51], v[50:51], v[190:191]
	v_sub_f32_e32 v97, v52, v53
	v_pk_mul_f32 v[52:53], v[50:51], v[192:193]
	v_mov_b32_e32 v82, v79
	v_sub_f32_e32 v100, v52, v53
	v_mov_b32_e32 v52, v118
	v_mov_b32_e32 v53, v90
	v_pk_mul_f32 v[50:51], v[50:51], v[52:53]
	v_mov_b32_e32 v118, v91
	v_add_f32_e32 v101, v51, v50
	v_pk_mul_f32 v[50:51], v[54:55], v[58:59] op_sel_hi:[0,1]
	v_pk_mul_f32 v[50:51], v[50:51], v[82:83]
	v_mov_b32_e32 v90, v119
	v_pk_mul_f32 v[52:53], v[50:51], v[118:119]
	v_pk_mul_f32 v[50:51], v[50:51], v[90:91]
	v_mov_b32_e32 v157, v84
	v_add_f32_e32 v59, v51, v50
	v_pk_mul_f32 v[50:51], v[54:55], v[154:155] op_sel_hi:[0,1]
	v_mov_b32_e32 v158, v92
	v_mov_b32_e32 v159, v120
	v_pk_mul_f32 v[50:51], v[50:51], v[156:157]
	v_sub_f32_e32 v58, v52, v53
	v_pk_mul_f32 v[52:53], v[50:51], v[158:159]
	v_mov_b32_e32 v84, v81
	v_sub_f32_e32 v79, v52, v53
	v_mov_b32_e32 v52, v120
	v_mov_b32_e32 v53, v92
	v_pk_mul_f32 v[50:51], v[50:51], v[52:53]
	v_mov_b32_e32 v120, v93
	v_add_f32_e32 v82, v51, v50
	v_pk_mul_f32 v[50:51], v[54:55], v[64:65] op_sel_hi:[0,1]
	v_pk_mul_f32 v[50:51], v[50:51], v[84:85]
	v_mov_b32_e32 v92, v121
	v_pk_mul_f32 v[52:53], v[50:51], v[120:121]
	v_pk_mul_f32 v[50:51], v[50:51], v[92:93]
	v_mov_b32_e32 v151, v70
	v_add_f32_e32 v65, v51, v50
	v_pk_mul_f32 v[50:51], v[54:55], v[148:149] op_sel_hi:[0,1]
	v_mov_b32_e32 v152, v74
	v_mov_b32_e32 v153, v86
	v_pk_mul_f32 v[50:51], v[50:51], v[150:151]
	v_sub_f32_e32 v64, v52, v53
	v_pk_mul_f32 v[52:53], v[50:51], v[152:153]
	v_mov_b32_e32 v70, v67
	v_sub_f32_e32 v81, v52, v53
	v_mov_b32_e32 v52, v86
	v_mov_b32_e32 v53, v74
	v_pk_mul_f32 v[50:51], v[50:51], v[52:53]
	v_mov_b32_e32 v86, v75
	v_add_f32_e32 v83, v51, v50
	v_pk_mul_f32 v[50:51], v[54:55], v[60:61] op_sel_hi:[0,1]
	v_pk_mul_f32 v[50:51], v[50:51], v[70:71]
	v_mov_b32_e32 v74, v87
	v_pk_mul_f32 v[52:53], v[50:51], v[86:87]
	v_pk_mul_f32 v[50:51], v[50:51], v[74:75]
	v_mov_b32_e32 v145, v72
	v_add_f32_e32 v61, v51, v50
	v_pk_mul_f32 v[50:51], v[54:55], v[142:143] op_sel_hi:[0,1]
	v_mov_b32_e32 v146, v76
	v_mov_b32_e32 v147, v88
	v_pk_mul_f32 v[50:51], v[50:51], v[144:145]
	v_sub_f32_e32 v60, v52, v53
	v_pk_mul_f32 v[52:53], v[50:51], v[146:147]
	v_mov_b32_e32 v72, v69
	v_lshl_add_u32 v182, v165, 2, s4
	global_load_dwordx4 v[144:147], v182, s[36:37] offset:0
	global_load_dwordx4 v[148:151], v182, s[36:37] offset:16
	global_load_dwordx4 v[152:155], v182, s[36:37] offset:32
	global_load_dwordx4 v[156:159], v182, s[36:37] offset:48
	global_load_dwordx4 v[184:187], v182, s[36:37] offset:64
	global_load_dwordx4 v[188:191], v182, s[36:37] offset:80
	global_load_dwordx4 v[192:195], v182, s[36:37] offset:96
	global_load_dwordx4 v[196:199], v182, s[36:37] offset:112
	global_load_dwordx4 v[218:221], v182, s[18:19] offset:0
	global_load_dwordx4 v[222:225], v182, s[18:19] offset:16
	global_load_dwordx4 v[226:229], v182, s[18:19] offset:32
	global_load_dwordx4 v[230:233], v182, s[18:19] offset:48
	global_load_dwordx4 v[234:237], v182, s[18:19] offset:64
	global_load_dwordx4 v[238:241], v182, s[18:19] offset:80
	global_load_dwordx4 v[242:245], v182, s[18:19] offset:96
	global_load_dwordx4 v[200:203], v182, s[18:19] offset:112
	v_sub_f32_e32 v67, v52, v53
	v_mov_b32_e32 v52, v88
	v_mov_b32_e32 v53, v76
	v_pk_mul_f32 v[50:51], v[50:51], v[52:53]
	v_mov_b32_e32 v88, v77
	v_add_f32_e32 v70, v51, v50
	v_pk_mul_f32 v[50:51], v[54:55], v[140:141] op_sel_hi:[0,1]
	v_pk_mul_f32 v[50:51], v[50:51], v[72:73]
	v_mov_b32_e32 v76, v89
	v_pk_mul_f32 v[52:53], v[50:51], v[88:89]
	v_pk_mul_f32 v[50:51], v[50:51], v[76:77]
	v_sub_f32_e32 v69, v52, v53
	v_add_f32_e32 v71, v51, v50
	v_mul_lo_u32 v50, v167, s59
	v_add3_u32 v0, 0, v50, v0
	v_cvt_pk_bf16_f32 v50, v55, v63
	v_cvt_pk_bf16_f32 v51, v68, v80
	v_cvt_pk_bf16_f32 v52, v96, v56
	v_cvt_pk_bf16_f32 v53, v57, v97
	v_cvt_pk_bf16_f32 v54, v100, v58
	v_cvt_pk_bf16_f32 v55, v79, v64
	v_cvt_pk_bf16_f32 v56, v81, v60
	v_cvt_pk_bf16_f32 v57, v67, v69
	s_waitcnt vmcnt(20)
; __device__ __forceinline__ unsigned cvt_pk_bf16(float lo, float hi) { unsigned r; asm volatile("v_cvt_pk_bf16_f32 %0, %1, %2" : "=v"(r) : "v"(lo), "v"(hi)); return r; }
; __device__ __forceinline__ float gelu_f(float x) { const float y2 = 1.5957691216057308f * x * (1.0f + 0.044715f * x * x); return x * sigmoid_f(y2); }
; #define LAS __attribute__((address_space(3)))
; __device__ __forceinline__ void unpack8(const u32x4 w, float* f) { f[0] = bf_lo(w.x); f[1] = bf_hi(w.x); f[2] = bf_lo(w.y); f[3] = bf_hi(w.y); f[4] = bf_lo(w.z); f[5] = bf_hi(w.z); f[6] = bf_lo(w.w); f[7] = bf_hi(w.w); }
; __device__ __forceinline__ void p2_block(LAS unsigned char* lds, const bf16_t* __restrict__ PROJ, bf16_t* __restrict__ ATT, bf16_t* __restrict__ SGU, const float* __restrict__ qn, const float* __restrict__ kn, ...
;     ...
;         *(LAS u32x4*)kdst = w0; *(LAS u32x4*)(kdst + 16) = w1;
;         w0.x = cvt_pk_bf16(o2[0], o2[1]); w0.y = cvt_pk_bf16(o2[2], o2[3]); w0.z = cvt_pk_bf16(o2[4], o2[5]); w0.w = cvt_pk_bf16(o2[6], o2[7]);
;         w1.x = cvt_pk_bf16(o2[8], o2[9]); w1.y = cvt_pk_bf16(o2[10], o2[11]); w1.z = cvt_pk_bf16(o2[12], o2[13]); w1.w = cvt_pk_bf16(o2[14], o2[15]);
;         *(LAS u32x4*)(kdst + 64) = w0; *(LAS u32x4*)(kdst + 80) = w1;
;     ...
;         float v[32];
; #pragma unroll
;         for (int c4 = 0; c4 < 4; ++c4) unpack8(sv[gi][c4], v + 8 * c4);
;         float sm = 0.f;
; #pragma unroll
;         for (int j = 0; j < 32; ++j) { v[j] = gelu_f(v[j]); sm += v[j]; }
	v_lshlrev_b32_e32 v73, 16, v46
	ds_write_b128 v0, v[50:53]
	ds_write_b128 v0, v[54:57] offset:16
	v_cvt_pk_bf16_f32 v50, v62, v66
	v_cvt_pk_bf16_f32 v51, v78, v94
	v_cvt_pk_bf16_f32 v52, v106, v95
	v_cvt_pk_bf16_f32 v53, v98, v99
	v_cvt_pk_bf16_f32 v54, v101, v59
	v_cvt_pk_bf16_f32 v55, v82, v65
	v_cvt_pk_bf16_f32 v56, v83, v61
	v_cvt_pk_bf16_f32 v57, v70, v71
	v_lshlrev_b32_e32 v70, 16, v48
	v_and_b32_e32 v69, 0xffff0000, v48
	v_lshlrev_b32_e32 v68, 16, v49
	v_and_b32_e32 v67, 0xffff0000, v49
	v_lshlrev_b32_e32 v66, 16, v42
	v_and_b32_e32 v65, 0xffff0000, v42
	v_lshlrev_b32_e32 v64, 16, v43
	v_and_b32_e32 v63, 0xffff0000, v43
	v_lshlrev_b32_e32 v62, 16, v44
	v_and_b32_e32 v61, 0xffff0000, v44
	v_lshlrev_b32_e32 v60, 16, v45
	v_and_b32_e32 v59, 0xffff0000, v45
	v_lshlrev_b32_e32 v49, 16, v40
	v_and_b32_e32 v48, 0xffff0000, v40
	v_lshlrev_b32_e32 v45, 16, v41
	v_and_b32_e32 v44, 0xffff0000, v41
	v_lshlrev_b32_e32 v43, 16, v34
	v_and_b32_e32 v42, 0xffff0000, v34
	v_lshlrev_b32_e32 v41, 16, v35
	v_and_b32_e32 v40, 0xffff0000, v35
	v_lshlrev_b32_e32 v35, 16, v37
	v_and_b32_e32 v34, 0xffff0000, v37
	v_mul_f32_e32 v37, 0x3d372713, v73
	ds_write_b128 v0, v[50:53] offset:64
	ds_write_b128 v0, v[54:57] offset:80
	v_lshlrev_b32_e32 v58, 16, v38
	v_and_b32_e32 v57, 0xffff0000, v38
	v_lshlrev_b32_e32 v56, 16, v39
	v_and_b32_e32 v55, 0xffff0000, v39
	v_lshlrev_b32_e32 v39, 16, v36
	v_and_b32_e32 v38, 0xffff0000, v36
	v_mul_f32_e32 v36, 0x3fcc422a, v73
	v_fma_f32 v37, v37, v73, 1.0
	v_mul_f32_e32 v36, v36, v37
	v_mul_f32_e32 v36, 0xbfb8aa3b, v36
	v_exp_f32_e32 v36, v36
	v_and_b32_e32 v74, 0xffff0000, v46
	v_mul_f32_e32 v37, 0x3d372713, v74
	v_fma_f32 v37, v37, v74, 1.0
	v_add_f32_e32 v36, 1.0, v36
	v_rcp_f32_e32 v75, v36
	v_mul_f32_e32 v36, 0x3fcc422a, v74
	v_mul_f32_e32 v36, v36, v37
	v_mul_f32_e32 v36, 0xbfb8aa3b, v36
	v_exp_f32_e32 v36, v36
	v_lshlrev_b32_e32 v72, 16, v47
	v_mul_f32_e32 v37, 0x3d372713, v72
	v_fma_f32 v37, v37, v72, 1.0
	v_add_f32_e32 v36, 1.0, v36
	v_rcp_f32_e32 v76, v36
	v_mul_f32_e32 v36, 0x3fcc422a, v72
	v_mul_f32_e32 v36, v36, v37
	v_mul_f32_e32 v36, 0xbfb8aa3b, v36
	v_exp_f32_e32 v36, v36
	v_and_b32_e32 v71, 0xffff0000, v47
	v_mul_f32_e32 v37, 0x3d372713, v71
	v_fma_f32 v37, v37, v71, 1.0
	v_add_f32_e32 v36, 1.0, v36
	v_rcp_f32_e32 v77, v36
	v_mul_f32_e32 v36, 0x3fcc422a, v71
	v_mul_f32_e32 v36, v36, v37
	v_mul_f32_e32 v36, 0xbfb8aa3b, v36
	v_exp_f32_e32 v36, v36
	v_mul_f32_e32 v37, 0x3d372713, v70
	v_fma_f32 v37, v37, v70, 1.0
	v_fma_f32 v46, v75, v73, 0
	v_add_f32_e32 v36, 1.0, v36
	v_rcp_f32_e32 v78, v36
	v_mul_f32_e32 v36, 0x3fcc422a, v70
	v_mul_f32_e32 v36, v36, v37
	v_mul_f32_e32 v36, 0xbfb8aa3b, v36
	v_exp_f32_e32 v36, v36
	v_mul_f32_e32 v37, 0x3d372713, v69
	v_fma_f32 v37, v37, v69, 1.0
	v_fmac_f32_e32 v46, v76, v74
	v_add_f32_e32 v36, 1.0, v36
	v_rcp_f32_e32 v79, v36
	v_mul_f32_e32 v36, 0x3fcc422a, v69
	v_mul_f32_e32 v36, v36, v37
	v_mul_f32_e32 v36, 0xbfb8aa3b, v36
	v_exp_f32_e32 v36, v36
	v_mul_f32_e32 v37, 0x3d372713, v68
	v_fma_f32 v37, v37, v68, 1.0
	v_fmac_f32_e32 v46, v77, v72
	v_add_f32_e32 v36, 1.0, v36
	v_rcp_f32_e32 v80, v36
	v_mul_f32_e32 v36, 0x3fcc422a, v68
	v_mul_f32_e32 v36, v36, v37
	v_mul_f32_e32 v36, 0xbfb8aa3b, v36
	v_exp_f32_e32 v36, v36
	v_mul_f32_e32 v37, 0x3d372713, v67
	v_fma_f32 v37, v37, v67, 1.0
	v_fmac_f32_e32 v46, v78, v71
	v_add_f32_e32 v36, 1.0, v36
	v_rcp_f32_e32 v81, v36
	v_mul_f32_e32 v36, 0x3fcc422a, v67
	v_mul_f32_e32 v36, v36, v37
	v_mul_f32_e32 v36, 0xbfb8aa3b, v36
	v_exp_f32_e32 v36, v36
	v_mul_f32_e32 v37, 0x3d372713, v66
	v_fma_f32 v37, v37, v66, 1.0
	v_fmac_f32_e32 v46, v79, v70
	v_add_f32_e32 v36, 1.0, v36
	v_rcp_f32_e32 v82, v36
	v_mul_f32_e32 v36, 0x3fcc422a, v66
	v_mul_f32_e32 v36, v36, v37
	v_mul_f32_e32 v36, 0xbfb8aa3b, v36
	v_exp_f32_e32 v36, v36
	v_mul_f32_e32 v37, 0x3d372713, v65
	v_fma_f32 v37, v37, v65, 1.0
	v_fmac_f32_e32 v46, v80, v69
	v_add_f32_e32 v36, 1.0, v36
	v_rcp_f32_e32 v84, v36
	v_mul_f32_e32 v36, 0x3fcc422a, v65
	v_mul_f32_e32 v36, v36, v37
	v_mul_f32_e32 v36, 0xbfb8aa3b, v36
	v_exp_f32_e32 v36, v36
	v_mul_f32_e32 v37, 0x3d372713, v64
	v_fma_f32 v37, v37, v64, 1.0
	v_fmac_f32_e32 v46, v81, v68
	v_add_f32_e32 v36, 1.0, v36
	v_rcp_f32_e32 v85, v36
	v_mul_f32_e32 v36, 0x3fcc422a, v64
	v_mul_f32_e32 v36, v36, v37
	v_mul_f32_e32 v36, 0xbfb8aa3b, v36
	v_exp_f32_e32 v36, v36
	v_mul_f32_e32 v37, 0x3d372713, v63
	v_fma_f32 v37, v37, v63, 1.0
	v_fmac_f32_e32 v46, v82, v67
	v_add_f32_e32 v36, 1.0, v36
	v_rcp_f32_e32 v86, v36
	v_mul_f32_e32 v36, 0x3fcc422a, v63
	v_mul_f32_e32 v36, v36, v37
	v_mul_f32_e32 v36, 0xbfb8aa3b, v36
	v_exp_f32_e32 v36, v36
	v_mul_f32_e32 v37, 0x3d372713, v62
	v_fma_f32 v37, v37, v62, 1.0
	v_fmac_f32_e32 v46, v84, v66
	v_add_f32_e32 v36, 1.0, v36
	v_rcp_f32_e32 v87, v36
	v_mul_f32_e32 v36, 0x3fcc422a, v62
	v_mul_f32_e32 v36, v36, v37
	v_mul_f32_e32 v36, 0xbfb8aa3b, v36
	v_exp_f32_e32 v36, v36
	v_mul_f32_e32 v37, 0x3d372713, v61
	v_fma_f32 v37, v37, v61, 1.0
	v_fmac_f32_e32 v46, v85, v65
	v_add_f32_e32 v36, 1.0, v36
	v_rcp_f32_e32 v88, v36
	v_mul_f32_e32 v36, 0x3fcc422a, v61
	v_mul_f32_e32 v36, v36, v37
	v_mul_f32_e32 v36, 0xbfb8aa3b, v36
	v_exp_f32_e32 v36, v36
	v_mul_f32_e32 v37, 0x3d372713, v60
	v_fma_f32 v37, v37, v60, 1.0
	v_fmac_f32_e32 v46, v86, v64
	v_add_f32_e32 v36, 1.0, v36
	v_rcp_f32_e32 v89, v36
	v_mul_f32_e32 v36, 0x3fcc422a, v60
	v_mul_f32_e32 v36, v36, v37
	v_mul_f32_e32 v36, 0xbfb8aa3b, v36
	v_exp_f32_e32 v36, v36
	v_mul_f32_e32 v37, 0x3d372713, v59
	v_fma_f32 v37, v37, v59, 1.0
	v_mul_f32_e32 v47, 0x3d372713, v42
	v_add_f32_e32 v36, 1.0, v36
	v_rcp_f32_e32 v90, v36
	v_mul_f32_e32 v36, 0x3fcc422a, v59
	v_mul_f32_e32 v36, v36, v37
; __device__ __forceinline__ float gelu_f(float x) { const float y2 = 1.5957691216057308f * x * (1.0f + 0.044715f * x * x); return x * sigmoid_f(y2); }
; #define LAS __attribute__((address_space(3)))
; __device__ __forceinline__ void p2_block(LAS unsigned char* lds, const bf16_t* __restrict__ PROJ, bf16_t* __restrict__ ATT, bf16_t* __restrict__ SGU, const float* __restrict__ qn, const float* __restrict__ kn, ...
;     ...
; #pragma unroll
;         for (int c4 = 0; c4 < 4; ++c4) { u32x4 t = vv[c4]; if (s < 0) t = (u32x4){0u, 0u, 0u, 0u};
;             LAS unsigned char* vd = VT + (32 * h + 8 * c4) * VT_STRIDE + kk * 2;
;             *(LAS unsigned short*)(vd + 0 * VT_STRIDE) = (unsigned short)(t.x & 0xffffu); *(LAS unsigned short*)(vd + 1 * VT_STRIDE) = (unsigned short)(t.x >> 16);
;             *(LAS unsigned short*)(vd + 2 * VT_STRIDE) = (unsigned short)(t.y & 0xffffu); *(LAS unsigned short*)(vd + 3 * VT_STRIDE) = (unsigned short)(t.y >> 16);
;             *(LAS unsigned short*)(vd + 4 * VT_STRIDE) = (unsigned short)(t.z & 0xffffu); *(LAS unsigned short*)(vd + 5 * VT_STRIDE) = (unsigned short)(t.z >> 16);
;             *(LAS unsigned short*)(vd + 6 * VT_STRIDE) = (unsigned short)(t.w & 0xffffu); *(LAS unsigned short*)(vd + 7 * VT_STRIDE) = (unsigned short)(t.w >> 16); }
;     ...
;         for (int j = 0; j < 32; ++j) { v[j] = gelu_f(v[j]); sm += v[j]; }
	v_mul_f32_e32 v36, 0xbfb8aa3b, v36
	v_exp_f32_e32 v36, v36
	v_mul_f32_e32 v37, 0x3d372713, v58
	v_fma_f32 v37, v37, v58, 1.0
	v_fmac_f32_e32 v46, v87, v63
	v_add_f32_e32 v36, 1.0, v36
	v_rcp_f32_e32 v91, v36
	v_mul_f32_e32 v36, 0x3fcc422a, v58
	v_mul_f32_e32 v36, v36, v37
	v_mul_f32_e32 v36, 0xbfb8aa3b, v36
	v_exp_f32_e32 v36, v36
	v_mul_f32_e32 v37, 0x3d372713, v57
	v_fma_f32 v37, v37, v57, 1.0
	v_fma_f32 v47, v47, v42, 1.0
	v_add_f32_e32 v36, 1.0, v36
	v_rcp_f32_e32 v98, v36
	v_mul_f32_e32 v36, 0x3fcc422a, v57
	v_mul_f32_e32 v36, v36, v37
	v_mul_f32_e32 v36, 0xbfb8aa3b, v36
	v_exp_f32_e32 v36, v36
	v_mul_f32_e32 v37, 0x3d372713, v56
	v_fma_f32 v37, v37, v56, 1.0
	v_fmac_f32_e32 v46, v88, v62
	v_add_f32_e32 v36, 1.0, v36
	v_rcp_f32_e32 v99, v36
	v_mul_f32_e32 v36, 0x3fcc422a, v56
	v_mul_f32_e32 v36, v36, v37
	v_mul_f32_e32 v36, 0xbfb8aa3b, v36
	v_exp_f32_e32 v36, v36
	v_mul_f32_e32 v37, 0x3d372713, v55
	v_fma_f32 v37, v37, v55, 1.0
	v_fmac_f32_e32 v46, v89, v61
	v_add_f32_e32 v36, 1.0, v36
	v_rcp_f32_e32 v100, v36
	v_mul_f32_e32 v36, 0x3fcc422a, v55
	v_mul_f32_e32 v36, v36, v37
	v_mul_f32_e32 v36, 0xbfb8aa3b, v36
	v_exp_f32_e32 v36, v36
	v_mul_f32_e32 v37, 0x3d372713, v49
	v_fma_f32 v37, v37, v49, 1.0
	v_fmac_f32_e32 v46, v90, v60
	v_add_f32_e32 v36, 1.0, v36
	v_rcp_f32_e32 v101, v36
	v_mul_f32_e32 v36, 0x3fcc422a, v49
	v_mul_f32_e32 v36, v36, v37
	v_mul_f32_e32 v36, 0xbfb8aa3b, v36
	v_exp_f32_e32 v36, v36
	v_mul_f32_e32 v37, 0x3d372713, v48
	v_fma_f32 v37, v37, v48, 1.0
	v_fmac_f32_e32 v46, v91, v59
	v_add_f32_e32 v36, 1.0, v36
	v_rcp_f32_e32 v102, v36
	v_mul_f32_e32 v36, 0x3fcc422a, v48
	v_mul_f32_e32 v36, v36, v37
	v_mul_f32_e32 v36, 0xbfb8aa3b, v36
	v_exp_f32_e32 v36, v36
	v_mul_f32_e32 v37, 0x3d372713, v45
	v_fma_f32 v37, v37, v45, 1.0
	v_fmac_f32_e32 v46, v98, v58
	v_add_f32_e32 v36, 1.0, v36
	v_rcp_f32_e32 v103, v36
	v_mul_f32_e32 v36, 0x3fcc422a, v45
	v_mul_f32_e32 v36, v36, v37
	v_mul_f32_e32 v36, 0xbfb8aa3b, v36
	v_exp_f32_e32 v36, v36
	v_mul_f32_e32 v37, 0x3d372713, v44
	v_fma_f32 v37, v37, v44, 1.0
	v_fmac_f32_e32 v46, v99, v57
	v_add_f32_e32 v36, 1.0, v36
	v_rcp_f32_e32 v104, v36
	v_mul_f32_e32 v36, 0x3fcc422a, v44
	v_mul_f32_e32 v36, v36, v37
	v_mul_f32_e32 v36, 0xbfb8aa3b, v36
	v_exp_f32_e32 v36, v36
	v_mul_f32_e32 v37, 0x3d372713, v43
	v_fma_f32 v37, v37, v43, 1.0
	v_fmac_f32_e32 v46, v100, v56
	v_add_f32_e32 v36, 1.0, v36
	v_rcp_f32_e32 v105, v36
	v_mul_f32_e32 v36, 0x3fcc422a, v43
	v_mul_f32_e32 v36, v36, v37
	v_mul_f32_e32 v36, 0xbfb8aa3b, v36
	v_exp_f32_e32 v36, v36
	v_fmac_f32_e32 v46, v101, v55
	v_fmac_f32_e32 v46, v102, v49
	v_fmac_f32_e32 v46, v103, v48
	v_add_f32_e32 v36, 1.0, v36
	v_rcp_f32_e32 v37, v36
	v_mul_f32_e32 v36, 0x3fcc422a, v42
	v_mul_f32_e32 v36, v36, v47
	v_mul_f32_e32 v36, 0xbfb8aa3b, v36
	v_exp_f32_e32 v36, v36
	v_fmac_f32_e32 v46, v104, v45
	v_fmac_f32_e32 v46, v105, v44
	v_mul_f32_e32 v47, 0x3d372713, v41
	v_add_f32_e32 v36, 1.0, v36
	v_rcp_f32_e32 v36, v36
	v_fma_f32 v47, v47, v41, 1.0
	v_mul_f32_e32 v94, 0x3d372713, v38
	v_fma_f32 v94, v94, v38, 1.0
	v_pk_mul_f32 v[92:93], v[36:37], v[42:43]
	v_mul_f32_e32 v96, 0x3d372713, v34
	v_add_f32_e32 v46, v93, v46
	v_add_f32_e32 v83, v92, v46
	v_mul_f32_e32 v46, 0x3fcc422a, v41
	v_mul_f32_e32 v46, v46, v47
	v_mul_f32_e32 v46, 0xbfb8aa3b, v46
	v_exp_f32_e32 v46, v46
	v_mul_f32_e32 v92, 0x3d372713, v40
	v_fma_f32 v92, v92, v40, 1.0
	v_fma_f32 v96, v96, v34, 1.0
	v_add_f32_e32 v46, 1.0, v46
	v_rcp_f32_e32 v47, v46
	v_mul_f32_e32 v46, 0x3fcc422a, v40
	v_mul_f32_e32 v46, v46, v92
	v_mul_f32_e32 v46, 0xbfb8aa3b, v46
	v_exp_f32_e32 v46, v46
	v_and_b32_e32 v0, -2, v160
	v_mul_u32_u24_e32 v50, 0x4200, v166
	s_waitcnt vmcnt(16)
	v_cndmask_b32_e64 v18, v18, 0, vcc
	v_add_f32_e32 v46, 1.0, v46
	v_rcp_f32_e32 v46, v46
	v_add3_u32 v0, 0, v0, v50
	v_cndmask_b32_e64 v14, v14, 0, vcc
	v_cndmask_b32_e64 v10, v10, 0, vcc
	v_pk_mul_f32 v[92:93], v[46:47], v[40:41]
	v_cndmask_b32_e64 v6, v6, 0, vcc
	v_add_f32_e32 v83, v93, v83
	v_mul_f32_e32 v93, 0x3d372713, v39
	v_add_f32_e32 v83, v92, v83
	v_mul_f32_e32 v92, 0x3fcc422a, v39
	v_fma_f32 v93, v93, v39, 1.0
	v_mul_f32_e32 v92, v92, v93
	v_mul_f32_e32 v92, 0xbfb8aa3b, v92
	v_exp_f32_e32 v92, v92
	v_cndmask_b32_e64 v21, v21, 0, vcc
	v_cndmask_b32_e64 v20, v20, 0, vcc
	v_cndmask_b32_e64 v19, v19, 0, vcc
	v_add_f32_e32 v92, 1.0, v92
	v_rcp_f32_e32 v93, v92
	v_mul_f32_e32 v92, 0x3fcc422a, v38
	v_mul_f32_e32 v92, v92, v94
	v_mul_f32_e32 v92, 0xbfb8aa3b, v92
	v_exp_f32_e32 v92, v92
	ds_write_b16 v0, v18 offset:36864
	ds_write_b16_d16_hi v0, v18 offset:37392
	ds_write_b16 v0, v19 offset:37920
	ds_write_b16_d16_hi v0, v19 offset:38448
	ds_write_b16 v0, v20 offset:38976
	ds_write_b16_d16_hi v0, v20 offset:39504
	ds_write_b16 v0, v21 offset:40032
	ds_write_b16_d16_hi v0, v21 offset:40560
	v_cndmask_b32_e64 v17, v17, 0, vcc
	v_cndmask_b32_e64 v16, v16, 0, vcc
	v_add_f32_e32 v92, 1.0, v92
	v_rcp_f32_e32 v92, v92
	v_cndmask_b32_e64 v15, v15, 0, vcc
	ds_write_b16 v0, v14 offset:41088
	ds_write_b16_d16_hi v0, v14 offset:41616
	ds_write_b16 v0, v15 offset:42144
	ds_write_b16_d16_hi v0, v15 offset:42672
	ds_write_b16 v0, v16 offset:43200
	ds_write_b16_d16_hi v0, v16 offset:43728
	ds_write_b16 v0, v17 offset:44256
	ds_write_b16_d16_hi v0, v17 offset:44784
	v_cndmask_b32_e64 v13, v13, 0, vcc
	v_pk_mul_f32 v[94:95], v[92:93], v[38:39]
	v_cndmask_b32_e64 v12, v12, 0, vcc
	v_add_f32_e32 v83, v95, v83
	v_mul_f32_e32 v95, 0x3d372713, v35
	v_add_f32_e32 v83, v94, v83
	v_mul_f32_e32 v94, 0x3fcc422a, v35
	v_fma_f32 v95, v95, v35, 1.0
	v_mul_f32_e32 v94, v94, v95
	v_mul_f32_e32 v94, 0xbfb8aa3b, v94
	v_exp_f32_e32 v94, v94
	v_cndmask_b32_e64 v11, v11, 0, vcc
; __device__ __forceinline__ float gelu_f(float x) { const float y2 = 1.5957691216057308f * x * (1.0f + 0.044715f * x * x); return x * sigmoid_f(y2); }
; #define LAS __attribute__((address_space(3)))
; __device__ __forceinline__ void unpack8(const u32x4 w, float* f) { f[0] = bf_lo(w.x); f[1] = bf_hi(w.x); f[2] = bf_lo(w.y); f[3] = bf_hi(w.y); f[4] = bf_lo(w.z); f[5] = bf_hi(w.z); f[6] = bf_lo(w.w); f[7] = bf_hi(w.w); }
; __device__ __forceinline__ void p2_block(LAS unsigned char* lds, const bf16_t* __restrict__ PROJ, bf16_t* __restrict__ ATT, bf16_t* __restrict__ SGU, const float* __restrict__ qn, const float* __restrict__ kn, ...
;     ...
;             *(LAS unsigned short*)(vd + 6 * VT_STRIDE) = (unsigned short)(t.w & 0xffffu); *(LAS unsigned short*)(vd + 7 * VT_STRIDE) = (unsigned short)(t.w >> 16); }
;     }
; #pragma unroll
;     for (int gi = 0; gi < 2; ++gi) {
;         const int gg = 2 * kvh + gi;
;         if (gi == 0) {
; #pragma unroll
;             for (int c4 = 0; c4 < 4; ++c4) sv[1][c4] = *(const u32x4*)(svsrc + 128 + 8 * c4); }
;         float v[32];
; #pragma unroll
;         for (int c4 = 0; c4 < 4; ++c4) unpack8(sv[gi][c4], v + 8 * c4);
;         float sm = 0.f;
; #pragma unroll
;         for (int j = 0; j < 32; ++j) { v[j] = gelu_f(v[j]); sm += v[j]; }
;         sm += __shfl_xor(sm, 1); sm += __shfl_xor(sm, 2);
;         const float mu = sm * (1.0f / 128.0f); float q = 0.f;
; #pragma unroll
;         for (int j = 0; j < 32; ++j) { v[j] -= mu; q += v[j] * v[j]; }
;         q += __shfl_xor(q, 1); q += __shfl_xor(q, 2);
;         const float rstd = rsqrtf(q * (1.0f / 128.0f) + pg8::EPS);
	ds_write_b16 v0, v10 offset:45312
	ds_write_b16_d16_hi v0, v10 offset:45840
	ds_write_b16 v0, v11 offset:46368
	ds_write_b16_d16_hi v0, v11 offset:46896
	ds_write_b16 v0, v12 offset:47424
	ds_write_b16_d16_hi v0, v12 offset:47952
	ds_write_b16 v0, v13 offset:48480
	ds_write_b16_d16_hi v0, v13 offset:49008
	v_cndmask_b32_e64 v9, v9, 0, vcc
	v_add_f32_e32 v94, 1.0, v94
	v_rcp_f32_e32 v95, v94
	v_mul_f32_e32 v94, 0x3fcc422a, v34
	v_mul_f32_e32 v94, v94, v96
	v_mul_f32_e32 v94, 0xbfb8aa3b, v94
	v_exp_f32_e32 v94, v94
	v_cndmask_b32_e64 v8, v8, 0, vcc
	v_cndmask_b32_e64 v7, v7, 0, vcc
	ds_write_b16 v0, v6 offset:49536
	ds_write_b16_d16_hi v0, v6 offset:50064
	ds_write_b16 v0, v7 offset:50592
	ds_write_b16_d16_hi v0, v7 offset:51120
	ds_write_b16 v0, v8 offset:51648
	ds_write_b16_d16_hi v0, v8 offset:52176
	ds_write_b16 v0, v9 offset:52704
	ds_write_b16_d16_hi v0, v9 offset:53232
	v_add_f32_e32 v94, 1.0, v94
	v_rcp_f32_e32 v94, v94
	v_xor_b32_e32 v0, 2, v211
	v_cmp_lt_i32_e32 vcc, v0, v133
	v_lshlrev_b32_e32 v6, 1, v136
	v_pk_mul_f32 v[96:97], v[94:95], v[34:35]
	v_cndmask_b32_e32 v0, v211, v0, vcc
	v_add_f32_e32 v83, v97, v83
	v_add_f32_e32 v83, v96, v83
	s_nop 1
	v_mov_b32_dpp v96, v83 quad_perm:[1,0,3,2] row_mask:0xf bank_mask:0xf
	v_lshlrev_b32_e32 v54, 2, v0
	v_lshlrev_b32_e32 v0, 2, v165
	v_lshl_add_u64 v[50:51], s[36:37], 0, v[0:1]
	v_lshl_add_u64 v[52:53], s[18:19], 0, v[0:1]
	s_waitcnt lgkmcnt(0)
	v_add_f32_e32 v83, v83, v96
	s_nop 1
	v_mov_b32_dpp v96, v83 quad_perm:[2,3,0,1] row_mask:0xf bank_mask:0xf
	v_mul_u32_u24_e32 v0, 0x110, v165
	v_add3_u32 v0, 0, v0, v6
	global_load_dwordx4 v[6:9], v[138:139], off offset:304
	global_load_dwordx4 v[10:13], v[138:139], off offset:288
	global_load_dwordx4 v[14:17], v[138:139], off offset:272
	global_load_dwordx4 v[18:21], v[138:139], off offset:256
	s_ashr_i32 s43, s42, 31
	s_waitcnt lgkmcnt(0)
	v_add_f32_e32 v83, v83, v96
	v_mul_f32_e32 v96, 0x3c000000, v83
	v_fma_f32 v83, v76, v74, -v96
	v_fma_f32 v97, v75, v73, -v96
	v_mul_f32_e32 v106, v83, v83
	v_fmac_f32_e32 v106, v97, v97
	v_fma_f32 v77, v77, v72, -v96
	v_fmac_f32_e32 v106, v77, v77
	v_fma_f32 v76, v78, v71, -v96
	v_fmac_f32_e32 v106, v76, v76
	v_fma_f32 v75, v79, v70, -v96
	v_fmac_f32_e32 v106, v75, v75
	v_fma_f32 v74, v80, v69, -v96
	v_fmac_f32_e32 v106, v74, v74
	v_fma_f32 v73, v81, v68, -v96
	v_fmac_f32_e32 v106, v73, v73
	v_fma_f32 v72, v82, v67, -v96
	v_fmac_f32_e32 v106, v72, v72
	v_fma_f32 v71, v84, v66, -v96
	v_fmac_f32_e32 v106, v71, v71
	v_fma_f32 v70, v85, v65, -v96
	v_fmac_f32_e32 v106, v70, v70
	v_fma_f32 v69, v86, v64, -v96
	v_fmac_f32_e32 v106, v69, v69
	v_fma_f32 v68, v87, v63, -v96
	v_fmac_f32_e32 v106, v68, v68
	v_fma_f32 v67, v88, v62, -v96
	v_fmac_f32_e32 v106, v67, v67
	v_fma_f32 v66, v89, v61, -v96
	v_fmac_f32_e32 v106, v66, v66
	v_fma_f32 v65, v90, v60, -v96
	v_fmac_f32_e32 v106, v65, v65
	v_fma_f32 v64, v91, v59, -v96
	v_fmac_f32_e32 v106, v64, v64
	v_fma_f32 v63, v98, v58, -v96
	v_fmac_f32_e32 v106, v63, v63
	v_fma_f32 v62, v99, v57, -v96
	v_fmac_f32_e32 v106, v62, v62
	v_fma_f32 v61, v100, v56, -v96
	v_fmac_f32_e32 v106, v61, v61
	v_fma_f32 v60, v101, v55, -v96
	v_fmac_f32_e32 v106, v60, v60
	v_fma_f32 v59, v102, v49, -v96
	v_fmac_f32_e32 v106, v59, v59
	v_fma_f32 v58, v103, v48, -v96
	v_fmac_f32_e32 v106, v58, v58
	v_fma_f32 v57, v104, v45, -v96
	v_fmac_f32_e32 v106, v57, v57
	v_fma_f32 v56, v105, v44, -v96
	v_pk_fma_f32 v[44:45], v[36:37], v[42:43], v[96:97] op_sel_hi:[1,1,0] neg_lo:[0,0,1] neg_hi:[0,0,1]
	v_fmac_f32_e32 v106, v56, v56
	v_pk_mul_f32 v[36:37], v[44:45], v[44:45]
	v_pk_fma_f32 v[42:43], v[46:47], v[40:41], v[96:97] op_sel_hi:[1,1,0] neg_lo:[0,0,1] neg_hi:[0,0,1]
	v_add_f32_e32 v37, v37, v106
	v_add_f32_e32 v48, v36, v37
	v_pk_mul_f32 v[36:37], v[42:43], v[42:43]
	v_pk_fma_f32 v[40:41], v[92:93], v[38:39], v[96:97] op_sel_hi:[1,1,0] neg_lo:[0,0,1] neg_hi:[0,0,1]
	v_add_f32_e32 v37, v37, v48
	v_add_f32_e32 v46, v36, v37
	v_pk_mul_f32 v[36:37], v[40:41], v[40:41]
	v_pk_fma_f32 v[38:39], v[94:95], v[34:35], v[96:97] op_sel_hi:[1,1,0] neg_lo:[0,0,1] neg_hi:[0,0,1]
	v_add_f32_e32 v37, v37, v46
	v_add_f32_e32 v36, v36, v37
	v_pk_mul_f32 v[34:35], v[38:39], v[38:39]
	v_lshlrev_b32_e32 v105, 16, v3
	v_add_f32_e32 v35, v35, v36
	v_add_f32_e32 v34, v34, v35
	s_nop 1
	v_mov_b32_dpp v35, v34 quad_perm:[1,0,3,2] row_mask:0xf bank_mask:0xf
	v_lshl_add_u64 v[36:37], v[52:53], 0, s[4:5]
	v_and_b32_e32 v109, 0xffff0000, v3
	v_lshlrev_b32_e32 v113, 16, v2
	v_lshlrev_b32_e32 v112, 16, v30
	s_waitcnt lgkmcnt(0)
	v_add_f32_e32 v34, v34, v35
	s_nop 1
	v_mov_b32_dpp v35, v34 quad_perm:[2,3,0,1] row_mask:0xf bank_mask:0xf
	v_and_b32_e32 v3, 0xffff0000, v2
	v_and_b32_e32 v2, 0xffff0000, v30
	v_and_b32_e32 v96, 0xffff0000, v33
	s_waitcnt vmcnt(1)
	v_lshlrev_b32_e32 v53, 16, v14
	s_waitcnt lgkmcnt(0)
	v_add_f32_e32 v34, v34, v35
	v_fmamk_f32 v34, v34, 0x3c000000, v209
	v_cmp_gt_f32_e32 vcc, s82, v34
	v_mul_f32_e32 v35, 0x4b800000, v34
	v_and_b32_e32 v52, 0xffff0000, v14
	v_cndmask_b32_e32 v34, v34, v35, vcc
	v_rsq_f32_e32 v34, v34
	v_and_b32_e32 v14, 0xffff0000, v6
	v_lshlrev_b32_e32 v104, 16, v31
	v_and_b32_e32 v108, 0xffff0000, v31
	v_mul_f32_e32 v35, 0x45800000, v34
	v_cndmask_b32_e32 v55, v34, v35, vcc
	v_lshl_add_u64 v[34:35], v[50:51], 0, s[4:5]
	v_mov_b64_e32 v[46:47], v[144:145]
	v_mov_b64_e32 v[48:49], v[218:219]
	v_mul_f32_e32 v51, v97, v55
	v_add_u32_e32 v50, 0x11800, v0
	v_mul_f32_e32 v45, v45, v55
	v_mul_f32_e32 v44, v44, v55
	v_mul_f32_e32 v43, v43, v55
	v_mul_f32_e32 v42, v42, v55
	v_mul_f32_e32 v41, v41, v55
	v_mul_f32_e32 v40, v40, v55
	v_mul_f32_e32 v39, v39, v55
	v_mul_f32_e32 v38, v38, v55
	v_mov_b32_e32 v116, v112
	v_mov_b32_e32 v117, v2
	v_and_b32_e32 v97, 0xffff0000, v5
	v_mov_b32_e32 v110, v108
	v_mov_b32_e32 v111, v104
	v_mov_b32_e32 v30, v113
	v_mov_b32_e32 v31, v3
	v_pk_mul_f32 v[116:117], v[116:117], v[116:117]
	v_lshlrev_b32_e32 v101, 16, v4
	v_lshlrev_b32_e32 v100, 16, v32
	v_pk_mul_f32 v[110:111], v[110:111], v[110:111]
	v_pk_fma_f32 v[30:31], v[30:31], v[30:31], v[116:117]
	v_lshlrev_b32_e32 v130, 3, v162
	v_mov_b32_e32 v131, v1
	s_mov_b32 s4, s5
	s_mov_b32 s52, 0xf149f2ca
	s_waitcnt vmcnt(0)
; __device__ __forceinline__ unsigned cvt_pk_bf16(float lo, float hi) { unsigned r; asm volatile("v_cvt_pk_bf16_f32 %0, %1, %2" : "=v"(r) : "v"(lo), "v"(hi)); return r; }
; #define LAS __attribute__((address_space(3)))
; __device__ __forceinline__ void p2_block(LAS unsigned char* lds, const bf16_t* __restrict__ PROJ, bf16_t* __restrict__ ATT, bf16_t* __restrict__ SGU, const float* __restrict__ qn, const float* __restrict__ kn, ...
;     ...
;         const float* gp = lng + gg * 128 + 32 * q4; const float* bp = lnb + gg * 128 + 32 * q4;
;         LAS unsigned char* dst = lds + (gi ? VN_OFF1 : VN_OFF0) + (32 * q4) * VN_STRIDE + sp_ * 2;
; #pragma unroll
;         for (int j = 0; j < 32; j += 2) { const unsigned pk = cvt_pk_bf16(v[j] * rstd * gp[j] + bp[j], v[j + 1] * rstd * gp[j + 1] + bp[j + 1]);
;             *(LAS unsigned short*)(dst + j * VN_STRIDE) = (unsigned short)(pk & 0xffffu); *(LAS unsigned short*)(dst + (j + 1) * VN_STRIDE) = (unsigned short)(pk >> 16); }
	v_fma_f32 v46, v46, v51, v48
	v_mul_f32_e32 v48, v83, v55
	v_fmac_f32_e32 v49, v47, v48
	v_add_u32_e32 v47, 0x11910, v0
	v_cvt_pk_bf16_f32 v46, v46, v49
	ds_write_b16 v50, v46
	ds_write_b16_d16_hi v47, v46
	v_mov_b64_e32 v[46:47], v[146:147]
	v_mov_b64_e32 v[48:49], v[220:221]
	v_mul_f32_e32 v50, v77, v55
	v_lshlrev_b32_e32 v51, 16, v15
	s_waitcnt vmcnt(0)
	v_fma_f32 v46, v46, v50, v48
	v_mul_f32_e32 v48, v76, v55
	v_fmac_f32_e32 v49, v47, v48
	v_add_u32_e32 v47, 0x11a20, v0
	v_cvt_pk_bf16_f32 v46, v46, v49
	ds_write_b16 v47, v46
	v_add_u32_e32 v47, 0x11b30, v0
	ds_write_b16_d16_hi v47, v46
	v_mov_b64_e32 v[46:47], v[148:149]
	v_mov_b64_e32 v[48:49], v[222:223]
	v_mul_f32_e32 v50, v75, v55
	s_waitcnt vmcnt(0)
	v_fma_f32 v46, v46, v50, v48
	v_mul_f32_e32 v48, v74, v55
	v_fmac_f32_e32 v49, v47, v48
	v_add_u32_e32 v47, 0x11c40, v0
	v_cvt_pk_bf16_f32 v46, v46, v49
	ds_write_b16 v47, v46
	v_add_u32_e32 v47, 0x11d50, v0
	ds_write_b16_d16_hi v47, v46
	v_mov_b64_e32 v[46:47], v[150:151]
	v_mov_b64_e32 v[48:49], v[224:225]
	v_mul_f32_e32 v50, v73, v55
	s_waitcnt vmcnt(0)
	v_fma_f32 v46, v46, v50, v48
	v_mul_f32_e32 v48, v72, v55
	v_fmac_f32_e32 v49, v47, v48
	v_add_u32_e32 v47, 0x11e60, v0
	v_cvt_pk_bf16_f32 v46, v46, v49
	ds_write_b16 v47, v46
	v_add_u32_e32 v47, 0x11f70, v0
	ds_write_b16_d16_hi v47, v46
	v_mov_b64_e32 v[46:47], v[152:153]
	v_mov_b64_e32 v[48:49], v[226:227]
	v_mul_f32_e32 v50, v71, v55
	s_waitcnt vmcnt(0)
	v_fma_f32 v46, v46, v50, v48
	v_mul_f32_e32 v48, v70, v55
	v_fmac_f32_e32 v49, v47, v48
	v_add_u32_e32 v47, 0x12080, v0
	v_cvt_pk_bf16_f32 v46, v46, v49
	ds_write_b16 v47, v46
	v_add_u32_e32 v47, 0x12190, v0
	ds_write_b16_d16_hi v47, v46
	v_mov_b64_e32 v[46:47], v[154:155]
	v_mov_b64_e32 v[48:49], v[228:229]
	v_mul_f32_e32 v50, v69, v55
	s_waitcnt vmcnt(0)
	v_fma_f32 v46, v46, v50, v48
	v_mul_f32_e32 v48, v68, v55
	v_fmac_f32_e32 v49, v47, v48
	v_add_u32_e32 v47, 0x122a0, v0
	v_cvt_pk_bf16_f32 v46, v46, v49
	ds_write_b16 v47, v46
	v_add_u32_e32 v47, 0x123b0, v0
	ds_write_b16_d16_hi v47, v46
	v_mov_b64_e32 v[46:47], v[156:157]
	v_mov_b64_e32 v[48:49], v[230:231]
	v_mul_f32_e32 v50, v67, v55
	s_waitcnt vmcnt(0)
	v_fma_f32 v46, v46, v50, v48
	v_mul_f32_e32 v48, v66, v55
	v_fmac_f32_e32 v49, v48, v47
	v_add_u32_e32 v47, 0x124c0, v0
	v_cvt_pk_bf16_f32 v46, v46, v49
	ds_write_b16 v47, v46
	v_add_u32_e32 v47, 0x125d0, v0
	ds_write_b16_d16_hi v47, v46
	v_mov_b64_e32 v[46:47], v[158:159]
	v_mov_b64_e32 v[48:49], v[232:233]
	v_mul_f32_e32 v50, v65, v55
	s_waitcnt vmcnt(0)
	v_fma_f32 v46, v50, v46, v48
	v_mul_f32_e32 v48, v64, v55
	v_fmac_f32_e32 v49, v48, v47
	v_add_u32_e32 v47, 0x126e0, v0
	v_cvt_pk_bf16_f32 v46, v46, v49
	ds_write_b16 v47, v46
	v_add_u32_e32 v47, 0x127f0, v0
	ds_write_b16_d16_hi v47, v46
	v_mov_b64_e32 v[46:47], v[184:185]
	v_mov_b64_e32 v[48:49], v[234:235]
	v_mul_f32_e32 v50, v63, v55
	s_waitcnt vmcnt(0)
	v_fma_f32 v46, v50, v46, v48
	v_mul_f32_e32 v48, v62, v55
	v_fmac_f32_e32 v49, v48, v47
	v_add_u32_e32 v47, 0x12900, v0
	v_cvt_pk_bf16_f32 v46, v46, v49
	ds_write_b16 v47, v46
	v_add_u32_e32 v47, 0x12a10, v0
	ds_write_b16_d16_hi v47, v46
	v_mov_b64_e32 v[46:47], v[186:187]
	v_mov_b64_e32 v[48:49], v[236:237]
	v_mul_f32_e32 v50, v61, v55
	v_lshlrev_b32_e32 v61, 16, v18
	v_and_b32_e32 v62, 0xffff0000, v18
	s_waitcnt vmcnt(0)
	v_fma_f32 v46, v50, v46, v48
	v_mul_f32_e32 v48, v60, v55
	v_fmac_f32_e32 v49, v48, v47
	v_add_u32_e32 v47, 0x12b20, v0
	v_cvt_pk_bf16_f32 v46, v46, v49
	ds_write_b16 v47, v46
	v_add_u32_e32 v47, 0x12c30, v0
	ds_write_b16_d16_hi v47, v46
	v_mov_b64_e32 v[46:47], v[188:189]
	v_mov_b64_e32 v[48:49], v[238:239]
	v_mul_f32_e32 v50, v59, v55
	v_lshlrev_b32_e32 v60, 16, v19
	v_and_b32_e32 v59, 0xffff0000, v19
	s_waitcnt vmcnt(0)
	v_fma_f32 v46, v50, v46, v48
	v_mul_f32_e32 v48, v58, v55
	v_fmac_f32_e32 v49, v48, v47
	v_add_u32_e32 v47, 0x12d40, v0
	v_cvt_pk_bf16_f32 v46, v46, v49
	ds_write_b16 v47, v46
	v_add_u32_e32 v47, 0x12e50, v0
	ds_write_b16_d16_hi v47, v46
	v_mov_b64_e32 v[46:47], v[190:191]
	v_mov_b64_e32 v[48:49], v[240:241]
	v_mul_f32_e32 v50, v57, v55
	v_lshlrev_b32_e32 v58, 16, v20
	v_and_b32_e32 v57, 0xffff0000, v20
	s_waitcnt vmcnt(0)
	v_fma_f32 v46, v50, v46, v48
	v_mul_f32_e32 v48, v56, v55
	v_fmac_f32_e32 v49, v48, v47
	v_add_u32_e32 v47, 0x12f60, v0
	v_cvt_pk_bf16_f32 v46, v46, v49
	ds_write_b16 v47, v46
	v_add_u32_e32 v47, 0x13070, v0
	ds_write_b16_d16_hi v47, v46
	v_mov_b64_e32 v[46:47], v[192:193]
	v_mov_b64_e32 v[48:49], v[242:243]
	v_and_b32_e32 v50, 0xffff0000, v15
	v_lshlrev_b32_e32 v15, 16, v6
	v_and_b32_e32 v6, 0xffff0000, v9
	v_lshlrev_b32_e32 v56, 16, v21
	v_and_b32_e32 v55, 0xffff0000, v21
	v_mul_f32_e32 v88, 0x3d372713, v6
	v_fma_f32 v88, v88, v6, 1.0
	s_waitcnt vmcnt(0)
	v_fma_f32 v45, v45, v46, v48
	v_fmac_f32_e32 v49, v44, v47
	v_cvt_pk_bf16_f32 v44, v45, v49
	v_add_u32_e32 v45, 0x13180, v0
	ds_write_b16 v45, v44
	v_add_u32_e32 v45, 0x13290, v0
	ds_write_b16_d16_hi v45, v44
	v_mov_b64_e32 v[44:45], v[194:195]
	v_mov_b64_e32 v[46:47], v[244:245]
	v_lshlrev_b32_e32 v49, 16, v16
	v_and_b32_e32 v48, 0xffff0000, v16
	s_waitcnt vmcnt(0)
	v_fma_f32 v43, v43, v44, v46
	v_fmac_f32_e32 v47, v42, v45
	v_cvt_pk_bf16_f32 v42, v43, v47
	v_add_u32_e32 v43, 0x133a0, v0
	ds_write_b16 v43, v42
	v_add_u32_e32 v43, 0x134b0, v0
	ds_write_b16_d16_hi v43, v42
	v_mov_b64_e32 v[42:43], v[196:197]
	v_mov_b64_e32 v[44:45], v[200:201]
	v_lshlrev_b32_e32 v47, 16, v17
	v_and_b32_e32 v46, 0xffff0000, v17
	v_mul_f32_e32 v17, 0x3d372713, v14
	v_fma_f32 v17, v17, v14, 1.0
	s_waitcnt vmcnt(0)
; __device__ __forceinline__ unsigned cvt_pk_bf16(float lo, float hi) { unsigned r; asm volatile("v_cvt_pk_bf16_f32 %0, %1, %2" : "=v"(r) : "v"(lo), "v"(hi)); return r; }
; __device__ __forceinline__ float gelu_f(float x) { const float y2 = 1.5957691216057308f * x * (1.0f + 0.044715f * x * x); return x * sigmoid_f(y2); }
; #define LAS __attribute__((address_space(3)))
; __device__ __forceinline__ void unpack8(const u32x4 w, float* f) { f[0] = bf_lo(w.x); f[1] = bf_hi(w.x); f[2] = bf_lo(w.y); f[3] = bf_hi(w.y); f[4] = bf_lo(w.z); f[5] = bf_hi(w.z); f[6] = bf_lo(w.w); f[7] = bf_hi(w.w); }
; __device__ __forceinline__ void p2_block(LAS unsigned char* lds, const bf16_t* __restrict__ PROJ, bf16_t* __restrict__ ATT, bf16_t* __restrict__ SGU, const float* __restrict__ qn, const float* __restrict__ kn, ...
;     ...
;             for (int c4 = 0; c4 < 4; ++c4) sv[1][c4] = *(const u32x4*)(svsrc + 128 + 8 * c4); }
;         float v[32];
; #pragma unroll
;         for (int c4 = 0; c4 < 4; ++c4) unpack8(sv[gi][c4], v + 8 * c4);
;         float sm = 0.f;
; #pragma unroll
;         for (int j = 0; j < 32; ++j) { v[j] = gelu_f(v[j]); sm += v[j]; }
;         sm += __shfl_xor(sm, 1); sm += __shfl_xor(sm, 2);
;         const float mu = sm * (1.0f / 128.0f); float q = 0.f;
; #pragma unroll
;         for (int j = 0; j < 32; ++j) { v[j] -= mu; q += v[j] * v[j]; }
;         q += __shfl_xor(q, 1); q += __shfl_xor(q, 2);
;         const float rstd = rsqrtf(q * (1.0f / 128.0f) + pg8::EPS);
;         const float* gp = lng + gg * 128 + 32 * q4; const float* bp = lnb + gg * 128 + 32 * q4;
;         LAS unsigned char* dst = lds + (gi ? VN_OFF1 : VN_OFF0) + (32 * q4) * VN_STRIDE + sp_ * 2;
; #pragma unroll
;         for (int j = 0; j < 32; j += 2) { const unsigned pk = cvt_pk_bf16(v[j] * rstd * gp[j] + bp[j], v[j + 1] * rstd * gp[j + 1] + bp[j + 1]);
;             *(LAS unsigned short*)(dst + j * VN_STRIDE) = (unsigned short)(pk & 0xffffu); *(LAS unsigned short*)(dst + (j + 1) * VN_STRIDE) = (unsigned short)(pk >> 16); }
	v_fma_f32 v41, v41, v42, v44
	v_fmac_f32_e32 v45, v40, v43
	v_cvt_pk_bf16_f32 v40, v41, v45
	v_add_u32_e32 v41, 0x135c0, v0
	ds_write_b16 v41, v40
	v_add_u32_e32 v41, 0x136d0, v0
	ds_write_b16_d16_hi v41, v40
	v_mov_b64_e32 v[40:41], v[198:199]
	v_mov_b64_e32 v[42:43], v[202:203]
	v_lshlrev_b32_e32 v45, 16, v10
	v_and_b32_e32 v44, 0xffff0000, v10
	v_and_b32_e32 v10, 0xffff0000, v8
	s_waitcnt vmcnt(0)
	global_load_dwordx4 v[144:147], v182, s[36:37] offset:512
	global_load_dwordx4 v[148:151], v182, s[36:37] offset:528
	global_load_dwordx4 v[152:155], v182, s[36:37] offset:544
	global_load_dwordx4 v[156:159], v182, s[36:37] offset:560
	global_load_dwordx4 v[184:187], v182, s[36:37] offset:576
	global_load_dwordx4 v[188:191], v182, s[36:37] offset:592
	global_load_dwordx4 v[192:195], v182, s[36:37] offset:608
	global_load_dwordx4 v[196:199], v182, s[36:37] offset:624
	global_load_dwordx4 v[218:221], v182, s[18:19] offset:512
	global_load_dwordx4 v[222:225], v182, s[18:19] offset:528
	global_load_dwordx4 v[226:229], v182, s[18:19] offset:544
	global_load_dwordx4 v[230:233], v182, s[18:19] offset:560
	global_load_dwordx4 v[234:237], v182, s[18:19] offset:576
	global_load_dwordx4 v[238:241], v182, s[18:19] offset:592
	global_load_dwordx4 v[242:245], v182, s[18:19] offset:608
	global_load_dwordx4 v[200:203], v182, s[18:19] offset:624
	v_fma_f32 v39, v39, v40, v42
	v_fmac_f32_e32 v43, v38, v41
	v_cvt_pk_bf16_f32 v38, v39, v43
	v_add_u32_e32 v39, 0x137e0, v0
	ds_write_b16 v39, v38
	v_add_u32_e32 v39, 0x138f0, v0
	ds_write_b16_d16_hi v39, v38
	v_lshlrev_b32_e32 v41, 16, v12
	v_and_b32_e32 v40, 0xffff0000, v12
	v_lshlrev_b32_e32 v39, 16, v13
	v_and_b32_e32 v38, 0xffff0000, v13
	v_lshlrev_b32_e32 v13, 16, v7
	v_and_b32_e32 v12, 0xffff0000, v7
	v_lshlrev_b32_e32 v7, 16, v9
	v_mul_f32_e32 v9, 0x3d372713, v61
	v_lshlrev_b32_e32 v43, 16, v11
	v_and_b32_e32 v42, 0xffff0000, v11
	v_lshlrev_b32_e32 v11, 16, v8
	v_mul_f32_e32 v8, 0x3fcc422a, v61
	v_fma_f32 v9, v9, v61, 1.0
	v_mul_f32_e32 v8, v8, v9
	v_mul_f32_e32 v8, 0xbfb8aa3b, v8
	v_exp_f32_e32 v8, v8
	v_mul_f32_e32 v9, 0x3d372713, v62
	v_fma_f32 v9, v9, v62, 1.0
	v_add_f32_e32 v8, 1.0, v8
	v_rcp_f32_e32 v63, v8
	v_mul_f32_e32 v8, 0x3fcc422a, v62
	v_mul_f32_e32 v8, v8, v9
	v_mul_f32_e32 v8, 0xbfb8aa3b, v8
	v_exp_f32_e32 v8, v8
	v_mul_f32_e32 v9, 0x3d372713, v60
	v_fma_f32 v9, v9, v60, 1.0
	v_fma_f32 v16, v63, v61, 0
	v_add_f32_e32 v8, 1.0, v8
	v_rcp_f32_e32 v64, v8
	v_mul_f32_e32 v8, 0x3fcc422a, v60
	v_mul_f32_e32 v8, v8, v9
	v_mul_f32_e32 v8, 0xbfb8aa3b, v8
	v_exp_f32_e32 v8, v8
	v_mul_f32_e32 v9, 0x3d372713, v59
	v_fma_f32 v9, v9, v59, 1.0
	v_fmac_f32_e32 v16, v64, v62
	v_add_f32_e32 v8, 1.0, v8
	v_rcp_f32_e32 v65, v8
	v_mul_f32_e32 v8, 0x3fcc422a, v59
	v_mul_f32_e32 v8, v8, v9
	v_mul_f32_e32 v8, 0xbfb8aa3b, v8
	v_exp_f32_e32 v8, v8
	v_mul_f32_e32 v9, 0x3d372713, v58
	v_fma_f32 v9, v9, v58, 1.0
	v_fmac_f32_e32 v16, v65, v60
	v_add_f32_e32 v8, 1.0, v8
	v_rcp_f32_e32 v66, v8
	v_mul_f32_e32 v8, 0x3fcc422a, v58
	v_mul_f32_e32 v8, v8, v9
	v_mul_f32_e32 v8, 0xbfb8aa3b, v8
	v_exp_f32_e32 v8, v8
	v_mul_f32_e32 v9, 0x3d372713, v57
	v_fma_f32 v9, v9, v57, 1.0
	v_fmac_f32_e32 v16, v66, v59
	v_add_f32_e32 v8, 1.0, v8
	v_rcp_f32_e32 v67, v8
	v_mul_f32_e32 v8, 0x3fcc422a, v57
	v_mul_f32_e32 v8, v8, v9
	v_mul_f32_e32 v8, 0xbfb8aa3b, v8
	v_exp_f32_e32 v8, v8
	v_mul_f32_e32 v9, 0x3d372713, v56
	v_fma_f32 v9, v9, v56, 1.0
	v_fmac_f32_e32 v16, v67, v58
	v_add_f32_e32 v8, 1.0, v8
	v_rcp_f32_e32 v68, v8
	v_mul_f32_e32 v8, 0x3fcc422a, v56
	v_mul_f32_e32 v8, v8, v9
	v_mul_f32_e32 v8, 0xbfb8aa3b, v8
	v_exp_f32_e32 v8, v8
	v_mul_f32_e32 v9, 0x3d372713, v55
	v_fma_f32 v9, v9, v55, 1.0
	v_fmac_f32_e32 v16, v68, v57
	v_add_f32_e32 v8, 1.0, v8
	v_rcp_f32_e32 v69, v8
	v_mul_f32_e32 v8, 0x3fcc422a, v55
	v_mul_f32_e32 v8, v8, v9
	v_mul_f32_e32 v8, 0xbfb8aa3b, v8
	v_exp_f32_e32 v8, v8
	v_mul_f32_e32 v9, 0x3d372713, v53
	v_fma_f32 v9, v9, v53, 1.0
	v_fmac_f32_e32 v16, v69, v56
	v_add_f32_e32 v8, 1.0, v8
	v_rcp_f32_e32 v70, v8
	v_mul_f32_e32 v8, 0x3fcc422a, v53
	v_mul_f32_e32 v8, v8, v9
	v_mul_f32_e32 v8, 0xbfb8aa3b, v8
	v_exp_f32_e32 v8, v8
	v_mul_f32_e32 v9, 0x3d372713, v52
	v_fma_f32 v9, v9, v52, 1.0
	v_fmac_f32_e32 v16, v70, v55
	v_add_f32_e32 v8, 1.0, v8
	v_rcp_f32_e32 v71, v8
	v_mul_f32_e32 v8, 0x3fcc422a, v52
	v_mul_f32_e32 v8, v8, v9
	v_mul_f32_e32 v8, 0xbfb8aa3b, v8
	v_exp_f32_e32 v8, v8
	v_mul_f32_e32 v9, 0x3d372713, v51
	v_fma_f32 v9, v9, v51, 1.0
	v_fmac_f32_e32 v16, v71, v53
	v_add_f32_e32 v8, 1.0, v8
	v_rcp_f32_e32 v72, v8
	v_mul_f32_e32 v8, 0x3fcc422a, v51
	v_mul_f32_e32 v8, v8, v9
	v_mul_f32_e32 v8, 0xbfb8aa3b, v8
	v_exp_f32_e32 v8, v8
	v_mul_f32_e32 v9, 0x3d372713, v50
	v_fma_f32 v9, v9, v50, 1.0
	v_fmac_f32_e32 v16, v72, v52
	v_add_f32_e32 v8, 1.0, v8
	v_rcp_f32_e32 v73, v8
	v_mul_f32_e32 v8, 0x3fcc422a, v50
	v_mul_f32_e32 v8, v8, v9
	v_mul_f32_e32 v8, 0xbfb8aa3b, v8
	v_exp_f32_e32 v8, v8
	v_mul_f32_e32 v9, 0x3d372713, v49
	v_fma_f32 v9, v9, v49, 1.0
	v_fmac_f32_e32 v16, v73, v51
	v_add_f32_e32 v8, 1.0, v8
	v_rcp_f32_e32 v74, v8
	v_mul_f32_e32 v8, 0x3fcc422a, v49
	v_mul_f32_e32 v8, v8, v9
	v_mul_f32_e32 v8, 0xbfb8aa3b, v8
	v_exp_f32_e32 v8, v8
	v_mul_f32_e32 v9, 0x3d372713, v48
	v_fma_f32 v9, v9, v48, 1.0
	v_fmac_f32_e32 v16, v74, v50
	v_add_f32_e32 v8, 1.0, v8
	v_rcp_f32_e32 v75, v8
	v_mul_f32_e32 v8, 0x3fcc422a, v48
	v_mul_f32_e32 v8, v8, v9
	v_mul_f32_e32 v8, 0xbfb8aa3b, v8
	v_exp_f32_e32 v8, v8
	v_mul_f32_e32 v9, 0x3d372713, v47
	v_fma_f32 v9, v9, v47, 1.0
	v_fmac_f32_e32 v16, v75, v49
	v_add_f32_e32 v8, 1.0, v8
	v_rcp_f32_e32 v76, v8
	v_mul_f32_e32 v8, 0x3fcc422a, v47
	v_mul_f32_e32 v8, v8, v9
	v_mul_f32_e32 v8, 0xbfb8aa3b, v8
; __device__ __forceinline__ float gelu_f(float x) { const float y2 = 1.5957691216057308f * x * (1.0f + 0.044715f * x * x); return x * sigmoid_f(y2); }
; __device__ __forceinline__ void unpack8(const u32x4 w, float* f) { f[0] = bf_lo(w.x); f[1] = bf_hi(w.x); f[2] = bf_lo(w.y); f[3] = bf_hi(w.y); f[4] = bf_lo(w.z); f[5] = bf_hi(w.z); f[6] = bf_lo(w.w); f[7] = bf_hi(w.w); }
; __device__ __forceinline__ void p2_block(LAS unsigned char* lds, const bf16_t* __restrict__ PROJ, bf16_t* __restrict__ ATT, bf16_t* __restrict__ SGU, const float* __restrict__ qn, const float* __restrict__ kn, ...
;     ...
;         for (int c4 = 0; c4 < 4; ++c4) unpack8(sv[gi][c4], v + 8 * c4);
;         float sm = 0.f;
; #pragma unroll
;         for (int j = 0; j < 32; ++j) { v[j] = gelu_f(v[j]); sm += v[j]; }
;         sm += __shfl_xor(sm, 1); sm += __shfl_xor(sm, 2);
	v_exp_f32_e32 v8, v8
	v_mul_f32_e32 v9, 0x3d372713, v46
	v_fma_f32 v9, v9, v46, 1.0
	v_fmac_f32_e32 v16, v76, v48
	v_add_f32_e32 v8, 1.0, v8
	v_rcp_f32_e32 v77, v8
	v_mul_f32_e32 v8, 0x3fcc422a, v46
	v_mul_f32_e32 v8, v8, v9
	v_mul_f32_e32 v8, 0xbfb8aa3b, v8
	v_exp_f32_e32 v8, v8
	v_mul_f32_e32 v9, 0x3d372713, v45
	v_fma_f32 v9, v9, v45, 1.0
	v_fmac_f32_e32 v16, v77, v47
	v_add_f32_e32 v8, 1.0, v8
	v_rcp_f32_e32 v78, v8
	v_mul_f32_e32 v8, 0x3fcc422a, v45
	v_mul_f32_e32 v8, v8, v9
	v_mul_f32_e32 v8, 0xbfb8aa3b, v8
	v_exp_f32_e32 v8, v8
	v_mul_f32_e32 v9, 0x3d372713, v44
	v_fma_f32 v9, v9, v44, 1.0
	v_fmac_f32_e32 v16, v78, v46
	v_add_f32_e32 v8, 1.0, v8
	v_rcp_f32_e32 v79, v8
	v_mul_f32_e32 v8, 0x3fcc422a, v44
	v_mul_f32_e32 v8, v8, v9
	v_mul_f32_e32 v8, 0xbfb8aa3b, v8
	v_exp_f32_e32 v8, v8
	v_mul_f32_e32 v9, 0x3d372713, v43
	v_fma_f32 v9, v9, v43, 1.0
	v_fmac_f32_e32 v16, v79, v45
	v_add_f32_e32 v8, 1.0, v8
	v_rcp_f32_e32 v80, v8
	v_mul_f32_e32 v8, 0x3fcc422a, v43
	v_mul_f32_e32 v8, v8, v9
	v_mul_f32_e32 v8, 0xbfb8aa3b, v8
	v_exp_f32_e32 v8, v8
	v_mul_f32_e32 v9, 0x3d372713, v42
	v_fma_f32 v9, v9, v42, 1.0
	v_fmac_f32_e32 v16, v80, v44
	v_add_f32_e32 v8, 1.0, v8
	v_rcp_f32_e32 v81, v8
	v_mul_f32_e32 v8, 0x3fcc422a, v42
	v_mul_f32_e32 v8, v8, v9
	v_mul_f32_e32 v8, 0xbfb8aa3b, v8
	v_exp_f32_e32 v8, v8
	v_mul_f32_e32 v9, 0x3d372713, v41
	v_fma_f32 v9, v9, v41, 1.0
	v_fmac_f32_e32 v16, v81, v43
	v_add_f32_e32 v8, 1.0, v8
	v_rcp_f32_e32 v82, v8
	v_mul_f32_e32 v8, 0x3fcc422a, v41
	v_mul_f32_e32 v8, v8, v9
	v_mul_f32_e32 v8, 0xbfb8aa3b, v8
	v_exp_f32_e32 v8, v8
	v_mul_f32_e32 v9, 0x3d372713, v40
	v_fma_f32 v9, v9, v40, 1.0
	v_fmac_f32_e32 v16, v82, v42
	v_add_f32_e32 v8, 1.0, v8
	v_rcp_f32_e32 v83, v8
	v_mul_f32_e32 v8, 0x3fcc422a, v40
	v_mul_f32_e32 v8, v8, v9
	v_mul_f32_e32 v8, 0xbfb8aa3b, v8
	v_exp_f32_e32 v8, v8
	v_mul_f32_e32 v9, 0x3d372713, v39
	v_fma_f32 v9, v9, v39, 1.0
	v_fmac_f32_e32 v16, v83, v41
	v_add_f32_e32 v8, 1.0, v8
	v_rcp_f32_e32 v84, v8
	v_mul_f32_e32 v8, 0x3fcc422a, v39
	v_mul_f32_e32 v8, v8, v9
	v_mul_f32_e32 v8, 0xbfb8aa3b, v8
	v_exp_f32_e32 v8, v8
	v_mul_f32_e32 v9, 0x3d372713, v38
	v_fma_f32 v9, v9, v38, 1.0
	v_fmac_f32_e32 v16, v84, v40
	v_add_f32_e32 v8, 1.0, v8
	v_rcp_f32_e32 v85, v8
	v_mul_f32_e32 v8, 0x3fcc422a, v38
	v_mul_f32_e32 v8, v8, v9
	v_mul_f32_e32 v8, 0xbfb8aa3b, v8
	v_exp_f32_e32 v8, v8
	v_mul_f32_e32 v9, 0x3d372713, v15
	v_fma_f32 v9, v9, v15, 1.0
	v_fmac_f32_e32 v16, v85, v39
	v_add_f32_e32 v8, 1.0, v8
	v_rcp_f32_e32 v86, v8
	v_mul_f32_e32 v8, 0x3fcc422a, v15
	v_mul_f32_e32 v8, v8, v9
	v_mul_f32_e32 v8, 0xbfb8aa3b, v8
	v_exp_f32_e32 v8, v8
	v_fmac_f32_e32 v16, v86, v38
	v_add_f32_e32 v8, 1.0, v8
	v_rcp_f32_e32 v9, v8
	v_mul_f32_e32 v8, 0x3fcc422a, v14
	v_mul_f32_e32 v8, v8, v17
	v_mul_f32_e32 v8, 0xbfb8aa3b, v8
	v_exp_f32_e32 v8, v8
	v_mul_f32_e32 v17, 0x3d372713, v13
	v_fma_f32 v17, v17, v13, 1.0
	v_add_f32_e32 v8, 1.0, v8
	v_rcp_f32_e32 v8, v8
	s_nop 0
	v_pk_mul_f32 v[18:19], v[8:9], v[14:15]
	s_nop 0
	v_add_f32_e32 v16, v19, v16
	v_add_f32_e32 v20, v18, v16
	v_mul_f32_e32 v16, 0x3fcc422a, v13
	v_mul_f32_e32 v16, v16, v17
	v_mul_f32_e32 v16, 0xbfb8aa3b, v16
	v_exp_f32_e32 v16, v16
	v_mul_f32_e32 v18, 0x3d372713, v12
	v_fma_f32 v18, v18, v12, 1.0
	v_add_f32_e32 v16, 1.0, v16
	v_rcp_f32_e32 v17, v16
	v_mul_f32_e32 v16, 0x3fcc422a, v12
	v_mul_f32_e32 v16, v16, v18
	v_mul_f32_e32 v16, 0xbfb8aa3b, v16
	v_exp_f32_e32 v16, v16
	s_nop 0
	v_add_f32_e32 v16, 1.0, v16
	v_rcp_f32_e32 v16, v16
	s_nop 0
	v_pk_mul_f32 v[18:19], v[16:17], v[12:13]
	s_nop 0
	v_add_f32_e32 v19, v19, v20
	v_add_f32_e32 v87, v18, v19
	v_mul_f32_e32 v19, 0x3d372713, v11
	v_mul_f32_e32 v18, 0x3fcc422a, v11
	v_fma_f32 v19, v19, v11, 1.0
	v_mul_f32_e32 v18, v18, v19
	v_mul_f32_e32 v18, 0xbfb8aa3b, v18
	v_exp_f32_e32 v18, v18
	v_mul_f32_e32 v20, 0x3d372713, v10
	v_fma_f32 v20, v20, v10, 1.0
	v_add_f32_e32 v18, 1.0, v18
	v_rcp_f32_e32 v19, v18
	v_mul_f32_e32 v18, 0x3fcc422a, v10
	v_mul_f32_e32 v18, v18, v20
	v_mul_f32_e32 v18, 0xbfb8aa3b, v18
	v_exp_f32_e32 v18, v18
	s_nop 0
	v_add_f32_e32 v18, 1.0, v18
	v_rcp_f32_e32 v18, v18
	s_nop 0
	v_pk_mul_f32 v[20:21], v[18:19], v[10:11]
	s_nop 0
	v_add_f32_e32 v21, v21, v87
	v_add_f32_e32 v87, v20, v21
	v_mul_f32_e32 v21, 0x3d372713, v7
	v_mul_f32_e32 v20, 0x3fcc422a, v7
	v_fma_f32 v21, v21, v7, 1.0
	v_mul_f32_e32 v20, v20, v21
	v_mul_f32_e32 v20, 0xbfb8aa3b, v20
	v_exp_f32_e32 v20, v20
	s_nop 0
	v_add_f32_e32 v20, 1.0, v20
	v_rcp_f32_e32 v21, v20
	v_mul_f32_e32 v20, 0x3fcc422a, v6
	v_mul_f32_e32 v20, v20, v88
	v_mul_f32_e32 v20, 0xbfb8aa3b, v20
	v_exp_f32_e32 v20, v20
	s_nop 0
	v_add_f32_e32 v20, 1.0, v20
	v_rcp_f32_e32 v20, v20
	s_nop 0
	v_pk_mul_f32 v[88:89], v[20:21], v[6:7]
	s_nop 0
	v_add_f32_e32 v87, v89, v87
	v_add_f32_e32 v87, v88, v87
	s_nop 1
	v_mov_b32_dpp v88, v87 quad_perm:[1,0,3,2] row_mask:0xf bank_mask:0xf
	s_waitcnt lgkmcnt(0)
	v_add_f32_e32 v87, v87, v88
	s_nop 1
	v_mov_b32_dpp v88, v87 quad_perm:[2,3,0,1] row_mask:0xf bank_mask:0xf
	s_waitcnt lgkmcnt(0)
; __device__ __forceinline__ unsigned cvt_pk_bf16(float lo, float hi) { unsigned r; asm volatile("v_cvt_pk_bf16_f32 %0, %1, %2" : "=v"(r) : "v"(lo), "v"(hi)); return r; }
; #define LAS __attribute__((address_space(3)))
; __device__ __forceinline__ void p2_block(LAS unsigned char* lds, const bf16_t* __restrict__ PROJ, bf16_t* __restrict__ ATT, bf16_t* __restrict__ SGU, const float* __restrict__ qn, const float* __restrict__ kn, ...
;     ...
;         const float mu = sm * (1.0f / 128.0f); float q = 0.f;
; #pragma unroll
;         for (int j = 0; j < 32; ++j) { v[j] -= mu; q += v[j] * v[j]; }
;         q += __shfl_xor(q, 1); q += __shfl_xor(q, 2);
;         const float rstd = rsqrtf(q * (1.0f / 128.0f) + pg8::EPS);
;         const float* gp = lng + gg * 128 + 32 * q4; const float* bp = lnb + gg * 128 + 32 * q4;
;         LAS unsigned char* dst = lds + (gi ? VN_OFF1 : VN_OFF0) + (32 * q4) * VN_STRIDE + sp_ * 2;
; #pragma unroll
;         for (int j = 0; j < 32; j += 2) { const unsigned pk = cvt_pk_bf16(v[j] * rstd * gp[j] + bp[j], v[j + 1] * rstd * gp[j + 1] + bp[j + 1]);
;             *(LAS unsigned short*)(dst + j * VN_STRIDE) = (unsigned short)(pk & 0xffffu); *(LAS unsigned short*)(dst + (j + 1) * VN_STRIDE) = (unsigned short)(pk >> 16); }
	v_add_f32_e32 v87, v87, v88
	v_mul_f32_e32 v88, 0x3c000000, v87
	v_fma_f32 v63, v63, v61, -v88
	v_fma_f32 v61, v64, v62, -v88
	v_mul_f32_e32 v62, v61, v61
	v_fmac_f32_e32 v62, v63, v63
	v_fma_f32 v60, v65, v60, -v88
	v_fmac_f32_e32 v62, v60, v60
	v_fma_f32 v59, v66, v59, -v88
	v_fmac_f32_e32 v62, v59, v59
	v_fma_f32 v58, v67, v58, -v88
	v_fmac_f32_e32 v62, v58, v58
	v_fma_f32 v57, v68, v57, -v88
	v_fmac_f32_e32 v62, v57, v57
	v_fma_f32 v56, v69, v56, -v88
	v_fmac_f32_e32 v62, v56, v56
	v_fma_f32 v55, v70, v55, -v88
	v_fmac_f32_e32 v62, v55, v55
	v_fma_f32 v53, v71, v53, -v88
	v_fmac_f32_e32 v62, v53, v53
	v_fma_f32 v52, v72, v52, -v88
	v_fmac_f32_e32 v62, v52, v52
	v_fma_f32 v51, v73, v51, -v88
	v_fmac_f32_e32 v62, v51, v51
	v_fma_f32 v50, v74, v50, -v88
	v_fmac_f32_e32 v62, v50, v50
	v_fma_f32 v49, v75, v49, -v88
	v_fmac_f32_e32 v62, v49, v49
	v_fma_f32 v48, v76, v48, -v88
	v_fmac_f32_e32 v62, v48, v48
	v_fma_f32 v47, v77, v47, -v88
	v_fmac_f32_e32 v62, v47, v47
	v_fma_f32 v46, v78, v46, -v88
	v_fmac_f32_e32 v62, v46, v46
	v_fma_f32 v45, v79, v45, -v88
	v_fmac_f32_e32 v62, v45, v45
	v_fma_f32 v44, v80, v44, -v88
	v_fmac_f32_e32 v62, v44, v44
	v_fma_f32 v43, v81, v43, -v88
	v_fmac_f32_e32 v62, v43, v43
	v_fma_f32 v42, v82, v42, -v88
	v_fmac_f32_e32 v62, v42, v42
	v_fma_f32 v41, v83, v41, -v88
	v_fmac_f32_e32 v62, v41, v41
	v_fma_f32 v40, v84, v40, -v88
	v_fmac_f32_e32 v62, v40, v40
	v_fma_f32 v39, v85, v39, -v88
	v_fmac_f32_e32 v62, v39, v39
	v_fma_f32 v38, v86, v38, -v88
	v_pk_fma_f32 v[14:15], v[8:9], v[14:15], v[88:89] op_sel_hi:[1,1,0] neg_lo:[0,0,1] neg_hi:[0,0,1]
	v_fmac_f32_e32 v62, v38, v38
	v_pk_mul_f32 v[8:9], v[14:15], v[14:15]
	v_pk_fma_f32 v[12:13], v[16:17], v[12:13], v[88:89] op_sel_hi:[1,1,0] neg_lo:[0,0,1] neg_hi:[0,0,1]
	v_add_f32_e32 v9, v9, v62
	v_add_f32_e32 v62, v8, v9
	v_pk_mul_f32 v[8:9], v[12:13], v[12:13]
	v_pk_fma_f32 v[6:7], v[20:21], v[6:7], v[88:89] op_sel_hi:[1,1,0] neg_lo:[0,0,1] neg_hi:[0,0,1]
	v_add_f32_e32 v9, v9, v62
	v_add_f32_e32 v16, v8, v9
	v_pk_fma_f32 v[8:9], v[18:19], v[10:11], v[88:89] op_sel_hi:[1,1,0] neg_lo:[0,0,1] neg_hi:[0,0,1]
	v_add_u32_e32 v19, 0x1a000, v0
	v_pk_mul_f32 v[10:11], v[8:9], v[8:9]
	v_lshlrev_b32_e32 v78, 16, v33
	v_add_f32_e32 v11, v11, v16
	v_add_f32_e32 v16, v10, v11
	v_pk_mul_f32 v[10:11], v[6:7], v[6:7]
	v_lshlrev_b32_e32 v79, 16, v5
	v_add_f32_e32 v11, v11, v16
	v_add_f32_e32 v10, v10, v11
	s_nop 1
	v_mov_b32_dpp v11, v10 quad_perm:[1,0,3,2] row_mask:0xf bank_mask:0xf
	v_and_b32_e32 v5, 0xffff0000, v4
	v_and_b32_e32 v4, 0xffff0000, v32
	v_mov_b32_e32 v32, v5
	v_mov_b32_e32 v33, v101
	s_waitcnt lgkmcnt(0)
	v_add_f32_e32 v10, v10, v11
	s_nop 1
	v_mov_b32_dpp v11, v10 quad_perm:[2,3,0,1] row_mask:0xf bank_mask:0xf
	v_mov_b32_e32 v54, v96
	v_add_u32_e32 v81, 0, v132
	v_lshlrev_b32_e32 v73, 2, v162
	v_sub_u32_e32 v74, v81, v130
	s_waitcnt lgkmcnt(0)
	v_add_f32_e32 v10, v10, v11
	v_fmamk_f32 v10, v10, 0x3c000000, v209
	v_cmp_gt_f32_e32 vcc, s82, v10
	v_mul_f32_e32 v11, 0x4b800000, v10
	v_or_b32_e32 v71, 2, v130
	v_cndmask_b32_e32 v10, v10, v11, vcc
	v_rsq_f32_e32 v10, v10
	v_or_b32_e32 v70, 3, v130
	v_or_b32_e32 v72, 4, v130
	v_mul_f32_e32 v11, 0x45800000, v10
	v_cndmask_b32_e32 v18, v10, v11, vcc
	s_waitcnt vmcnt(0)
	v_mov_b64_e32 v[10:11], v[144:145]
	v_mov_b64_e32 v[16:17], v[218:219]
	v_mul_f32_e32 v20, v63, v18
	v_mul_f32_e32 v15, v15, v18
	v_mul_f32_e32 v14, v14, v18
	v_mul_f32_e32 v13, v13, v18
	v_mul_f32_e32 v12, v12, v18
	v_mul_f32_e32 v9, v9, v18
	v_mul_f32_e32 v8, v8, v18
	v_mul_f32_e32 v7, v7, v18
	v_mul_f32_e32 v6, v6, v18
	s_waitcnt vmcnt(0)
	v_fma_f32 v10, v10, v20, v16
	v_mul_f32_e32 v16, v61, v18
	v_fmac_f32_e32 v17, v11, v16
	v_add_u32_e32 v11, 0x1a110, v0
	v_cvt_pk_bf16_f32 v10, v10, v17
	ds_write_b16 v19, v10
	ds_write_b16_d16_hi v11, v10
	v_mov_b64_e32 v[10:11], v[146:147]
	v_mov_b64_e32 v[16:17], v[220:221]
	v_mul_f32_e32 v19, v60, v18
	s_waitcnt vmcnt(0)
	v_fma_f32 v10, v10, v19, v16
	v_mul_f32_e32 v16, v59, v18
	v_fmac_f32_e32 v17, v11, v16
	v_add_u32_e32 v11, 0x1a220, v0
	v_cvt_pk_bf16_f32 v10, v10, v17
	ds_write_b16 v11, v10
	v_add_u32_e32 v11, 0x1a330, v0
	ds_write_b16_d16_hi v11, v10
	v_mov_b64_e32 v[10:11], v[148:149]
	v_mov_b64_e32 v[16:17], v[222:223]
	v_mul_f32_e32 v19, v58, v18
	s_waitcnt vmcnt(0)
	v_fma_f32 v10, v10, v19, v16
	v_mul_f32_e32 v16, v57, v18
	v_fmac_f32_e32 v17, v11, v16
	v_add_u32_e32 v11, 0x1a440, v0
	v_cvt_pk_bf16_f32 v10, v10, v17
	ds_write_b16 v11, v10
	v_add_u32_e32 v11, 0x1a550, v0
	ds_write_b16_d16_hi v11, v10
	v_mov_b64_e32 v[10:11], v[150:151]
	v_mov_b64_e32 v[16:17], v[224:225]
	v_mul_f32_e32 v19, v56, v18
	v_mov_b32_e32 v56, v109
	v_mov_b32_e32 v57, v105
	v_pk_fma_f32 v[110:111], v[56:57], v[56:57], v[110:111]
	s_waitcnt vmcnt(0)
	v_fma_f32 v10, v10, v19, v16
	v_mul_f32_e32 v16, v55, v18
	v_fmac_f32_e32 v17, v11, v16
	v_add_u32_e32 v11, 0x1a660, v0
	v_cvt_pk_bf16_f32 v10, v10, v17
	ds_write_b16 v11, v10
	v_add_u32_e32 v11, 0x1a770, v0
	ds_write_b16_d16_hi v11, v10
	v_mov_b64_e32 v[10:11], v[152:153]
	v_mov_b64_e32 v[16:17], v[226:227]
	v_mul_f32_e32 v19, v53, v18
	v_mov_b32_e32 v55, v78
	v_pk_mul_f32 v[54:55], v[54:55], v[54:55]
	s_waitcnt vmcnt(0)
	v_fma_f32 v10, v10, v19, v16
	v_mul_f32_e32 v16, v52, v18
	v_fmac_f32_e32 v17, v11, v16
	v_add_u32_e32 v11, 0x1a880, v0
	v_cvt_pk_bf16_f32 v10, v10, v17
	ds_write_b16 v11, v10
	v_add_u32_e32 v11, 0x1a990, v0
	ds_write_b16_d16_hi v11, v10
	v_mov_b64_e32 v[10:11], v[154:155]
	v_mov_b64_e32 v[16:17], v[228:229]
	v_mul_f32_e32 v19, v51, v18
	s_waitcnt vmcnt(0)
; __device__ __forceinline__ unsigned cvt_pk_bf16(float lo, float hi) { unsigned r; asm volatile("v_cvt_pk_bf16_f32 %0, %1, %2" : "=v"(r) : "v"(lo), "v"(hi)); return r; }
; #define LAS __attribute__((address_space(3)))
; __device__ __forceinline__ void unpack8(const u32x4 w, float* f) { f[0] = bf_lo(w.x); f[1] = bf_hi(w.x); f[2] = bf_lo(w.y); f[3] = bf_hi(w.y); f[4] = bf_lo(w.z); f[5] = bf_hi(w.z); f[6] = bf_lo(w.w); f[7] = bf_hi(w.w); }
; __device__ __forceinline__ void p2_block(LAS unsigned char* lds, const bf16_t* __restrict__ PROJ, bf16_t* __restrict__ ATT, bf16_t* __restrict__ SGU, const float* __restrict__ qn, const float* __restrict__ kn, ...
;     ...
;     const int lane = tid & 63, w = __builtin_amdgcn_readfirstlane(tid >> 6), fr = lane & 15, fq = lane >> 4;
;     LAS unsigned char* KS = lds; LAS unsigned char* VT = lds + KS_BYTES;
;     const int g = w >> 1, rbase = (w & 1) * 64, hq = kvh * 4 + g;
;     ...
;         for (int j = 0; j < 32; j += 2) { const unsigned pk = cvt_pk_bf16(v[j] * rstd * gp[j] + bp[j], v[j + 1] * rstd * gp[j + 1] + bp[j + 1]);
;             *(LAS unsigned short*)(dst + j * VN_STRIDE) = (unsigned short)(pk & 0xffffu); *(LAS unsigned short*)(dst + (j + 1) * VN_STRIDE) = (unsigned short)(pk >> 16); }
;     }
;     __syncthreads();
; #pragma unroll
;     for (int c = 2; c < 4; ++c) { const bf16_t* qp = PROJ + ((size_t)b * pg8::SEQ + n * 128 + rbase + 16 * c + fr) * pg8::IN_W + hq * 64 + 8 * fq; qa[c] = *(const u32x4*)qp; qb[c] = *(const u32x4*)(qp + 32); }
;     const float sink = sinks[hq];
;     constexpr float LOG2E = 1.4426950408889634f;
; #pragma unroll
;     for (int c = 0; c < 4; ++c) {
;         const int i0 = rbase + 16 * c, irow = i0 + fr, pos = n * 128 + irow; const size_t grow = (size_t)b * pg8::SEQ + pos;
;         bf16x8 qf0, qf1;
;         {
;             float x1[8], x2[8]; unpack8(qa[c], x1); unpack8(qb[c], x2);
;             float ss = 0.f;
; #pragma unroll
;             for (int j = 0; j < 8; ++j) ss += x1[j] * x1[j] + x2[j] * x2[j];
;             ss += __shfl_xor(ss, 16); ss += __shfl_xor(ss, 32);
;             const float rinv = rsqrtf(ss * (1.0f / 64.0f) + pg8::EPS) * 0.125f;
;             const float* cp = COS + pos * 32 + 8 * fq; const float* sp = SIN + pos * 32 + 8 * fq;
	v_fma_f32 v10, v10, v19, v16
	v_mul_f32_e32 v16, v50, v18
	v_fmac_f32_e32 v17, v11, v16
	v_add_u32_e32 v11, 0x1aaa0, v0
	v_cvt_pk_bf16_f32 v10, v10, v17
	ds_write_b16 v11, v10
	v_add_u32_e32 v11, 0x1abb0, v0
	ds_write_b16_d16_hi v11, v10
	v_mov_b64_e32 v[10:11], v[156:157]
	v_mov_b64_e32 v[16:17], v[230:231]
	v_mul_f32_e32 v19, v49, v18
	s_waitcnt vmcnt(0)
	v_fma_f32 v10, v10, v19, v16
	v_mul_f32_e32 v16, v48, v18
	v_fmac_f32_e32 v17, v16, v11
	v_add_u32_e32 v11, 0x1acc0, v0
	v_cvt_pk_bf16_f32 v10, v10, v17
	ds_write_b16 v11, v10
	v_add_u32_e32 v11, 0x1add0, v0
	ds_write_b16_d16_hi v11, v10
	v_mov_b64_e32 v[10:11], v[158:159]
	v_mov_b64_e32 v[16:17], v[232:233]
	v_mul_f32_e32 v19, v47, v18
	s_waitcnt vmcnt(0)
	v_fma_f32 v10, v19, v10, v16
	v_mul_f32_e32 v16, v46, v18
	v_fmac_f32_e32 v17, v16, v11
	v_add_u32_e32 v11, 0x1aee0, v0
	v_cvt_pk_bf16_f32 v10, v10, v17
	ds_write_b16 v11, v10
	v_add_u32_e32 v11, 0x1aff0, v0
	ds_write_b16_d16_hi v11, v10
	v_mov_b64_e32 v[10:11], v[184:185]
	v_mov_b64_e32 v[16:17], v[234:235]
	v_mul_f32_e32 v19, v45, v18
	s_waitcnt vmcnt(0)
	v_fma_f32 v10, v19, v10, v16
	v_mul_f32_e32 v16, v44, v18
	v_fmac_f32_e32 v17, v16, v11
	v_add_u32_e32 v11, 0x1b100, v0
	v_cvt_pk_bf16_f32 v10, v10, v17
	ds_write_b16 v11, v10
	v_add_u32_e32 v11, 0x1b210, v0
	ds_write_b16_d16_hi v11, v10
	v_mov_b64_e32 v[10:11], v[186:187]
	v_mov_b64_e32 v[16:17], v[236:237]
	v_mul_f32_e32 v19, v43, v18
	v_or_b32_e32 v44, s17, v161
	s_waitcnt vmcnt(0)
	v_fma_f32 v10, v19, v10, v16
	v_mul_f32_e32 v16, v42, v18
	v_fmac_f32_e32 v17, v16, v11
	v_add_u32_e32 v11, 0x1b320, v0
	v_cvt_pk_bf16_f32 v10, v10, v17
	ds_write_b16 v11, v10
	v_add_u32_e32 v11, 0x1b430, v0
	ds_write_b16_d16_hi v11, v10
	v_mov_b64_e32 v[10:11], v[188:189]
	v_mov_b64_e32 v[16:17], v[238:239]
	v_mul_f32_e32 v19, v41, v18
	s_waitcnt vmcnt(0)
	v_fma_f32 v10, v19, v10, v16
	v_mul_f32_e32 v16, v40, v18
	v_fmac_f32_e32 v17, v16, v11
	v_add_u32_e32 v11, 0x1b540, v0
	v_cvt_pk_bf16_f32 v10, v10, v17
	ds_write_b16 v11, v10
	v_add_u32_e32 v11, 0x1b650, v0
	ds_write_b16_d16_hi v11, v10
	v_mov_b64_e32 v[10:11], v[190:191]
	v_mov_b64_e32 v[16:17], v[240:241]
	v_mul_f32_e32 v19, v39, v18
	s_waitcnt vmcnt(0)
	v_fma_f32 v10, v19, v10, v16
	v_mul_f32_e32 v16, v38, v18
	v_fmac_f32_e32 v17, v16, v11
	v_add_u32_e32 v11, 0x1b760, v0
	v_cvt_pk_bf16_f32 v10, v10, v17
	ds_write_b16 v11, v10
	v_add_u32_e32 v11, 0x1b870, v0
	ds_write_b16_d16_hi v11, v10
	v_mov_b64_e32 v[10:11], v[192:193]
	v_mov_b64_e32 v[16:17], v[242:243]
	s_waitcnt vmcnt(0)
	v_fma_f32 v10, v15, v10, v16
	v_fmac_f32_e32 v17, v14, v11
	v_add_u32_e32 v11, 0x1b980, v0
	v_cvt_pk_bf16_f32 v10, v10, v17
	ds_write_b16 v11, v10
	v_add_u32_e32 v11, 0x1ba90, v0
	ds_write_b16_d16_hi v11, v10
	v_mov_b64_e32 v[10:11], v[194:195]
	v_mov_b64_e32 v[14:15], v[244:245]
	s_waitcnt vmcnt(0)
	v_fma_f32 v10, v13, v10, v14
	v_fmac_f32_e32 v15, v12, v11
	v_add_u32_e32 v11, 0x1bba0, v0
	v_cvt_pk_bf16_f32 v10, v10, v15
	ds_write_b16 v11, v10
	v_add_u32_e32 v11, 0x1bcb0, v0
	ds_write_b16_d16_hi v11, v10
	v_mov_b64_e32 v[10:11], v[196:197]
	v_mov_b64_e32 v[12:13], v[200:201]
	v_lshlrev_b32_e32 v14, 7, v44
	v_mov_b32_e32 v15, v1
	v_or_b32_e32 v44, s48, v44
	s_waitcnt vmcnt(0)
	v_fma_f32 v9, v9, v10, v12
	v_fmac_f32_e32 v13, v8, v11
	v_cvt_pk_bf16_f32 v8, v9, v13
	v_add_u32_e32 v9, 0x1bdc0, v0
	ds_write_b16 v9, v8
	v_add_u32_e32 v9, 0x1bed0, v0
	ds_write_b16_d16_hi v9, v8
	v_mov_b64_e32 v[8:9], v[198:199]
	v_mov_b64_e32 v[10:11], v[202:203]
	s_waitcnt vmcnt(0)
	v_fma_f32 v7, v7, v8, v10
	v_fmac_f32_e32 v11, v6, v9
	v_cvt_pk_bf16_f32 v6, v7, v11
	v_add_u32_e32 v7, 0x1bfe0, v0
	v_add_u32_e32 v0, 0x1c0f0, v0
	ds_write_b16_d16_hi v0, v6
	v_or_b32_e32 v0, 32, v163
	ds_write_b16 v7, v6
	v_mad_u64_u32 v[6:7], s[28:29], v0, s83, v[134:135]
	v_mad_i32_i24 v7, s49, v212, v7
	v_or_b32_e32 v0, 48, v163
	v_readfirstlane_b32 s16, v204
	v_and_b32_e32 v43, 15, v204
	v_bfe_u32 v44, v204, 4, 2
	s_and_b32 s24, s2, 3
	s_lshr_b32 s16, s16, 6
	s_bfe_u32 s27, s2, 0x40002
	s_lshr_b32 s17, s16, 1
	s_lshr_b32 s25, s16, 2
	s_xor_b32 s25, s25, s16
	s_and_b32 s25, s25, 1
	s_lshl_b32 s25, s25, 6
	s_lshl_b32 s26, s24, 2
	s_add_i32 s26, s26, s17
	s_and_b32 s28, s2, -4
	s_lshl_b32 s28, s28, 5
	s_lshl_b32 s29, s27, 7
	s_add_i32 s28, s28, s25
	s_add_i32 s29, s29, s25
	s_lshl_b32 s4, s26, 7
	v_add_u32_e32 v166, s28, v43
	v_mul_u32_u24_e32 v46, 0x3c00, v166
	v_lshl_add_u32 v46, v44, 4, v46
	v_add_u32_e32 v46, s4, v46
	v_lshlrev_b32_e32 v48, 11, v166
	v_lshl_add_u32 v48, v44, 3, v48
	v_add_u32_e32 v48, s4, v48
	v_add_u32_e32 v166, s29, v43
	v_lshlrev_b32_e32 v47, 7, v166
	v_lshl_add_u32 v47, v44, 5, v47
	v_mul_u32_u24_e32 v45, 0x90, v43
	v_lshl_add_u32 v45, v44, 4, v45
	v_mul_u32_u24_e32 v166, 0x210, v43
	v_lshl_add_u32 v166, v44, 3, v166
	v_add_u32_e32 v194, 0x9000, v166
	v_add_u32_e32 v195, 0xb100, v166
	v_add_u32_e32 v196, 0xd200, v166
	v_add_u32_e32 v197, 0xf300, v166
	v_lshlrev_b32_e32 v166, 2, v44
	v_sub_u32_e32 v166, v43, v166
	v_cmp_gt_i32_e64 s[40:41], 0, v166
	v_cmp_gt_i32_e64 s[42:43], 1, v166
	v_cmp_gt_i32_e64 s[44:45], 2, v166
	v_cmp_gt_i32_e64 s[46:47], 3, v166
	v_mov_b32_e32 v49, 0xf149f2ca
	v_lshlrev_b32_e32 v167, 5, v44
	v_mov_b32_e32 v166, s26
	v_lshlrev_b32_e32 v166, 2, v166
	s_mov_b32 s4, s25
	s_mov_b32 vcc_lo, s63
	s_mov_b32 vcc_hi, s78
	s_cmp_lg_u32 s27, 0
	s_cselect_b64 s[28:29], -1, 0
	s_and_b64 s[48:49], s[40:41], s[28:29]
	s_and_b64 s[50:51], s[42:43], s[28:29]
	s_and_b64 s[52:53], s[44:45], s[28:29]
	s_and_b64 s[26:27], s[46:47], s[28:29]
	v_readlane_b32 s6, v250, 36
	v_readlane_b32 s7, v250, 37
	v_readlane_b32 s16, v250, 38
	v_readlane_b32 s17, v250, 39
	v_readlane_b32 s24, v248, 54
	v_readlane_b32 s25, v248, 55
	global_load_dwordx4 v[26:29], v167, s[38:39]
	global_load_dwordx4 v[30:33], v167, s[38:39] offset:16
	global_load_dwordx4 v[34:37], v167, s[38:39] offset:128
	global_load_dwordx4 v[38:41], v167, s[38:39] offset:144
	global_load_dword v42, v166, vcc
	s_nop 1
	global_load_dwordx4 v[2:5], v46, s[10:11]
	global_load_dwordx4 v[6:9], v46, s[10:11] offset:64
	global_load_dwordx4 v[10:13], v47, s[6:7]
	global_load_dwordx4 v[14:17], v47, s[6:7] offset:16
	global_load_dwordx4 v[18:21], v47, s[16:17]
	global_load_dwordx4 v[22:25], v47, s[16:17] offset:16
	v_add_u32_e32 v46, 0x3c000, v46
	v_add_u32_e32 v47, 0x800, v47
	global_load_dwordx4 v[218:221], v46, s[10:11]
	global_load_dwordx4 v[222:225], v46, s[10:11] offset:64
	global_load_dwordx4 v[226:229], v47, s[6:7]
	global_load_dwordx4 v[230:233], v47, s[6:7] offset:16
	global_load_dwordx4 v[234:237], v47, s[16:17]
	global_load_dwordx4 v[238:241], v47, s[16:17] offset:16
	v_add_u32_e32 v46, 0x3c000, v46
	v_add_u32_e32 v47, 0x800, v47
	s_waitcnt lgkmcnt(0)
	s_barrier
	s_cmp_eq_u32 s4, 0
	s_cbranch_scc1 .Latt_r0
; __device__ __forceinline__ unsigned cvt_pk_bf16(float lo, float hi) { unsigned r; asm volatile("v_cvt_pk_bf16_f32 %0, %1, %2" : "=v"(r) : "v"(lo), "v"(hi)); return r; }
; #define LAS __attribute__((address_space(3)))
; #define MFMA16(a, b, c) __builtin_amdgcn_mfma_f32_16x16x32_bf16((a), (b), (c), 0, 0, 0)
; __device__ __forceinline__ void unpack8(const u32x4 w, float* f) { f[0] = bf_lo(w.x); f[1] = bf_hi(w.x); f[2] = bf_lo(w.y); f[3] = bf_hi(w.y); f[4] = bf_lo(w.z); f[5] = bf_hi(w.z); f[6] = bf_lo(w.w); f[7] = bf_hi(w.w); }
; __device__ __forceinline__ void p2_block(LAS unsigned char* lds, const bf16_t* __restrict__ PROJ, bf16_t* __restrict__ ATT, bf16_t* __restrict__ SGU, const float* __restrict__ qn, const float* __restrict__ kn, ...
;     ...
;         {
;             float x1[8], x2[8]; unpack8(qa[c], x1); unpack8(qb[c], x2);
;             float ss = 0.f;
; #pragma unroll
;             for (int j = 0; j < 8; ++j) ss += x1[j] * x1[j] + x2[j] * x2[j];
;             ss += __shfl_xor(ss, 16); ss += __shfl_xor(ss, 32);
;             const float rinv = rsqrtf(ss * (1.0f / 64.0f) + pg8::EPS) * 0.125f;
;             const float* cp = COS + pos * 32 + 8 * fq; const float* sp = SIN + pos * 32 + 8 * fq;
;             float o1[8], o2[8];
; #pragma unroll
;             for (int j = 0; j < 8; ++j) { const float a1 = x1[j] * rinv * qn[8 * fq + j], a2 = x2[j] * rinv * qn[32 + 8 * fq + j], cc = cp[j], sn = sp[j]; o1[j] = a1 * cc - a2 * sn; o2[j] = a2 * cc + a1 * sn; }
;             u32x4 w0, w1;
;             w0.x = cvt_pk_bf16(o1[0], o1[1]); w0.y = cvt_pk_bf16(o1[2], o1[3]); w0.z = cvt_pk_bf16(o1[4], o1[5]); w0.w = cvt_pk_bf16(o1[6], o1[7]);
;             w1.x = cvt_pk_bf16(o2[0], o2[1]); w1.y = cvt_pk_bf16(o2[2], o2[3]); w1.z = cvt_pk_bf16(o2[4], o2[5]); w1.w = cvt_pk_bf16(o2[6], o2[7]);
;             qf0 = __builtin_bit_cast(bf16x8, w0); qf1 = __builtin_bit_cast(bf16x8, w1);
;         }
;         const int t0 = (i0 >> 4) < 6 ? (i0 >> 4) : 6;
;         f32x4 sc_[10];
;         const LAS unsigned char* kbase = KS + (16 * t0 + fr) * KS_STRIDE + 16 * fq;
; #pragma unroll
;         for (int t = 0; t < 10; ++t) { const bf16x8 k0 = *(const LAS bf16x8*)(kbase + t * 16 * KS_STRIDE), k1 = *(const LAS bf16x8*)(kbase + t * 16 * KS_STRIDE + 64);
;             f32x4 z = (f32x4){0.f, 0.f, 0.f, 0.f}; z = MFMA16(k0, qf0, z); sc_[t] = MFMA16(k1, qf1, z); }
.Latt_r64:
	ds_read_b128 v[98:101], v45 offset:9216
	ds_read_b128 v[102:105], v45 offset:9280
	ds_read_b128 v[106:109], v45 offset:11520
	ds_read_b128 v[110:113], v45 offset:11584
	ds_read_b128 v[114:117], v45 offset:13824
	ds_read_b128 v[118:121], v45 offset:13888
	ds_read_b128 v[122:125], v45 offset:16128
	ds_read_b128 v[126:129], v45 offset:16192
	ds_read_b128 v[130:133], v45 offset:18432
	ds_read_b128 v[134:137], v45 offset:18496
	ds_read_b128 v[138:141], v45 offset:20736
	ds_read_b128 v[142:145], v45 offset:20800
	ds_read_b128 v[146:149], v45 offset:23040
	ds_read_b128 v[150:153], v45 offset:23104
	s_waitcnt vmcnt(6)
	v_lshlrev_b32_e32 v58, 16, v2
	v_and_b32_e32 v59, 0xffff0000, v2
	v_lshlrev_b32_e32 v66, 16, v6
	v_and_b32_e32 v67, 0xffff0000, v6
	v_lshlrev_b32_e32 v60, 16, v3
	v_and_b32_e32 v61, 0xffff0000, v3
	v_lshlrev_b32_e32 v68, 16, v7
	v_and_b32_e32 v69, 0xffff0000, v7
	v_lshlrev_b32_e32 v62, 16, v4
	v_and_b32_e32 v63, 0xffff0000, v4
	v_lshlrev_b32_e32 v70, 16, v8
	v_and_b32_e32 v71, 0xffff0000, v8
	v_lshlrev_b32_e32 v64, 16, v5
	v_and_b32_e32 v65, 0xffff0000, v5
	v_lshlrev_b32_e32 v72, 16, v9
	v_and_b32_e32 v73, 0xffff0000, v9
	v_mul_f32_e32 v74, v58, v58
	v_mul_f32_e32 v75, v59, v59
	v_fmac_f32_e32 v74, v60, v60
	v_fmac_f32_e32 v75, v61, v61
	v_fmac_f32_e32 v74, v62, v62
	v_fmac_f32_e32 v75, v63, v63
	v_fmac_f32_e32 v74, v64, v64
	v_fmac_f32_e32 v75, v65, v65
	v_fmac_f32_e32 v74, v66, v66
	v_fmac_f32_e32 v75, v67, v67
	v_fmac_f32_e32 v74, v68, v68
	v_fmac_f32_e32 v75, v69, v69
	v_fmac_f32_e32 v74, v70, v70
	v_fmac_f32_e32 v75, v71, v71
	v_fmac_f32_e32 v74, v72, v72
	v_fmac_f32_e32 v75, v73, v73
	v_add_f32_e32 v74, v74, v75
	v_mov_b32_e32 v166, v74
	s_nop 1
	v_permlane16_swap_b32_e32 v74, v166
	v_add_f32_e32 v74, v74, v166
	v_mov_b32_e32 v166, v74
	s_nop 1
	v_permlane32_swap_b32_e32 v74, v166
	v_add_f32_e32 v74, v74, v166
	v_fmamk_f32 v74, v74, 0x3c800000, v209
	v_rsq_f32_e32 v76, v74
	s_nop 0
	v_mul_f32_e32 v76, 0x3e000000, v76
	v_mul_f32_e32 v58, v58, v76
	v_mul_f32_e32 v66, v66, v76
	v_mul_f32_e32 v59, v59, v76
	v_mul_f32_e32 v67, v67, v76
	v_mul_f32_e32 v60, v60, v76
	v_mul_f32_e32 v68, v68, v76
	v_mul_f32_e32 v61, v61, v76
	v_mul_f32_e32 v69, v69, v76
	v_mul_f32_e32 v62, v62, v76
	v_mul_f32_e32 v70, v70, v76
	v_mul_f32_e32 v63, v63, v76
	v_mul_f32_e32 v71, v71, v76
	v_mul_f32_e32 v64, v64, v76
	v_mul_f32_e32 v72, v72, v76
	v_mul_f32_e32 v65, v65, v76
	v_mul_f32_e32 v73, v73, v76
	v_mul_f32_e32 v58, v58, v26
	v_mul_f32_e32 v66, v66, v34
	v_mul_f32_e32 v59, v59, v27
	v_mul_f32_e32 v67, v67, v35
	v_mul_f32_e32 v60, v60, v28
	v_mul_f32_e32 v68, v68, v36
	v_mul_f32_e32 v61, v61, v29
	v_mul_f32_e32 v69, v69, v37
	v_mul_f32_e32 v62, v62, v30
	v_mul_f32_e32 v70, v70, v38
	v_mul_f32_e32 v63, v63, v31
	v_mul_f32_e32 v71, v71, v39
	v_mul_f32_e32 v64, v64, v32
	v_mul_f32_e32 v72, v72, v40
	v_mul_f32_e32 v65, v65, v33
	v_mul_f32_e32 v73, v73, v41
	v_mul_f32_e32 v78, v66, v18
	v_mul_f32_e32 v86, v58, v18
	v_mul_f32_e32 v79, v67, v19
	v_mul_f32_e32 v87, v59, v19
	v_mul_f32_e32 v80, v68, v20
	v_mul_f32_e32 v88, v60, v20
	v_mul_f32_e32 v81, v69, v21
	v_mul_f32_e32 v89, v61, v21
	v_mul_f32_e32 v82, v70, v22
	v_mul_f32_e32 v90, v62, v22
	v_mul_f32_e32 v83, v71, v23
	v_mul_f32_e32 v91, v63, v23
	v_mul_f32_e32 v84, v72, v24
	v_mul_f32_e32 v92, v64, v24
	v_mul_f32_e32 v85, v73, v25
	v_mul_f32_e32 v93, v65, v25
	v_fma_f32 v78, v58, v10, -v78
	v_fmac_f32_e32 v86, v66, v10
	v_fma_f32 v79, v59, v11, -v79
	v_fmac_f32_e32 v87, v67, v11
	v_fma_f32 v80, v60, v12, -v80
	v_fmac_f32_e32 v88, v68, v12
	v_fma_f32 v81, v61, v13, -v81
	v_fmac_f32_e32 v89, v69, v13
	v_fma_f32 v82, v62, v14, -v82
	v_fmac_f32_e32 v90, v70, v14
	v_fma_f32 v83, v63, v15, -v83
	v_fmac_f32_e32 v91, v71, v15
	v_fma_f32 v84, v64, v16, -v84
	v_fmac_f32_e32 v92, v72, v16
	v_fma_f32 v85, v65, v17, -v85
	v_fmac_f32_e32 v93, v73, v17
	v_cvt_pk_bf16_f32 v50, v78, v79
	v_cvt_pk_bf16_f32 v54, v86, v87
	v_cvt_pk_bf16_f32 v51, v80, v81
	v_cvt_pk_bf16_f32 v55, v88, v89
	v_cvt_pk_bf16_f32 v52, v82, v83
	v_cvt_pk_bf16_f32 v56, v90, v91
	v_cvt_pk_bf16_f32 v53, v84, v85
	v_cvt_pk_bf16_f32 v57, v92, v93
	global_load_dwordx4 v[2:5], v46, s[10:11]
	global_load_dwordx4 v[6:9], v46, s[10:11] offset:64
	global_load_dwordx4 v[10:13], v47, s[6:7]
	global_load_dwordx4 v[14:17], v47, s[6:7] offset:16
	global_load_dwordx4 v[18:21], v47, s[16:17]
	global_load_dwordx4 v[22:25], v47, s[16:17] offset:16
	v_add_u32_e32 v46, 0x3c000, v46
	v_add_u32_e32 v47, 0x800, v47
	s_nop 1
	s_waitcnt lgkmcnt(13)
	v_mfma_f32_16x16x32_bf16 v[58:61], v[98:101], v[50:53], 0
	s_waitcnt lgkmcnt(12)
	v_mfma_f32_16x16x32_bf16 v[58:61], v[102:105], v[54:57], v[58:61]
	ds_read_b128 v[154:157], v45 offset:25344
	ds_read_b128 v[158:161], v45 offset:25408
	s_waitcnt lgkmcnt(13)
	v_mfma_f32_16x16x32_bf16 v[62:65], v[106:109], v[50:53], 0
	s_waitcnt lgkmcnt(12)
	v_mfma_f32_16x16x32_bf16 v[62:65], v[110:113], v[54:57], v[62:65]
	ds_read_b128 v[162:165], v45 offset:27648
	ds_read_b128 v[182:185], v45 offset:27712
	s_waitcnt lgkmcnt(13)
	v_mfma_f32_16x16x32_bf16 v[66:69], v[114:117], v[50:53], 0
	s_waitcnt lgkmcnt(12)
	v_mfma_f32_16x16x32_bf16 v[66:69], v[118:121], v[54:57], v[66:69]
	s_waitcnt lgkmcnt(11)
	v_mfma_f32_16x16x32_bf16 v[70:73], v[122:125], v[50:53], 0
	s_waitcnt lgkmcnt(10)
	v_mfma_f32_16x16x32_bf16 v[70:73], v[126:129], v[54:57], v[70:73]
	s_waitcnt lgkmcnt(9)
	v_mfma_f32_16x16x32_bf16 v[74:77], v[130:133], v[50:53], 0
	s_waitcnt lgkmcnt(8)
	v_mfma_f32_16x16x32_bf16 v[74:77], v[134:137], v[54:57], v[74:77]
	s_waitcnt lgkmcnt(7)
	v_mfma_f32_16x16x32_bf16 v[78:81], v[138:141], v[50:53], 0
	s_waitcnt lgkmcnt(6)
; #define LAS __attribute__((address_space(3)))
; #define MFMA16(a, b, c) __builtin_amdgcn_mfma_f32_16x16x32_bf16((a), (b), (c), 0, 0, 0)
; __device__ __forceinline__ void p2_block(LAS unsigned char* lds, const bf16_t* __restrict__ PROJ, bf16_t* __restrict__ ATT, bf16_t* __restrict__ SGU, const float* __restrict__ qn, const float* __restrict__ kn, ...
;     ...
;         for (int t = 0; t < 10; ++t) { const bf16x8 k0 = *(const LAS bf16x8*)(kbase + t * 16 * KS_STRIDE), k1 = *(const LAS bf16x8*)(kbase + t * 16 * KS_STRIDE + 64);
;             f32x4 z = (f32x4){0.f, 0.f, 0.f, 0.f}; z = MFMA16(k0, qf0, z); sc_[t] = MFMA16(k1, qf1, z); }
;         float mx = -1e30f;
; #pragma unroll
;         for (int t = 0; t < 10; ++t)
; #pragma unroll
;             for (int e = 0; e < 4; ++e) { const int kx = 16 * (t0 + t) + 4 * fq + e, d = kx - irow; const bool ok = (d >= 1) && (d <= 128) && (n > 0 || kx >= 128);
;                 const float v = ok ? sc_[t][e] : -1e30f; sc_[t][e] = v; mx = fmaxf(mx, v); }
;         mx = fmaxf(mx, __shfl_xor(mx, 16)); mx = fmaxf(mx, __shfl_xor(mx, 32)); mx = fmaxf(mx, sink);
;         float sum = 0.f;
; #pragma unroll
;         for (int t = 0; t < 10; ++t)
; #pragma unroll
;             for (int e = 0; e < 4; ++e) { const float p = __builtin_amdgcn_exp2f((sc_[t][e] - mx) * LOG2E); sc_[t][e] = p; sum += p; }
;         sum += __shfl_xor(sum, 16); sum += __shfl_xor(sum, 32);
;         const float inv = 1.0f / (sum + __builtin_amdgcn_exp2f((sink - mx) * LOG2E));
	v_mfma_f32_16x16x32_bf16 v[78:81], v[142:145], v[54:57], v[78:81]
	s_waitcnt lgkmcnt(5)
	v_mfma_f32_16x16x32_bf16 v[82:85], v[146:149], v[50:53], 0
	s_waitcnt lgkmcnt(4)
	v_mfma_f32_16x16x32_bf16 v[82:85], v[150:153], v[54:57], v[82:85]
	s_waitcnt lgkmcnt(3)
	v_mfma_f32_16x16x32_bf16 v[86:89], v[154:157], v[50:53], 0
	s_waitcnt lgkmcnt(2)
	v_mfma_f32_16x16x32_bf16 v[86:89], v[158:161], v[54:57], v[86:89]
	s_waitcnt lgkmcnt(1)
	v_mfma_f32_16x16x32_bf16 v[90:93], v[162:165], v[50:53], 0
	s_waitcnt lgkmcnt(0)
	v_mfma_f32_16x16x32_bf16 v[90:93], v[182:185], v[54:57], v[90:93]
	ds_read2_b64 v[98:101], v194 offset0:16 offset1:20
	ds_read2_b64 v[102:105], v195 offset0:16 offset1:20
	ds_read2_b64 v[106:109], v196 offset0:16 offset1:20
	ds_read2_b64 v[110:113], v197 offset0:16 offset1:20
	ds_read2_b64 v[114:117], v194 offset0:24 offset1:28
	ds_read2_b64 v[118:121], v195 offset0:24 offset1:28
	ds_read2_b64 v[122:125], v196 offset0:24 offset1:28
	ds_read2_b64 v[126:129], v197 offset0:24 offset1:28
	ds_read2_b64 v[130:133], v194 offset0:32 offset1:36
	ds_read2_b64 v[134:137], v195 offset0:32 offset1:36
	ds_read2_b64 v[138:141], v196 offset0:32 offset1:36
	ds_read2_b64 v[142:145], v197 offset0:32 offset1:36
	ds_read2_b64 v[146:149], v194 offset0:40 offset1:44
	ds_read2_b64 v[150:153], v195 offset0:40 offset1:44
	ds_read2_b64 v[154:157], v196 offset0:40 offset1:44
	s_nop 4
	v_cndmask_b32_e64 v58, v49, v58, s[48:49]
	v_cndmask_b32_e64 v59, v49, v59, s[50:51]
	v_cndmask_b32_e64 v60, v49, v60, s[52:53]
	v_cndmask_b32_e64 v61, v49, v61, s[26:27]
	v_cndmask_b32_e64 v62, v49, v62, s[28:29]
	v_cndmask_b32_e64 v63, v49, v63, s[28:29]
	v_cndmask_b32_e64 v64, v49, v64, s[28:29]
	v_cndmask_b32_e64 v65, v49, v65, s[28:29]
	v_cndmask_b32_e64 v66, v49, v66, s[28:29]
	v_cndmask_b32_e64 v67, v49, v67, s[28:29]
	v_cndmask_b32_e64 v68, v49, v68, s[28:29]
	v_cndmask_b32_e64 v69, v49, v69, s[28:29]
	v_cndmask_b32_e64 v70, v49, v70, s[28:29]
	v_cndmask_b32_e64 v71, v49, v71, s[28:29]
	v_cndmask_b32_e64 v72, v49, v72, s[28:29]
	v_cndmask_b32_e64 v73, v49, v73, s[28:29]
	v_cndmask_b32_e64 v90, v90, v49, s[40:41]
	v_cndmask_b32_e64 v91, v91, v49, s[42:43]
	v_cndmask_b32_e64 v92, v92, v49, s[44:45]
	v_cndmask_b32_e64 v93, v93, v49, s[46:47]
	v_max_f32_e32 v167, v58, v59
	v_max_f32_e32 v94, v60, v61
	v_max3_f32 v167, v167, v62, v63
	v_max3_f32 v94, v94, v64, v65
	v_max3_f32 v167, v167, v66, v67
	v_max3_f32 v94, v94, v68, v69
	v_max3_f32 v167, v167, v70, v71
	v_max3_f32 v94, v94, v72, v73
	v_max3_f32 v167, v167, v74, v75
	v_max3_f32 v94, v94, v76, v77
	v_max3_f32 v167, v167, v78, v79
	v_max3_f32 v94, v94, v80, v81
	v_max3_f32 v167, v167, v82, v83
	v_max3_f32 v94, v94, v84, v85
	v_max3_f32 v167, v167, v86, v87
	v_max3_f32 v94, v94, v88, v89
	v_max3_f32 v167, v167, v90, v91
	v_max3_f32 v94, v94, v92, v93
	v_max_f32_e32 v167, v167, v94
	v_mov_b32_e32 v166, v167
	s_nop 1
	v_permlane16_swap_b32_e32 v167, v166
	v_max_f32_e32 v167, v167, v166
	v_mov_b32_e32 v166, v167
	s_nop 1
	v_permlane32_swap_b32_e32 v167, v166
	v_max_f32_e32 v167, v167, v166
	v_max_f32_e32 v167, v167, v42
	v_mul_f32_e32 v94, 0xbfb8aa3b, v167
	v_fmamk_f32 v58, v58, 0x3fb8aa3b, v94
	v_fmamk_f32 v59, v59, 0x3fb8aa3b, v94
	v_fmamk_f32 v60, v60, 0x3fb8aa3b, v94
	v_fmamk_f32 v61, v61, 0x3fb8aa3b, v94
	v_fmamk_f32 v62, v62, 0x3fb8aa3b, v94
	v_fmamk_f32 v63, v63, 0x3fb8aa3b, v94
	v_fmamk_f32 v64, v64, 0x3fb8aa3b, v94
	v_fmamk_f32 v65, v65, 0x3fb8aa3b, v94
	v_fmamk_f32 v66, v66, 0x3fb8aa3b, v94
	v_fmamk_f32 v67, v67, 0x3fb8aa3b, v94
	v_fmamk_f32 v68, v68, 0x3fb8aa3b, v94
	v_fmamk_f32 v69, v69, 0x3fb8aa3b, v94
	v_fmamk_f32 v70, v70, 0x3fb8aa3b, v94
	v_fmamk_f32 v71, v71, 0x3fb8aa3b, v94
	v_fmamk_f32 v72, v72, 0x3fb8aa3b, v94
	v_fmamk_f32 v73, v73, 0x3fb8aa3b, v94
	v_fmamk_f32 v74, v74, 0x3fb8aa3b, v94
	v_fmamk_f32 v75, v75, 0x3fb8aa3b, v94
	v_fmamk_f32 v76, v76, 0x3fb8aa3b, v94
	v_fmamk_f32 v77, v77, 0x3fb8aa3b, v94
	v_fmamk_f32 v78, v78, 0x3fb8aa3b, v94
	v_fmamk_f32 v79, v79, 0x3fb8aa3b, v94
	v_fmamk_f32 v80, v80, 0x3fb8aa3b, v94
	v_fmamk_f32 v81, v81, 0x3fb8aa3b, v94
	v_fmamk_f32 v82, v82, 0x3fb8aa3b, v94
	v_fmamk_f32 v83, v83, 0x3fb8aa3b, v94
	v_fmamk_f32 v84, v84, 0x3fb8aa3b, v94
	v_fmamk_f32 v85, v85, 0x3fb8aa3b, v94
	v_fmamk_f32 v86, v86, 0x3fb8aa3b, v94
	v_fmamk_f32 v87, v87, 0x3fb8aa3b, v94
	v_fmamk_f32 v88, v88, 0x3fb8aa3b, v94
	v_fmamk_f32 v89, v89, 0x3fb8aa3b, v94
	v_fmamk_f32 v90, v90, 0x3fb8aa3b, v94
	v_fmamk_f32 v91, v91, 0x3fb8aa3b, v94
	v_fmamk_f32 v92, v92, 0x3fb8aa3b, v94
	v_fmamk_f32 v93, v93, 0x3fb8aa3b, v94
	v_exp_f32_e32 v58, v58
	v_exp_f32_e32 v59, v59
	v_exp_f32_e32 v60, v60
	v_exp_f32_e32 v61, v61
	v_exp_f32_e32 v62, v62
	v_exp_f32_e32 v63, v63
	v_exp_f32_e32 v64, v64
	v_exp_f32_e32 v65, v65
	v_exp_f32_e32 v66, v66
	v_exp_f32_e32 v67, v67
	v_exp_f32_e32 v68, v68
	v_exp_f32_e32 v69, v69
	v_exp_f32_e32 v70, v70
	v_exp_f32_e32 v71, v71
	v_exp_f32_e32 v72, v72
	v_exp_f32_e32 v73, v73
	v_exp_f32_e32 v74, v74
	v_exp_f32_e32 v75, v75
	v_exp_f32_e32 v76, v76
	v_exp_f32_e32 v77, v77
	v_exp_f32_e32 v78, v78
	v_exp_f32_e32 v79, v79
	v_exp_f32_e32 v80, v80
	v_exp_f32_e32 v81, v81
	v_exp_f32_e32 v82, v82
	v_exp_f32_e32 v83, v83
	v_exp_f32_e32 v84, v84
	v_exp_f32_e32 v85, v85
	v_exp_f32_e32 v86, v86
	v_exp_f32_e32 v87, v87
	v_exp_f32_e32 v88, v88
	v_exp_f32_e32 v89, v89
	v_exp_f32_e32 v90, v90
	v_exp_f32_e32 v91, v91
	v_exp_f32_e32 v92, v92
	v_exp_f32_e32 v93, v93
	v_fmamk_f32 v95, v42, 0x3fb8aa3b, v94
	v_exp_f32_e32 v95, v95
	v_add_f32_e32 v167, v58, v59
	v_add_f32_e32 v94, v60, v61
	v_add_f32_e32 v167, v167, v62
	v_add_f32_e32 v94, v94, v63
	v_add_f32_e32 v167, v167, v64
	v_add_f32_e32 v94, v94, v65
; __device__ __forceinline__ unsigned cvt_pk_bf16(float lo, float hi) { unsigned r; asm volatile("v_cvt_pk_bf16_f32 %0, %1, %2" : "=v"(r) : "v"(lo), "v"(hi)); return r; }
; #define LAS __attribute__((address_space(3)))
; #define MFMA16(a, b, c) __builtin_amdgcn_mfma_f32_16x16x32_bf16((a), (b), (c), 0, 0, 0)
; __device__ __forceinline__ void p2_block(LAS unsigned char* lds, const bf16_t* __restrict__ PROJ, bf16_t* __restrict__ ATT, bf16_t* __restrict__ SGU, const float* __restrict__ qn, const float* __restrict__ kn, ...
;     ...
;             for (int e = 0; e < 4; ++e) { const float p = __builtin_amdgcn_exp2f((sc_[t][e] - mx) * LOG2E); sc_[t][e] = p; sum += p; }
;         sum += __shfl_xor(sum, 16); sum += __shfl_xor(sum, 32);
;         const float inv = 1.0f / (sum + __builtin_amdgcn_exp2f((sink - mx) * LOG2E));
;         f32x4 o[4];
; #pragma unroll
;         for (int dt = 0; dt < 4; ++dt) o[dt] = (f32x4){0.f, 0.f, 0.f, 0.f};
; #pragma unroll
;         for (int j = 0; j < 5; ++j) {
;             u32x4 pw; pw.x = cvt_pk_bf16(sc_[2 * j][0], sc_[2 * j][1]); pw.y = cvt_pk_bf16(sc_[2 * j][2], sc_[2 * j][3]); pw.z = cvt_pk_bf16(sc_[2 * j + 1][0], sc_[2 * j + 1][1]); pw.w = cvt_pk_bf16(sc_[2 * j + 1][2], sc_[2 * j + 1][3]);
;             const bf16x8 pf = __builtin_bit_cast(bf16x8, pw);
; #pragma unroll
;             for (int dt = 0; dt < 4; ++dt) { const LAS unsigned char* vb = VT + (16 * dt + fr) * VT_STRIDE + (16 * (t0 + 2 * j) + 4 * fq) * 2;
;                 const u32x2 va = *(const LAS u32x2*)vb, vc = *(const LAS u32x2*)(vb + 32); u32x4 vw; vw.x = va.x; vw.y = va.y; vw.z = vc.x; vw.w = vc.y;
;                 o[dt] = MFMA16(__builtin_bit_cast(bf16x8, vw), pf, o[dt]); }
;         }
;         bf16_t* op = ATT + grow * 1024 + hq * 64 + 4 * fq;
; #pragma unroll
;         for (int dt = 0; dt < 4; ++dt) { u32x2 ow; ow.x = cvt_pk_bf16(o[dt][0] * inv, o[dt][1] * inv); ow.y = cvt_pk_bf16(o[dt][2] * inv, o[dt][3] * inv); *(u32x2*)(op + 16 * dt) = ow; }
	v_add_f32_e32 v167, v167, v66
	v_add_f32_e32 v94, v94, v67
	v_add_f32_e32 v167, v167, v68
	v_add_f32_e32 v94, v94, v69
	v_add_f32_e32 v167, v167, v70
	v_add_f32_e32 v94, v94, v71
	v_add_f32_e32 v167, v167, v72
	v_add_f32_e32 v94, v94, v73
	v_add_f32_e32 v167, v167, v74
	v_add_f32_e32 v94, v94, v75
	v_add_f32_e32 v167, v167, v76
	v_add_f32_e32 v94, v94, v77
	v_add_f32_e32 v167, v167, v78
	v_add_f32_e32 v94, v94, v79
	v_add_f32_e32 v167, v167, v80
	v_add_f32_e32 v94, v94, v81
	v_add_f32_e32 v167, v167, v82
	v_add_f32_e32 v94, v94, v83
	v_add_f32_e32 v167, v167, v84
	v_add_f32_e32 v94, v94, v85
	v_add_f32_e32 v167, v167, v86
	v_add_f32_e32 v94, v94, v87
	v_add_f32_e32 v167, v167, v88
	v_add_f32_e32 v94, v94, v89
	v_add_f32_e32 v167, v167, v90
	v_add_f32_e32 v94, v94, v91
	v_add_f32_e32 v167, v167, v92
	v_add_f32_e32 v94, v94, v93
	v_add_f32_e32 v167, v167, v94
	v_mov_b32_e32 v166, v167
	s_nop 1
	v_permlane16_swap_b32_e32 v167, v166
	v_add_f32_e32 v167, v167, v166
	v_mov_b32_e32 v166, v167
	s_nop 1
	v_permlane32_swap_b32_e32 v167, v166
	v_add_f32_e32 v167, v167, v166
	v_add_f32_e32 v167, v167, v95
	v_rcp_f32_e32 v167, v167
	v_mov_b32_e32 v94, 0
	v_mov_b32_e32 v95, 0
	v_mov_b32_e32 v96, 0
	v_mov_b32_e32 v97, 0
	v_cvt_pk_bf16_f32 v58, v58, v59
	v_cvt_pk_bf16_f32 v59, v60, v61
	v_cvt_pk_bf16_f32 v60, v62, v63
	v_cvt_pk_bf16_f32 v61, v64, v65
	v_cvt_pk_bf16_f32 v66, v66, v67
	v_cvt_pk_bf16_f32 v67, v68, v69
	v_cvt_pk_bf16_f32 v68, v70, v71
	v_cvt_pk_bf16_f32 v69, v72, v73
	v_cvt_pk_bf16_f32 v74, v74, v75
	v_cvt_pk_bf16_f32 v75, v76, v77
	v_cvt_pk_bf16_f32 v76, v78, v79
	v_cvt_pk_bf16_f32 v77, v80, v81
	v_cvt_pk_bf16_f32 v82, v82, v83
	v_cvt_pk_bf16_f32 v83, v84, v85
	v_cvt_pk_bf16_f32 v84, v86, v87
	v_cvt_pk_bf16_f32 v85, v88, v89
	v_cvt_pk_bf16_f32 v90, v90, v91
	v_cvt_pk_bf16_f32 v91, v92, v93
	v_cvt_pk_bf16_f32 v92, v94, v95
	v_cvt_pk_bf16_f32 v93, v96, v97
	s_nop 1
	s_waitcnt lgkmcnt(14)
	v_mfma_f32_16x16x32_bf16 v[62:65], v[98:101], v[58:61], 0
	ds_read2_b64 v[158:161], v197 offset0:40 offset1:44
	s_waitcnt lgkmcnt(14)
	v_mfma_f32_16x16x32_bf16 v[70:73], v[102:105], v[58:61], 0
	ds_read2_b64 v[162:165], v194 offset0:48 offset1:52
	s_waitcnt lgkmcnt(14)
	v_mfma_f32_16x16x32_bf16 v[78:81], v[106:109], v[58:61], 0
	ds_read2_b64 v[182:185], v195 offset0:48 offset1:52
	s_waitcnt lgkmcnt(14)
	v_mfma_f32_16x16x32_bf16 v[86:89], v[110:113], v[58:61], 0
	ds_read2_b64 v[186:189], v196 offset0:48 offset1:52
	s_waitcnt lgkmcnt(14)
	v_mfma_f32_16x16x32_bf16 v[62:65], v[114:117], v[66:69], v[62:65]
	ds_read2_b64 v[190:193], v197 offset0:48 offset1:52
	s_waitcnt lgkmcnt(14)
	v_mfma_f32_16x16x32_bf16 v[70:73], v[118:121], v[66:69], v[70:73]
	s_waitcnt lgkmcnt(13)
	v_mfma_f32_16x16x32_bf16 v[78:81], v[122:125], v[66:69], v[78:81]
	s_waitcnt lgkmcnt(12)
	v_mfma_f32_16x16x32_bf16 v[86:89], v[126:129], v[66:69], v[86:89]
	s_waitcnt lgkmcnt(11)
	v_mfma_f32_16x16x32_bf16 v[62:65], v[130:133], v[74:77], v[62:65]
	s_waitcnt lgkmcnt(10)
	v_mfma_f32_16x16x32_bf16 v[70:73], v[134:137], v[74:77], v[70:73]
	s_waitcnt lgkmcnt(9)
	v_mfma_f32_16x16x32_bf16 v[78:81], v[138:141], v[74:77], v[78:81]
	s_waitcnt lgkmcnt(8)
	v_mfma_f32_16x16x32_bf16 v[86:89], v[142:145], v[74:77], v[86:89]
	s_waitcnt lgkmcnt(7)
	v_mfma_f32_16x16x32_bf16 v[62:65], v[146:149], v[82:85], v[62:65]
	s_waitcnt lgkmcnt(6)
	v_mfma_f32_16x16x32_bf16 v[70:73], v[150:153], v[82:85], v[70:73]
	s_waitcnt lgkmcnt(5)
	v_mfma_f32_16x16x32_bf16 v[78:81], v[154:157], v[82:85], v[78:81]
	s_waitcnt lgkmcnt(4)
	v_mfma_f32_16x16x32_bf16 v[86:89], v[158:161], v[82:85], v[86:89]
	s_waitcnt lgkmcnt(3)
	v_mfma_f32_16x16x32_bf16 v[62:65], v[162:165], v[90:93], v[62:65]
	s_waitcnt lgkmcnt(2)
	v_mfma_f32_16x16x32_bf16 v[70:73], v[182:185], v[90:93], v[70:73]
	s_waitcnt lgkmcnt(1)
	v_mfma_f32_16x16x32_bf16 v[78:81], v[186:189], v[90:93], v[78:81]
	s_waitcnt lgkmcnt(0)
	v_mfma_f32_16x16x32_bf16 v[86:89], v[190:193], v[90:93], v[86:89]
	ds_read_b128 v[98:101], v45 offset:11520
	ds_read_b128 v[102:105], v45 offset:11584
	ds_read_b128 v[106:109], v45 offset:13824
	ds_read_b128 v[110:113], v45 offset:13888
	ds_read_b128 v[114:117], v45 offset:16128
	ds_read_b128 v[118:121], v45 offset:16192
	ds_read_b128 v[122:125], v45 offset:18432
	ds_read_b128 v[126:129], v45 offset:18496
	ds_read_b128 v[130:133], v45 offset:20736
	ds_read_b128 v[134:137], v45 offset:20800
	ds_read_b128 v[138:141], v45 offset:23040
	ds_read_b128 v[142:145], v45 offset:23104
	ds_read_b128 v[146:149], v45 offset:25344
	ds_read_b128 v[150:153], v45 offset:25408
	s_nop 7
	v_mul_f32_e32 v62, v62, v167
	v_mul_f32_e32 v63, v63, v167
	v_mul_f32_e32 v64, v64, v167
	v_mul_f32_e32 v65, v65, v167
	v_mul_f32_e32 v70, v70, v167
	v_mul_f32_e32 v71, v71, v167
	v_mul_f32_e32 v72, v72, v167
	v_mul_f32_e32 v73, v73, v167
	v_mul_f32_e32 v78, v78, v167
	v_mul_f32_e32 v79, v79, v167
	v_mul_f32_e32 v80, v80, v167
	v_mul_f32_e32 v81, v81, v167
	v_mul_f32_e32 v86, v86, v167
	v_mul_f32_e32 v87, v87, v167
	v_mul_f32_e32 v88, v88, v167
	v_mul_f32_e32 v89, v89, v167
	v_cvt_pk_bf16_f32 v62, v62, v63
	v_cvt_pk_bf16_f32 v63, v64, v65
	global_store_dwordx2 v48, v[62:63], s[24:25] offset:0
	v_cvt_pk_bf16_f32 v70, v70, v71
	v_cvt_pk_bf16_f32 v71, v72, v73
	global_store_dwordx2 v48, v[70:71], s[24:25] offset:32
	v_cvt_pk_bf16_f32 v78, v78, v79
	v_cvt_pk_bf16_f32 v79, v80, v81
	global_store_dwordx2 v48, v[78:79], s[24:25] offset:64
	v_cvt_pk_bf16_f32 v86, v86, v87
	v_cvt_pk_bf16_f32 v87, v88, v89
	global_store_dwordx2 v48, v[86:87], s[24:25] offset:96
	v_add_u32_e32 v48, 0x8000, v48
	s_waitcnt vmcnt(10)
; __device__ __forceinline__ unsigned cvt_pk_bf16(float lo, float hi) { unsigned r; asm volatile("v_cvt_pk_bf16_f32 %0, %1, %2" : "=v"(r) : "v"(lo), "v"(hi)); return r; }
; #define LAS __attribute__((address_space(3)))
; #define MFMA16(a, b, c) __builtin_amdgcn_mfma_f32_16x16x32_bf16((a), (b), (c), 0, 0, 0)
; __device__ __forceinline__ void unpack8(const u32x4 w, float* f) { f[0] = bf_lo(w.x); f[1] = bf_hi(w.x); f[2] = bf_lo(w.y); f[3] = bf_hi(w.y); f[4] = bf_lo(w.z); f[5] = bf_hi(w.z); f[6] = bf_lo(w.w); f[7] = bf_hi(w.w); }
; __device__ __forceinline__ void p2_block(LAS unsigned char* lds, const bf16_t* __restrict__ PROJ, bf16_t* __restrict__ ATT, bf16_t* __restrict__ SGU, const float* __restrict__ qn, const float* __restrict__ kn, ...
;     ...
;         {
;             float x1[8], x2[8]; unpack8(qa[c], x1); unpack8(qb[c], x2);
;             float ss = 0.f;
; #pragma unroll
;             for (int j = 0; j < 8; ++j) ss += x1[j] * x1[j] + x2[j] * x2[j];
;             ss += __shfl_xor(ss, 16); ss += __shfl_xor(ss, 32);
;             const float rinv = rsqrtf(ss * (1.0f / 64.0f) + pg8::EPS) * 0.125f;
;             const float* cp = COS + pos * 32 + 8 * fq; const float* sp = SIN + pos * 32 + 8 * fq;
;             float o1[8], o2[8];
; #pragma unroll
;             for (int j = 0; j < 8; ++j) { const float a1 = x1[j] * rinv * qn[8 * fq + j], a2 = x2[j] * rinv * qn[32 + 8 * fq + j], cc = cp[j], sn = sp[j]; o1[j] = a1 * cc - a2 * sn; o2[j] = a2 * cc + a1 * sn; }
;             u32x4 w0, w1;
;             w0.x = cvt_pk_bf16(o1[0], o1[1]); w0.y = cvt_pk_bf16(o1[2], o1[3]); w0.z = cvt_pk_bf16(o1[4], o1[5]); w0.w = cvt_pk_bf16(o1[6], o1[7]);
;             w1.x = cvt_pk_bf16(o2[0], o2[1]); w1.y = cvt_pk_bf16(o2[2], o2[3]); w1.z = cvt_pk_bf16(o2[4], o2[5]); w1.w = cvt_pk_bf16(o2[6], o2[7]);
;             qf0 = __builtin_bit_cast(bf16x8, w0); qf1 = __builtin_bit_cast(bf16x8, w1);
;         }
;         const int t0 = (i0 >> 4) < 6 ? (i0 >> 4) : 6;
;         f32x4 sc_[10];
;         const LAS unsigned char* kbase = KS + (16 * t0 + fr) * KS_STRIDE + 16 * fq;
; #pragma unroll
;         for (int t = 0; t < 10; ++t) { const bf16x8 k0 = *(const LAS bf16x8*)(kbase + t * 16 * KS_STRIDE), k1 = *(const LAS bf16x8*)(kbase + t * 16 * KS_STRIDE + 64);
;             f32x4 z = (f32x4){0.f, 0.f, 0.f, 0.f}; z = MFMA16(k0, qf0, z); sc_[t] = MFMA16(k1, qf1, z); }
	v_lshlrev_b32_e32 v58, 16, v218
	v_and_b32_e32 v59, 0xffff0000, v218
	v_lshlrev_b32_e32 v66, 16, v222
	v_and_b32_e32 v67, 0xffff0000, v222
	v_lshlrev_b32_e32 v60, 16, v219
	v_and_b32_e32 v61, 0xffff0000, v219
	v_lshlrev_b32_e32 v68, 16, v223
	v_and_b32_e32 v69, 0xffff0000, v223
	v_lshlrev_b32_e32 v62, 16, v220
	v_and_b32_e32 v63, 0xffff0000, v220
	v_lshlrev_b32_e32 v70, 16, v224
	v_and_b32_e32 v71, 0xffff0000, v224
	v_lshlrev_b32_e32 v64, 16, v221
	v_and_b32_e32 v65, 0xffff0000, v221
	v_lshlrev_b32_e32 v72, 16, v225
	v_and_b32_e32 v73, 0xffff0000, v225
	v_mul_f32_e32 v74, v58, v58
	v_mul_f32_e32 v75, v59, v59
	v_fmac_f32_e32 v74, v60, v60
	v_fmac_f32_e32 v75, v61, v61
	v_fmac_f32_e32 v74, v62, v62
	v_fmac_f32_e32 v75, v63, v63
	v_fmac_f32_e32 v74, v64, v64
	v_fmac_f32_e32 v75, v65, v65
	v_fmac_f32_e32 v74, v66, v66
	v_fmac_f32_e32 v75, v67, v67
	v_fmac_f32_e32 v74, v68, v68
	v_fmac_f32_e32 v75, v69, v69
	v_fmac_f32_e32 v74, v70, v70
	v_fmac_f32_e32 v75, v71, v71
	v_fmac_f32_e32 v74, v72, v72
	v_fmac_f32_e32 v75, v73, v73
	v_add_f32_e32 v74, v74, v75
	v_mov_b32_e32 v166, v74
	s_nop 1
	v_permlane16_swap_b32_e32 v74, v166
	v_add_f32_e32 v74, v74, v166
	v_mov_b32_e32 v166, v74
	s_nop 1
	v_permlane32_swap_b32_e32 v74, v166
	v_add_f32_e32 v74, v74, v166
	v_fmamk_f32 v74, v74, 0x3c800000, v209
	v_rsq_f32_e32 v76, v74
	s_nop 0
	v_mul_f32_e32 v76, 0x3e000000, v76
	v_mul_f32_e32 v58, v58, v76
	v_mul_f32_e32 v66, v66, v76
	v_mul_f32_e32 v59, v59, v76
	v_mul_f32_e32 v67, v67, v76
	v_mul_f32_e32 v60, v60, v76
	v_mul_f32_e32 v68, v68, v76
	v_mul_f32_e32 v61, v61, v76
	v_mul_f32_e32 v69, v69, v76
	v_mul_f32_e32 v62, v62, v76
	v_mul_f32_e32 v70, v70, v76
	v_mul_f32_e32 v63, v63, v76
	v_mul_f32_e32 v71, v71, v76
	v_mul_f32_e32 v64, v64, v76
	v_mul_f32_e32 v72, v72, v76
	v_mul_f32_e32 v65, v65, v76
	v_mul_f32_e32 v73, v73, v76
	v_mul_f32_e32 v58, v58, v26
	v_mul_f32_e32 v66, v66, v34
	v_mul_f32_e32 v59, v59, v27
	v_mul_f32_e32 v67, v67, v35
	v_mul_f32_e32 v60, v60, v28
	v_mul_f32_e32 v68, v68, v36
	v_mul_f32_e32 v61, v61, v29
	v_mul_f32_e32 v69, v69, v37
	v_mul_f32_e32 v62, v62, v30
	v_mul_f32_e32 v70, v70, v38
	v_mul_f32_e32 v63, v63, v31
	v_mul_f32_e32 v71, v71, v39
	v_mul_f32_e32 v64, v64, v32
	v_mul_f32_e32 v72, v72, v40
	v_mul_f32_e32 v65, v65, v33
	v_mul_f32_e32 v73, v73, v41
	v_mul_f32_e32 v78, v66, v234
	v_mul_f32_e32 v86, v58, v234
	v_mul_f32_e32 v79, v67, v235
	v_mul_f32_e32 v87, v59, v235
	v_mul_f32_e32 v80, v68, v236
	v_mul_f32_e32 v88, v60, v236
	v_mul_f32_e32 v81, v69, v237
	v_mul_f32_e32 v89, v61, v237
	v_mul_f32_e32 v82, v70, v238
	v_mul_f32_e32 v90, v62, v238
	v_mul_f32_e32 v83, v71, v239
	v_mul_f32_e32 v91, v63, v239
	v_mul_f32_e32 v84, v72, v240
	v_mul_f32_e32 v92, v64, v240
	v_mul_f32_e32 v85, v73, v241
	v_mul_f32_e32 v93, v65, v241
	v_fma_f32 v78, v58, v226, -v78
	v_fmac_f32_e32 v86, v66, v226
	v_fma_f32 v79, v59, v227, -v79
	v_fmac_f32_e32 v87, v67, v227
	v_fma_f32 v80, v60, v228, -v80
	v_fmac_f32_e32 v88, v68, v228
	v_fma_f32 v81, v61, v229, -v81
	v_fmac_f32_e32 v89, v69, v229
	v_fma_f32 v82, v62, v230, -v82
	v_fmac_f32_e32 v90, v70, v230
	v_fma_f32 v83, v63, v231, -v83
	v_fmac_f32_e32 v91, v71, v231
	v_fma_f32 v84, v64, v232, -v84
	v_fmac_f32_e32 v92, v72, v232
	v_fma_f32 v85, v65, v233, -v85
	v_fmac_f32_e32 v93, v73, v233
	v_cvt_pk_bf16_f32 v50, v78, v79
	v_cvt_pk_bf16_f32 v54, v86, v87
	v_cvt_pk_bf16_f32 v51, v80, v81
	v_cvt_pk_bf16_f32 v55, v88, v89
	v_cvt_pk_bf16_f32 v52, v82, v83
	v_cvt_pk_bf16_f32 v56, v90, v91
	v_cvt_pk_bf16_f32 v53, v84, v85
	v_cvt_pk_bf16_f32 v57, v92, v93
	global_load_dwordx4 v[218:221], v46, s[10:11]
	global_load_dwordx4 v[222:225], v46, s[10:11] offset:64
	global_load_dwordx4 v[226:229], v47, s[6:7]
	global_load_dwordx4 v[230:233], v47, s[6:7] offset:16
	global_load_dwordx4 v[234:237], v47, s[16:17]
	global_load_dwordx4 v[238:241], v47, s[16:17] offset:16
	v_add_u32_e32 v46, 0x3c000, v46
	v_add_u32_e32 v47, 0x800, v47
	s_nop 1
	s_waitcnt lgkmcnt(13)
	v_mfma_f32_16x16x32_bf16 v[58:61], v[98:101], v[50:53], 0
	s_waitcnt lgkmcnt(12)
	v_mfma_f32_16x16x32_bf16 v[58:61], v[102:105], v[54:57], v[58:61]
	ds_read_b128 v[154:157], v45 offset:27648
	ds_read_b128 v[158:161], v45 offset:27712
	s_waitcnt lgkmcnt(13)
	v_mfma_f32_16x16x32_bf16 v[62:65], v[106:109], v[50:53], 0
	s_waitcnt lgkmcnt(12)
	v_mfma_f32_16x16x32_bf16 v[62:65], v[110:113], v[54:57], v[62:65]
	ds_read_b128 v[162:165], v45 offset:29952
	ds_read_b128 v[182:185], v45 offset:30016
	s_waitcnt lgkmcnt(13)
	v_mfma_f32_16x16x32_bf16 v[66:69], v[114:117], v[50:53], 0
	s_waitcnt lgkmcnt(12)
	v_mfma_f32_16x16x32_bf16 v[66:69], v[118:121], v[54:57], v[66:69]
	s_waitcnt lgkmcnt(11)
	v_mfma_f32_16x16x32_bf16 v[70:73], v[122:125], v[50:53], 0
	s_waitcnt lgkmcnt(10)
	v_mfma_f32_16x16x32_bf16 v[70:73], v[126:129], v[54:57], v[70:73]
	s_waitcnt lgkmcnt(9)
	v_mfma_f32_16x16x32_bf16 v[74:77], v[130:133], v[50:53], 0
	s_waitcnt lgkmcnt(8)
	v_mfma_f32_16x16x32_bf16 v[74:77], v[134:137], v[54:57], v[74:77]
	s_waitcnt lgkmcnt(7)
	v_mfma_f32_16x16x32_bf16 v[78:81], v[138:141], v[50:53], 0
	s_waitcnt lgkmcnt(6)
	v_mfma_f32_16x16x32_bf16 v[78:81], v[142:145], v[54:57], v[78:81]
	s_waitcnt lgkmcnt(5)
	v_mfma_f32_16x16x32_bf16 v[82:85], v[146:149], v[50:53], 0
	s_waitcnt lgkmcnt(4)
	v_mfma_f32_16x16x32_bf16 v[82:85], v[150:153], v[54:57], v[82:85]
	s_waitcnt lgkmcnt(3)
	v_mfma_f32_16x16x32_bf16 v[86:89], v[154:157], v[50:53], 0
	s_waitcnt lgkmcnt(2)
	v_mfma_f32_16x16x32_bf16 v[86:89], v[158:161], v[54:57], v[86:89]
	s_waitcnt lgkmcnt(1)
	v_mfma_f32_16x16x32_bf16 v[90:93], v[162:165], v[50:53], 0
	s_waitcnt lgkmcnt(0)
; #define LAS __attribute__((address_space(3)))
; #define MFMA16(a, b, c) __builtin_amdgcn_mfma_f32_16x16x32_bf16((a), (b), (c), 0, 0, 0)
; __device__ __forceinline__ void p2_block(LAS unsigned char* lds, const bf16_t* __restrict__ PROJ, bf16_t* __restrict__ ATT, bf16_t* __restrict__ SGU, const float* __restrict__ qn, const float* __restrict__ kn, ...
;     ...
;         for (int t = 0; t < 10; ++t) { const bf16x8 k0 = *(const LAS bf16x8*)(kbase + t * 16 * KS_STRIDE), k1 = *(const LAS bf16x8*)(kbase + t * 16 * KS_STRIDE + 64);
;             f32x4 z = (f32x4){0.f, 0.f, 0.f, 0.f}; z = MFMA16(k0, qf0, z); sc_[t] = MFMA16(k1, qf1, z); }
;         float mx = -1e30f;
; #pragma unroll
;         for (int t = 0; t < 10; ++t)
; #pragma unroll
;             for (int e = 0; e < 4; ++e) { const int kx = 16 * (t0 + t) + 4 * fq + e, d = kx - irow; const bool ok = (d >= 1) && (d <= 128) && (n > 0 || kx >= 128);
;                 const float v = ok ? sc_[t][e] : -1e30f; sc_[t][e] = v; mx = fmaxf(mx, v); }
;         mx = fmaxf(mx, __shfl_xor(mx, 16)); mx = fmaxf(mx, __shfl_xor(mx, 32)); mx = fmaxf(mx, sink);
;         float sum = 0.f;
; #pragma unroll
;         for (int t = 0; t < 10; ++t)
; #pragma unroll
;             for (int e = 0; e < 4; ++e) { const float p = __builtin_amdgcn_exp2f((sc_[t][e] - mx) * LOG2E); sc_[t][e] = p; sum += p; }
;         sum += __shfl_xor(sum, 16); sum += __shfl_xor(sum, 32);
;         const float inv = 1.0f / (sum + __builtin_amdgcn_exp2f((sink - mx) * LOG2E));
	v_mfma_f32_16x16x32_bf16 v[90:93], v[182:185], v[54:57], v[90:93]
	ds_read2_b64 v[98:101], v194 offset0:20 offset1:24
	ds_read2_b64 v[102:105], v195 offset0:20 offset1:24
	ds_read2_b64 v[106:109], v196 offset0:20 offset1:24
	ds_read2_b64 v[110:113], v197 offset0:20 offset1:24
	ds_read2_b64 v[114:117], v194 offset0:28 offset1:32
	ds_read2_b64 v[118:121], v195 offset0:28 offset1:32
	ds_read2_b64 v[122:125], v196 offset0:28 offset1:32
	ds_read2_b64 v[126:129], v197 offset0:28 offset1:32
	ds_read2_b64 v[130:133], v194 offset0:36 offset1:40
	ds_read2_b64 v[134:137], v195 offset0:36 offset1:40
	ds_read2_b64 v[138:141], v196 offset0:36 offset1:40
	ds_read2_b64 v[142:145], v197 offset0:36 offset1:40
	ds_read2_b64 v[146:149], v194 offset0:44 offset1:48
	ds_read2_b64 v[150:153], v195 offset0:44 offset1:48
	ds_read2_b64 v[154:157], v196 offset0:44 offset1:48
	s_nop 4
	v_cndmask_b32_e64 v58, v49, v58, s[48:49]
	v_cndmask_b32_e64 v59, v49, v59, s[50:51]
	v_cndmask_b32_e64 v60, v49, v60, s[52:53]
	v_cndmask_b32_e64 v61, v49, v61, s[26:27]
	v_cndmask_b32_e64 v62, v49, v62, s[28:29]
	v_cndmask_b32_e64 v63, v49, v63, s[28:29]
	v_cndmask_b32_e64 v64, v49, v64, s[28:29]
	v_cndmask_b32_e64 v65, v49, v65, s[28:29]
	v_cndmask_b32_e64 v66, v49, v66, s[28:29]
	v_cndmask_b32_e64 v67, v49, v67, s[28:29]
	v_cndmask_b32_e64 v68, v49, v68, s[28:29]
	v_cndmask_b32_e64 v69, v49, v69, s[28:29]
	v_cndmask_b32_e64 v90, v90, v49, s[40:41]
	v_cndmask_b32_e64 v91, v91, v49, s[42:43]
	v_cndmask_b32_e64 v92, v92, v49, s[44:45]
	v_cndmask_b32_e64 v93, v93, v49, s[46:47]
	v_max_f32_e32 v167, v58, v59
	v_max_f32_e32 v94, v60, v61
	v_max3_f32 v167, v167, v62, v63
	v_max3_f32 v94, v94, v64, v65
	v_max3_f32 v167, v167, v66, v67
	v_max3_f32 v94, v94, v68, v69
	v_max3_f32 v167, v167, v70, v71
	v_max3_f32 v94, v94, v72, v73
	v_max3_f32 v167, v167, v74, v75
	v_max3_f32 v94, v94, v76, v77
	v_max3_f32 v167, v167, v78, v79
	v_max3_f32 v94, v94, v80, v81
	v_max3_f32 v167, v167, v82, v83
	v_max3_f32 v94, v94, v84, v85
	v_max3_f32 v167, v167, v86, v87
	v_max3_f32 v94, v94, v88, v89
	v_max3_f32 v167, v167, v90, v91
	v_max3_f32 v94, v94, v92, v93
	v_max_f32_e32 v167, v167, v94
	v_mov_b32_e32 v166, v167
	s_nop 1
	v_permlane16_swap_b32_e32 v167, v166
	v_max_f32_e32 v167, v167, v166
	v_mov_b32_e32 v166, v167
	s_nop 1
	v_permlane32_swap_b32_e32 v167, v166
	v_max_f32_e32 v167, v167, v166
	v_max_f32_e32 v167, v167, v42
	v_mul_f32_e32 v94, 0xbfb8aa3b, v167
	v_fmamk_f32 v58, v58, 0x3fb8aa3b, v94
	v_fmamk_f32 v59, v59, 0x3fb8aa3b, v94
	v_fmamk_f32 v60, v60, 0x3fb8aa3b, v94
	v_fmamk_f32 v61, v61, 0x3fb8aa3b, v94
	v_fmamk_f32 v62, v62, 0x3fb8aa3b, v94
	v_fmamk_f32 v63, v63, 0x3fb8aa3b, v94
	v_fmamk_f32 v64, v64, 0x3fb8aa3b, v94
	v_fmamk_f32 v65, v65, 0x3fb8aa3b, v94
	v_fmamk_f32 v66, v66, 0x3fb8aa3b, v94
	v_fmamk_f32 v67, v67, 0x3fb8aa3b, v94
	v_fmamk_f32 v68, v68, 0x3fb8aa3b, v94
	v_fmamk_f32 v69, v69, 0x3fb8aa3b, v94
	v_fmamk_f32 v70, v70, 0x3fb8aa3b, v94
	v_fmamk_f32 v71, v71, 0x3fb8aa3b, v94
	v_fmamk_f32 v72, v72, 0x3fb8aa3b, v94
	v_fmamk_f32 v73, v73, 0x3fb8aa3b, v94
	v_fmamk_f32 v74, v74, 0x3fb8aa3b, v94
	v_fmamk_f32 v75, v75, 0x3fb8aa3b, v94
	v_fmamk_f32 v76, v76, 0x3fb8aa3b, v94
	v_fmamk_f32 v77, v77, 0x3fb8aa3b, v94
	v_fmamk_f32 v78, v78, 0x3fb8aa3b, v94
	v_fmamk_f32 v79, v79, 0x3fb8aa3b, v94
	v_fmamk_f32 v80, v80, 0x3fb8aa3b, v94
	v_fmamk_f32 v81, v81, 0x3fb8aa3b, v94
	v_fmamk_f32 v82, v82, 0x3fb8aa3b, v94
	v_fmamk_f32 v83, v83, 0x3fb8aa3b, v94
	v_fmamk_f32 v84, v84, 0x3fb8aa3b, v94
	v_fmamk_f32 v85, v85, 0x3fb8aa3b, v94
	v_fmamk_f32 v86, v86, 0x3fb8aa3b, v94
	v_fmamk_f32 v87, v87, 0x3fb8aa3b, v94
	v_fmamk_f32 v88, v88, 0x3fb8aa3b, v94
	v_fmamk_f32 v89, v89, 0x3fb8aa3b, v94
	v_fmamk_f32 v90, v90, 0x3fb8aa3b, v94
	v_fmamk_f32 v91, v91, 0x3fb8aa3b, v94
	v_fmamk_f32 v92, v92, 0x3fb8aa3b, v94
	v_fmamk_f32 v93, v93, 0x3fb8aa3b, v94
	v_exp_f32_e32 v58, v58
	v_exp_f32_e32 v59, v59
	v_exp_f32_e32 v60, v60
	v_exp_f32_e32 v61, v61
	v_exp_f32_e32 v62, v62
	v_exp_f32_e32 v63, v63
	v_exp_f32_e32 v64, v64
	v_exp_f32_e32 v65, v65
	v_exp_f32_e32 v66, v66
	v_exp_f32_e32 v67, v67
	v_exp_f32_e32 v68, v68
	v_exp_f32_e32 v69, v69
	v_exp_f32_e32 v70, v70
	v_exp_f32_e32 v71, v71
	v_exp_f32_e32 v72, v72
	v_exp_f32_e32 v73, v73
	v_exp_f32_e32 v74, v74
	v_exp_f32_e32 v75, v75
	v_exp_f32_e32 v76, v76
	v_exp_f32_e32 v77, v77
	v_exp_f32_e32 v78, v78
	v_exp_f32_e32 v79, v79
	v_exp_f32_e32 v80, v80
	v_exp_f32_e32 v81, v81
	v_exp_f32_e32 v82, v82
	v_exp_f32_e32 v83, v83
	v_exp_f32_e32 v84, v84
	v_exp_f32_e32 v85, v85
	v_exp_f32_e32 v86, v86
	v_exp_f32_e32 v87, v87
	v_exp_f32_e32 v88, v88
	v_exp_f32_e32 v89, v89
	v_exp_f32_e32 v90, v90
	v_exp_f32_e32 v91, v91
	v_exp_f32_e32 v92, v92
	v_exp_f32_e32 v93, v93
	v_fmamk_f32 v95, v42, 0x3fb8aa3b, v94
	v_exp_f32_e32 v95, v95
	v_add_f32_e32 v167, v58, v59
	v_add_f32_e32 v94, v60, v61
	v_add_f32_e32 v167, v167, v62
	v_add_f32_e32 v94, v94, v63
	v_add_f32_e32 v167, v167, v64
	v_add_f32_e32 v94, v94, v65
	v_add_f32_e32 v167, v167, v66
	v_add_f32_e32 v94, v94, v67
	v_add_f32_e32 v167, v167, v68
	v_add_f32_e32 v94, v94, v69
	v_add_f32_e32 v167, v167, v70
	v_add_f32_e32 v94, v94, v71
	v_add_f32_e32 v167, v167, v72
	v_add_f32_e32 v94, v94, v73
	v_add_f32_e32 v167, v167, v74
	v_add_f32_e32 v94, v94, v75
	v_add_f32_e32 v167, v167, v76
	v_add_f32_e32 v94, v94, v77
	v_add_f32_e32 v167, v167, v78
	v_add_f32_e32 v94, v94, v79
	v_add_f32_e32 v167, v167, v80
	v_add_f32_e32 v94, v94, v81
	v_add_f32_e32 v167, v167, v82
	v_add_f32_e32 v94, v94, v83
	v_add_f32_e32 v167, v167, v84
	v_add_f32_e32 v94, v94, v85
	v_add_f32_e32 v167, v167, v86
	v_add_f32_e32 v94, v94, v87
	v_add_f32_e32 v167, v167, v88
	v_add_f32_e32 v94, v94, v89
	v_add_f32_e32 v167, v167, v90
	v_add_f32_e32 v94, v94, v91
	v_add_f32_e32 v167, v167, v92
	v_add_f32_e32 v94, v94, v93
	v_add_f32_e32 v167, v167, v94
	v_mov_b32_e32 v166, v167
	s_nop 1
	v_permlane16_swap_b32_e32 v167, v166
	v_add_f32_e32 v167, v167, v166
	v_mov_b32_e32 v166, v167
	s_nop 1
	v_permlane32_swap_b32_e32 v167, v166
	v_add_f32_e32 v167, v167, v166
	v_add_f32_e32 v167, v167, v95
	v_rcp_f32_e32 v167, v167
	v_mov_b32_e32 v94, 0
	v_mov_b32_e32 v95, 0
	v_mov_b32_e32 v96, 0
	v_mov_b32_e32 v97, 0
	v_cvt_pk_bf16_f32 v58, v58, v59
	v_cvt_pk_bf16_f32 v59, v60, v61
	v_cvt_pk_bf16_f32 v60, v62, v63
	v_cvt_pk_bf16_f32 v61, v64, v65
	v_cvt_pk_bf16_f32 v66, v66, v67
	v_cvt_pk_bf16_f32 v67, v68, v69
	v_cvt_pk_bf16_f32 v68, v70, v71
	v_cvt_pk_bf16_f32 v69, v72, v73
	v_cvt_pk_bf16_f32 v74, v74, v75
	v_cvt_pk_bf16_f32 v75, v76, v77
	v_cvt_pk_bf16_f32 v76, v78, v79
	v_cvt_pk_bf16_f32 v77, v80, v81
	v_cvt_pk_bf16_f32 v82, v82, v83
	v_cvt_pk_bf16_f32 v83, v84, v85
	v_cvt_pk_bf16_f32 v84, v86, v87
	v_cvt_pk_bf16_f32 v85, v88, v89
	v_cvt_pk_bf16_f32 v90, v90, v91
	v_cvt_pk_bf16_f32 v91, v92, v93
	v_cvt_pk_bf16_f32 v92, v94, v95
	v_cvt_pk_bf16_f32 v93, v96, v97
	s_nop 1
	s_waitcnt lgkmcnt(14)
; __device__ __forceinline__ unsigned cvt_pk_bf16(float lo, float hi) { unsigned r; asm volatile("v_cvt_pk_bf16_f32 %0, %1, %2" : "=v"(r) : "v"(lo), "v"(hi)); return r; }
; #define LAS __attribute__((address_space(3)))
; #define MFMA16(a, b, c) __builtin_amdgcn_mfma_f32_16x16x32_bf16((a), (b), (c), 0, 0, 0)
; __device__ __forceinline__ void p2_block(LAS unsigned char* lds, const bf16_t* __restrict__ PROJ, bf16_t* __restrict__ ATT, bf16_t* __restrict__ SGU, const float* __restrict__ qn, const float* __restrict__ kn, ...
;     ...
;         {
;             float x1[8], x2[8]; unpack8(qa[c], x1); unpack8(qb[c], x2);
;             float ss = 0.f;
; #pragma unroll
;             for (int j = 0; j < 8; ++j) ss += x1[j] * x1[j] + x2[j] * x2[j];
;             ss += __shfl_xor(ss, 16); ss += __shfl_xor(ss, 32);
;             const float rinv = rsqrtf(ss * (1.0f / 64.0f) + pg8::EPS) * 0.125f;
;             const float* cp = COS + pos * 32 + 8 * fq; const float* sp = SIN + pos * 32 + 8 * fq;
;             float o1[8], o2[8];
; #pragma unroll
;             for (int j = 0; j < 8; ++j) { const float a1 = x1[j] * rinv * qn[8 * fq + j], a2 = x2[j] * rinv * qn[32 + 8 * fq + j], cc = cp[j], sn = sp[j]; o1[j] = a1 * cc - a2 * sn; o2[j] = a2 * cc + a1 * sn; }
;     ...
; #pragma unroll
;         for (int dt = 0; dt < 4; ++dt) o[dt] = (f32x4){0.f, 0.f, 0.f, 0.f};
; #pragma unroll
;         for (int j = 0; j < 5; ++j) {
;             u32x4 pw; pw.x = cvt_pk_bf16(sc_[2 * j][0], sc_[2 * j][1]); pw.y = cvt_pk_bf16(sc_[2 * j][2], sc_[2 * j][3]); pw.z = cvt_pk_bf16(sc_[2 * j + 1][0], sc_[2 * j + 1][1]); pw.w = cvt_pk_bf16(sc_[2 * j + 1][2], sc_[2 * j + 1][3]);
;             const bf16x8 pf = __builtin_bit_cast(bf16x8, pw);
; #pragma unroll
;             for (int dt = 0; dt < 4; ++dt) { const LAS unsigned char* vb = VT + (16 * dt + fr) * VT_STRIDE + (16 * (t0 + 2 * j) + 4 * fq) * 2;
;                 const u32x2 va = *(const LAS u32x2*)vb, vc = *(const LAS u32x2*)(vb + 32); u32x4 vw; vw.x = va.x; vw.y = va.y; vw.z = vc.x; vw.w = vc.y;
;                 o[dt] = MFMA16(__builtin_bit_cast(bf16x8, vw), pf, o[dt]); }
;         }
;         bf16_t* op = ATT + grow * 1024 + hq * 64 + 4 * fq;
; #pragma unroll
;         for (int dt = 0; dt < 4; ++dt) { u32x2 ow; ow.x = cvt_pk_bf16(o[dt][0] * inv, o[dt][1] * inv); ow.y = cvt_pk_bf16(o[dt][2] * inv, o[dt][3] * inv); *(u32x2*)(op + 16 * dt) = ow; }
	v_mfma_f32_16x16x32_bf16 v[62:65], v[98:101], v[58:61], 0
	ds_read2_b64 v[158:161], v197 offset0:44 offset1:48
	s_waitcnt lgkmcnt(14)
	v_mfma_f32_16x16x32_bf16 v[70:73], v[102:105], v[58:61], 0
	ds_read2_b64 v[162:165], v194 offset0:52 offset1:56
	s_waitcnt lgkmcnt(14)
	v_mfma_f32_16x16x32_bf16 v[78:81], v[106:109], v[58:61], 0
	ds_read2_b64 v[182:185], v195 offset0:52 offset1:56
	s_waitcnt lgkmcnt(14)
	v_mfma_f32_16x16x32_bf16 v[86:89], v[110:113], v[58:61], 0
	ds_read2_b64 v[186:189], v196 offset0:52 offset1:56
	s_waitcnt lgkmcnt(14)
	v_mfma_f32_16x16x32_bf16 v[62:65], v[114:117], v[66:69], v[62:65]
	ds_read2_b64 v[190:193], v197 offset0:52 offset1:56
	s_waitcnt lgkmcnt(14)
	v_mfma_f32_16x16x32_bf16 v[70:73], v[118:121], v[66:69], v[70:73]
	s_waitcnt lgkmcnt(13)
	v_mfma_f32_16x16x32_bf16 v[78:81], v[122:125], v[66:69], v[78:81]
	s_waitcnt lgkmcnt(12)
	v_mfma_f32_16x16x32_bf16 v[86:89], v[126:129], v[66:69], v[86:89]
	s_waitcnt lgkmcnt(11)
	v_mfma_f32_16x16x32_bf16 v[62:65], v[130:133], v[74:77], v[62:65]
	s_waitcnt lgkmcnt(10)
	v_mfma_f32_16x16x32_bf16 v[70:73], v[134:137], v[74:77], v[70:73]
	s_waitcnt lgkmcnt(9)
	v_mfma_f32_16x16x32_bf16 v[78:81], v[138:141], v[74:77], v[78:81]
	s_waitcnt lgkmcnt(8)
	v_mfma_f32_16x16x32_bf16 v[86:89], v[142:145], v[74:77], v[86:89]
	s_waitcnt lgkmcnt(7)
	v_mfma_f32_16x16x32_bf16 v[62:65], v[146:149], v[82:85], v[62:65]
	s_waitcnt lgkmcnt(6)
	v_mfma_f32_16x16x32_bf16 v[70:73], v[150:153], v[82:85], v[70:73]
	s_waitcnt lgkmcnt(5)
	v_mfma_f32_16x16x32_bf16 v[78:81], v[154:157], v[82:85], v[78:81]
	s_waitcnt lgkmcnt(4)
	v_mfma_f32_16x16x32_bf16 v[86:89], v[158:161], v[82:85], v[86:89]
	s_waitcnt lgkmcnt(3)
	v_mfma_f32_16x16x32_bf16 v[62:65], v[162:165], v[90:93], v[62:65]
	s_waitcnt lgkmcnt(2)
	v_mfma_f32_16x16x32_bf16 v[70:73], v[182:185], v[90:93], v[70:73]
	s_waitcnt lgkmcnt(1)
	v_mfma_f32_16x16x32_bf16 v[78:81], v[186:189], v[90:93], v[78:81]
	s_waitcnt lgkmcnt(0)
	v_mfma_f32_16x16x32_bf16 v[86:89], v[190:193], v[90:93], v[86:89]
	ds_read_b128 v[98:101], v45 offset:13824
	ds_read_b128 v[102:105], v45 offset:13888
	ds_read_b128 v[106:109], v45 offset:16128
	ds_read_b128 v[110:113], v45 offset:16192
	ds_read_b128 v[114:117], v45 offset:18432
	ds_read_b128 v[118:121], v45 offset:18496
	ds_read_b128 v[122:125], v45 offset:20736
	ds_read_b128 v[126:129], v45 offset:20800
	ds_read_b128 v[130:133], v45 offset:23040
	ds_read_b128 v[134:137], v45 offset:23104
	ds_read_b128 v[138:141], v45 offset:25344
	ds_read_b128 v[142:145], v45 offset:25408
	ds_read_b128 v[146:149], v45 offset:27648
	ds_read_b128 v[150:153], v45 offset:27712
	s_nop 7
	v_mul_f32_e32 v62, v62, v167
	v_mul_f32_e32 v63, v63, v167
	v_mul_f32_e32 v64, v64, v167
	v_mul_f32_e32 v65, v65, v167
	v_mul_f32_e32 v70, v70, v167
	v_mul_f32_e32 v71, v71, v167
	v_mul_f32_e32 v72, v72, v167
	v_mul_f32_e32 v73, v73, v167
	v_mul_f32_e32 v78, v78, v167
	v_mul_f32_e32 v79, v79, v167
	v_mul_f32_e32 v80, v80, v167
	v_mul_f32_e32 v81, v81, v167
	v_mul_f32_e32 v86, v86, v167
	v_mul_f32_e32 v87, v87, v167
	v_mul_f32_e32 v88, v88, v167
	v_mul_f32_e32 v89, v89, v167
	v_cvt_pk_bf16_f32 v62, v62, v63
	v_cvt_pk_bf16_f32 v63, v64, v65
	global_store_dwordx2 v48, v[62:63], s[24:25] offset:0
	v_cvt_pk_bf16_f32 v70, v70, v71
	v_cvt_pk_bf16_f32 v71, v72, v73
	global_store_dwordx2 v48, v[70:71], s[24:25] offset:32
	v_cvt_pk_bf16_f32 v78, v78, v79
	v_cvt_pk_bf16_f32 v79, v80, v81
	global_store_dwordx2 v48, v[78:79], s[24:25] offset:64
	v_cvt_pk_bf16_f32 v86, v86, v87
	v_cvt_pk_bf16_f32 v87, v88, v89
	global_store_dwordx2 v48, v[86:87], s[24:25] offset:96
	v_add_u32_e32 v48, 0x8000, v48
	s_waitcnt vmcnt(14)
	v_lshlrev_b32_e32 v58, 16, v2
	v_and_b32_e32 v59, 0xffff0000, v2
	v_lshlrev_b32_e32 v66, 16, v6
	v_and_b32_e32 v67, 0xffff0000, v6
	v_lshlrev_b32_e32 v60, 16, v3
	v_and_b32_e32 v61, 0xffff0000, v3
	v_lshlrev_b32_e32 v68, 16, v7
	v_and_b32_e32 v69, 0xffff0000, v7
	v_lshlrev_b32_e32 v62, 16, v4
	v_and_b32_e32 v63, 0xffff0000, v4
	v_lshlrev_b32_e32 v70, 16, v8
	v_and_b32_e32 v71, 0xffff0000, v8
	v_lshlrev_b32_e32 v64, 16, v5
	v_and_b32_e32 v65, 0xffff0000, v5
	v_lshlrev_b32_e32 v72, 16, v9
	v_and_b32_e32 v73, 0xffff0000, v9
	v_mul_f32_e32 v74, v58, v58
	v_mul_f32_e32 v75, v59, v59
	v_fmac_f32_e32 v74, v60, v60
	v_fmac_f32_e32 v75, v61, v61
	v_fmac_f32_e32 v74, v62, v62
	v_fmac_f32_e32 v75, v63, v63
	v_fmac_f32_e32 v74, v64, v64
	v_fmac_f32_e32 v75, v65, v65
	v_fmac_f32_e32 v74, v66, v66
	v_fmac_f32_e32 v75, v67, v67
	v_fmac_f32_e32 v74, v68, v68
	v_fmac_f32_e32 v75, v69, v69
	v_fmac_f32_e32 v74, v70, v70
	v_fmac_f32_e32 v75, v71, v71
	v_fmac_f32_e32 v74, v72, v72
	v_fmac_f32_e32 v75, v73, v73
	v_add_f32_e32 v74, v74, v75
	v_mov_b32_e32 v166, v74
	s_nop 1
	v_permlane16_swap_b32_e32 v74, v166
	v_add_f32_e32 v74, v74, v166
	v_mov_b32_e32 v166, v74
	s_nop 1
	v_permlane32_swap_b32_e32 v74, v166
	v_add_f32_e32 v74, v74, v166
	v_fmamk_f32 v74, v74, 0x3c800000, v209
	v_rsq_f32_e32 v76, v74
	s_nop 0
	v_mul_f32_e32 v76, 0x3e000000, v76
	v_mul_f32_e32 v58, v58, v76
	v_mul_f32_e32 v66, v66, v76
	v_mul_f32_e32 v59, v59, v76
	v_mul_f32_e32 v67, v67, v76
	v_mul_f32_e32 v60, v60, v76
	v_mul_f32_e32 v68, v68, v76
	v_mul_f32_e32 v61, v61, v76
	v_mul_f32_e32 v69, v69, v76
	v_mul_f32_e32 v62, v62, v76
	v_mul_f32_e32 v70, v70, v76
	v_mul_f32_e32 v63, v63, v76
	v_mul_f32_e32 v71, v71, v76
	v_mul_f32_e32 v64, v64, v76
	v_mul_f32_e32 v72, v72, v76
	v_mul_f32_e32 v65, v65, v76
	v_mul_f32_e32 v73, v73, v76
	v_mul_f32_e32 v58, v58, v26
	v_mul_f32_e32 v66, v66, v34
	v_mul_f32_e32 v59, v59, v27
	v_mul_f32_e32 v67, v67, v35
	v_mul_f32_e32 v60, v60, v28
	v_mul_f32_e32 v68, v68, v36
	v_mul_f32_e32 v61, v61, v29
; __device__ __forceinline__ unsigned cvt_pk_bf16(float lo, float hi) { unsigned r; asm volatile("v_cvt_pk_bf16_f32 %0, %1, %2" : "=v"(r) : "v"(lo), "v"(hi)); return r; }
; #define LAS __attribute__((address_space(3)))
; __device__ __forceinline__ void p2_block(LAS unsigned char* lds, const bf16_t* __restrict__ PROJ, bf16_t* __restrict__ ATT, bf16_t* __restrict__ SGU, const float* __restrict__ qn, const float* __restrict__ kn, ...
;     ...
;             for (int j = 0; j < 8; ++j) { const float a1 = x1[j] * rinv * qn[8 * fq + j], a2 = x2[j] * rinv * qn[32 + 8 * fq + j], cc = cp[j], sn = sp[j]; o1[j] = a1 * cc - a2 * sn; o2[j] = a2 * cc + a1 * sn; }
;             u32x4 w0, w1;
;             w0.x = cvt_pk_bf16(o1[0], o1[1]); w0.y = cvt_pk_bf16(o1[2], o1[3]); w0.z = cvt_pk_bf16(o1[4], o1[5]); w0.w = cvt_pk_bf16(o1[6], o1[7]);
;             w1.x = cvt_pk_bf16(o2[0], o2[1]); w1.y = cvt_pk_bf16(o2[2], o2[3]); w1.z = cvt_pk_bf16(o2[4], o2[5]); w1.w = cvt_pk_bf16(o2[6], o2[7]);
;             qf0 = __builtin_bit_cast(bf16x8, w0); qf1 = __builtin_bit_cast(bf16x8, w1);
;         }
;         const int t0 = (i0 >> 4) < 6 ? (i0 >> 4) : 6;
;         f32x4 sc_[10];
;         const LAS unsigned char* kbase = KS + (16 * t0 + fr) * KS_STRIDE + 16 * fq;
; #pragma unroll
;         for (int t = 0; t < 10; ++t) { const bf16x8 k0 = *(const LAS bf16x8*)(kbase + t * 16 * KS_STRIDE), k1 = *(const LAS bf16x8*)(kbase + t * 16 * KS_STRIDE + 64);
;             f32x4 z = (f32x4){0.f, 0.f, 0.f, 0.f}; z = MFMA16(k0, qf0, z); sc_[t] = MFMA16(k1, qf1, z); }
;         float mx = -1e30f;
; #pragma unroll
;         for (int t = 0; t < 10; ++t)
; #pragma unroll
;             for (int e = 0; e < 4; ++e) { const int kx = 16 * (t0 + t) + 4 * fq + e, d = kx - irow; const bool ok = (d >= 1) && (d <= 128) && (n > 0 || kx >= 128);
;                 const float v = ok ? sc_[t][e] : -1e30f; sc_[t][e] = v; mx = fmaxf(mx, v); }
;         mx = fmaxf(mx, __shfl_xor(mx, 16)); mx = fmaxf(mx, __shfl_xor(mx, 32)); mx = fmaxf(mx, sink);
;         float sum = 0.f;
; #pragma unroll
;         for (int t = 0; t < 10; ++t)
; #pragma unroll
;             for (int e = 0; e < 4; ++e) { const float p = __builtin_amdgcn_exp2f((sc_[t][e] - mx) * LOG2E); sc_[t][e] = p; sum += p; }
;         sum += __shfl_xor(sum, 16); sum += __shfl_xor(sum, 32);
;         const float inv = 1.0f / (sum + __builtin_amdgcn_exp2f((sink - mx) * LOG2E));
	v_mul_f32_e32 v69, v69, v37
	v_mul_f32_e32 v62, v62, v30
	v_mul_f32_e32 v70, v70, v38
	v_mul_f32_e32 v63, v63, v31
	v_mul_f32_e32 v71, v71, v39
	v_mul_f32_e32 v64, v64, v32
	v_mul_f32_e32 v72, v72, v40
	v_mul_f32_e32 v65, v65, v33
	v_mul_f32_e32 v73, v73, v41
	v_mul_f32_e32 v78, v66, v18
	v_mul_f32_e32 v86, v58, v18
	v_mul_f32_e32 v79, v67, v19
	v_mul_f32_e32 v87, v59, v19
	v_mul_f32_e32 v80, v68, v20
	v_mul_f32_e32 v88, v60, v20
	v_mul_f32_e32 v81, v69, v21
	v_mul_f32_e32 v89, v61, v21
	v_mul_f32_e32 v82, v70, v22
	v_mul_f32_e32 v90, v62, v22
	v_mul_f32_e32 v83, v71, v23
	v_mul_f32_e32 v91, v63, v23
	v_mul_f32_e32 v84, v72, v24
	v_mul_f32_e32 v92, v64, v24
	v_mul_f32_e32 v85, v73, v25
	v_mul_f32_e32 v93, v65, v25
	v_fma_f32 v78, v58, v10, -v78
	v_fmac_f32_e32 v86, v66, v10
	v_fma_f32 v79, v59, v11, -v79
	v_fmac_f32_e32 v87, v67, v11
	v_fma_f32 v80, v60, v12, -v80
	v_fmac_f32_e32 v88, v68, v12
	v_fma_f32 v81, v61, v13, -v81
	v_fmac_f32_e32 v89, v69, v13
	v_fma_f32 v82, v62, v14, -v82
	v_fmac_f32_e32 v90, v70, v14
	v_fma_f32 v83, v63, v15, -v83
	v_fmac_f32_e32 v91, v71, v15
	v_fma_f32 v84, v64, v16, -v84
	v_fmac_f32_e32 v92, v72, v16
	v_fma_f32 v85, v65, v17, -v85
	v_fmac_f32_e32 v93, v73, v17
	v_cvt_pk_bf16_f32 v50, v78, v79
	v_cvt_pk_bf16_f32 v54, v86, v87
	v_cvt_pk_bf16_f32 v51, v80, v81
	v_cvt_pk_bf16_f32 v55, v88, v89
	v_cvt_pk_bf16_f32 v52, v82, v83
	v_cvt_pk_bf16_f32 v56, v90, v91
	v_cvt_pk_bf16_f32 v53, v84, v85
	v_cvt_pk_bf16_f32 v57, v92, v93
	s_nop 1
	s_waitcnt lgkmcnt(13)
	v_mfma_f32_16x16x32_bf16 v[58:61], v[98:101], v[50:53], 0
	s_waitcnt lgkmcnt(12)
	v_mfma_f32_16x16x32_bf16 v[58:61], v[102:105], v[54:57], v[58:61]
	ds_read_b128 v[154:157], v45 offset:29952
	ds_read_b128 v[158:161], v45 offset:30016
	s_waitcnt lgkmcnt(13)
	v_mfma_f32_16x16x32_bf16 v[62:65], v[106:109], v[50:53], 0
	s_waitcnt lgkmcnt(12)
	v_mfma_f32_16x16x32_bf16 v[62:65], v[110:113], v[54:57], v[62:65]
	ds_read_b128 v[162:165], v45 offset:32256
	ds_read_b128 v[182:185], v45 offset:32320
	s_waitcnt lgkmcnt(13)
	v_mfma_f32_16x16x32_bf16 v[66:69], v[114:117], v[50:53], 0
	s_waitcnt lgkmcnt(12)
	v_mfma_f32_16x16x32_bf16 v[66:69], v[118:121], v[54:57], v[66:69]
	s_waitcnt lgkmcnt(11)
	v_mfma_f32_16x16x32_bf16 v[70:73], v[122:125], v[50:53], 0
	s_waitcnt lgkmcnt(10)
	v_mfma_f32_16x16x32_bf16 v[70:73], v[126:129], v[54:57], v[70:73]
	s_waitcnt lgkmcnt(9)
	v_mfma_f32_16x16x32_bf16 v[74:77], v[130:133], v[50:53], 0
	s_waitcnt lgkmcnt(8)
	v_mfma_f32_16x16x32_bf16 v[74:77], v[134:137], v[54:57], v[74:77]
	s_waitcnt lgkmcnt(7)
	v_mfma_f32_16x16x32_bf16 v[78:81], v[138:141], v[50:53], 0
	s_waitcnt lgkmcnt(6)
	v_mfma_f32_16x16x32_bf16 v[78:81], v[142:145], v[54:57], v[78:81]
	s_waitcnt lgkmcnt(5)
	v_mfma_f32_16x16x32_bf16 v[82:85], v[146:149], v[50:53], 0
	s_waitcnt lgkmcnt(4)
	v_mfma_f32_16x16x32_bf16 v[82:85], v[150:153], v[54:57], v[82:85]
	s_waitcnt lgkmcnt(3)
	v_mfma_f32_16x16x32_bf16 v[86:89], v[154:157], v[50:53], 0
	s_waitcnt lgkmcnt(2)
	v_mfma_f32_16x16x32_bf16 v[86:89], v[158:161], v[54:57], v[86:89]
	s_waitcnt lgkmcnt(1)
	v_mfma_f32_16x16x32_bf16 v[90:93], v[162:165], v[50:53], 0
	s_waitcnt lgkmcnt(0)
	v_mfma_f32_16x16x32_bf16 v[90:93], v[182:185], v[54:57], v[90:93]
	ds_read2_b64 v[98:101], v194 offset0:24 offset1:28
	ds_read2_b64 v[102:105], v195 offset0:24 offset1:28
	ds_read2_b64 v[106:109], v196 offset0:24 offset1:28
	ds_read2_b64 v[110:113], v197 offset0:24 offset1:28
	ds_read2_b64 v[114:117], v194 offset0:32 offset1:36
	ds_read2_b64 v[118:121], v195 offset0:32 offset1:36
	ds_read2_b64 v[122:125], v196 offset0:32 offset1:36
	ds_read2_b64 v[126:129], v197 offset0:32 offset1:36
	ds_read2_b64 v[130:133], v194 offset0:40 offset1:44
	ds_read2_b64 v[134:137], v195 offset0:40 offset1:44
	ds_read2_b64 v[138:141], v196 offset0:40 offset1:44
	ds_read2_b64 v[142:145], v197 offset0:40 offset1:44
	ds_read2_b64 v[146:149], v194 offset0:48 offset1:52
	ds_read2_b64 v[150:153], v195 offset0:48 offset1:52
	ds_read2_b64 v[154:157], v196 offset0:48 offset1:52
	s_nop 4
	v_cndmask_b32_e64 v58, v49, v58, s[48:49]
	v_cndmask_b32_e64 v59, v49, v59, s[50:51]
	v_cndmask_b32_e64 v60, v49, v60, s[52:53]
	v_cndmask_b32_e64 v61, v49, v61, s[26:27]
	v_cndmask_b32_e64 v62, v49, v62, s[28:29]
	v_cndmask_b32_e64 v63, v49, v63, s[28:29]
	v_cndmask_b32_e64 v64, v49, v64, s[28:29]
	v_cndmask_b32_e64 v65, v49, v65, s[28:29]
	v_cndmask_b32_e64 v90, v90, v49, s[40:41]
	v_cndmask_b32_e64 v91, v91, v49, s[42:43]
	v_cndmask_b32_e64 v92, v92, v49, s[44:45]
	v_cndmask_b32_e64 v93, v93, v49, s[46:47]
	v_max_f32_e32 v167, v58, v59
	v_max_f32_e32 v94, v60, v61
	v_max3_f32 v167, v167, v62, v63
	v_max3_f32 v94, v94, v64, v65
	v_max3_f32 v167, v167, v66, v67
	v_max3_f32 v94, v94, v68, v69
	v_max3_f32 v167, v167, v70, v71
	v_max3_f32 v94, v94, v72, v73
	v_max3_f32 v167, v167, v74, v75
	v_max3_f32 v94, v94, v76, v77
	v_max3_f32 v167, v167, v78, v79
	v_max3_f32 v94, v94, v80, v81
	v_max3_f32 v167, v167, v82, v83
	v_max3_f32 v94, v94, v84, v85
	v_max3_f32 v167, v167, v86, v87
	v_max3_f32 v94, v94, v88, v89
	v_max3_f32 v167, v167, v90, v91
	v_max3_f32 v94, v94, v92, v93
	v_max_f32_e32 v167, v167, v94
	v_mov_b32_e32 v166, v167
	s_nop 1
	v_permlane16_swap_b32_e32 v167, v166
	v_max_f32_e32 v167, v167, v166
	v_mov_b32_e32 v166, v167
	s_nop 1
	v_permlane32_swap_b32_e32 v167, v166
	v_max_f32_e32 v167, v167, v166
	v_max_f32_e32 v167, v167, v42
	v_mul_f32_e32 v94, 0xbfb8aa3b, v167
	v_fmamk_f32 v58, v58, 0x3fb8aa3b, v94
	v_fmamk_f32 v59, v59, 0x3fb8aa3b, v94
	v_fmamk_f32 v60, v60, 0x3fb8aa3b, v94
	v_fmamk_f32 v61, v61, 0x3fb8aa3b, v94
	v_fmamk_f32 v62, v62, 0x3fb8aa3b, v94
	v_fmamk_f32 v63, v63, 0x3fb8aa3b, v94
; __device__ __forceinline__ unsigned cvt_pk_bf16(float lo, float hi) { unsigned r; asm volatile("v_cvt_pk_bf16_f32 %0, %1, %2" : "=v"(r) : "v"(lo), "v"(hi)); return r; }
; #define LAS __attribute__((address_space(3)))
; #define MFMA16(a, b, c) __builtin_amdgcn_mfma_f32_16x16x32_bf16((a), (b), (c), 0, 0, 0)
; __device__ __forceinline__ void p2_block(LAS unsigned char* lds, const bf16_t* __restrict__ PROJ, bf16_t* __restrict__ ATT, bf16_t* __restrict__ SGU, const float* __restrict__ qn, const float* __restrict__ kn, ...
;     ...
;             for (int e = 0; e < 4; ++e) { const int kx = 16 * (t0 + t) + 4 * fq + e, d = kx - irow; const bool ok = (d >= 1) && (d <= 128) && (n > 0 || kx >= 128);
;                 const float v = ok ? sc_[t][e] : -1e30f; sc_[t][e] = v; mx = fmaxf(mx, v); }
;         mx = fmaxf(mx, __shfl_xor(mx, 16)); mx = fmaxf(mx, __shfl_xor(mx, 32)); mx = fmaxf(mx, sink);
;         float sum = 0.f;
; #pragma unroll
;         for (int t = 0; t < 10; ++t)
; #pragma unroll
;             for (int e = 0; e < 4; ++e) { const float p = __builtin_amdgcn_exp2f((sc_[t][e] - mx) * LOG2E); sc_[t][e] = p; sum += p; }
;         sum += __shfl_xor(sum, 16); sum += __shfl_xor(sum, 32);
;         const float inv = 1.0f / (sum + __builtin_amdgcn_exp2f((sink - mx) * LOG2E));
;         f32x4 o[4];
; #pragma unroll
;         for (int dt = 0; dt < 4; ++dt) o[dt] = (f32x4){0.f, 0.f, 0.f, 0.f};
; #pragma unroll
;         for (int j = 0; j < 5; ++j) {
;             u32x4 pw; pw.x = cvt_pk_bf16(sc_[2 * j][0], sc_[2 * j][1]); pw.y = cvt_pk_bf16(sc_[2 * j][2], sc_[2 * j][3]); pw.z = cvt_pk_bf16(sc_[2 * j + 1][0], sc_[2 * j + 1][1]); pw.w = cvt_pk_bf16(sc_[2 * j + 1][2], sc_[2 * j + 1][3]);
;             const bf16x8 pf = __builtin_bit_cast(bf16x8, pw);
; #pragma unroll
;             for (int dt = 0; dt < 4; ++dt) { const LAS unsigned char* vb = VT + (16 * dt + fr) * VT_STRIDE + (16 * (t0 + 2 * j) + 4 * fq) * 2;
;                 const u32x2 va = *(const LAS u32x2*)vb, vc = *(const LAS u32x2*)(vb + 32); u32x4 vw; vw.x = va.x; vw.y = va.y; vw.z = vc.x; vw.w = vc.y;
;                 o[dt] = MFMA16(__builtin_bit_cast(bf16x8, vw), pf, o[dt]); }
	v_fmamk_f32 v64, v64, 0x3fb8aa3b, v94
	v_fmamk_f32 v65, v65, 0x3fb8aa3b, v94
	v_fmamk_f32 v66, v66, 0x3fb8aa3b, v94
	v_fmamk_f32 v67, v67, 0x3fb8aa3b, v94
	v_fmamk_f32 v68, v68, 0x3fb8aa3b, v94
	v_fmamk_f32 v69, v69, 0x3fb8aa3b, v94
	v_fmamk_f32 v70, v70, 0x3fb8aa3b, v94
	v_fmamk_f32 v71, v71, 0x3fb8aa3b, v94
	v_fmamk_f32 v72, v72, 0x3fb8aa3b, v94
	v_fmamk_f32 v73, v73, 0x3fb8aa3b, v94
	v_fmamk_f32 v74, v74, 0x3fb8aa3b, v94
	v_fmamk_f32 v75, v75, 0x3fb8aa3b, v94
	v_fmamk_f32 v76, v76, 0x3fb8aa3b, v94
	v_fmamk_f32 v77, v77, 0x3fb8aa3b, v94
	v_fmamk_f32 v78, v78, 0x3fb8aa3b, v94
	v_fmamk_f32 v79, v79, 0x3fb8aa3b, v94
	v_fmamk_f32 v80, v80, 0x3fb8aa3b, v94
	v_fmamk_f32 v81, v81, 0x3fb8aa3b, v94
	v_fmamk_f32 v82, v82, 0x3fb8aa3b, v94
	v_fmamk_f32 v83, v83, 0x3fb8aa3b, v94
	v_fmamk_f32 v84, v84, 0x3fb8aa3b, v94
	v_fmamk_f32 v85, v85, 0x3fb8aa3b, v94
	v_fmamk_f32 v86, v86, 0x3fb8aa3b, v94
	v_fmamk_f32 v87, v87, 0x3fb8aa3b, v94
	v_fmamk_f32 v88, v88, 0x3fb8aa3b, v94
	v_fmamk_f32 v89, v89, 0x3fb8aa3b, v94
	v_fmamk_f32 v90, v90, 0x3fb8aa3b, v94
	v_fmamk_f32 v91, v91, 0x3fb8aa3b, v94
	v_fmamk_f32 v92, v92, 0x3fb8aa3b, v94
	v_fmamk_f32 v93, v93, 0x3fb8aa3b, v94
	v_exp_f32_e32 v58, v58
	v_exp_f32_e32 v59, v59
	v_exp_f32_e32 v60, v60
	v_exp_f32_e32 v61, v61
	v_exp_f32_e32 v62, v62
	v_exp_f32_e32 v63, v63
	v_exp_f32_e32 v64, v64
	v_exp_f32_e32 v65, v65
	v_exp_f32_e32 v66, v66
	v_exp_f32_e32 v67, v67
	v_exp_f32_e32 v68, v68
	v_exp_f32_e32 v69, v69
	v_exp_f32_e32 v70, v70
	v_exp_f32_e32 v71, v71
	v_exp_f32_e32 v72, v72
	v_exp_f32_e32 v73, v73
	v_exp_f32_e32 v74, v74
	v_exp_f32_e32 v75, v75
	v_exp_f32_e32 v76, v76
	v_exp_f32_e32 v77, v77
	v_exp_f32_e32 v78, v78
	v_exp_f32_e32 v79, v79
	v_exp_f32_e32 v80, v80
	v_exp_f32_e32 v81, v81
	v_exp_f32_e32 v82, v82
	v_exp_f32_e32 v83, v83
	v_exp_f32_e32 v84, v84
	v_exp_f32_e32 v85, v85
	v_exp_f32_e32 v86, v86
	v_exp_f32_e32 v87, v87
	v_exp_f32_e32 v88, v88
	v_exp_f32_e32 v89, v89
	v_exp_f32_e32 v90, v90
	v_exp_f32_e32 v91, v91
	v_exp_f32_e32 v92, v92
	v_exp_f32_e32 v93, v93
	v_fmamk_f32 v95, v42, 0x3fb8aa3b, v94
	v_exp_f32_e32 v95, v95
	v_add_f32_e32 v167, v58, v59
	v_add_f32_e32 v94, v60, v61
	v_add_f32_e32 v167, v167, v62
	v_add_f32_e32 v94, v94, v63
	v_add_f32_e32 v167, v167, v64
	v_add_f32_e32 v94, v94, v65
	v_add_f32_e32 v167, v167, v66
	v_add_f32_e32 v94, v94, v67
	v_add_f32_e32 v167, v167, v68
	v_add_f32_e32 v94, v94, v69
	v_add_f32_e32 v167, v167, v70
	v_add_f32_e32 v94, v94, v71
	v_add_f32_e32 v167, v167, v72
	v_add_f32_e32 v94, v94, v73
	v_add_f32_e32 v167, v167, v74
	v_add_f32_e32 v94, v94, v75
	v_add_f32_e32 v167, v167, v76
	v_add_f32_e32 v94, v94, v77
	v_add_f32_e32 v167, v167, v78
	v_add_f32_e32 v94, v94, v79
	v_add_f32_e32 v167, v167, v80
	v_add_f32_e32 v94, v94, v81
	v_add_f32_e32 v167, v167, v82
	v_add_f32_e32 v94, v94, v83
	v_add_f32_e32 v167, v167, v84
	v_add_f32_e32 v94, v94, v85
	v_add_f32_e32 v167, v167, v86
	v_add_f32_e32 v94, v94, v87
	v_add_f32_e32 v167, v167, v88
	v_add_f32_e32 v94, v94, v89
	v_add_f32_e32 v167, v167, v90
	v_add_f32_e32 v94, v94, v91
	v_add_f32_e32 v167, v167, v92
	v_add_f32_e32 v94, v94, v93
	v_add_f32_e32 v167, v167, v94
	v_mov_b32_e32 v166, v167
	s_nop 1
	v_permlane16_swap_b32_e32 v167, v166
	v_add_f32_e32 v167, v167, v166
	v_mov_b32_e32 v166, v167
	s_nop 1
	v_permlane32_swap_b32_e32 v167, v166
	v_add_f32_e32 v167, v167, v166
	v_add_f32_e32 v167, v167, v95
	v_rcp_f32_e32 v167, v167
	v_mov_b32_e32 v94, 0
	v_mov_b32_e32 v95, 0
	v_mov_b32_e32 v96, 0
	v_mov_b32_e32 v97, 0
	v_cvt_pk_bf16_f32 v58, v58, v59
	v_cvt_pk_bf16_f32 v59, v60, v61
	v_cvt_pk_bf16_f32 v60, v62, v63
	v_cvt_pk_bf16_f32 v61, v64, v65
	v_cvt_pk_bf16_f32 v66, v66, v67
	v_cvt_pk_bf16_f32 v67, v68, v69
	v_cvt_pk_bf16_f32 v68, v70, v71
	v_cvt_pk_bf16_f32 v69, v72, v73
	v_cvt_pk_bf16_f32 v74, v74, v75
	v_cvt_pk_bf16_f32 v75, v76, v77
	v_cvt_pk_bf16_f32 v76, v78, v79
	v_cvt_pk_bf16_f32 v77, v80, v81
	v_cvt_pk_bf16_f32 v82, v82, v83
	v_cvt_pk_bf16_f32 v83, v84, v85
	v_cvt_pk_bf16_f32 v84, v86, v87
	v_cvt_pk_bf16_f32 v85, v88, v89
	v_cvt_pk_bf16_f32 v90, v90, v91
	v_cvt_pk_bf16_f32 v91, v92, v93
	v_cvt_pk_bf16_f32 v92, v94, v95
	v_cvt_pk_bf16_f32 v93, v96, v97
	s_nop 1
	s_waitcnt lgkmcnt(14)
	v_mfma_f32_16x16x32_bf16 v[62:65], v[98:101], v[58:61], 0
	ds_read2_b64 v[158:161], v197 offset0:48 offset1:52
	s_waitcnt lgkmcnt(14)
	v_mfma_f32_16x16x32_bf16 v[70:73], v[102:105], v[58:61], 0
	ds_read2_b64 v[162:165], v194 offset0:56 offset1:60
	s_waitcnt lgkmcnt(14)
	v_mfma_f32_16x16x32_bf16 v[78:81], v[106:109], v[58:61], 0
	ds_read2_b64 v[182:185], v195 offset0:56 offset1:60
	s_waitcnt lgkmcnt(14)
	v_mfma_f32_16x16x32_bf16 v[86:89], v[110:113], v[58:61], 0
	ds_read2_b64 v[186:189], v196 offset0:56 offset1:60
	s_waitcnt lgkmcnt(14)
	v_mfma_f32_16x16x32_bf16 v[62:65], v[114:117], v[66:69], v[62:65]
	ds_read2_b64 v[190:193], v197 offset0:56 offset1:60
	s_waitcnt lgkmcnt(14)
	v_mfma_f32_16x16x32_bf16 v[70:73], v[118:121], v[66:69], v[70:73]
	s_waitcnt lgkmcnt(13)
	v_mfma_f32_16x16x32_bf16 v[78:81], v[122:125], v[66:69], v[78:81]
	s_waitcnt lgkmcnt(12)
	v_mfma_f32_16x16x32_bf16 v[86:89], v[126:129], v[66:69], v[86:89]
	s_waitcnt lgkmcnt(11)
	v_mfma_f32_16x16x32_bf16 v[62:65], v[130:133], v[74:77], v[62:65]
	s_waitcnt lgkmcnt(10)
	v_mfma_f32_16x16x32_bf16 v[70:73], v[134:137], v[74:77], v[70:73]
	s_waitcnt lgkmcnt(9)
	v_mfma_f32_16x16x32_bf16 v[78:81], v[138:141], v[74:77], v[78:81]
	s_waitcnt lgkmcnt(8)
	v_mfma_f32_16x16x32_bf16 v[86:89], v[142:145], v[74:77], v[86:89]
	s_waitcnt lgkmcnt(7)
	v_mfma_f32_16x16x32_bf16 v[62:65], v[146:149], v[82:85], v[62:65]
	s_waitcnt lgkmcnt(6)
; __device__ __forceinline__ unsigned cvt_pk_bf16(float lo, float hi) { unsigned r; asm volatile("v_cvt_pk_bf16_f32 %0, %1, %2" : "=v"(r) : "v"(lo), "v"(hi)); return r; }
; #define LAS __attribute__((address_space(3)))
; #define MFMA16(a, b, c) __builtin_amdgcn_mfma_f32_16x16x32_bf16((a), (b), (c), 0, 0, 0)
; __device__ __forceinline__ void p2_block(LAS unsigned char* lds, const bf16_t* __restrict__ PROJ, bf16_t* __restrict__ ATT, bf16_t* __restrict__ SGU, const float* __restrict__ qn, const float* __restrict__ kn, ...
;     ...
;         {
;             float x1[8], x2[8]; unpack8(qa[c], x1); unpack8(qb[c], x2);
;             float ss = 0.f;
; #pragma unroll
;             for (int j = 0; j < 8; ++j) ss += x1[j] * x1[j] + x2[j] * x2[j];
;             ss += __shfl_xor(ss, 16); ss += __shfl_xor(ss, 32);
;             const float rinv = rsqrtf(ss * (1.0f / 64.0f) + pg8::EPS) * 0.125f;
;             const float* cp = COS + pos * 32 + 8 * fq; const float* sp = SIN + pos * 32 + 8 * fq;
;             float o1[8], o2[8];
; #pragma unroll
;             for (int j = 0; j < 8; ++j) { const float a1 = x1[j] * rinv * qn[8 * fq + j], a2 = x2[j] * rinv * qn[32 + 8 * fq + j], cc = cp[j], sn = sp[j]; o1[j] = a1 * cc - a2 * sn; o2[j] = a2 * cc + a1 * sn; }
;     ...
;         for (int j = 0; j < 5; ++j) {
;             u32x4 pw; pw.x = cvt_pk_bf16(sc_[2 * j][0], sc_[2 * j][1]); pw.y = cvt_pk_bf16(sc_[2 * j][2], sc_[2 * j][3]); pw.z = cvt_pk_bf16(sc_[2 * j + 1][0], sc_[2 * j + 1][1]); pw.w = cvt_pk_bf16(sc_[2 * j + 1][2], sc_[2 * j + 1][3]);
;             const bf16x8 pf = __builtin_bit_cast(bf16x8, pw);
; #pragma unroll
;             for (int dt = 0; dt < 4; ++dt) { const LAS unsigned char* vb = VT + (16 * dt + fr) * VT_STRIDE + (16 * (t0 + 2 * j) + 4 * fq) * 2;
;                 const u32x2 va = *(const LAS u32x2*)vb, vc = *(const LAS u32x2*)(vb + 32); u32x4 vw; vw.x = va.x; vw.y = va.y; vw.z = vc.x; vw.w = vc.y;
;                 o[dt] = MFMA16(__builtin_bit_cast(bf16x8, vw), pf, o[dt]); }
;         }
;         bf16_t* op = ATT + grow * 1024 + hq * 64 + 4 * fq;
; #pragma unroll
;         for (int dt = 0; dt < 4; ++dt) { u32x2 ow; ow.x = cvt_pk_bf16(o[dt][0] * inv, o[dt][1] * inv); ow.y = cvt_pk_bf16(o[dt][2] * inv, o[dt][3] * inv); *(u32x2*)(op + 16 * dt) = ow; }
	v_mfma_f32_16x16x32_bf16 v[70:73], v[150:153], v[82:85], v[70:73]
	s_waitcnt lgkmcnt(5)
	v_mfma_f32_16x16x32_bf16 v[78:81], v[154:157], v[82:85], v[78:81]
	s_waitcnt lgkmcnt(4)
	v_mfma_f32_16x16x32_bf16 v[86:89], v[158:161], v[82:85], v[86:89]
	s_waitcnt lgkmcnt(3)
	v_mfma_f32_16x16x32_bf16 v[62:65], v[162:165], v[90:93], v[62:65]
	s_waitcnt lgkmcnt(2)
	v_mfma_f32_16x16x32_bf16 v[70:73], v[182:185], v[90:93], v[70:73]
	s_waitcnt lgkmcnt(1)
	v_mfma_f32_16x16x32_bf16 v[78:81], v[186:189], v[90:93], v[78:81]
	s_waitcnt lgkmcnt(0)
	v_mfma_f32_16x16x32_bf16 v[86:89], v[190:193], v[90:93], v[86:89]
	ds_read_b128 v[106:109], v45 offset:16128
	ds_read_b128 v[110:113], v45 offset:16192
	ds_read_b128 v[114:117], v45 offset:18432
	ds_read_b128 v[118:121], v45 offset:18496
	ds_read_b128 v[122:125], v45 offset:20736
	ds_read_b128 v[126:129], v45 offset:20800
	ds_read_b128 v[130:133], v45 offset:23040
	ds_read_b128 v[134:137], v45 offset:23104
	ds_read_b128 v[138:141], v45 offset:25344
	ds_read_b128 v[142:145], v45 offset:25408
	ds_read_b128 v[146:149], v45 offset:27648
	ds_read_b128 v[150:153], v45 offset:27712
	ds_read_b128 v[154:157], v45 offset:29952
	ds_read_b128 v[158:161], v45 offset:30016
	s_nop 7
	v_mul_f32_e32 v62, v62, v167
	v_mul_f32_e32 v63, v63, v167
	v_mul_f32_e32 v64, v64, v167
	v_mul_f32_e32 v65, v65, v167
	v_mul_f32_e32 v70, v70, v167
	v_mul_f32_e32 v71, v71, v167
	v_mul_f32_e32 v72, v72, v167
	v_mul_f32_e32 v73, v73, v167
	v_mul_f32_e32 v78, v78, v167
	v_mul_f32_e32 v79, v79, v167
	v_mul_f32_e32 v80, v80, v167
	v_mul_f32_e32 v81, v81, v167
	v_mul_f32_e32 v86, v86, v167
	v_mul_f32_e32 v87, v87, v167
	v_mul_f32_e32 v88, v88, v167
	v_mul_f32_e32 v89, v89, v167
	v_cvt_pk_bf16_f32 v62, v62, v63
	v_cvt_pk_bf16_f32 v63, v64, v65
	global_store_dwordx2 v48, v[62:63], s[24:25] offset:0
	v_cvt_pk_bf16_f32 v70, v70, v71
	v_cvt_pk_bf16_f32 v71, v72, v73
	global_store_dwordx2 v48, v[70:71], s[24:25] offset:32
	v_cvt_pk_bf16_f32 v78, v78, v79
	v_cvt_pk_bf16_f32 v79, v80, v81
	global_store_dwordx2 v48, v[78:79], s[24:25] offset:64
	v_cvt_pk_bf16_f32 v86, v86, v87
	v_cvt_pk_bf16_f32 v87, v88, v89
	global_store_dwordx2 v48, v[86:87], s[24:25] offset:96
	v_add_u32_e32 v48, 0x8000, v48
	s_waitcnt vmcnt(8)
	v_lshlrev_b32_e32 v58, 16, v218
	v_and_b32_e32 v59, 0xffff0000, v218
	v_lshlrev_b32_e32 v66, 16, v222
	v_and_b32_e32 v67, 0xffff0000, v222
	v_lshlrev_b32_e32 v60, 16, v219
	v_and_b32_e32 v61, 0xffff0000, v219
	v_lshlrev_b32_e32 v68, 16, v223
	v_and_b32_e32 v69, 0xffff0000, v223
	v_lshlrev_b32_e32 v62, 16, v220
	v_and_b32_e32 v63, 0xffff0000, v220
	v_lshlrev_b32_e32 v70, 16, v224
	v_and_b32_e32 v71, 0xffff0000, v224
	v_lshlrev_b32_e32 v64, 16, v221
	v_and_b32_e32 v65, 0xffff0000, v221
	v_lshlrev_b32_e32 v72, 16, v225
	v_and_b32_e32 v73, 0xffff0000, v225
	v_mul_f32_e32 v74, v58, v58
	v_mul_f32_e32 v75, v59, v59
	v_fmac_f32_e32 v74, v60, v60
	v_fmac_f32_e32 v75, v61, v61
	v_fmac_f32_e32 v74, v62, v62
	v_fmac_f32_e32 v75, v63, v63
	v_fmac_f32_e32 v74, v64, v64
	v_fmac_f32_e32 v75, v65, v65
	v_fmac_f32_e32 v74, v66, v66
	v_fmac_f32_e32 v75, v67, v67
	v_fmac_f32_e32 v74, v68, v68
	v_fmac_f32_e32 v75, v69, v69
	v_fmac_f32_e32 v74, v70, v70
	v_fmac_f32_e32 v75, v71, v71
	v_fmac_f32_e32 v74, v72, v72
	v_fmac_f32_e32 v75, v73, v73
	v_add_f32_e32 v74, v74, v75
	v_mov_b32_e32 v166, v74
	s_nop 1
	v_permlane16_swap_b32_e32 v74, v166
	v_add_f32_e32 v74, v74, v166
	v_mov_b32_e32 v166, v74
	s_nop 1
	v_permlane32_swap_b32_e32 v74, v166
	v_add_f32_e32 v74, v74, v166
	v_fmamk_f32 v74, v74, 0x3c800000, v209
	v_rsq_f32_e32 v76, v74
	s_nop 0
	v_mul_f32_e32 v76, 0x3e000000, v76
	v_mul_f32_e32 v58, v58, v76
	v_mul_f32_e32 v66, v66, v76
	v_mul_f32_e32 v59, v59, v76
	v_mul_f32_e32 v67, v67, v76
	v_mul_f32_e32 v60, v60, v76
	v_mul_f32_e32 v68, v68, v76
	v_mul_f32_e32 v61, v61, v76
	v_mul_f32_e32 v69, v69, v76
	v_mul_f32_e32 v62, v62, v76
	v_mul_f32_e32 v70, v70, v76
	v_mul_f32_e32 v63, v63, v76
	v_mul_f32_e32 v71, v71, v76
	v_mul_f32_e32 v64, v64, v76
	v_mul_f32_e32 v72, v72, v76
	v_mul_f32_e32 v65, v65, v76
	v_mul_f32_e32 v73, v73, v76
	v_mul_f32_e32 v58, v58, v26
	v_mul_f32_e32 v66, v66, v34
	v_mul_f32_e32 v59, v59, v27
	v_mul_f32_e32 v67, v67, v35
	v_mul_f32_e32 v60, v60, v28
	v_mul_f32_e32 v68, v68, v36
	v_mul_f32_e32 v61, v61, v29
	v_mul_f32_e32 v69, v69, v37
	v_mul_f32_e32 v62, v62, v30
	v_mul_f32_e32 v70, v70, v38
	v_mul_f32_e32 v63, v63, v31
	v_mul_f32_e32 v71, v71, v39
	v_mul_f32_e32 v64, v64, v32
	v_mul_f32_e32 v72, v72, v40
	v_mul_f32_e32 v65, v65, v33
	v_mul_f32_e32 v73, v73, v41
	v_mul_f32_e32 v78, v66, v234
	v_mul_f32_e32 v86, v58, v234
	v_mul_f32_e32 v79, v67, v235
	v_mul_f32_e32 v87, v59, v235
	v_mul_f32_e32 v80, v68, v236
	v_mul_f32_e32 v88, v60, v236
	v_mul_f32_e32 v81, v69, v237
	v_mul_f32_e32 v89, v61, v237
	v_mul_f32_e32 v82, v70, v238
	v_mul_f32_e32 v90, v62, v238
	v_mul_f32_e32 v83, v71, v239
	v_mul_f32_e32 v91, v63, v239
	v_mul_f32_e32 v84, v72, v240
	v_mul_f32_e32 v92, v64, v240
	v_mul_f32_e32 v85, v73, v241
	v_mul_f32_e32 v93, v65, v241
	v_fma_f32 v78, v58, v226, -v78
	v_fmac_f32_e32 v86, v66, v226
	v_fma_f32 v79, v59, v227, -v79
	v_fmac_f32_e32 v87, v67, v227
	v_fma_f32 v80, v60, v228, -v80
	v_fmac_f32_e32 v88, v68, v228
	v_fma_f32 v81, v61, v229, -v81
	v_fmac_f32_e32 v89, v69, v229
	v_fma_f32 v82, v62, v230, -v82
	v_fmac_f32_e32 v90, v70, v230
	v_fma_f32 v83, v63, v231, -v83
	v_fmac_f32_e32 v91, v71, v231
	v_fma_f32 v84, v64, v232, -v84
	v_fmac_f32_e32 v92, v72, v232
	v_fma_f32 v85, v65, v233, -v85
	v_fmac_f32_e32 v93, v73, v233
	v_cvt_pk_bf16_f32 v50, v78, v79
	v_cvt_pk_bf16_f32 v54, v86, v87
	v_cvt_pk_bf16_f32 v51, v80, v81
	v_cvt_pk_bf16_f32 v55, v88, v89
; __device__ __forceinline__ void p2_block(LAS unsigned char* lds, const bf16_t* __restrict__ PROJ, bf16_t* __restrict__ ATT, bf16_t* __restrict__ SGU, const float* __restrict__ qn, const float* __restrict__ kn, ...
;     ...
;         const int t0 = (i0 >> 4) < 6 ? (i0 >> 4) : 6;
;         f32x4 sc_[10];
;         const LAS unsigned char* kbase = KS + (16 * t0 + fr) * KS_STRIDE + 16 * fq;
; #pragma unroll
;         for (int t = 0; t < 10; ++t) { const bf16x8 k0 = *(const LAS bf16x8*)(kbase + t * 16 * KS_STRIDE), k1 = *(const LAS bf16x8*)(kbase + t * 16 * KS_STRIDE + 64);
;             f32x4 z = (f32x4){0.f, 0.f, 0.f, 0.f}; z = MFMA16(k0, qf0, z); sc_[t] = MFMA16(k1, qf1, z); }
;         float mx = -1e30f;
; #pragma unroll
;         for (int t = 0; t < 10; ++t)
; #pragma unroll
;             for (int e = 0; e < 4; ++e) { const int kx = 16 * (t0 + t) + 4 * fq + e, d = kx - irow; const bool ok = (d >= 1) && (d <= 128) && (n > 0 || kx >= 128);
;                 const float v = ok ? sc_[t][e] : -1e30f; sc_[t][e] = v; mx = fmaxf(mx, v); }
;         mx = fmaxf(mx, __shfl_xor(mx, 16)); mx = fmaxf(mx, __shfl_xor(mx, 32)); mx = fmaxf(mx, sink);
;     ...
;         const int gg = 2 * kvh + gi, irow = 16 * w + fr, nks = (w >> 1) + 1;
;         const LAS unsigned char* VNT = lds + (gi ? VN_OFF1 : VN_OFF0);
;         f32x4 acc[8];
; #pragma unroll
;         for (int dt = 0; dt < 8; ++dt) acc[dt] = (f32x4){0.f, 0.f, 0.f, 0.f};
;         const float* wrow = wsp + (size_t)gg * 16384 + irow * 128 + 8 * fq;
; #pragma unroll
;         for (int ks = 0; ks < 4; ++ks) if (ks < nks) {
;             const f32x4 wa = *(const f32x4*)(wrow + 32 * ks), wb = *(const f32x4*)(wrow + 32 * ks + 4);
;             const int j0 = 32 * ks + 8 * fq; float wv[8];
; #pragma unroll
;             for (int e = 0; e < 4; ++e) { wv[e] = (j0 + e <= irow) ? wa[e] : 0.f; wv[4 + e] = (j0 + 4 + e <= irow) ? wb[e] : 0.f; }
;             u32x4 ww; ww.x = cvt_pk_bf16(wv[0], wv[1]); ww.y = cvt_pk_bf16(wv[2], wv[3]); ww.z = cvt_pk_bf16(wv[4], wv[5]); ww.w = cvt_pk_bf16(wv[6], wv[7]);
;             const bf16x8 wf = __builtin_bit_cast(bf16x8, ww);
; #pragma unroll
;             for (int dt = 0; dt < 8; ++dt) { const bf16x8 af = *(const LAS bf16x8*)(VNT + (16 * dt + fr) * VN_STRIDE + (32 * ks + 8 * fq) * 2); acc[dt] = MFMA16(af, wf, acc[dt]); }
;         }
;         const float bias = bsp[gg * 128 + irow];
	v_cvt_pk_bf16_f32 v52, v82, v83
	v_cvt_pk_bf16_f32 v56, v90, v91
	v_cvt_pk_bf16_f32 v53, v84, v85
	v_cvt_pk_bf16_f32 v57, v92, v93
	v_lshrrev_b32_e32 v242, 6, v204
	v_sub_u32_e32 v243, 11, v242
	v_cmp_lt_u32_e32 vcc, 3, v242
	v_and_b32_e32 v244, 15, v204
	s_nop 1
	v_cndmask_b32_e32 v242, v242, v243, vcc
	v_lshl_or_b32 v242, v242, 4, v244
	v_lshrrev_b32_e32 v243, 1, v204
	v_and_b32_e32 v243, 24, v243
	v_and_b32_e64 v244, s2, 3
	v_lshlrev_b32_e32 v244, 9, v244
	v_and_b32_e64 v245, s2, -4
	v_lshl_add_u32 v245, v245, 5, v242
	v_mul_u32_u24_e32 v245, 0x3c00, v245
	v_add3_u32 v245, v245, v244, v243
	v_lshlrev_b32_e32 v244, 1, v244
	v_lshl_add_u32 v244, v242, 2, v244
	global_load_dword v198, v244, s[22:23]
	global_load_dword v199, v244, s[22:23] offset:512
	global_load_dwordx2 v[218:219], v245, s[10:11] offset:3072
	global_load_dwordx2 v[220:221], v245, s[10:11] offset:3104
	global_load_dwordx2 v[222:223], v245, s[10:11] offset:3136
	global_load_dwordx2 v[224:225], v245, s[10:11] offset:3168
	global_load_dwordx2 v[226:227], v245, s[10:11] offset:3200
	global_load_dwordx2 v[228:229], v245, s[10:11] offset:3232
	global_load_dwordx2 v[230:231], v245, s[10:11] offset:3264
	global_load_dwordx2 v[232:233], v245, s[10:11] offset:3296
	global_load_dwordx2 v[234:235], v245, s[10:11] offset:3328
	global_load_dwordx2 v[236:237], v245, s[10:11] offset:3360
	global_load_dwordx2 v[238:239], v245, s[10:11] offset:3392
	global_load_dwordx2 v[240:241], v245, s[10:11] offset:3424
	global_load_dwordx2 v[242:243], v245, s[10:11] offset:3456
	global_load_dwordx2 v[200:201], v245, s[10:11] offset:3520
	global_load_dwordx2 v[202:203], v245, s[10:11] offset:3552
	global_load_dwordx2 v[244:245], v245, s[10:11] offset:3488
	s_nop 1
	s_waitcnt lgkmcnt(13)
	v_mfma_f32_16x16x32_bf16 v[62:65], v[106:109], v[50:53], 0
	s_waitcnt lgkmcnt(12)
	v_mfma_f32_16x16x32_bf16 v[62:65], v[110:113], v[54:57], v[62:65]
	ds_read_b128 v[162:165], v45 offset:32256
	ds_read_b128 v[182:185], v45 offset:32320
	s_waitcnt lgkmcnt(13)
	v_mfma_f32_16x16x32_bf16 v[66:69], v[114:117], v[50:53], 0
	s_waitcnt lgkmcnt(12)
	v_mfma_f32_16x16x32_bf16 v[66:69], v[118:121], v[54:57], v[66:69]
	ds_read_b128 v[186:189], v45 offset:34560
	ds_read_b128 v[190:193], v45 offset:34624
	s_waitcnt lgkmcnt(13)
	v_mfma_f32_16x16x32_bf16 v[70:73], v[122:125], v[50:53], 0
	s_waitcnt lgkmcnt(12)
	v_mfma_f32_16x16x32_bf16 v[70:73], v[126:129], v[54:57], v[70:73]
	s_waitcnt lgkmcnt(11)
	v_mfma_f32_16x16x32_bf16 v[74:77], v[130:133], v[50:53], 0
	s_waitcnt lgkmcnt(10)
	v_mfma_f32_16x16x32_bf16 v[74:77], v[134:137], v[54:57], v[74:77]
	s_waitcnt lgkmcnt(9)
	v_mfma_f32_16x16x32_bf16 v[78:81], v[138:141], v[50:53], 0
	s_waitcnt lgkmcnt(8)
	v_mfma_f32_16x16x32_bf16 v[78:81], v[142:145], v[54:57], v[78:81]
	s_waitcnt lgkmcnt(7)
	v_mfma_f32_16x16x32_bf16 v[82:85], v[146:149], v[50:53], 0
	s_waitcnt lgkmcnt(6)
	v_mfma_f32_16x16x32_bf16 v[82:85], v[150:153], v[54:57], v[82:85]
	s_waitcnt lgkmcnt(5)
	v_mfma_f32_16x16x32_bf16 v[86:89], v[154:157], v[50:53], 0
	s_waitcnt lgkmcnt(4)
	v_mfma_f32_16x16x32_bf16 v[86:89], v[158:161], v[54:57], v[86:89]
	s_waitcnt lgkmcnt(3)
	v_mfma_f32_16x16x32_bf16 v[90:93], v[162:165], v[50:53], 0
	s_waitcnt lgkmcnt(2)
	v_mfma_f32_16x16x32_bf16 v[90:93], v[182:185], v[54:57], v[90:93]
	s_waitcnt lgkmcnt(1)
	v_mfma_f32_16x16x32_bf16 v[94:97], v[186:189], v[50:53], 0
	s_waitcnt lgkmcnt(0)
	v_mfma_f32_16x16x32_bf16 v[94:97], v[190:193], v[54:57], v[94:97]
	ds_read2_b64 v[98:101], v194 offset0:24 offset1:28
	ds_read2_b64 v[102:105], v195 offset0:24 offset1:28
	ds_read2_b64 v[106:109], v196 offset0:24 offset1:28
	ds_read2_b64 v[110:113], v197 offset0:24 offset1:28
	ds_read2_b64 v[114:117], v194 offset0:32 offset1:36
	ds_read2_b64 v[118:121], v195 offset0:32 offset1:36
	ds_read2_b64 v[122:125], v196 offset0:32 offset1:36
	ds_read2_b64 v[126:129], v197 offset0:32 offset1:36
	ds_read2_b64 v[130:133], v194 offset0:40 offset1:44
	ds_read2_b64 v[134:137], v195 offset0:40 offset1:44
	ds_read2_b64 v[138:141], v196 offset0:40 offset1:44
	ds_read2_b64 v[142:145], v197 offset0:40 offset1:44
	ds_read2_b64 v[146:149], v194 offset0:48 offset1:52
	ds_read2_b64 v[150:153], v195 offset0:48 offset1:52
	ds_read2_b64 v[154:157], v196 offset0:48 offset1:52
	s_nop 4
	v_cndmask_b32_e64 v62, v49, v62, s[48:49]
	v_cndmask_b32_e64 v63, v49, v63, s[50:51]
	v_cndmask_b32_e64 v64, v49, v64, s[52:53]
	v_cndmask_b32_e64 v65, v49, v65, s[26:27]
	v_cndmask_b32_e64 v94, v94, v49, s[40:41]
	v_cndmask_b32_e64 v95, v95, v49, s[42:43]
	v_cndmask_b32_e64 v96, v96, v49, s[44:45]
	v_cndmask_b32_e64 v97, v97, v49, s[46:47]
	v_max_f32_e32 v167, v62, v63
	v_max_f32_e32 v58, v64, v65
	v_max3_f32 v167, v167, v66, v67
	v_max3_f32 v58, v58, v68, v69
	v_max3_f32 v167, v167, v70, v71
	v_max3_f32 v58, v58, v72, v73
	v_max3_f32 v167, v167, v74, v75
	v_max3_f32 v58, v58, v76, v77
	v_max3_f32 v167, v167, v78, v79
	v_max3_f32 v58, v58, v80, v81
	v_max3_f32 v167, v167, v82, v83
	v_max3_f32 v58, v58, v84, v85
	v_max3_f32 v167, v167, v86, v87
	v_max3_f32 v58, v58, v88, v89
	v_max3_f32 v167, v167, v90, v91
	v_max3_f32 v58, v58, v92, v93
	v_max3_f32 v167, v167, v94, v95
	v_max3_f32 v58, v58, v96, v97
	v_max_f32_e32 v167, v167, v58
	v_mov_b32_e32 v166, v167
	s_nop 1
	v_permlane16_swap_b32_e32 v167, v166
	v_max_f32_e32 v167, v167, v166
	v_mov_b32_e32 v166, v167
	s_nop 1
	v_permlane32_swap_b32_e32 v167, v166
	v_max_f32_e32 v167, v167, v166
	v_max_f32_e32 v167, v167, v42
	v_mul_f32_e32 v58, 0xbfb8aa3b, v167
	v_fmamk_f32 v62, v62, 0x3fb8aa3b, v58
	v_fmamk_f32 v63, v63, 0x3fb8aa3b, v58
	v_fmamk_f32 v64, v64, 0x3fb8aa3b, v58
	v_fmamk_f32 v65, v65, 0x3fb8aa3b, v58
; __device__ __forceinline__ unsigned cvt_pk_bf16(float lo, float hi) { unsigned r; asm volatile("v_cvt_pk_bf16_f32 %0, %1, %2" : "=v"(r) : "v"(lo), "v"(hi)); return r; }
; #define LAS __attribute__((address_space(3)))
; #define MFMA16(a, b, c) __builtin_amdgcn_mfma_f32_16x16x32_bf16((a), (b), (c), 0, 0, 0)
; __device__ __forceinline__ void p2_block(LAS unsigned char* lds, const bf16_t* __restrict__ PROJ, bf16_t* __restrict__ ATT, bf16_t* __restrict__ SGU, const float* __restrict__ qn, const float* __restrict__ kn, ...
;     ...
;         float sum = 0.f;
; #pragma unroll
;         for (int t = 0; t < 10; ++t)
; #pragma unroll
;             for (int e = 0; e < 4; ++e) { const float p = __builtin_amdgcn_exp2f((sc_[t][e] - mx) * LOG2E); sc_[t][e] = p; sum += p; }
;         sum += __shfl_xor(sum, 16); sum += __shfl_xor(sum, 32);
;         const float inv = 1.0f / (sum + __builtin_amdgcn_exp2f((sink - mx) * LOG2E));
;         f32x4 o[4];
; #pragma unroll
;         for (int dt = 0; dt < 4; ++dt) o[dt] = (f32x4){0.f, 0.f, 0.f, 0.f};
; #pragma unroll
;         for (int j = 0; j < 5; ++j) {
;             u32x4 pw; pw.x = cvt_pk_bf16(sc_[2 * j][0], sc_[2 * j][1]); pw.y = cvt_pk_bf16(sc_[2 * j][2], sc_[2 * j][3]); pw.z = cvt_pk_bf16(sc_[2 * j + 1][0], sc_[2 * j + 1][1]); pw.w = cvt_pk_bf16(sc_[2 * j + 1][2], sc_[2 * j + 1][3]);
;             const bf16x8 pf = __builtin_bit_cast(bf16x8, pw);
; #pragma unroll
;             for (int dt = 0; dt < 4; ++dt) { const LAS unsigned char* vb = VT + (16 * dt + fr) * VT_STRIDE + (16 * (t0 + 2 * j) + 4 * fq) * 2;
;                 const u32x2 va = *(const LAS u32x2*)vb, vc = *(const LAS u32x2*)(vb + 32); u32x4 vw; vw.x = va.x; vw.y = va.y; vw.z = vc.x; vw.w = vc.y;
;                 o[dt] = MFMA16(__builtin_bit_cast(bf16x8, vw), pf, o[dt]); }
	v_fmamk_f32 v66, v66, 0x3fb8aa3b, v58
	v_fmamk_f32 v67, v67, 0x3fb8aa3b, v58
	v_fmamk_f32 v68, v68, 0x3fb8aa3b, v58
	v_fmamk_f32 v69, v69, 0x3fb8aa3b, v58
	v_fmamk_f32 v70, v70, 0x3fb8aa3b, v58
	v_fmamk_f32 v71, v71, 0x3fb8aa3b, v58
	v_fmamk_f32 v72, v72, 0x3fb8aa3b, v58
	v_fmamk_f32 v73, v73, 0x3fb8aa3b, v58
	v_fmamk_f32 v74, v74, 0x3fb8aa3b, v58
	v_fmamk_f32 v75, v75, 0x3fb8aa3b, v58
	v_fmamk_f32 v76, v76, 0x3fb8aa3b, v58
	v_fmamk_f32 v77, v77, 0x3fb8aa3b, v58
	v_fmamk_f32 v78, v78, 0x3fb8aa3b, v58
	v_fmamk_f32 v79, v79, 0x3fb8aa3b, v58
	v_fmamk_f32 v80, v80, 0x3fb8aa3b, v58
	v_fmamk_f32 v81, v81, 0x3fb8aa3b, v58
	v_fmamk_f32 v82, v82, 0x3fb8aa3b, v58
	v_fmamk_f32 v83, v83, 0x3fb8aa3b, v58
	v_fmamk_f32 v84, v84, 0x3fb8aa3b, v58
	v_fmamk_f32 v85, v85, 0x3fb8aa3b, v58
	v_fmamk_f32 v86, v86, 0x3fb8aa3b, v58
	v_fmamk_f32 v87, v87, 0x3fb8aa3b, v58
	v_fmamk_f32 v88, v88, 0x3fb8aa3b, v58
	v_fmamk_f32 v89, v89, 0x3fb8aa3b, v58
	v_fmamk_f32 v90, v90, 0x3fb8aa3b, v58
	v_fmamk_f32 v91, v91, 0x3fb8aa3b, v58
	v_fmamk_f32 v92, v92, 0x3fb8aa3b, v58
	v_fmamk_f32 v93, v93, 0x3fb8aa3b, v58
	v_fmamk_f32 v94, v94, 0x3fb8aa3b, v58
	v_fmamk_f32 v95, v95, 0x3fb8aa3b, v58
	v_fmamk_f32 v96, v96, 0x3fb8aa3b, v58
	v_fmamk_f32 v97, v97, 0x3fb8aa3b, v58
	v_exp_f32_e32 v62, v62
	v_exp_f32_e32 v63, v63
	v_exp_f32_e32 v64, v64
	v_exp_f32_e32 v65, v65
	v_exp_f32_e32 v66, v66
	v_exp_f32_e32 v67, v67
	v_exp_f32_e32 v68, v68
	v_exp_f32_e32 v69, v69
	v_exp_f32_e32 v70, v70
	v_exp_f32_e32 v71, v71
	v_exp_f32_e32 v72, v72
	v_exp_f32_e32 v73, v73
	v_exp_f32_e32 v74, v74
	v_exp_f32_e32 v75, v75
	v_exp_f32_e32 v76, v76
	v_exp_f32_e32 v77, v77
	v_exp_f32_e32 v78, v78
	v_exp_f32_e32 v79, v79
	v_exp_f32_e32 v80, v80
	v_exp_f32_e32 v81, v81
	v_exp_f32_e32 v82, v82
	v_exp_f32_e32 v83, v83
	v_exp_f32_e32 v84, v84
	v_exp_f32_e32 v85, v85
	v_exp_f32_e32 v86, v86
	v_exp_f32_e32 v87, v87
	v_exp_f32_e32 v88, v88
	v_exp_f32_e32 v89, v89
	v_exp_f32_e32 v90, v90
	v_exp_f32_e32 v91, v91
	v_exp_f32_e32 v92, v92
	v_exp_f32_e32 v93, v93
	v_exp_f32_e32 v94, v94
	v_exp_f32_e32 v95, v95
	v_exp_f32_e32 v96, v96
	v_exp_f32_e32 v97, v97
	v_fmamk_f32 v59, v42, 0x3fb8aa3b, v58
	v_exp_f32_e32 v59, v59
	v_add_f32_e32 v167, v62, v63
	v_add_f32_e32 v58, v64, v65
	v_add_f32_e32 v167, v167, v66
	v_add_f32_e32 v58, v58, v67
	v_add_f32_e32 v167, v167, v68
	v_add_f32_e32 v58, v58, v69
	v_add_f32_e32 v167, v167, v70
	v_add_f32_e32 v58, v58, v71
	v_add_f32_e32 v167, v167, v72
	v_add_f32_e32 v58, v58, v73
	v_add_f32_e32 v167, v167, v74
	v_add_f32_e32 v58, v58, v75
	v_add_f32_e32 v167, v167, v76
	v_add_f32_e32 v58, v58, v77
	v_add_f32_e32 v167, v167, v78
	v_add_f32_e32 v58, v58, v79
	v_add_f32_e32 v167, v167, v80
	v_add_f32_e32 v58, v58, v81
	v_add_f32_e32 v167, v167, v82
	v_add_f32_e32 v58, v58, v83
	v_add_f32_e32 v167, v167, v84
	v_add_f32_e32 v58, v58, v85
	v_add_f32_e32 v167, v167, v86
	v_add_f32_e32 v58, v58, v87
	v_add_f32_e32 v167, v167, v88
	v_add_f32_e32 v58, v58, v89
	v_add_f32_e32 v167, v167, v90
	v_add_f32_e32 v58, v58, v91
	v_add_f32_e32 v167, v167, v92
	v_add_f32_e32 v58, v58, v93
	v_add_f32_e32 v167, v167, v94
	v_add_f32_e32 v58, v58, v95
	v_add_f32_e32 v167, v167, v96
	v_add_f32_e32 v58, v58, v97
	v_add_f32_e32 v167, v167, v58
	v_mov_b32_e32 v166, v167
	s_nop 1
	v_permlane16_swap_b32_e32 v167, v166
	v_add_f32_e32 v167, v167, v166
	v_mov_b32_e32 v166, v167
	s_nop 1
	v_permlane32_swap_b32_e32 v167, v166
	v_add_f32_e32 v167, v167, v166
	v_add_f32_e32 v167, v167, v59
	v_rcp_f32_e32 v167, v167
	v_mov_b32_e32 v58, 0
	v_mov_b32_e32 v59, 0
	v_mov_b32_e32 v60, 0
	v_mov_b32_e32 v61, 0
	v_cvt_pk_bf16_f32 v58, v58, v59
	v_cvt_pk_bf16_f32 v59, v60, v61
	v_cvt_pk_bf16_f32 v60, v62, v63
	v_cvt_pk_bf16_f32 v61, v64, v65
	v_cvt_pk_bf16_f32 v66, v66, v67
	v_cvt_pk_bf16_f32 v67, v68, v69
	v_cvt_pk_bf16_f32 v68, v70, v71
	v_cvt_pk_bf16_f32 v69, v72, v73
	v_cvt_pk_bf16_f32 v74, v74, v75
	v_cvt_pk_bf16_f32 v75, v76, v77
	v_cvt_pk_bf16_f32 v76, v78, v79
	v_cvt_pk_bf16_f32 v77, v80, v81
	v_cvt_pk_bf16_f32 v82, v82, v83
	v_cvt_pk_bf16_f32 v83, v84, v85
	v_cvt_pk_bf16_f32 v84, v86, v87
	v_cvt_pk_bf16_f32 v85, v88, v89
	v_cvt_pk_bf16_f32 v90, v90, v91
	v_cvt_pk_bf16_f32 v91, v92, v93
	v_cvt_pk_bf16_f32 v92, v94, v95
	v_cvt_pk_bf16_f32 v93, v96, v97
	s_nop 1
	s_waitcnt lgkmcnt(14)
	v_mfma_f32_16x16x32_bf16 v[62:65], v[98:101], v[58:61], 0
	ds_read2_b64 v[158:161], v197 offset0:48 offset1:52
	s_waitcnt lgkmcnt(14)
	v_mfma_f32_16x16x32_bf16 v[70:73], v[102:105], v[58:61], 0
	ds_read2_b64 v[162:165], v194 offset0:56 offset1:60
	s_waitcnt lgkmcnt(14)
	v_mfma_f32_16x16x32_bf16 v[78:81], v[106:109], v[58:61], 0
	ds_read2_b64 v[182:185], v195 offset0:56 offset1:60
	s_waitcnt lgkmcnt(14)
	v_mfma_f32_16x16x32_bf16 v[86:89], v[110:113], v[58:61], 0
	ds_read2_b64 v[186:189], v196 offset0:56 offset1:60
	s_waitcnt lgkmcnt(14)
	v_mfma_f32_16x16x32_bf16 v[62:65], v[114:117], v[66:69], v[62:65]
	ds_read2_b64 v[190:193], v197 offset0:56 offset1:60
	s_waitcnt lgkmcnt(14)
	v_mfma_f32_16x16x32_bf16 v[70:73], v[118:121], v[66:69], v[70:73]
	s_waitcnt lgkmcnt(13)
	v_mfma_f32_16x16x32_bf16 v[78:81], v[122:125], v[66:69], v[78:81]
	s_waitcnt lgkmcnt(12)
	v_mfma_f32_16x16x32_bf16 v[86:89], v[126:129], v[66:69], v[86:89]
	s_waitcnt lgkmcnt(11)
	v_mfma_f32_16x16x32_bf16 v[62:65], v[130:133], v[74:77], v[62:65]
	s_waitcnt lgkmcnt(10)
	v_mfma_f32_16x16x32_bf16 v[70:73], v[134:137], v[74:77], v[70:73]
	s_waitcnt lgkmcnt(9)
	v_mfma_f32_16x16x32_bf16 v[78:81], v[138:141], v[74:77], v[78:81]
	s_waitcnt lgkmcnt(8)
	v_mfma_f32_16x16x32_bf16 v[86:89], v[142:145], v[74:77], v[86:89]
	s_waitcnt lgkmcnt(7)
	v_mfma_f32_16x16x32_bf16 v[62:65], v[146:149], v[82:85], v[62:65]
	s_waitcnt lgkmcnt(6)
; #define LAS __attribute__((address_space(3)))
; #define MFMA16(a, b, c) __builtin_amdgcn_mfma_f32_16x16x32_bf16((a), (b), (c), 0, 0, 0)
; __device__ __forceinline__ void p2_block(LAS unsigned char* lds, const bf16_t* __restrict__ PROJ, bf16_t* __restrict__ ATT, bf16_t* __restrict__ SGU, const float* __restrict__ qn, const float* __restrict__ kn, ...
;     ...
;         const int i0 = rbase + 16 * c, irow = i0 + fr, pos = n * 128 + irow; const size_t grow = (size_t)b * pg8::SEQ + pos;
;         bf16x8 qf0, qf1;
;         {
;             float x1[8], x2[8]; unpack8(qa[c], x1); unpack8(qb[c], x2);
;             float ss = 0.f;
; #pragma unroll
;             for (int j = 0; j < 8; ++j) ss += x1[j] * x1[j] + x2[j] * x2[j];
;             ss += __shfl_xor(ss, 16); ss += __shfl_xor(ss, 32);
;             const float rinv = rsqrtf(ss * (1.0f / 64.0f) + pg8::EPS) * 0.125f;
;             const float* cp = COS + pos * 32 + 8 * fq; const float* sp = SIN + pos * 32 + 8 * fq;
;             float o1[8], o2[8];
; #pragma unroll
;             for (int j = 0; j < 8; ++j) { const float a1 = x1[j] * rinv * qn[8 * fq + j], a2 = x2[j] * rinv * qn[32 + 8 * fq + j], cc = cp[j], sn = sp[j]; o1[j] = a1 * cc - a2 * sn; o2[j] = a2 * cc + a1 * sn; }
;             u32x4 w0, w1;
;             w0.x = cvt_pk_bf16(o1[0], o1[1]); w0.y = cvt_pk_bf16(o1[2], o1[3]); w0.z = cvt_pk_bf16(o1[4], o1[5]); w0.w = cvt_pk_bf16(o1[6], o1[7]);
;             w1.x = cvt_pk_bf16(o2[0], o2[1]); w1.y = cvt_pk_bf16(o2[2], o2[3]); w1.z = cvt_pk_bf16(o2[4], o2[5]); w1.w = cvt_pk_bf16(o2[6], o2[7]);
;             qf0 = __builtin_bit_cast(bf16x8, w0); qf1 = __builtin_bit_cast(bf16x8, w1);
;         }
;         const int t0 = (i0 >> 4) < 6 ? (i0 >> 4) : 6;
;         f32x4 sc_[10];
;         const LAS unsigned char* kbase = KS + (16 * t0 + fr) * KS_STRIDE + 16 * fq;
; #pragma unroll
;         for (int t = 0; t < 10; ++t) { const bf16x8 k0 = *(const LAS bf16x8*)(kbase + t * 16 * KS_STRIDE), k1 = *(const LAS bf16x8*)(kbase + t * 16 * KS_STRIDE + 64);
;     ...
;                 o[dt] = MFMA16(__builtin_bit_cast(bf16x8, vw), pf, o[dt]); }
;         }
;         bf16_t* op = ATT + grow * 1024 + hq * 64 + 4 * fq;
; #pragma unroll
;         for (int dt = 0; dt < 4; ++dt) { u32x2 ow; ow.x = cvt_pk_bf16(o[dt][0] * inv, o[dt][1] * inv); ow.y = cvt_pk_bf16(o[dt][2] * inv, o[dt][3] * inv); *(u32x2*)(op + 16 * dt) = ow; }
	v_mfma_f32_16x16x32_bf16 v[70:73], v[150:153], v[82:85], v[70:73]
	s_waitcnt lgkmcnt(5)
	v_mfma_f32_16x16x32_bf16 v[78:81], v[154:157], v[82:85], v[78:81]
	s_waitcnt lgkmcnt(4)
	v_mfma_f32_16x16x32_bf16 v[86:89], v[158:161], v[82:85], v[86:89]
	s_waitcnt lgkmcnt(3)
	v_mfma_f32_16x16x32_bf16 v[62:65], v[162:165], v[90:93], v[62:65]
	s_waitcnt lgkmcnt(2)
	v_mfma_f32_16x16x32_bf16 v[70:73], v[182:185], v[90:93], v[70:73]
	s_waitcnt lgkmcnt(1)
	v_mfma_f32_16x16x32_bf16 v[78:81], v[186:189], v[90:93], v[78:81]
	s_waitcnt lgkmcnt(0)
	v_mfma_f32_16x16x32_bf16 v[86:89], v[190:193], v[90:93], v[86:89]
	s_nop 7
	v_mul_f32_e32 v62, v62, v167
	v_mul_f32_e32 v63, v63, v167
	v_mul_f32_e32 v64, v64, v167
	v_mul_f32_e32 v65, v65, v167
	v_mul_f32_e32 v70, v70, v167
	v_mul_f32_e32 v71, v71, v167
	v_mul_f32_e32 v72, v72, v167
	v_mul_f32_e32 v73, v73, v167
	v_mul_f32_e32 v78, v78, v167
	v_mul_f32_e32 v79, v79, v167
	v_mul_f32_e32 v80, v80, v167
	v_mul_f32_e32 v81, v81, v167
	v_mul_f32_e32 v86, v86, v167
	v_mul_f32_e32 v87, v87, v167
	v_mul_f32_e32 v88, v88, v167
	v_mul_f32_e32 v89, v89, v167
	v_cvt_pk_bf16_f32 v62, v62, v63
	v_cvt_pk_bf16_f32 v63, v64, v65
	global_store_dwordx2 v48, v[62:63], s[24:25] offset:0
	v_cvt_pk_bf16_f32 v70, v70, v71
	v_cvt_pk_bf16_f32 v71, v72, v73
	global_store_dwordx2 v48, v[70:71], s[24:25] offset:32
	v_cvt_pk_bf16_f32 v78, v78, v79
	v_cvt_pk_bf16_f32 v79, v80, v81
	global_store_dwordx2 v48, v[78:79], s[24:25] offset:64
	v_cvt_pk_bf16_f32 v86, v86, v87
	v_cvt_pk_bf16_f32 v87, v88, v89
	global_store_dwordx2 v48, v[86:87], s[24:25] offset:96
	v_add_u32_e32 v48, 0x8000, v48
	s_branch .Latt_done
.Latt_r0:
	ds_read_b128 v[98:101], v45 offset:0
	ds_read_b128 v[102:105], v45 offset:64
	ds_read_b128 v[106:109], v45 offset:2304
	ds_read_b128 v[110:113], v45 offset:2368
	ds_read_b128 v[114:117], v45 offset:4608
	ds_read_b128 v[118:121], v45 offset:4672
	ds_read_b128 v[122:125], v45 offset:6912
	ds_read_b128 v[126:129], v45 offset:6976
	ds_read_b128 v[130:133], v45 offset:9216
	ds_read_b128 v[134:137], v45 offset:9280
	ds_read_b128 v[138:141], v45 offset:11520
	ds_read_b128 v[142:145], v45 offset:11584
	ds_read_b128 v[146:149], v45 offset:13824
	ds_read_b128 v[150:153], v45 offset:13888
	s_waitcnt vmcnt(6)
	v_lshlrev_b32_e32 v58, 16, v2
	v_and_b32_e32 v59, 0xffff0000, v2
	v_lshlrev_b32_e32 v66, 16, v6
	v_and_b32_e32 v67, 0xffff0000, v6
	v_lshlrev_b32_e32 v60, 16, v3
	v_and_b32_e32 v61, 0xffff0000, v3
	v_lshlrev_b32_e32 v68, 16, v7
	v_and_b32_e32 v69, 0xffff0000, v7
	v_lshlrev_b32_e32 v62, 16, v4
	v_and_b32_e32 v63, 0xffff0000, v4
	v_lshlrev_b32_e32 v70, 16, v8
	v_and_b32_e32 v71, 0xffff0000, v8
	v_lshlrev_b32_e32 v64, 16, v5
	v_and_b32_e32 v65, 0xffff0000, v5
	v_lshlrev_b32_e32 v72, 16, v9
	v_and_b32_e32 v73, 0xffff0000, v9
	v_mul_f32_e32 v74, v58, v58
	v_mul_f32_e32 v75, v59, v59
	v_fmac_f32_e32 v74, v60, v60
	v_fmac_f32_e32 v75, v61, v61
	v_fmac_f32_e32 v74, v62, v62
	v_fmac_f32_e32 v75, v63, v63
	v_fmac_f32_e32 v74, v64, v64
	v_fmac_f32_e32 v75, v65, v65
	v_fmac_f32_e32 v74, v66, v66
	v_fmac_f32_e32 v75, v67, v67
	v_fmac_f32_e32 v74, v68, v68
	v_fmac_f32_e32 v75, v69, v69
	v_fmac_f32_e32 v74, v70, v70
	v_fmac_f32_e32 v75, v71, v71
	v_fmac_f32_e32 v74, v72, v72
	v_fmac_f32_e32 v75, v73, v73
	v_add_f32_e32 v74, v74, v75
	v_mov_b32_e32 v166, v74
	s_nop 1
	v_permlane16_swap_b32_e32 v74, v166
	v_add_f32_e32 v74, v74, v166
	v_mov_b32_e32 v166, v74
	s_nop 1
	v_permlane32_swap_b32_e32 v74, v166
	v_add_f32_e32 v74, v74, v166
	v_fmamk_f32 v74, v74, 0x3c800000, v209
	v_rsq_f32_e32 v76, v74
	s_nop 0
	v_mul_f32_e32 v76, 0x3e000000, v76
	v_mul_f32_e32 v58, v58, v76
	v_mul_f32_e32 v66, v66, v76
	v_mul_f32_e32 v59, v59, v76
	v_mul_f32_e32 v67, v67, v76
	v_mul_f32_e32 v60, v60, v76
	v_mul_f32_e32 v68, v68, v76
	v_mul_f32_e32 v61, v61, v76
	v_mul_f32_e32 v69, v69, v76
	v_mul_f32_e32 v62, v62, v76
	v_mul_f32_e32 v70, v70, v76
	v_mul_f32_e32 v63, v63, v76
	v_mul_f32_e32 v71, v71, v76
	v_mul_f32_e32 v64, v64, v76
	v_mul_f32_e32 v72, v72, v76
	v_mul_f32_e32 v65, v65, v76
	v_mul_f32_e32 v73, v73, v76
	v_mul_f32_e32 v58, v58, v26
	v_mul_f32_e32 v66, v66, v34
	v_mul_f32_e32 v59, v59, v27
	v_mul_f32_e32 v67, v67, v35
	v_mul_f32_e32 v60, v60, v28
	v_mul_f32_e32 v68, v68, v36
	v_mul_f32_e32 v61, v61, v29
	v_mul_f32_e32 v69, v69, v37
	v_mul_f32_e32 v62, v62, v30
	v_mul_f32_e32 v70, v70, v38
	v_mul_f32_e32 v63, v63, v31
	v_mul_f32_e32 v71, v71, v39
	v_mul_f32_e32 v64, v64, v32
	v_mul_f32_e32 v72, v72, v40
	v_mul_f32_e32 v65, v65, v33
	v_mul_f32_e32 v73, v73, v41
	v_mul_f32_e32 v78, v66, v18
	v_mul_f32_e32 v86, v58, v18
	v_mul_f32_e32 v79, v67, v19
	v_mul_f32_e32 v87, v59, v19
	v_mul_f32_e32 v80, v68, v20
	v_mul_f32_e32 v88, v60, v20
	v_mul_f32_e32 v81, v69, v21
	v_mul_f32_e32 v89, v61, v21
	v_mul_f32_e32 v82, v70, v22
	v_mul_f32_e32 v90, v62, v22
	v_mul_f32_e32 v83, v71, v23
	v_mul_f32_e32 v91, v63, v23
	v_mul_f32_e32 v84, v72, v24
	v_mul_f32_e32 v92, v64, v24
	v_mul_f32_e32 v85, v73, v25
	v_mul_f32_e32 v93, v65, v25
	v_fma_f32 v78, v58, v10, -v78
	v_fmac_f32_e32 v86, v66, v10
	v_fma_f32 v79, v59, v11, -v79
	v_fmac_f32_e32 v87, v67, v11
	v_fma_f32 v80, v60, v12, -v80
	v_fmac_f32_e32 v88, v68, v12
	v_fma_f32 v81, v61, v13, -v81
	v_fmac_f32_e32 v89, v69, v13
	v_fma_f32 v82, v62, v14, -v82
	v_fmac_f32_e32 v90, v70, v14
	v_fma_f32 v83, v63, v15, -v83
	v_fmac_f32_e32 v91, v71, v15
	v_fma_f32 v84, v64, v16, -v84
	v_fmac_f32_e32 v92, v72, v16
	v_fma_f32 v85, v65, v17, -v85
	v_fmac_f32_e32 v93, v73, v17
	v_cvt_pk_bf16_f32 v50, v78, v79
	v_cvt_pk_bf16_f32 v54, v86, v87
	v_cvt_pk_bf16_f32 v51, v80, v81
	v_cvt_pk_bf16_f32 v55, v88, v89
	v_cvt_pk_bf16_f32 v52, v82, v83
	v_cvt_pk_bf16_f32 v56, v90, v91
	v_cvt_pk_bf16_f32 v53, v84, v85
	v_cvt_pk_bf16_f32 v57, v92, v93
	global_load_dwordx4 v[2:5], v46, s[10:11]
	global_load_dwordx4 v[6:9], v46, s[10:11] offset:64
	global_load_dwordx4 v[10:13], v47, s[6:7]
	global_load_dwordx4 v[14:17], v47, s[6:7] offset:16
	global_load_dwordx4 v[18:21], v47, s[16:17]
	global_load_dwordx4 v[22:25], v47, s[16:17] offset:16
	v_add_u32_e32 v46, 0x3c000, v46
	v_add_u32_e32 v47, 0x800, v47
	s_nop 1
	s_waitcnt lgkmcnt(13)
; #define LAS __attribute__((address_space(3)))
; #define MFMA16(a, b, c) __builtin_amdgcn_mfma_f32_16x16x32_bf16((a), (b), (c), 0, 0, 0)
; __device__ __forceinline__ void p2_block(LAS unsigned char* lds, const bf16_t* __restrict__ PROJ, bf16_t* __restrict__ ATT, bf16_t* __restrict__ SGU, const float* __restrict__ qn, const float* __restrict__ kn, ...
;     ...
;         for (int t = 0; t < 10; ++t) { const bf16x8 k0 = *(const LAS bf16x8*)(kbase + t * 16 * KS_STRIDE), k1 = *(const LAS bf16x8*)(kbase + t * 16 * KS_STRIDE + 64);
;             f32x4 z = (f32x4){0.f, 0.f, 0.f, 0.f}; z = MFMA16(k0, qf0, z); sc_[t] = MFMA16(k1, qf1, z); }
;         float mx = -1e30f;
; #pragma unroll
;         for (int t = 0; t < 10; ++t)
; #pragma unroll
;             for (int e = 0; e < 4; ++e) { const int kx = 16 * (t0 + t) + 4 * fq + e, d = kx - irow; const bool ok = (d >= 1) && (d <= 128) && (n > 0 || kx >= 128);
;                 const float v = ok ? sc_[t][e] : -1e30f; sc_[t][e] = v; mx = fmaxf(mx, v); }
;         mx = fmaxf(mx, __shfl_xor(mx, 16)); mx = fmaxf(mx, __shfl_xor(mx, 32)); mx = fmaxf(mx, sink);
;         float sum = 0.f;
; #pragma unroll
;         for (int t = 0; t < 10; ++t)
; #pragma unroll
;             for (int e = 0; e < 4; ++e) { const float p = __builtin_amdgcn_exp2f((sc_[t][e] - mx) * LOG2E); sc_[t][e] = p; sum += p; }
	v_mfma_f32_16x16x32_bf16 v[58:61], v[98:101], v[50:53], 0
	s_waitcnt lgkmcnt(12)
	v_mfma_f32_16x16x32_bf16 v[58:61], v[102:105], v[54:57], v[58:61]
	ds_read_b128 v[154:157], v45 offset:16128
	ds_read_b128 v[158:161], v45 offset:16192
	s_waitcnt lgkmcnt(13)
	v_mfma_f32_16x16x32_bf16 v[62:65], v[106:109], v[50:53], 0
	s_waitcnt lgkmcnt(12)
	v_mfma_f32_16x16x32_bf16 v[62:65], v[110:113], v[54:57], v[62:65]
	ds_read_b128 v[162:165], v45 offset:18432
	ds_read_b128 v[182:185], v45 offset:18496
	s_waitcnt lgkmcnt(13)
	v_mfma_f32_16x16x32_bf16 v[66:69], v[114:117], v[50:53], 0
	s_waitcnt lgkmcnt(12)
	v_mfma_f32_16x16x32_bf16 v[66:69], v[118:121], v[54:57], v[66:69]
	s_waitcnt lgkmcnt(11)
	v_mfma_f32_16x16x32_bf16 v[70:73], v[122:125], v[50:53], 0
	s_waitcnt lgkmcnt(10)
	v_mfma_f32_16x16x32_bf16 v[70:73], v[126:129], v[54:57], v[70:73]
	s_waitcnt lgkmcnt(9)
	v_mfma_f32_16x16x32_bf16 v[74:77], v[130:133], v[50:53], 0
	s_waitcnt lgkmcnt(8)
	v_mfma_f32_16x16x32_bf16 v[74:77], v[134:137], v[54:57], v[74:77]
	s_waitcnt lgkmcnt(7)
	v_mfma_f32_16x16x32_bf16 v[78:81], v[138:141], v[50:53], 0
	s_waitcnt lgkmcnt(6)
	v_mfma_f32_16x16x32_bf16 v[78:81], v[142:145], v[54:57], v[78:81]
	s_waitcnt lgkmcnt(5)
	v_mfma_f32_16x16x32_bf16 v[82:85], v[146:149], v[50:53], 0
	s_waitcnt lgkmcnt(4)
	v_mfma_f32_16x16x32_bf16 v[82:85], v[150:153], v[54:57], v[82:85]
	s_waitcnt lgkmcnt(3)
	v_mfma_f32_16x16x32_bf16 v[86:89], v[154:157], v[50:53], 0
	s_waitcnt lgkmcnt(2)
	v_mfma_f32_16x16x32_bf16 v[86:89], v[158:161], v[54:57], v[86:89]
	s_waitcnt lgkmcnt(1)
	v_mfma_f32_16x16x32_bf16 v[90:93], v[162:165], v[50:53], 0
	s_waitcnt lgkmcnt(0)
	v_mfma_f32_16x16x32_bf16 v[90:93], v[182:185], v[54:57], v[90:93]
	ds_read2_b64 v[98:101], v194 offset0:0 offset1:4
	ds_read2_b64 v[102:105], v195 offset0:0 offset1:4
	ds_read2_b64 v[106:109], v196 offset0:0 offset1:4
	ds_read2_b64 v[110:113], v197 offset0:0 offset1:4
	ds_read2_b64 v[114:117], v194 offset0:8 offset1:12
	ds_read2_b64 v[118:121], v195 offset0:8 offset1:12
	ds_read2_b64 v[122:125], v196 offset0:8 offset1:12
	ds_read2_b64 v[126:129], v197 offset0:8 offset1:12
	ds_read2_b64 v[130:133], v194 offset0:16 offset1:20
	ds_read2_b64 v[134:137], v195 offset0:16 offset1:20
	ds_read2_b64 v[138:141], v196 offset0:16 offset1:20
	ds_read2_b64 v[142:145], v197 offset0:16 offset1:20
	ds_read2_b64 v[146:149], v194 offset0:24 offset1:28
	ds_read2_b64 v[150:153], v195 offset0:24 offset1:28
	ds_read2_b64 v[154:157], v196 offset0:24 offset1:28
	s_nop 4
	v_cndmask_b32_e64 v58, v49, v58, s[48:49]
	v_cndmask_b32_e64 v59, v49, v59, s[50:51]
	v_cndmask_b32_e64 v60, v49, v60, s[52:53]
	v_cndmask_b32_e64 v61, v49, v61, s[26:27]
	v_cndmask_b32_e64 v62, v49, v62, s[28:29]
	v_cndmask_b32_e64 v63, v49, v63, s[28:29]
	v_cndmask_b32_e64 v64, v49, v64, s[28:29]
	v_cndmask_b32_e64 v65, v49, v65, s[28:29]
	v_cndmask_b32_e64 v66, v49, v66, s[28:29]
	v_cndmask_b32_e64 v67, v49, v67, s[28:29]
	v_cndmask_b32_e64 v68, v49, v68, s[28:29]
	v_cndmask_b32_e64 v69, v49, v69, s[28:29]
	v_cndmask_b32_e64 v70, v49, v70, s[28:29]
	v_cndmask_b32_e64 v71, v49, v71, s[28:29]
	v_cndmask_b32_e64 v72, v49, v72, s[28:29]
	v_cndmask_b32_e64 v73, v49, v73, s[28:29]
	v_cndmask_b32_e64 v74, v49, v74, s[28:29]
	v_cndmask_b32_e64 v75, v49, v75, s[28:29]
	v_cndmask_b32_e64 v76, v49, v76, s[28:29]
	v_cndmask_b32_e64 v77, v49, v77, s[28:29]
	v_cndmask_b32_e64 v78, v49, v78, s[28:29]
	v_cndmask_b32_e64 v79, v49, v79, s[28:29]
	v_cndmask_b32_e64 v80, v49, v80, s[28:29]
	v_cndmask_b32_e64 v81, v49, v81, s[28:29]
	v_cndmask_b32_e64 v82, v49, v82, s[28:29]
	v_cndmask_b32_e64 v83, v49, v83, s[28:29]
	v_cndmask_b32_e64 v84, v49, v84, s[28:29]
	v_cndmask_b32_e64 v85, v49, v85, s[28:29]
	v_cndmask_b32_e64 v86, v49, v86, s[28:29]
	v_cndmask_b32_e64 v87, v49, v87, s[28:29]
	v_cndmask_b32_e64 v88, v49, v88, s[28:29]
	v_cndmask_b32_e64 v89, v49, v89, s[28:29]
	v_cndmask_b32_e64 v90, v90, v49, s[40:41]
	v_cndmask_b32_e64 v91, v91, v49, s[42:43]
	v_cndmask_b32_e64 v92, v92, v49, s[44:45]
	v_cndmask_b32_e64 v93, v93, v49, s[46:47]
	v_max_f32_e32 v167, v58, v59
	v_max_f32_e32 v94, v60, v61
	v_max3_f32 v167, v167, v62, v63
	v_max3_f32 v94, v94, v64, v65
	v_max3_f32 v167, v167, v66, v67
	v_max3_f32 v94, v94, v68, v69
	v_max3_f32 v167, v167, v70, v71
	v_max3_f32 v94, v94, v72, v73
	v_max3_f32 v167, v167, v74, v75
	v_max3_f32 v94, v94, v76, v77
	v_max3_f32 v167, v167, v78, v79
	v_max3_f32 v94, v94, v80, v81
	v_max3_f32 v167, v167, v82, v83
	v_max3_f32 v94, v94, v84, v85
	v_max3_f32 v167, v167, v86, v87
	v_max3_f32 v94, v94, v88, v89
	v_max3_f32 v167, v167, v90, v91
	v_max3_f32 v94, v94, v92, v93
	v_max_f32_e32 v167, v167, v94
	v_mov_b32_e32 v166, v167
	s_nop 1
	v_permlane16_swap_b32_e32 v167, v166
	v_max_f32_e32 v167, v167, v166
	v_mov_b32_e32 v166, v167
	s_nop 1
	v_permlane32_swap_b32_e32 v167, v166
	v_max_f32_e32 v167, v167, v166
	v_max_f32_e32 v167, v167, v42
	v_mul_f32_e32 v94, 0xbfb8aa3b, v167
	v_fmamk_f32 v58, v58, 0x3fb8aa3b, v94
	v_fmamk_f32 v59, v59, 0x3fb8aa3b, v94
	v_fmamk_f32 v60, v60, 0x3fb8aa3b, v94
	v_fmamk_f32 v61, v61, 0x3fb8aa3b, v94
	v_fmamk_f32 v62, v62, 0x3fb8aa3b, v94
	v_fmamk_f32 v63, v63, 0x3fb8aa3b, v94
	v_fmamk_f32 v64, v64, 0x3fb8aa3b, v94
	v_fmamk_f32 v65, v65, 0x3fb8aa3b, v94
	v_fmamk_f32 v66, v66, 0x3fb8aa3b, v94
	v_fmamk_f32 v67, v67, 0x3fb8aa3b, v94
	v_fmamk_f32 v68, v68, 0x3fb8aa3b, v94
	v_fmamk_f32 v69, v69, 0x3fb8aa3b, v94
	v_fmamk_f32 v70, v70, 0x3fb8aa3b, v94
	v_fmamk_f32 v71, v71, 0x3fb8aa3b, v94
	v_fmamk_f32 v72, v72, 0x3fb8aa3b, v94
	v_fmamk_f32 v73, v73, 0x3fb8aa3b, v94
	v_fmamk_f32 v74, v74, 0x3fb8aa3b, v94
	v_fmamk_f32 v75, v75, 0x3fb8aa3b, v94
	v_fmamk_f32 v76, v76, 0x3fb8aa3b, v94
; __device__ __forceinline__ unsigned cvt_pk_bf16(float lo, float hi) { unsigned r; asm volatile("v_cvt_pk_bf16_f32 %0, %1, %2" : "=v"(r) : "v"(lo), "v"(hi)); return r; }
; #define LAS __attribute__((address_space(3)))
; #define MFMA16(a, b, c) __builtin_amdgcn_mfma_f32_16x16x32_bf16((a), (b), (c), 0, 0, 0)
; __device__ __forceinline__ void p2_block(LAS unsigned char* lds, const bf16_t* __restrict__ PROJ, bf16_t* __restrict__ ATT, bf16_t* __restrict__ SGU, const float* __restrict__ qn, const float* __restrict__ kn, ...
;     ...
;             for (int e = 0; e < 4; ++e) { const float p = __builtin_amdgcn_exp2f((sc_[t][e] - mx) * LOG2E); sc_[t][e] = p; sum += p; }
;         sum += __shfl_xor(sum, 16); sum += __shfl_xor(sum, 32);
;         const float inv = 1.0f / (sum + __builtin_amdgcn_exp2f((sink - mx) * LOG2E));
;         f32x4 o[4];
; #pragma unroll
;         for (int dt = 0; dt < 4; ++dt) o[dt] = (f32x4){0.f, 0.f, 0.f, 0.f};
; #pragma unroll
;         for (int j = 0; j < 5; ++j) {
;             u32x4 pw; pw.x = cvt_pk_bf16(sc_[2 * j][0], sc_[2 * j][1]); pw.y = cvt_pk_bf16(sc_[2 * j][2], sc_[2 * j][3]); pw.z = cvt_pk_bf16(sc_[2 * j + 1][0], sc_[2 * j + 1][1]); pw.w = cvt_pk_bf16(sc_[2 * j + 1][2], sc_[2 * j + 1][3]);
;             const bf16x8 pf = __builtin_bit_cast(bf16x8, pw);
; #pragma unroll
;             for (int dt = 0; dt < 4; ++dt) { const LAS unsigned char* vb = VT + (16 * dt + fr) * VT_STRIDE + (16 * (t0 + 2 * j) + 4 * fq) * 2;
;                 const u32x2 va = *(const LAS u32x2*)vb, vc = *(const LAS u32x2*)(vb + 32); u32x4 vw; vw.x = va.x; vw.y = va.y; vw.z = vc.x; vw.w = vc.y;
;                 o[dt] = MFMA16(__builtin_bit_cast(bf16x8, vw), pf, o[dt]); }
	v_fmamk_f32 v77, v77, 0x3fb8aa3b, v94
	v_fmamk_f32 v78, v78, 0x3fb8aa3b, v94
	v_fmamk_f32 v79, v79, 0x3fb8aa3b, v94
	v_fmamk_f32 v80, v80, 0x3fb8aa3b, v94
	v_fmamk_f32 v81, v81, 0x3fb8aa3b, v94
	v_fmamk_f32 v82, v82, 0x3fb8aa3b, v94
	v_fmamk_f32 v83, v83, 0x3fb8aa3b, v94
	v_fmamk_f32 v84, v84, 0x3fb8aa3b, v94
	v_fmamk_f32 v85, v85, 0x3fb8aa3b, v94
	v_fmamk_f32 v86, v86, 0x3fb8aa3b, v94
	v_fmamk_f32 v87, v87, 0x3fb8aa3b, v94
	v_fmamk_f32 v88, v88, 0x3fb8aa3b, v94
	v_fmamk_f32 v89, v89, 0x3fb8aa3b, v94
	v_fmamk_f32 v90, v90, 0x3fb8aa3b, v94
	v_fmamk_f32 v91, v91, 0x3fb8aa3b, v94
	v_fmamk_f32 v92, v92, 0x3fb8aa3b, v94
	v_fmamk_f32 v93, v93, 0x3fb8aa3b, v94
	v_exp_f32_e32 v58, v58
	v_exp_f32_e32 v59, v59
	v_exp_f32_e32 v60, v60
	v_exp_f32_e32 v61, v61
	v_exp_f32_e32 v62, v62
	v_exp_f32_e32 v63, v63
	v_exp_f32_e32 v64, v64
	v_exp_f32_e32 v65, v65
	v_exp_f32_e32 v66, v66
	v_exp_f32_e32 v67, v67
	v_exp_f32_e32 v68, v68
	v_exp_f32_e32 v69, v69
	v_exp_f32_e32 v70, v70
	v_exp_f32_e32 v71, v71
	v_exp_f32_e32 v72, v72
	v_exp_f32_e32 v73, v73
	v_exp_f32_e32 v74, v74
	v_exp_f32_e32 v75, v75
	v_exp_f32_e32 v76, v76
	v_exp_f32_e32 v77, v77
	v_exp_f32_e32 v78, v78
	v_exp_f32_e32 v79, v79
	v_exp_f32_e32 v80, v80
	v_exp_f32_e32 v81, v81
	v_exp_f32_e32 v82, v82
	v_exp_f32_e32 v83, v83
	v_exp_f32_e32 v84, v84
	v_exp_f32_e32 v85, v85
	v_exp_f32_e32 v86, v86
	v_exp_f32_e32 v87, v87
	v_exp_f32_e32 v88, v88
	v_exp_f32_e32 v89, v89
	v_exp_f32_e32 v90, v90
	v_exp_f32_e32 v91, v91
	v_exp_f32_e32 v92, v92
	v_exp_f32_e32 v93, v93
	v_fmamk_f32 v95, v42, 0x3fb8aa3b, v94
	v_exp_f32_e32 v95, v95
	v_add_f32_e32 v167, v58, v59
	v_add_f32_e32 v94, v60, v61
	v_add_f32_e32 v167, v167, v62
	v_add_f32_e32 v94, v94, v63
	v_add_f32_e32 v167, v167, v64
	v_add_f32_e32 v94, v94, v65
	v_add_f32_e32 v167, v167, v66
	v_add_f32_e32 v94, v94, v67
	v_add_f32_e32 v167, v167, v68
	v_add_f32_e32 v94, v94, v69
	v_add_f32_e32 v167, v167, v70
	v_add_f32_e32 v94, v94, v71
	v_add_f32_e32 v167, v167, v72
	v_add_f32_e32 v94, v94, v73
	v_add_f32_e32 v167, v167, v74
	v_add_f32_e32 v94, v94, v75
	v_add_f32_e32 v167, v167, v76
	v_add_f32_e32 v94, v94, v77
	v_add_f32_e32 v167, v167, v78
	v_add_f32_e32 v94, v94, v79
	v_add_f32_e32 v167, v167, v80
	v_add_f32_e32 v94, v94, v81
	v_add_f32_e32 v167, v167, v82
	v_add_f32_e32 v94, v94, v83
	v_add_f32_e32 v167, v167, v84
	v_add_f32_e32 v94, v94, v85
	v_add_f32_e32 v167, v167, v86
	v_add_f32_e32 v94, v94, v87
	v_add_f32_e32 v167, v167, v88
	v_add_f32_e32 v94, v94, v89
	v_add_f32_e32 v167, v167, v90
	v_add_f32_e32 v94, v94, v91
	v_add_f32_e32 v167, v167, v92
	v_add_f32_e32 v94, v94, v93
	v_add_f32_e32 v167, v167, v94
	v_mov_b32_e32 v166, v167
	s_nop 1
	v_permlane16_swap_b32_e32 v167, v166
	v_add_f32_e32 v167, v167, v166
	v_mov_b32_e32 v166, v167
	s_nop 1
	v_permlane32_swap_b32_e32 v167, v166
	v_add_f32_e32 v167, v167, v166
	v_add_f32_e32 v167, v167, v95
	v_rcp_f32_e32 v167, v167
	v_mov_b32_e32 v94, 0
	v_mov_b32_e32 v95, 0
	v_mov_b32_e32 v96, 0
	v_mov_b32_e32 v97, 0
	v_cvt_pk_bf16_f32 v58, v58, v59
	v_cvt_pk_bf16_f32 v59, v60, v61
	v_cvt_pk_bf16_f32 v60, v62, v63
	v_cvt_pk_bf16_f32 v61, v64, v65
	v_cvt_pk_bf16_f32 v66, v66, v67
	v_cvt_pk_bf16_f32 v67, v68, v69
	v_cvt_pk_bf16_f32 v68, v70, v71
	v_cvt_pk_bf16_f32 v69, v72, v73
	v_cvt_pk_bf16_f32 v74, v74, v75
	v_cvt_pk_bf16_f32 v75, v76, v77
	v_cvt_pk_bf16_f32 v76, v78, v79
	v_cvt_pk_bf16_f32 v77, v80, v81
	v_cvt_pk_bf16_f32 v82, v82, v83
	v_cvt_pk_bf16_f32 v83, v84, v85
	v_cvt_pk_bf16_f32 v84, v86, v87
	v_cvt_pk_bf16_f32 v85, v88, v89
	v_cvt_pk_bf16_f32 v90, v90, v91
	v_cvt_pk_bf16_f32 v91, v92, v93
	v_cvt_pk_bf16_f32 v92, v94, v95
	v_cvt_pk_bf16_f32 v93, v96, v97
	s_nop 1
	s_waitcnt lgkmcnt(14)
	v_mfma_f32_16x16x32_bf16 v[62:65], v[98:101], v[58:61], 0
	ds_read2_b64 v[158:161], v197 offset0:24 offset1:28
	s_waitcnt lgkmcnt(14)
	v_mfma_f32_16x16x32_bf16 v[70:73], v[102:105], v[58:61], 0
	ds_read2_b64 v[162:165], v194 offset0:32 offset1:36
	s_waitcnt lgkmcnt(14)
	v_mfma_f32_16x16x32_bf16 v[78:81], v[106:109], v[58:61], 0
	ds_read2_b64 v[182:185], v195 offset0:32 offset1:36
	s_waitcnt lgkmcnt(14)
	v_mfma_f32_16x16x32_bf16 v[86:89], v[110:113], v[58:61], 0
	ds_read2_b64 v[186:189], v196 offset0:32 offset1:36
	s_waitcnt lgkmcnt(14)
	v_mfma_f32_16x16x32_bf16 v[62:65], v[114:117], v[66:69], v[62:65]
	ds_read2_b64 v[190:193], v197 offset0:32 offset1:36
	s_waitcnt lgkmcnt(14)
	v_mfma_f32_16x16x32_bf16 v[70:73], v[118:121], v[66:69], v[70:73]
	s_waitcnt lgkmcnt(13)
	v_mfma_f32_16x16x32_bf16 v[78:81], v[122:125], v[66:69], v[78:81]
	s_waitcnt lgkmcnt(12)
	v_mfma_f32_16x16x32_bf16 v[86:89], v[126:129], v[66:69], v[86:89]
	s_waitcnt lgkmcnt(11)
	v_mfma_f32_16x16x32_bf16 v[62:65], v[130:133], v[74:77], v[62:65]
	s_waitcnt lgkmcnt(10)
	v_mfma_f32_16x16x32_bf16 v[70:73], v[134:137], v[74:77], v[70:73]
	s_waitcnt lgkmcnt(9)
	v_mfma_f32_16x16x32_bf16 v[78:81], v[138:141], v[74:77], v[78:81]
	s_waitcnt lgkmcnt(8)
	v_mfma_f32_16x16x32_bf16 v[86:89], v[142:145], v[74:77], v[86:89]
	s_waitcnt lgkmcnt(7)
	v_mfma_f32_16x16x32_bf16 v[62:65], v[146:149], v[82:85], v[62:65]
	s_waitcnt lgkmcnt(6)
	v_mfma_f32_16x16x32_bf16 v[70:73], v[150:153], v[82:85], v[70:73]
	s_waitcnt lgkmcnt(5)
	v_mfma_f32_16x16x32_bf16 v[78:81], v[154:157], v[82:85], v[78:81]
	s_waitcnt lgkmcnt(4)
	v_mfma_f32_16x16x32_bf16 v[86:89], v[158:161], v[82:85], v[86:89]
	s_waitcnt lgkmcnt(3)
	v_mfma_f32_16x16x32_bf16 v[62:65], v[162:165], v[90:93], v[62:65]
	s_waitcnt lgkmcnt(2)
	v_mfma_f32_16x16x32_bf16 v[70:73], v[182:185], v[90:93], v[70:73]
	s_waitcnt lgkmcnt(1)
	v_mfma_f32_16x16x32_bf16 v[78:81], v[186:189], v[90:93], v[78:81]
	s_waitcnt lgkmcnt(0)
; __device__ __forceinline__ unsigned cvt_pk_bf16(float lo, float hi) { unsigned r; asm volatile("v_cvt_pk_bf16_f32 %0, %1, %2" : "=v"(r) : "v"(lo), "v"(hi)); return r; }
; #define MFMA16(a, b, c) __builtin_amdgcn_mfma_f32_16x16x32_bf16((a), (b), (c), 0, 0, 0)
; __device__ __forceinline__ void unpack8(const u32x4 w, float* f) { f[0] = bf_lo(w.x); f[1] = bf_hi(w.x); f[2] = bf_lo(w.y); f[3] = bf_hi(w.y); f[4] = bf_lo(w.z); f[5] = bf_hi(w.z); f[6] = bf_lo(w.w); f[7] = bf_hi(w.w); }
; __device__ __forceinline__ void p2_block(LAS unsigned char* lds, const bf16_t* __restrict__ PROJ, bf16_t* __restrict__ ATT, bf16_t* __restrict__ SGU, const float* __restrict__ qn, const float* __restrict__ kn, ...
;     ...
;         const int i0 = rbase + 16 * c, irow = i0 + fr, pos = n * 128 + irow; const size_t grow = (size_t)b * pg8::SEQ + pos;
;         bf16x8 qf0, qf1;
;         {
;             float x1[8], x2[8]; unpack8(qa[c], x1); unpack8(qb[c], x2);
;             float ss = 0.f;
; #pragma unroll
;             for (int j = 0; j < 8; ++j) ss += x1[j] * x1[j] + x2[j] * x2[j];
;             ss += __shfl_xor(ss, 16); ss += __shfl_xor(ss, 32);
;             const float rinv = rsqrtf(ss * (1.0f / 64.0f) + pg8::EPS) * 0.125f;
;             const float* cp = COS + pos * 32 + 8 * fq; const float* sp = SIN + pos * 32 + 8 * fq;
;             float o1[8], o2[8];
; #pragma unroll
;             for (int j = 0; j < 8; ++j) { const float a1 = x1[j] * rinv * qn[8 * fq + j], a2 = x2[j] * rinv * qn[32 + 8 * fq + j], cc = cp[j], sn = sp[j]; o1[j] = a1 * cc - a2 * sn; o2[j] = a2 * cc + a1 * sn; }
;             u32x4 w0, w1;
;             w0.x = cvt_pk_bf16(o1[0], o1[1]); w0.y = cvt_pk_bf16(o1[2], o1[3]); w0.z = cvt_pk_bf16(o1[4], o1[5]); w0.w = cvt_pk_bf16(o1[6], o1[7]);
;             w1.x = cvt_pk_bf16(o2[0], o2[1]); w1.y = cvt_pk_bf16(o2[2], o2[3]); w1.z = cvt_pk_bf16(o2[4], o2[5]); w1.w = cvt_pk_bf16(o2[6], o2[7]);
;             qf0 = __builtin_bit_cast(bf16x8, w0); qf1 = __builtin_bit_cast(bf16x8, w1);
;     ...
;                 o[dt] = MFMA16(__builtin_bit_cast(bf16x8, vw), pf, o[dt]); }
;         }
;         bf16_t* op = ATT + grow * 1024 + hq * 64 + 4 * fq;
; #pragma unroll
;         for (int dt = 0; dt < 4; ++dt) { u32x2 ow; ow.x = cvt_pk_bf16(o[dt][0] * inv, o[dt][1] * inv); ow.y = cvt_pk_bf16(o[dt][2] * inv, o[dt][3] * inv); *(u32x2*)(op + 16 * dt) = ow; }
	v_mfma_f32_16x16x32_bf16 v[86:89], v[190:193], v[90:93], v[86:89]
	ds_read_b128 v[98:101], v45 offset:2304
	ds_read_b128 v[102:105], v45 offset:2368
	ds_read_b128 v[106:109], v45 offset:4608
	ds_read_b128 v[110:113], v45 offset:4672
	ds_read_b128 v[114:117], v45 offset:6912
	ds_read_b128 v[118:121], v45 offset:6976
	ds_read_b128 v[122:125], v45 offset:9216
	ds_read_b128 v[126:129], v45 offset:9280
	ds_read_b128 v[130:133], v45 offset:11520
	ds_read_b128 v[134:137], v45 offset:11584
	ds_read_b128 v[138:141], v45 offset:13824
	ds_read_b128 v[142:145], v45 offset:13888
	ds_read_b128 v[146:149], v45 offset:16128
	ds_read_b128 v[150:153], v45 offset:16192
	s_nop 7
	v_mul_f32_e32 v62, v62, v167
	v_mul_f32_e32 v63, v63, v167
	v_mul_f32_e32 v64, v64, v167
	v_mul_f32_e32 v65, v65, v167
	v_mul_f32_e32 v70, v70, v167
	v_mul_f32_e32 v71, v71, v167
	v_mul_f32_e32 v72, v72, v167
	v_mul_f32_e32 v73, v73, v167
	v_mul_f32_e32 v78, v78, v167
	v_mul_f32_e32 v79, v79, v167
	v_mul_f32_e32 v80, v80, v167
	v_mul_f32_e32 v81, v81, v167
	v_mul_f32_e32 v86, v86, v167
	v_mul_f32_e32 v87, v87, v167
	v_mul_f32_e32 v88, v88, v167
	v_mul_f32_e32 v89, v89, v167
	v_cvt_pk_bf16_f32 v62, v62, v63
	v_cvt_pk_bf16_f32 v63, v64, v65
	global_store_dwordx2 v48, v[62:63], s[24:25] offset:0
	v_cvt_pk_bf16_f32 v70, v70, v71
	v_cvt_pk_bf16_f32 v71, v72, v73
	global_store_dwordx2 v48, v[70:71], s[24:25] offset:32
	v_cvt_pk_bf16_f32 v78, v78, v79
	v_cvt_pk_bf16_f32 v79, v80, v81
	global_store_dwordx2 v48, v[78:79], s[24:25] offset:64
	v_cvt_pk_bf16_f32 v86, v86, v87
	v_cvt_pk_bf16_f32 v87, v88, v89
	global_store_dwordx2 v48, v[86:87], s[24:25] offset:96
	v_add_u32_e32 v48, 0x8000, v48
	s_waitcnt vmcnt(10)
	v_lshlrev_b32_e32 v58, 16, v218
	v_and_b32_e32 v59, 0xffff0000, v218
	v_lshlrev_b32_e32 v66, 16, v222
	v_and_b32_e32 v67, 0xffff0000, v222
	v_lshlrev_b32_e32 v60, 16, v219
	v_and_b32_e32 v61, 0xffff0000, v219
	v_lshlrev_b32_e32 v68, 16, v223
	v_and_b32_e32 v69, 0xffff0000, v223
	v_lshlrev_b32_e32 v62, 16, v220
	v_and_b32_e32 v63, 0xffff0000, v220
	v_lshlrev_b32_e32 v70, 16, v224
	v_and_b32_e32 v71, 0xffff0000, v224
	v_lshlrev_b32_e32 v64, 16, v221
	v_and_b32_e32 v65, 0xffff0000, v221
	v_lshlrev_b32_e32 v72, 16, v225
	v_and_b32_e32 v73, 0xffff0000, v225
	v_mul_f32_e32 v74, v58, v58
	v_mul_f32_e32 v75, v59, v59
	v_fmac_f32_e32 v74, v60, v60
	v_fmac_f32_e32 v75, v61, v61
	v_fmac_f32_e32 v74, v62, v62
	v_fmac_f32_e32 v75, v63, v63
	v_fmac_f32_e32 v74, v64, v64
	v_fmac_f32_e32 v75, v65, v65
	v_fmac_f32_e32 v74, v66, v66
	v_fmac_f32_e32 v75, v67, v67
	v_fmac_f32_e32 v74, v68, v68
	v_fmac_f32_e32 v75, v69, v69
	v_fmac_f32_e32 v74, v70, v70
	v_fmac_f32_e32 v75, v71, v71
	v_fmac_f32_e32 v74, v72, v72
	v_fmac_f32_e32 v75, v73, v73
	v_add_f32_e32 v74, v74, v75
	v_mov_b32_e32 v166, v74
	s_nop 1
	v_permlane16_swap_b32_e32 v74, v166
	v_add_f32_e32 v74, v74, v166
	v_mov_b32_e32 v166, v74
	s_nop 1
	v_permlane32_swap_b32_e32 v74, v166
	v_add_f32_e32 v74, v74, v166
	v_fmamk_f32 v74, v74, 0x3c800000, v209
	v_rsq_f32_e32 v76, v74
	s_nop 0
	v_mul_f32_e32 v76, 0x3e000000, v76
	v_mul_f32_e32 v58, v58, v76
	v_mul_f32_e32 v66, v66, v76
	v_mul_f32_e32 v59, v59, v76
	v_mul_f32_e32 v67, v67, v76
	v_mul_f32_e32 v60, v60, v76
	v_mul_f32_e32 v68, v68, v76
	v_mul_f32_e32 v61, v61, v76
	v_mul_f32_e32 v69, v69, v76
	v_mul_f32_e32 v62, v62, v76
	v_mul_f32_e32 v70, v70, v76
	v_mul_f32_e32 v63, v63, v76
	v_mul_f32_e32 v71, v71, v76
	v_mul_f32_e32 v64, v64, v76
	v_mul_f32_e32 v72, v72, v76
	v_mul_f32_e32 v65, v65, v76
	v_mul_f32_e32 v73, v73, v76
	v_mul_f32_e32 v58, v58, v26
	v_mul_f32_e32 v66, v66, v34
	v_mul_f32_e32 v59, v59, v27
	v_mul_f32_e32 v67, v67, v35
	v_mul_f32_e32 v60, v60, v28
	v_mul_f32_e32 v68, v68, v36
	v_mul_f32_e32 v61, v61, v29
	v_mul_f32_e32 v69, v69, v37
	v_mul_f32_e32 v62, v62, v30
	v_mul_f32_e32 v70, v70, v38
	v_mul_f32_e32 v63, v63, v31
	v_mul_f32_e32 v71, v71, v39
	v_mul_f32_e32 v64, v64, v32
	v_mul_f32_e32 v72, v72, v40
	v_mul_f32_e32 v65, v65, v33
	v_mul_f32_e32 v73, v73, v41
	v_mul_f32_e32 v78, v66, v234
	v_mul_f32_e32 v86, v58, v234
	v_mul_f32_e32 v79, v67, v235
	v_mul_f32_e32 v87, v59, v235
	v_mul_f32_e32 v80, v68, v236
	v_mul_f32_e32 v88, v60, v236
	v_mul_f32_e32 v81, v69, v237
	v_mul_f32_e32 v89, v61, v237
	v_mul_f32_e32 v82, v70, v238
	v_mul_f32_e32 v90, v62, v238
	v_mul_f32_e32 v83, v71, v239
	v_mul_f32_e32 v91, v63, v239
	v_mul_f32_e32 v84, v72, v240
	v_mul_f32_e32 v92, v64, v240
	v_mul_f32_e32 v85, v73, v241
	v_mul_f32_e32 v93, v65, v241
	v_fma_f32 v78, v58, v226, -v78
	v_fmac_f32_e32 v86, v66, v226
	v_fma_f32 v79, v59, v227, -v79
	v_fmac_f32_e32 v87, v67, v227
	v_fma_f32 v80, v60, v228, -v80
	v_fmac_f32_e32 v88, v68, v228
	v_fma_f32 v81, v61, v229, -v81
	v_fmac_f32_e32 v89, v69, v229
	v_fma_f32 v82, v62, v230, -v82
	v_fmac_f32_e32 v90, v70, v230
	v_fma_f32 v83, v63, v231, -v83
	v_fmac_f32_e32 v91, v71, v231
	v_fma_f32 v84, v64, v232, -v84
	v_fmac_f32_e32 v92, v72, v232
	v_fma_f32 v85, v65, v233, -v85
	v_fmac_f32_e32 v93, v73, v233
	v_cvt_pk_bf16_f32 v50, v78, v79
	v_cvt_pk_bf16_f32 v54, v86, v87
	v_cvt_pk_bf16_f32 v51, v80, v81
	v_cvt_pk_bf16_f32 v55, v88, v89
	v_cvt_pk_bf16_f32 v52, v82, v83
	v_cvt_pk_bf16_f32 v56, v90, v91
	v_cvt_pk_bf16_f32 v53, v84, v85
	v_cvt_pk_bf16_f32 v57, v92, v93
	global_load_dwordx4 v[218:221], v46, s[10:11]
	global_load_dwordx4 v[222:225], v46, s[10:11] offset:64
	global_load_dwordx4 v[226:229], v47, s[6:7]
	global_load_dwordx4 v[230:233], v47, s[6:7] offset:16
	global_load_dwordx4 v[234:237], v47, s[16:17]
	global_load_dwordx4 v[238:241], v47, s[16:17] offset:16
	v_add_u32_e32 v46, 0x3c000, v46
	v_add_u32_e32 v47, 0x800, v47
	s_nop 1
	s_waitcnt lgkmcnt(13)
; #define LAS __attribute__((address_space(3)))
; #define MFMA16(a, b, c) __builtin_amdgcn_mfma_f32_16x16x32_bf16((a), (b), (c), 0, 0, 0)
; __device__ __forceinline__ void p2_block(LAS unsigned char* lds, const bf16_t* __restrict__ PROJ, bf16_t* __restrict__ ATT, bf16_t* __restrict__ SGU, const float* __restrict__ qn, const float* __restrict__ kn, ...
;     ...
;         for (int t = 0; t < 10; ++t) { const bf16x8 k0 = *(const LAS bf16x8*)(kbase + t * 16 * KS_STRIDE), k1 = *(const LAS bf16x8*)(kbase + t * 16 * KS_STRIDE + 64);
;             f32x4 z = (f32x4){0.f, 0.f, 0.f, 0.f}; z = MFMA16(k0, qf0, z); sc_[t] = MFMA16(k1, qf1, z); }
;         float mx = -1e30f;
; #pragma unroll
;         for (int t = 0; t < 10; ++t)
; #pragma unroll
;             for (int e = 0; e < 4; ++e) { const int kx = 16 * (t0 + t) + 4 * fq + e, d = kx - irow; const bool ok = (d >= 1) && (d <= 128) && (n > 0 || kx >= 128);
;                 const float v = ok ? sc_[t][e] : -1e30f; sc_[t][e] = v; mx = fmaxf(mx, v); }
;         mx = fmaxf(mx, __shfl_xor(mx, 16)); mx = fmaxf(mx, __shfl_xor(mx, 32)); mx = fmaxf(mx, sink);
;         float sum = 0.f;
; #pragma unroll
;         for (int t = 0; t < 10; ++t)
; #pragma unroll
;             for (int e = 0; e < 4; ++e) { const float p = __builtin_amdgcn_exp2f((sc_[t][e] - mx) * LOG2E); sc_[t][e] = p; sum += p; }
	v_mfma_f32_16x16x32_bf16 v[58:61], v[98:101], v[50:53], 0
	s_waitcnt lgkmcnt(12)
	v_mfma_f32_16x16x32_bf16 v[58:61], v[102:105], v[54:57], v[58:61]
	ds_read_b128 v[154:157], v45 offset:18432
	ds_read_b128 v[158:161], v45 offset:18496
	s_waitcnt lgkmcnt(13)
	v_mfma_f32_16x16x32_bf16 v[62:65], v[106:109], v[50:53], 0
	s_waitcnt lgkmcnt(12)
	v_mfma_f32_16x16x32_bf16 v[62:65], v[110:113], v[54:57], v[62:65]
	ds_read_b128 v[162:165], v45 offset:20736
	ds_read_b128 v[182:185], v45 offset:20800
	s_waitcnt lgkmcnt(13)
	v_mfma_f32_16x16x32_bf16 v[66:69], v[114:117], v[50:53], 0
	s_waitcnt lgkmcnt(12)
	v_mfma_f32_16x16x32_bf16 v[66:69], v[118:121], v[54:57], v[66:69]
	s_waitcnt lgkmcnt(11)
	v_mfma_f32_16x16x32_bf16 v[70:73], v[122:125], v[50:53], 0
	s_waitcnt lgkmcnt(10)
	v_mfma_f32_16x16x32_bf16 v[70:73], v[126:129], v[54:57], v[70:73]
	s_waitcnt lgkmcnt(9)
	v_mfma_f32_16x16x32_bf16 v[74:77], v[130:133], v[50:53], 0
	s_waitcnt lgkmcnt(8)
	v_mfma_f32_16x16x32_bf16 v[74:77], v[134:137], v[54:57], v[74:77]
	s_waitcnt lgkmcnt(7)
	v_mfma_f32_16x16x32_bf16 v[78:81], v[138:141], v[50:53], 0
	s_waitcnt lgkmcnt(6)
	v_mfma_f32_16x16x32_bf16 v[78:81], v[142:145], v[54:57], v[78:81]
	s_waitcnt lgkmcnt(5)
	v_mfma_f32_16x16x32_bf16 v[82:85], v[146:149], v[50:53], 0
	s_waitcnt lgkmcnt(4)
	v_mfma_f32_16x16x32_bf16 v[82:85], v[150:153], v[54:57], v[82:85]
	s_waitcnt lgkmcnt(3)
	v_mfma_f32_16x16x32_bf16 v[86:89], v[154:157], v[50:53], 0
	s_waitcnt lgkmcnt(2)
	v_mfma_f32_16x16x32_bf16 v[86:89], v[158:161], v[54:57], v[86:89]
	s_waitcnt lgkmcnt(1)
	v_mfma_f32_16x16x32_bf16 v[90:93], v[162:165], v[50:53], 0
	s_waitcnt lgkmcnt(0)
	v_mfma_f32_16x16x32_bf16 v[90:93], v[182:185], v[54:57], v[90:93]
	ds_read2_b64 v[98:101], v194 offset0:4 offset1:8
	ds_read2_b64 v[102:105], v195 offset0:4 offset1:8
	ds_read2_b64 v[106:109], v196 offset0:4 offset1:8
	ds_read2_b64 v[110:113], v197 offset0:4 offset1:8
	ds_read2_b64 v[114:117], v194 offset0:12 offset1:16
	ds_read2_b64 v[118:121], v195 offset0:12 offset1:16
	ds_read2_b64 v[122:125], v196 offset0:12 offset1:16
	ds_read2_b64 v[126:129], v197 offset0:12 offset1:16
	ds_read2_b64 v[130:133], v194 offset0:20 offset1:24
	ds_read2_b64 v[134:137], v195 offset0:20 offset1:24
	ds_read2_b64 v[138:141], v196 offset0:20 offset1:24
	ds_read2_b64 v[142:145], v197 offset0:20 offset1:24
	ds_read2_b64 v[146:149], v194 offset0:28 offset1:32
	ds_read2_b64 v[150:153], v195 offset0:28 offset1:32
	ds_read2_b64 v[154:157], v196 offset0:28 offset1:32
	s_nop 4
	v_cndmask_b32_e64 v58, v49, v58, s[48:49]
	v_cndmask_b32_e64 v59, v49, v59, s[50:51]
	v_cndmask_b32_e64 v60, v49, v60, s[52:53]
	v_cndmask_b32_e64 v61, v49, v61, s[26:27]
	v_cndmask_b32_e64 v62, v49, v62, s[28:29]
	v_cndmask_b32_e64 v63, v49, v63, s[28:29]
	v_cndmask_b32_e64 v64, v49, v64, s[28:29]
	v_cndmask_b32_e64 v65, v49, v65, s[28:29]
	v_cndmask_b32_e64 v66, v49, v66, s[28:29]
	v_cndmask_b32_e64 v67, v49, v67, s[28:29]
	v_cndmask_b32_e64 v68, v49, v68, s[28:29]
	v_cndmask_b32_e64 v69, v49, v69, s[28:29]
	v_cndmask_b32_e64 v70, v49, v70, s[28:29]
	v_cndmask_b32_e64 v71, v49, v71, s[28:29]
	v_cndmask_b32_e64 v72, v49, v72, s[28:29]
	v_cndmask_b32_e64 v73, v49, v73, s[28:29]
	v_cndmask_b32_e64 v74, v49, v74, s[28:29]
	v_cndmask_b32_e64 v75, v49, v75, s[28:29]
	v_cndmask_b32_e64 v76, v49, v76, s[28:29]
	v_cndmask_b32_e64 v77, v49, v77, s[28:29]
	v_cndmask_b32_e64 v78, v49, v78, s[28:29]
	v_cndmask_b32_e64 v79, v49, v79, s[28:29]
	v_cndmask_b32_e64 v80, v49, v80, s[28:29]
	v_cndmask_b32_e64 v81, v49, v81, s[28:29]
	v_cndmask_b32_e64 v82, v49, v82, s[28:29]
	v_cndmask_b32_e64 v83, v49, v83, s[28:29]
	v_cndmask_b32_e64 v84, v49, v84, s[28:29]
	v_cndmask_b32_e64 v85, v49, v85, s[28:29]
	v_cndmask_b32_e64 v90, v90, v49, s[40:41]
	v_cndmask_b32_e64 v91, v91, v49, s[42:43]
	v_cndmask_b32_e64 v92, v92, v49, s[44:45]
	v_cndmask_b32_e64 v93, v93, v49, s[46:47]
	v_max_f32_e32 v167, v58, v59
	v_max_f32_e32 v94, v60, v61
	v_max3_f32 v167, v167, v62, v63
	v_max3_f32 v94, v94, v64, v65
	v_max3_f32 v167, v167, v66, v67
	v_max3_f32 v94, v94, v68, v69
	v_max3_f32 v167, v167, v70, v71
	v_max3_f32 v94, v94, v72, v73
	v_max3_f32 v167, v167, v74, v75
	v_max3_f32 v94, v94, v76, v77
	v_max3_f32 v167, v167, v78, v79
	v_max3_f32 v94, v94, v80, v81
	v_max3_f32 v167, v167, v82, v83
	v_max3_f32 v94, v94, v84, v85
	v_max3_f32 v167, v167, v86, v87
	v_max3_f32 v94, v94, v88, v89
	v_max3_f32 v167, v167, v90, v91
	v_max3_f32 v94, v94, v92, v93
	v_max_f32_e32 v167, v167, v94
	v_mov_b32_e32 v166, v167
	s_nop 1
	v_permlane16_swap_b32_e32 v167, v166
	v_max_f32_e32 v167, v167, v166
	v_mov_b32_e32 v166, v167
	s_nop 1
	v_permlane32_swap_b32_e32 v167, v166
	v_max_f32_e32 v167, v167, v166
	v_max_f32_e32 v167, v167, v42
	v_mul_f32_e32 v94, 0xbfb8aa3b, v167
	v_fmamk_f32 v58, v58, 0x3fb8aa3b, v94
	v_fmamk_f32 v59, v59, 0x3fb8aa3b, v94
	v_fmamk_f32 v60, v60, 0x3fb8aa3b, v94
	v_fmamk_f32 v61, v61, 0x3fb8aa3b, v94
	v_fmamk_f32 v62, v62, 0x3fb8aa3b, v94
	v_fmamk_f32 v63, v63, 0x3fb8aa3b, v94
	v_fmamk_f32 v64, v64, 0x3fb8aa3b, v94
	v_fmamk_f32 v65, v65, 0x3fb8aa3b, v94
	v_fmamk_f32 v66, v66, 0x3fb8aa3b, v94
	v_fmamk_f32 v67, v67, 0x3fb8aa3b, v94
	v_fmamk_f32 v68, v68, 0x3fb8aa3b, v94
	v_fmamk_f32 v69, v69, 0x3fb8aa3b, v94
	v_fmamk_f32 v70, v70, 0x3fb8aa3b, v94
	v_fmamk_f32 v71, v71, 0x3fb8aa3b, v94
	v_fmamk_f32 v72, v72, 0x3fb8aa3b, v94
	v_fmamk_f32 v73, v73, 0x3fb8aa3b, v94
	v_fmamk_f32 v74, v74, 0x3fb8aa3b, v94
	v_fmamk_f32 v75, v75, 0x3fb8aa3b, v94
	v_fmamk_f32 v76, v76, 0x3fb8aa3b, v94
	v_fmamk_f32 v77, v77, 0x3fb8aa3b, v94
	v_fmamk_f32 v78, v78, 0x3fb8aa3b, v94
	v_fmamk_f32 v79, v79, 0x3fb8aa3b, v94
	v_fmamk_f32 v80, v80, 0x3fb8aa3b, v94
; __device__ __forceinline__ unsigned cvt_pk_bf16(float lo, float hi) { unsigned r; asm volatile("v_cvt_pk_bf16_f32 %0, %1, %2" : "=v"(r) : "v"(lo), "v"(hi)); return r; }
; #define LAS __attribute__((address_space(3)))
; #define MFMA16(a, b, c) __builtin_amdgcn_mfma_f32_16x16x32_bf16((a), (b), (c), 0, 0, 0)
; __device__ __forceinline__ void p2_block(LAS unsigned char* lds, const bf16_t* __restrict__ PROJ, bf16_t* __restrict__ ATT, bf16_t* __restrict__ SGU, const float* __restrict__ qn, const float* __restrict__ kn, ...
;     ...
;             for (int e = 0; e < 4; ++e) { const float p = __builtin_amdgcn_exp2f((sc_[t][e] - mx) * LOG2E); sc_[t][e] = p; sum += p; }
;         sum += __shfl_xor(sum, 16); sum += __shfl_xor(sum, 32);
;         const float inv = 1.0f / (sum + __builtin_amdgcn_exp2f((sink - mx) * LOG2E));
;         f32x4 o[4];
; #pragma unroll
;         for (int dt = 0; dt < 4; ++dt) o[dt] = (f32x4){0.f, 0.f, 0.f, 0.f};
; #pragma unroll
;         for (int j = 0; j < 5; ++j) {
;             u32x4 pw; pw.x = cvt_pk_bf16(sc_[2 * j][0], sc_[2 * j][1]); pw.y = cvt_pk_bf16(sc_[2 * j][2], sc_[2 * j][3]); pw.z = cvt_pk_bf16(sc_[2 * j + 1][0], sc_[2 * j + 1][1]); pw.w = cvt_pk_bf16(sc_[2 * j + 1][2], sc_[2 * j + 1][3]);
;             const bf16x8 pf = __builtin_bit_cast(bf16x8, pw);
; #pragma unroll
;             for (int dt = 0; dt < 4; ++dt) { const LAS unsigned char* vb = VT + (16 * dt + fr) * VT_STRIDE + (16 * (t0 + 2 * j) + 4 * fq) * 2;
;                 const u32x2 va = *(const LAS u32x2*)vb, vc = *(const LAS u32x2*)(vb + 32); u32x4 vw; vw.x = va.x; vw.y = va.y; vw.z = vc.x; vw.w = vc.y;
;                 o[dt] = MFMA16(__builtin_bit_cast(bf16x8, vw), pf, o[dt]); }
	v_fmamk_f32 v81, v81, 0x3fb8aa3b, v94
	v_fmamk_f32 v82, v82, 0x3fb8aa3b, v94
	v_fmamk_f32 v83, v83, 0x3fb8aa3b, v94
	v_fmamk_f32 v84, v84, 0x3fb8aa3b, v94
	v_fmamk_f32 v85, v85, 0x3fb8aa3b, v94
	v_fmamk_f32 v86, v86, 0x3fb8aa3b, v94
	v_fmamk_f32 v87, v87, 0x3fb8aa3b, v94
	v_fmamk_f32 v88, v88, 0x3fb8aa3b, v94
	v_fmamk_f32 v89, v89, 0x3fb8aa3b, v94
	v_fmamk_f32 v90, v90, 0x3fb8aa3b, v94
	v_fmamk_f32 v91, v91, 0x3fb8aa3b, v94
	v_fmamk_f32 v92, v92, 0x3fb8aa3b, v94
	v_fmamk_f32 v93, v93, 0x3fb8aa3b, v94
	v_exp_f32_e32 v58, v58
	v_exp_f32_e32 v59, v59
	v_exp_f32_e32 v60, v60
	v_exp_f32_e32 v61, v61
	v_exp_f32_e32 v62, v62
	v_exp_f32_e32 v63, v63
	v_exp_f32_e32 v64, v64
	v_exp_f32_e32 v65, v65
	v_exp_f32_e32 v66, v66
	v_exp_f32_e32 v67, v67
	v_exp_f32_e32 v68, v68
	v_exp_f32_e32 v69, v69
	v_exp_f32_e32 v70, v70
	v_exp_f32_e32 v71, v71
	v_exp_f32_e32 v72, v72
	v_exp_f32_e32 v73, v73
	v_exp_f32_e32 v74, v74
	v_exp_f32_e32 v75, v75
	v_exp_f32_e32 v76, v76
	v_exp_f32_e32 v77, v77
	v_exp_f32_e32 v78, v78
	v_exp_f32_e32 v79, v79
	v_exp_f32_e32 v80, v80
	v_exp_f32_e32 v81, v81
	v_exp_f32_e32 v82, v82
	v_exp_f32_e32 v83, v83
	v_exp_f32_e32 v84, v84
	v_exp_f32_e32 v85, v85
	v_exp_f32_e32 v86, v86
	v_exp_f32_e32 v87, v87
	v_exp_f32_e32 v88, v88
	v_exp_f32_e32 v89, v89
	v_exp_f32_e32 v90, v90
	v_exp_f32_e32 v91, v91
	v_exp_f32_e32 v92, v92
	v_exp_f32_e32 v93, v93
	v_fmamk_f32 v95, v42, 0x3fb8aa3b, v94
	v_exp_f32_e32 v95, v95
	v_add_f32_e32 v167, v58, v59
	v_add_f32_e32 v94, v60, v61
	v_add_f32_e32 v167, v167, v62
	v_add_f32_e32 v94, v94, v63
	v_add_f32_e32 v167, v167, v64
	v_add_f32_e32 v94, v94, v65
	v_add_f32_e32 v167, v167, v66
	v_add_f32_e32 v94, v94, v67
	v_add_f32_e32 v167, v167, v68
	v_add_f32_e32 v94, v94, v69
	v_add_f32_e32 v167, v167, v70
	v_add_f32_e32 v94, v94, v71
	v_add_f32_e32 v167, v167, v72
	v_add_f32_e32 v94, v94, v73
	v_add_f32_e32 v167, v167, v74
	v_add_f32_e32 v94, v94, v75
	v_add_f32_e32 v167, v167, v76
	v_add_f32_e32 v94, v94, v77
	v_add_f32_e32 v167, v167, v78
	v_add_f32_e32 v94, v94, v79
	v_add_f32_e32 v167, v167, v80
	v_add_f32_e32 v94, v94, v81
	v_add_f32_e32 v167, v167, v82
	v_add_f32_e32 v94, v94, v83
	v_add_f32_e32 v167, v167, v84
	v_add_f32_e32 v94, v94, v85
	v_add_f32_e32 v167, v167, v86
	v_add_f32_e32 v94, v94, v87
	v_add_f32_e32 v167, v167, v88
	v_add_f32_e32 v94, v94, v89
	v_add_f32_e32 v167, v167, v90
	v_add_f32_e32 v94, v94, v91
	v_add_f32_e32 v167, v167, v92
	v_add_f32_e32 v94, v94, v93
	v_add_f32_e32 v167, v167, v94
	v_mov_b32_e32 v166, v167
	s_nop 1
	v_permlane16_swap_b32_e32 v167, v166
	v_add_f32_e32 v167, v167, v166
	v_mov_b32_e32 v166, v167
	s_nop 1
	v_permlane32_swap_b32_e32 v167, v166
	v_add_f32_e32 v167, v167, v166
	v_add_f32_e32 v167, v167, v95
	v_rcp_f32_e32 v167, v167
	v_mov_b32_e32 v94, 0
	v_mov_b32_e32 v95, 0
	v_mov_b32_e32 v96, 0
	v_mov_b32_e32 v97, 0
	v_cvt_pk_bf16_f32 v58, v58, v59
	v_cvt_pk_bf16_f32 v59, v60, v61
	v_cvt_pk_bf16_f32 v60, v62, v63
	v_cvt_pk_bf16_f32 v61, v64, v65
	v_cvt_pk_bf16_f32 v66, v66, v67
	v_cvt_pk_bf16_f32 v67, v68, v69
	v_cvt_pk_bf16_f32 v68, v70, v71
	v_cvt_pk_bf16_f32 v69, v72, v73
	v_cvt_pk_bf16_f32 v74, v74, v75
	v_cvt_pk_bf16_f32 v75, v76, v77
	v_cvt_pk_bf16_f32 v76, v78, v79
	v_cvt_pk_bf16_f32 v77, v80, v81
	v_cvt_pk_bf16_f32 v82, v82, v83
	v_cvt_pk_bf16_f32 v83, v84, v85
	v_cvt_pk_bf16_f32 v84, v86, v87
	v_cvt_pk_bf16_f32 v85, v88, v89
	v_cvt_pk_bf16_f32 v90, v90, v91
	v_cvt_pk_bf16_f32 v91, v92, v93
	v_cvt_pk_bf16_f32 v92, v94, v95
	v_cvt_pk_bf16_f32 v93, v96, v97
	s_nop 1
	s_waitcnt lgkmcnt(14)
	v_mfma_f32_16x16x32_bf16 v[62:65], v[98:101], v[58:61], 0
	ds_read2_b64 v[158:161], v197 offset0:28 offset1:32
	s_waitcnt lgkmcnt(14)
	v_mfma_f32_16x16x32_bf16 v[70:73], v[102:105], v[58:61], 0
	ds_read2_b64 v[162:165], v194 offset0:36 offset1:40
	s_waitcnt lgkmcnt(14)
	v_mfma_f32_16x16x32_bf16 v[78:81], v[106:109], v[58:61], 0
	ds_read2_b64 v[182:185], v195 offset0:36 offset1:40
	s_waitcnt lgkmcnt(14)
	v_mfma_f32_16x16x32_bf16 v[86:89], v[110:113], v[58:61], 0
	ds_read2_b64 v[186:189], v196 offset0:36 offset1:40
	s_waitcnt lgkmcnt(14)
	v_mfma_f32_16x16x32_bf16 v[62:65], v[114:117], v[66:69], v[62:65]
	ds_read2_b64 v[190:193], v197 offset0:36 offset1:40
	s_waitcnt lgkmcnt(14)
	v_mfma_f32_16x16x32_bf16 v[70:73], v[118:121], v[66:69], v[70:73]
	s_waitcnt lgkmcnt(13)
	v_mfma_f32_16x16x32_bf16 v[78:81], v[122:125], v[66:69], v[78:81]
	s_waitcnt lgkmcnt(12)
	v_mfma_f32_16x16x32_bf16 v[86:89], v[126:129], v[66:69], v[86:89]
	s_waitcnt lgkmcnt(11)
	v_mfma_f32_16x16x32_bf16 v[62:65], v[130:133], v[74:77], v[62:65]
	s_waitcnt lgkmcnt(10)
	v_mfma_f32_16x16x32_bf16 v[70:73], v[134:137], v[74:77], v[70:73]
	s_waitcnt lgkmcnt(9)
	v_mfma_f32_16x16x32_bf16 v[78:81], v[138:141], v[74:77], v[78:81]
	s_waitcnt lgkmcnt(8)
	v_mfma_f32_16x16x32_bf16 v[86:89], v[142:145], v[74:77], v[86:89]
	s_waitcnt lgkmcnt(7)
	v_mfma_f32_16x16x32_bf16 v[62:65], v[146:149], v[82:85], v[62:65]
	s_waitcnt lgkmcnt(6)
	v_mfma_f32_16x16x32_bf16 v[70:73], v[150:153], v[82:85], v[70:73]
	s_waitcnt lgkmcnt(5)
	v_mfma_f32_16x16x32_bf16 v[78:81], v[154:157], v[82:85], v[78:81]
	s_waitcnt lgkmcnt(4)
	v_mfma_f32_16x16x32_bf16 v[86:89], v[158:161], v[82:85], v[86:89]
	s_waitcnt lgkmcnt(3)
	v_mfma_f32_16x16x32_bf16 v[62:65], v[162:165], v[90:93], v[62:65]
	s_waitcnt lgkmcnt(2)
	v_mfma_f32_16x16x32_bf16 v[70:73], v[182:185], v[90:93], v[70:73]
	s_waitcnt lgkmcnt(1)
	v_mfma_f32_16x16x32_bf16 v[78:81], v[186:189], v[90:93], v[78:81]
	s_waitcnt lgkmcnt(0)
; #define LAS __attribute__((address_space(3)))
; __device__ __forceinline__ void p2_block(LAS unsigned char* lds, const bf16_t* __restrict__ PROJ, bf16_t* __restrict__ ATT, bf16_t* __restrict__ SGU, const float* __restrict__ qn, const float* __restrict__ kn, ...
;     ...
;         const int i0 = rbase + 16 * c, irow = i0 + fr, pos = n * 128 + irow; const size_t grow = (size_t)b * pg8::SEQ + pos;
;         bf16x8 qf0, qf1;
;         {
;             float x1[8], x2[8]; unpack8(qa[c], x1); unpack8(qb[c], x2);
;             float ss = 0.f;
; #pragma unroll
;             for (int j = 0; j < 8; ++j) ss += x1[j] * x1[j] + x2[j] * x2[j];
;             ss += __shfl_xor(ss, 16); ss += __shfl_xor(ss, 32);
;             const float rinv = rsqrtf(ss * (1.0f / 64.0f) + pg8::EPS) * 0.125f;
;             const float* cp = COS + pos * 32 + 8 * fq; const float* sp = SIN + pos * 32 + 8 * fq;
;             float o1[8], o2[8];
; #pragma unroll
;             for (int j = 0; j < 8; ++j) { const float a1 = x1[j] * rinv * qn[8 * fq + j], a2 = x2[j] * rinv * qn[32 + 8 * fq + j], cc = cp[j], sn = sp[j]; o1[j] = a1 * cc - a2 * sn; o2[j] = a2 * cc + a1 * sn; }
;             u32x4 w0, w1;
;             w0.x = cvt_pk_bf16(o1[0], o1[1]); w0.y = cvt_pk_bf16(o1[2], o1[3]); w0.z = cvt_pk_bf16(o1[4], o1[5]); w0.w = cvt_pk_bf16(o1[6], o1[7]);
;             w1.x = cvt_pk_bf16(o2[0], o2[1]); w1.y = cvt_pk_bf16(o2[2], o2[3]); w1.z = cvt_pk_bf16(o2[4], o2[5]); w1.w = cvt_pk_bf16(o2[6], o2[7]);
;             qf0 = __builtin_bit_cast(bf16x8, w0); qf1 = __builtin_bit_cast(bf16x8, w1);
;         }
;         const int t0 = (i0 >> 4) < 6 ? (i0 >> 4) : 6;
;         f32x4 sc_[10];
;         const LAS unsigned char* kbase = KS + (16 * t0 + fr) * KS_STRIDE + 16 * fq;
; #pragma unroll
;         for (int t = 0; t < 10; ++t) { const bf16x8 k0 = *(const LAS bf16x8*)(kbase + t * 16 * KS_STRIDE), k1 = *(const LAS bf16x8*)(kbase + t * 16 * KS_STRIDE + 64);
;             f32x4 z = (f32x4){0.f, 0.f, 0.f, 0.f}; z = MFMA16(k0, qf0, z); sc_[t] = MFMA16(k1, qf1, z); }
;     ...
;                 o[dt] = MFMA16(__builtin_bit_cast(bf16x8, vw), pf, o[dt]); }
;         }
;         bf16_t* op = ATT + grow * 1024 + hq * 64 + 4 * fq;
; #pragma unroll
;         for (int dt = 0; dt < 4; ++dt) { u32x2 ow; ow.x = cvt_pk_bf16(o[dt][0] * inv, o[dt][1] * inv); ow.y = cvt_pk_bf16(o[dt][2] * inv, o[dt][3] * inv); *(u32x2*)(op + 16 * dt) = ow; }
	v_mfma_f32_16x16x32_bf16 v[86:89], v[190:193], v[90:93], v[86:89]
	ds_read_b128 v[98:101], v45 offset:4608
	ds_read_b128 v[102:105], v45 offset:4672
	ds_read_b128 v[106:109], v45 offset:6912
	ds_read_b128 v[110:113], v45 offset:6976
	ds_read_b128 v[114:117], v45 offset:9216
	ds_read_b128 v[118:121], v45 offset:9280
	ds_read_b128 v[122:125], v45 offset:11520
	ds_read_b128 v[126:129], v45 offset:11584
	ds_read_b128 v[130:133], v45 offset:13824
	ds_read_b128 v[134:137], v45 offset:13888
	ds_read_b128 v[138:141], v45 offset:16128
	ds_read_b128 v[142:145], v45 offset:16192
	ds_read_b128 v[146:149], v45 offset:18432
	ds_read_b128 v[150:153], v45 offset:18496
	s_nop 7
	v_mul_f32_e32 v62, v62, v167
	v_mul_f32_e32 v63, v63, v167
	v_mul_f32_e32 v64, v64, v167
	v_mul_f32_e32 v65, v65, v167
	v_mul_f32_e32 v70, v70, v167
	v_mul_f32_e32 v71, v71, v167
	v_mul_f32_e32 v72, v72, v167
	v_mul_f32_e32 v73, v73, v167
	v_mul_f32_e32 v78, v78, v167
	v_mul_f32_e32 v79, v79, v167
	v_mul_f32_e32 v80, v80, v167
	v_mul_f32_e32 v81, v81, v167
	v_mul_f32_e32 v86, v86, v167
	v_mul_f32_e32 v87, v87, v167
	v_mul_f32_e32 v88, v88, v167
	v_mul_f32_e32 v89, v89, v167
	v_cvt_pk_bf16_f32 v62, v62, v63
	v_cvt_pk_bf16_f32 v63, v64, v65
	global_store_dwordx2 v48, v[62:63], s[24:25] offset:0
	v_cvt_pk_bf16_f32 v70, v70, v71
	v_cvt_pk_bf16_f32 v71, v72, v73
	global_store_dwordx2 v48, v[70:71], s[24:25] offset:32
	v_cvt_pk_bf16_f32 v78, v78, v79
	v_cvt_pk_bf16_f32 v79, v80, v81
	global_store_dwordx2 v48, v[78:79], s[24:25] offset:64
	v_cvt_pk_bf16_f32 v86, v86, v87
	v_cvt_pk_bf16_f32 v87, v88, v89
	global_store_dwordx2 v48, v[86:87], s[24:25] offset:96
	v_add_u32_e32 v48, 0x8000, v48
	s_waitcnt vmcnt(14)
	v_lshlrev_b32_e32 v58, 16, v2
	v_and_b32_e32 v59, 0xffff0000, v2
	v_lshlrev_b32_e32 v66, 16, v6
	v_and_b32_e32 v67, 0xffff0000, v6
	v_lshlrev_b32_e32 v60, 16, v3
	v_and_b32_e32 v61, 0xffff0000, v3
	v_lshlrev_b32_e32 v68, 16, v7
	v_and_b32_e32 v69, 0xffff0000, v7
	v_lshlrev_b32_e32 v62, 16, v4
	v_and_b32_e32 v63, 0xffff0000, v4
	v_lshlrev_b32_e32 v70, 16, v8
	v_and_b32_e32 v71, 0xffff0000, v8
	v_lshlrev_b32_e32 v64, 16, v5
	v_and_b32_e32 v65, 0xffff0000, v5
	v_lshlrev_b32_e32 v72, 16, v9
	v_and_b32_e32 v73, 0xffff0000, v9
	v_mul_f32_e32 v74, v58, v58
	v_mul_f32_e32 v75, v59, v59
	v_fmac_f32_e32 v74, v60, v60
	v_fmac_f32_e32 v75, v61, v61
	v_fmac_f32_e32 v74, v62, v62
	v_fmac_f32_e32 v75, v63, v63
	v_fmac_f32_e32 v74, v64, v64
	v_fmac_f32_e32 v75, v65, v65
	v_fmac_f32_e32 v74, v66, v66
	v_fmac_f32_e32 v75, v67, v67
	v_fmac_f32_e32 v74, v68, v68
	v_fmac_f32_e32 v75, v69, v69
	v_fmac_f32_e32 v74, v70, v70
	v_fmac_f32_e32 v75, v71, v71
	v_fmac_f32_e32 v74, v72, v72
	v_fmac_f32_e32 v75, v73, v73
	v_add_f32_e32 v74, v74, v75
	v_mov_b32_e32 v166, v74
	s_nop 1
	v_permlane16_swap_b32_e32 v74, v166
	v_add_f32_e32 v74, v74, v166
	v_mov_b32_e32 v166, v74
	s_nop 1
	v_permlane32_swap_b32_e32 v74, v166
	v_add_f32_e32 v74, v74, v166
	v_fmamk_f32 v74, v74, 0x3c800000, v209
	v_rsq_f32_e32 v76, v74
	s_nop 0
	v_mul_f32_e32 v76, 0x3e000000, v76
	v_mul_f32_e32 v58, v58, v76
	v_mul_f32_e32 v66, v66, v76
	v_mul_f32_e32 v59, v59, v76
	v_mul_f32_e32 v67, v67, v76
	v_mul_f32_e32 v60, v60, v76
	v_mul_f32_e32 v68, v68, v76
	v_mul_f32_e32 v61, v61, v76
	v_mul_f32_e32 v69, v69, v76
	v_mul_f32_e32 v62, v62, v76
	v_mul_f32_e32 v70, v70, v76
	v_mul_f32_e32 v63, v63, v76
	v_mul_f32_e32 v71, v71, v76
	v_mul_f32_e32 v64, v64, v76
	v_mul_f32_e32 v72, v72, v76
	v_mul_f32_e32 v65, v65, v76
	v_mul_f32_e32 v73, v73, v76
	v_mul_f32_e32 v58, v58, v26
	v_mul_f32_e32 v66, v66, v34
	v_mul_f32_e32 v59, v59, v27
	v_mul_f32_e32 v67, v67, v35
	v_mul_f32_e32 v60, v60, v28
	v_mul_f32_e32 v68, v68, v36
	v_mul_f32_e32 v61, v61, v29
	v_mul_f32_e32 v69, v69, v37
	v_mul_f32_e32 v62, v62, v30
	v_mul_f32_e32 v70, v70, v38
	v_mul_f32_e32 v63, v63, v31
	v_mul_f32_e32 v71, v71, v39
	v_mul_f32_e32 v64, v64, v32
	v_mul_f32_e32 v72, v72, v40
	v_mul_f32_e32 v65, v65, v33
	v_mul_f32_e32 v73, v73, v41
	v_mul_f32_e32 v78, v66, v18
	v_mul_f32_e32 v86, v58, v18
	v_mul_f32_e32 v79, v67, v19
	v_mul_f32_e32 v87, v59, v19
	v_mul_f32_e32 v80, v68, v20
	v_mul_f32_e32 v88, v60, v20
	v_mul_f32_e32 v81, v69, v21
	v_mul_f32_e32 v89, v61, v21
	v_mul_f32_e32 v82, v70, v22
	v_mul_f32_e32 v90, v62, v22
	v_mul_f32_e32 v83, v71, v23
	v_mul_f32_e32 v91, v63, v23
	v_mul_f32_e32 v84, v72, v24
	v_mul_f32_e32 v92, v64, v24
	v_mul_f32_e32 v85, v73, v25
	v_mul_f32_e32 v93, v65, v25
	v_fma_f32 v78, v58, v10, -v78
	v_fmac_f32_e32 v86, v66, v10
	v_fma_f32 v79, v59, v11, -v79
	v_fmac_f32_e32 v87, v67, v11
	v_fma_f32 v80, v60, v12, -v80
	v_fmac_f32_e32 v88, v68, v12
	v_fma_f32 v81, v61, v13, -v81
	v_fmac_f32_e32 v89, v69, v13
	v_fma_f32 v82, v62, v14, -v82
	v_fmac_f32_e32 v90, v70, v14
	v_fma_f32 v83, v63, v15, -v83
	v_fmac_f32_e32 v91, v71, v15
	v_fma_f32 v84, v64, v16, -v84
	v_fmac_f32_e32 v92, v72, v16
	v_fma_f32 v85, v65, v17, -v85
	v_fmac_f32_e32 v93, v73, v17
	v_cvt_pk_bf16_f32 v50, v78, v79
	v_cvt_pk_bf16_f32 v54, v86, v87
	v_cvt_pk_bf16_f32 v51, v80, v81
	v_cvt_pk_bf16_f32 v55, v88, v89
	v_cvt_pk_bf16_f32 v52, v82, v83
	v_cvt_pk_bf16_f32 v56, v90, v91
	v_cvt_pk_bf16_f32 v53, v84, v85
	v_cvt_pk_bf16_f32 v57, v92, v93
	s_nop 1
	s_waitcnt lgkmcnt(13)
	v_mfma_f32_16x16x32_bf16 v[58:61], v[98:101], v[50:53], 0
	s_waitcnt lgkmcnt(12)
	v_mfma_f32_16x16x32_bf16 v[58:61], v[102:105], v[54:57], v[58:61]
	ds_read_b128 v[154:157], v45 offset:20736
	ds_read_b128 v[158:161], v45 offset:20800
	s_waitcnt lgkmcnt(13)
	v_mfma_f32_16x16x32_bf16 v[62:65], v[106:109], v[50:53], 0
	s_waitcnt lgkmcnt(12)
; #define LAS __attribute__((address_space(3)))
; #define MFMA16(a, b, c) __builtin_amdgcn_mfma_f32_16x16x32_bf16((a), (b), (c), 0, 0, 0)
; __device__ __forceinline__ void p2_block(LAS unsigned char* lds, const bf16_t* __restrict__ PROJ, bf16_t* __restrict__ ATT, bf16_t* __restrict__ SGU, const float* __restrict__ qn, const float* __restrict__ kn, ...
;     ...
;         for (int t = 0; t < 10; ++t) { const bf16x8 k0 = *(const LAS bf16x8*)(kbase + t * 16 * KS_STRIDE), k1 = *(const LAS bf16x8*)(kbase + t * 16 * KS_STRIDE + 64);
;             f32x4 z = (f32x4){0.f, 0.f, 0.f, 0.f}; z = MFMA16(k0, qf0, z); sc_[t] = MFMA16(k1, qf1, z); }
;         float mx = -1e30f;
; #pragma unroll
;         for (int t = 0; t < 10; ++t)
; #pragma unroll
;             for (int e = 0; e < 4; ++e) { const int kx = 16 * (t0 + t) + 4 * fq + e, d = kx - irow; const bool ok = (d >= 1) && (d <= 128) && (n > 0 || kx >= 128);
;                 const float v = ok ? sc_[t][e] : -1e30f; sc_[t][e] = v; mx = fmaxf(mx, v); }
;         mx = fmaxf(mx, __shfl_xor(mx, 16)); mx = fmaxf(mx, __shfl_xor(mx, 32)); mx = fmaxf(mx, sink);
;         float sum = 0.f;
; #pragma unroll
;         for (int t = 0; t < 10; ++t)
; #pragma unroll
;             for (int e = 0; e < 4; ++e) { const float p = __builtin_amdgcn_exp2f((sc_[t][e] - mx) * LOG2E); sc_[t][e] = p; sum += p; }
	v_mfma_f32_16x16x32_bf16 v[62:65], v[110:113], v[54:57], v[62:65]
	ds_read_b128 v[162:165], v45 offset:23040
	ds_read_b128 v[182:185], v45 offset:23104
	s_waitcnt lgkmcnt(13)
	v_mfma_f32_16x16x32_bf16 v[66:69], v[114:117], v[50:53], 0
	s_waitcnt lgkmcnt(12)
	v_mfma_f32_16x16x32_bf16 v[66:69], v[118:121], v[54:57], v[66:69]
	s_waitcnt lgkmcnt(11)
	v_mfma_f32_16x16x32_bf16 v[70:73], v[122:125], v[50:53], 0
	s_waitcnt lgkmcnt(10)
	v_mfma_f32_16x16x32_bf16 v[70:73], v[126:129], v[54:57], v[70:73]
	s_waitcnt lgkmcnt(9)
	v_mfma_f32_16x16x32_bf16 v[74:77], v[130:133], v[50:53], 0
	s_waitcnt lgkmcnt(8)
	v_mfma_f32_16x16x32_bf16 v[74:77], v[134:137], v[54:57], v[74:77]
	s_waitcnt lgkmcnt(7)
	v_mfma_f32_16x16x32_bf16 v[78:81], v[138:141], v[50:53], 0
	s_waitcnt lgkmcnt(6)
	v_mfma_f32_16x16x32_bf16 v[78:81], v[142:145], v[54:57], v[78:81]
	s_waitcnt lgkmcnt(5)
	v_mfma_f32_16x16x32_bf16 v[82:85], v[146:149], v[50:53], 0
	s_waitcnt lgkmcnt(4)
	v_mfma_f32_16x16x32_bf16 v[82:85], v[150:153], v[54:57], v[82:85]
	s_waitcnt lgkmcnt(3)
	v_mfma_f32_16x16x32_bf16 v[86:89], v[154:157], v[50:53], 0
	s_waitcnt lgkmcnt(2)
	v_mfma_f32_16x16x32_bf16 v[86:89], v[158:161], v[54:57], v[86:89]
	s_waitcnt lgkmcnt(1)
	v_mfma_f32_16x16x32_bf16 v[90:93], v[162:165], v[50:53], 0
	s_waitcnt lgkmcnt(0)
	v_mfma_f32_16x16x32_bf16 v[90:93], v[182:185], v[54:57], v[90:93]
	ds_read2_b64 v[98:101], v194 offset0:8 offset1:12
	ds_read2_b64 v[102:105], v195 offset0:8 offset1:12
	ds_read2_b64 v[106:109], v196 offset0:8 offset1:12
	ds_read2_b64 v[110:113], v197 offset0:8 offset1:12
	ds_read2_b64 v[114:117], v194 offset0:16 offset1:20
	ds_read2_b64 v[118:121], v195 offset0:16 offset1:20
	ds_read2_b64 v[122:125], v196 offset0:16 offset1:20
	ds_read2_b64 v[126:129], v197 offset0:16 offset1:20
	ds_read2_b64 v[130:133], v194 offset0:24 offset1:28
	ds_read2_b64 v[134:137], v195 offset0:24 offset1:28
	ds_read2_b64 v[138:141], v196 offset0:24 offset1:28
	ds_read2_b64 v[142:145], v197 offset0:24 offset1:28
	ds_read2_b64 v[146:149], v194 offset0:32 offset1:36
	ds_read2_b64 v[150:153], v195 offset0:32 offset1:36
	ds_read2_b64 v[154:157], v196 offset0:32 offset1:36
	s_nop 4
	v_cndmask_b32_e64 v58, v49, v58, s[48:49]
	v_cndmask_b32_e64 v59, v49, v59, s[50:51]
	v_cndmask_b32_e64 v60, v49, v60, s[52:53]
	v_cndmask_b32_e64 v61, v49, v61, s[26:27]
	v_cndmask_b32_e64 v62, v49, v62, s[28:29]
	v_cndmask_b32_e64 v63, v49, v63, s[28:29]
	v_cndmask_b32_e64 v64, v49, v64, s[28:29]
	v_cndmask_b32_e64 v65, v49, v65, s[28:29]
	v_cndmask_b32_e64 v66, v49, v66, s[28:29]
	v_cndmask_b32_e64 v67, v49, v67, s[28:29]
	v_cndmask_b32_e64 v68, v49, v68, s[28:29]
	v_cndmask_b32_e64 v69, v49, v69, s[28:29]
	v_cndmask_b32_e64 v70, v49, v70, s[28:29]
	v_cndmask_b32_e64 v71, v49, v71, s[28:29]
	v_cndmask_b32_e64 v72, v49, v72, s[28:29]
	v_cndmask_b32_e64 v73, v49, v73, s[28:29]
	v_cndmask_b32_e64 v74, v49, v74, s[28:29]
	v_cndmask_b32_e64 v75, v49, v75, s[28:29]
	v_cndmask_b32_e64 v76, v49, v76, s[28:29]
	v_cndmask_b32_e64 v77, v49, v77, s[28:29]
	v_cndmask_b32_e64 v78, v49, v78, s[28:29]
	v_cndmask_b32_e64 v79, v49, v79, s[28:29]
	v_cndmask_b32_e64 v80, v49, v80, s[28:29]
	v_cndmask_b32_e64 v81, v49, v81, s[28:29]
	v_cndmask_b32_e64 v90, v90, v49, s[40:41]
	v_cndmask_b32_e64 v91, v91, v49, s[42:43]
	v_cndmask_b32_e64 v92, v92, v49, s[44:45]
	v_cndmask_b32_e64 v93, v93, v49, s[46:47]
	v_max_f32_e32 v167, v58, v59
	v_max_f32_e32 v94, v60, v61
	v_max3_f32 v167, v167, v62, v63
	v_max3_f32 v94, v94, v64, v65
	v_max3_f32 v167, v167, v66, v67
	v_max3_f32 v94, v94, v68, v69
	v_max3_f32 v167, v167, v70, v71
	v_max3_f32 v94, v94, v72, v73
	v_max3_f32 v167, v167, v74, v75
	v_max3_f32 v94, v94, v76, v77
	v_max3_f32 v167, v167, v78, v79
	v_max3_f32 v94, v94, v80, v81
	v_max3_f32 v167, v167, v82, v83
	v_max3_f32 v94, v94, v84, v85
	v_max3_f32 v167, v167, v86, v87
	v_max3_f32 v94, v94, v88, v89
	v_max3_f32 v167, v167, v90, v91
	v_max3_f32 v94, v94, v92, v93
	v_max_f32_e32 v167, v167, v94
	v_mov_b32_e32 v166, v167
	s_nop 1
	v_permlane16_swap_b32_e32 v167, v166
	v_max_f32_e32 v167, v167, v166
	v_mov_b32_e32 v166, v167
	s_nop 1
	v_permlane32_swap_b32_e32 v167, v166
	v_max_f32_e32 v167, v167, v166
	v_max_f32_e32 v167, v167, v42
	v_mul_f32_e32 v94, 0xbfb8aa3b, v167
	v_fmamk_f32 v58, v58, 0x3fb8aa3b, v94
	v_fmamk_f32 v59, v59, 0x3fb8aa3b, v94
	v_fmamk_f32 v60, v60, 0x3fb8aa3b, v94
	v_fmamk_f32 v61, v61, 0x3fb8aa3b, v94
	v_fmamk_f32 v62, v62, 0x3fb8aa3b, v94
	v_fmamk_f32 v63, v63, 0x3fb8aa3b, v94
	v_fmamk_f32 v64, v64, 0x3fb8aa3b, v94
	v_fmamk_f32 v65, v65, 0x3fb8aa3b, v94
	v_fmamk_f32 v66, v66, 0x3fb8aa3b, v94
	v_fmamk_f32 v67, v67, 0x3fb8aa3b, v94
	v_fmamk_f32 v68, v68, 0x3fb8aa3b, v94
	v_fmamk_f32 v69, v69, 0x3fb8aa3b, v94
	v_fmamk_f32 v70, v70, 0x3fb8aa3b, v94
	v_fmamk_f32 v71, v71, 0x3fb8aa3b, v94
	v_fmamk_f32 v72, v72, 0x3fb8aa3b, v94
	v_fmamk_f32 v73, v73, 0x3fb8aa3b, v94
	v_fmamk_f32 v74, v74, 0x3fb8aa3b, v94
	v_fmamk_f32 v75, v75, 0x3fb8aa3b, v94
	v_fmamk_f32 v76, v76, 0x3fb8aa3b, v94
	v_fmamk_f32 v77, v77, 0x3fb8aa3b, v94
	v_fmamk_f32 v78, v78, 0x3fb8aa3b, v94
	v_fmamk_f32 v79, v79, 0x3fb8aa3b, v94
	v_fmamk_f32 v80, v80, 0x3fb8aa3b, v94
	v_fmamk_f32 v81, v81, 0x3fb8aa3b, v94
	v_fmamk_f32 v82, v82, 0x3fb8aa3b, v94
	v_fmamk_f32 v83, v83, 0x3fb8aa3b, v94
	v_fmamk_f32 v84, v84, 0x3fb8aa3b, v94
	v_fmamk_f32 v85, v85, 0x3fb8aa3b, v94
	v_fmamk_f32 v86, v86, 0x3fb8aa3b, v94
	v_fmamk_f32 v87, v87, 0x3fb8aa3b, v94
	v_fmamk_f32 v88, v88, 0x3fb8aa3b, v94
	v_fmamk_f32 v89, v89, 0x3fb8aa3b, v94
	v_fmamk_f32 v90, v90, 0x3fb8aa3b, v94
	v_fmamk_f32 v91, v91, 0x3fb8aa3b, v94
	v_fmamk_f32 v92, v92, 0x3fb8aa3b, v94
	v_fmamk_f32 v93, v93, 0x3fb8aa3b, v94
; __device__ __forceinline__ unsigned cvt_pk_bf16(float lo, float hi) { unsigned r; asm volatile("v_cvt_pk_bf16_f32 %0, %1, %2" : "=v"(r) : "v"(lo), "v"(hi)); return r; }
; #define LAS __attribute__((address_space(3)))
; #define MFMA16(a, b, c) __builtin_amdgcn_mfma_f32_16x16x32_bf16((a), (b), (c), 0, 0, 0)
; __device__ __forceinline__ void p2_block(LAS unsigned char* lds, const bf16_t* __restrict__ PROJ, bf16_t* __restrict__ ATT, bf16_t* __restrict__ SGU, const float* __restrict__ qn, const float* __restrict__ kn, ...
;     ...
;             for (int e = 0; e < 4; ++e) { const float p = __builtin_amdgcn_exp2f((sc_[t][e] - mx) * LOG2E); sc_[t][e] = p; sum += p; }
;         sum += __shfl_xor(sum, 16); sum += __shfl_xor(sum, 32);
;         const float inv = 1.0f / (sum + __builtin_amdgcn_exp2f((sink - mx) * LOG2E));
;         f32x4 o[4];
; #pragma unroll
;         for (int dt = 0; dt < 4; ++dt) o[dt] = (f32x4){0.f, 0.f, 0.f, 0.f};
; #pragma unroll
;         for (int j = 0; j < 5; ++j) {
;             u32x4 pw; pw.x = cvt_pk_bf16(sc_[2 * j][0], sc_[2 * j][1]); pw.y = cvt_pk_bf16(sc_[2 * j][2], sc_[2 * j][3]); pw.z = cvt_pk_bf16(sc_[2 * j + 1][0], sc_[2 * j + 1][1]); pw.w = cvt_pk_bf16(sc_[2 * j + 1][2], sc_[2 * j + 1][3]);
;             const bf16x8 pf = __builtin_bit_cast(bf16x8, pw);
; #pragma unroll
;             for (int dt = 0; dt < 4; ++dt) { const LAS unsigned char* vb = VT + (16 * dt + fr) * VT_STRIDE + (16 * (t0 + 2 * j) + 4 * fq) * 2;
;                 const u32x2 va = *(const LAS u32x2*)vb, vc = *(const LAS u32x2*)(vb + 32); u32x4 vw; vw.x = va.x; vw.y = va.y; vw.z = vc.x; vw.w = vc.y;
;                 o[dt] = MFMA16(__builtin_bit_cast(bf16x8, vw), pf, o[dt]); }
	v_exp_f32_e32 v58, v58
	v_exp_f32_e32 v59, v59
	v_exp_f32_e32 v60, v60
	v_exp_f32_e32 v61, v61
	v_exp_f32_e32 v62, v62
	v_exp_f32_e32 v63, v63
	v_exp_f32_e32 v64, v64
	v_exp_f32_e32 v65, v65
	v_exp_f32_e32 v66, v66
	v_exp_f32_e32 v67, v67
	v_exp_f32_e32 v68, v68
	v_exp_f32_e32 v69, v69
	v_exp_f32_e32 v70, v70
	v_exp_f32_e32 v71, v71
	v_exp_f32_e32 v72, v72
	v_exp_f32_e32 v73, v73
	v_exp_f32_e32 v74, v74
	v_exp_f32_e32 v75, v75
	v_exp_f32_e32 v76, v76
	v_exp_f32_e32 v77, v77
	v_exp_f32_e32 v78, v78
	v_exp_f32_e32 v79, v79
	v_exp_f32_e32 v80, v80
	v_exp_f32_e32 v81, v81
	v_exp_f32_e32 v82, v82
	v_exp_f32_e32 v83, v83
	v_exp_f32_e32 v84, v84
	v_exp_f32_e32 v85, v85
	v_exp_f32_e32 v86, v86
	v_exp_f32_e32 v87, v87
	v_exp_f32_e32 v88, v88
	v_exp_f32_e32 v89, v89
	v_exp_f32_e32 v90, v90
	v_exp_f32_e32 v91, v91
	v_exp_f32_e32 v92, v92
	v_exp_f32_e32 v93, v93
	v_fmamk_f32 v95, v42, 0x3fb8aa3b, v94
	v_exp_f32_e32 v95, v95
	v_add_f32_e32 v167, v58, v59
	v_add_f32_e32 v94, v60, v61
	v_add_f32_e32 v167, v167, v62
	v_add_f32_e32 v94, v94, v63
	v_add_f32_e32 v167, v167, v64
	v_add_f32_e32 v94, v94, v65
	v_add_f32_e32 v167, v167, v66
	v_add_f32_e32 v94, v94, v67
	v_add_f32_e32 v167, v167, v68
	v_add_f32_e32 v94, v94, v69
	v_add_f32_e32 v167, v167, v70
	v_add_f32_e32 v94, v94, v71
	v_add_f32_e32 v167, v167, v72
	v_add_f32_e32 v94, v94, v73
	v_add_f32_e32 v167, v167, v74
	v_add_f32_e32 v94, v94, v75
	v_add_f32_e32 v167, v167, v76
	v_add_f32_e32 v94, v94, v77
	v_add_f32_e32 v167, v167, v78
	v_add_f32_e32 v94, v94, v79
	v_add_f32_e32 v167, v167, v80
	v_add_f32_e32 v94, v94, v81
	v_add_f32_e32 v167, v167, v82
	v_add_f32_e32 v94, v94, v83
	v_add_f32_e32 v167, v167, v84
	v_add_f32_e32 v94, v94, v85
	v_add_f32_e32 v167, v167, v86
	v_add_f32_e32 v94, v94, v87
	v_add_f32_e32 v167, v167, v88
	v_add_f32_e32 v94, v94, v89
	v_add_f32_e32 v167, v167, v90
	v_add_f32_e32 v94, v94, v91
	v_add_f32_e32 v167, v167, v92
	v_add_f32_e32 v94, v94, v93
	v_add_f32_e32 v167, v167, v94
	v_mov_b32_e32 v166, v167
	s_nop 1
	v_permlane16_swap_b32_e32 v167, v166
	v_add_f32_e32 v167, v167, v166
	v_mov_b32_e32 v166, v167
	s_nop 1
	v_permlane32_swap_b32_e32 v167, v166
	v_add_f32_e32 v167, v167, v166
	v_add_f32_e32 v167, v167, v95
	v_rcp_f32_e32 v167, v167
	v_mov_b32_e32 v94, 0
	v_mov_b32_e32 v95, 0
	v_mov_b32_e32 v96, 0
	v_mov_b32_e32 v97, 0
	v_cvt_pk_bf16_f32 v58, v58, v59
	v_cvt_pk_bf16_f32 v59, v60, v61
	v_cvt_pk_bf16_f32 v60, v62, v63
	v_cvt_pk_bf16_f32 v61, v64, v65
	v_cvt_pk_bf16_f32 v66, v66, v67
	v_cvt_pk_bf16_f32 v67, v68, v69
	v_cvt_pk_bf16_f32 v68, v70, v71
	v_cvt_pk_bf16_f32 v69, v72, v73
	v_cvt_pk_bf16_f32 v74, v74, v75
	v_cvt_pk_bf16_f32 v75, v76, v77
	v_cvt_pk_bf16_f32 v76, v78, v79
	v_cvt_pk_bf16_f32 v77, v80, v81
	v_cvt_pk_bf16_f32 v82, v82, v83
	v_cvt_pk_bf16_f32 v83, v84, v85
	v_cvt_pk_bf16_f32 v84, v86, v87
	v_cvt_pk_bf16_f32 v85, v88, v89
	v_cvt_pk_bf16_f32 v90, v90, v91
	v_cvt_pk_bf16_f32 v91, v92, v93
	v_cvt_pk_bf16_f32 v92, v94, v95
	v_cvt_pk_bf16_f32 v93, v96, v97
	s_nop 1
	s_waitcnt lgkmcnt(14)
	v_mfma_f32_16x16x32_bf16 v[62:65], v[98:101], v[58:61], 0
	ds_read2_b64 v[158:161], v197 offset0:32 offset1:36
	s_waitcnt lgkmcnt(14)
	v_mfma_f32_16x16x32_bf16 v[70:73], v[102:105], v[58:61], 0
	ds_read2_b64 v[162:165], v194 offset0:40 offset1:44
	s_waitcnt lgkmcnt(14)
	v_mfma_f32_16x16x32_bf16 v[78:81], v[106:109], v[58:61], 0
	ds_read2_b64 v[182:185], v195 offset0:40 offset1:44
	s_waitcnt lgkmcnt(14)
	v_mfma_f32_16x16x32_bf16 v[86:89], v[110:113], v[58:61], 0
	ds_read2_b64 v[186:189], v196 offset0:40 offset1:44
	s_waitcnt lgkmcnt(14)
	v_mfma_f32_16x16x32_bf16 v[62:65], v[114:117], v[66:69], v[62:65]
	ds_read2_b64 v[190:193], v197 offset0:40 offset1:44
	s_waitcnt lgkmcnt(14)
	v_mfma_f32_16x16x32_bf16 v[70:73], v[118:121], v[66:69], v[70:73]
	s_waitcnt lgkmcnt(13)
	v_mfma_f32_16x16x32_bf16 v[78:81], v[122:125], v[66:69], v[78:81]
	s_waitcnt lgkmcnt(12)
	v_mfma_f32_16x16x32_bf16 v[86:89], v[126:129], v[66:69], v[86:89]
	s_waitcnt lgkmcnt(11)
	v_mfma_f32_16x16x32_bf16 v[62:65], v[130:133], v[74:77], v[62:65]
	s_waitcnt lgkmcnt(10)
	v_mfma_f32_16x16x32_bf16 v[70:73], v[134:137], v[74:77], v[70:73]
	s_waitcnt lgkmcnt(9)
	v_mfma_f32_16x16x32_bf16 v[78:81], v[138:141], v[74:77], v[78:81]
	s_waitcnt lgkmcnt(8)
	v_mfma_f32_16x16x32_bf16 v[86:89], v[142:145], v[74:77], v[86:89]
	s_waitcnt lgkmcnt(7)
	v_mfma_f32_16x16x32_bf16 v[62:65], v[146:149], v[82:85], v[62:65]
	s_waitcnt lgkmcnt(6)
	v_mfma_f32_16x16x32_bf16 v[70:73], v[150:153], v[82:85], v[70:73]
	s_waitcnt lgkmcnt(5)
	v_mfma_f32_16x16x32_bf16 v[78:81], v[154:157], v[82:85], v[78:81]
	s_waitcnt lgkmcnt(4)
	v_mfma_f32_16x16x32_bf16 v[86:89], v[158:161], v[82:85], v[86:89]
	s_waitcnt lgkmcnt(3)
	v_mfma_f32_16x16x32_bf16 v[62:65], v[162:165], v[90:93], v[62:65]
	s_waitcnt lgkmcnt(2)
	v_mfma_f32_16x16x32_bf16 v[70:73], v[182:185], v[90:93], v[70:73]
	s_waitcnt lgkmcnt(1)
	v_mfma_f32_16x16x32_bf16 v[78:81], v[186:189], v[90:93], v[78:81]
	s_waitcnt lgkmcnt(0)
; #define LAS __attribute__((address_space(3)))
; __device__ __forceinline__ void p2_block(LAS unsigned char* lds, const bf16_t* __restrict__ PROJ, bf16_t* __restrict__ ATT, bf16_t* __restrict__ SGU, const float* __restrict__ qn, const float* __restrict__ kn, ...
;     ...
;             float x1[8], x2[8]; unpack8(qa[c], x1); unpack8(qb[c], x2);
;             float ss = 0.f;
; #pragma unroll
;             for (int j = 0; j < 8; ++j) ss += x1[j] * x1[j] + x2[j] * x2[j];
;             ss += __shfl_xor(ss, 16); ss += __shfl_xor(ss, 32);
;             const float rinv = rsqrtf(ss * (1.0f / 64.0f) + pg8::EPS) * 0.125f;
;             const float* cp = COS + pos * 32 + 8 * fq; const float* sp = SIN + pos * 32 + 8 * fq;
;             float o1[8], o2[8];
; #pragma unroll
;             for (int j = 0; j < 8; ++j) { const float a1 = x1[j] * rinv * qn[8 * fq + j], a2 = x2[j] * rinv * qn[32 + 8 * fq + j], cc = cp[j], sn = sp[j]; o1[j] = a1 * cc - a2 * sn; o2[j] = a2 * cc + a1 * sn; }
;             u32x4 w0, w1;
;             w0.x = cvt_pk_bf16(o1[0], o1[1]); w0.y = cvt_pk_bf16(o1[2], o1[3]); w0.z = cvt_pk_bf16(o1[4], o1[5]); w0.w = cvt_pk_bf16(o1[6], o1[7]);
;             w1.x = cvt_pk_bf16(o2[0], o2[1]); w1.y = cvt_pk_bf16(o2[2], o2[3]); w1.z = cvt_pk_bf16(o2[4], o2[5]); w1.w = cvt_pk_bf16(o2[6], o2[7]);
;             qf0 = __builtin_bit_cast(bf16x8, w0); qf1 = __builtin_bit_cast(bf16x8, w1);
;     ...
;         const int gg = 2 * kvh + gi, irow = 16 * w + fr, nks = (w >> 1) + 1;
;         const LAS unsigned char* VNT = lds + (gi ? VN_OFF1 : VN_OFF0);
;         f32x4 acc[8];
; #pragma unroll
;         for (int dt = 0; dt < 8; ++dt) acc[dt] = (f32x4){0.f, 0.f, 0.f, 0.f};
;         const float* wrow = wsp + (size_t)gg * 16384 + irow * 128 + 8 * fq;
; #pragma unroll
;         for (int ks = 0; ks < 4; ++ks) if (ks < nks) {
;             const f32x4 wa = *(const f32x4*)(wrow + 32 * ks), wb = *(const f32x4*)(wrow + 32 * ks + 4);
;             const int j0 = 32 * ks + 8 * fq; float wv[8];
; #pragma unroll
;             for (int e = 0; e < 4; ++e) { wv[e] = (j0 + e <= irow) ? wa[e] : 0.f; wv[4 + e] = (j0 + 4 + e <= irow) ? wb[e] : 0.f; }
;             u32x4 ww; ww.x = cvt_pk_bf16(wv[0], wv[1]); ww.y = cvt_pk_bf16(wv[2], wv[3]); ww.z = cvt_pk_bf16(wv[4], wv[5]); ww.w = cvt_pk_bf16(wv[6], wv[7]);
;             const bf16x8 wf = __builtin_bit_cast(bf16x8, ww);
; #pragma unroll
	v_mfma_f32_16x16x32_bf16 v[86:89], v[190:193], v[90:93], v[86:89]
	ds_read_b128 v[98:101], v45 offset:6912
	ds_read_b128 v[102:105], v45 offset:6976
	ds_read_b128 v[106:109], v45 offset:9216
	ds_read_b128 v[110:113], v45 offset:9280
	ds_read_b128 v[114:117], v45 offset:11520
	ds_read_b128 v[118:121], v45 offset:11584
	ds_read_b128 v[122:125], v45 offset:13824
	ds_read_b128 v[126:129], v45 offset:13888
	ds_read_b128 v[130:133], v45 offset:16128
	ds_read_b128 v[134:137], v45 offset:16192
	ds_read_b128 v[138:141], v45 offset:18432
	ds_read_b128 v[142:145], v45 offset:18496
	ds_read_b128 v[146:149], v45 offset:20736
	ds_read_b128 v[150:153], v45 offset:20800
	s_nop 7
	v_mul_f32_e32 v62, v62, v167
	v_mul_f32_e32 v63, v63, v167
	v_mul_f32_e32 v64, v64, v167
	v_mul_f32_e32 v65, v65, v167
	v_mul_f32_e32 v70, v70, v167
	v_mul_f32_e32 v71, v71, v167
	v_mul_f32_e32 v72, v72, v167
	v_mul_f32_e32 v73, v73, v167
	v_mul_f32_e32 v78, v78, v167
	v_mul_f32_e32 v79, v79, v167
	v_mul_f32_e32 v80, v80, v167
	v_mul_f32_e32 v81, v81, v167
	v_mul_f32_e32 v86, v86, v167
	v_mul_f32_e32 v87, v87, v167
	v_mul_f32_e32 v88, v88, v167
	v_mul_f32_e32 v89, v89, v167
	v_cvt_pk_bf16_f32 v62, v62, v63
	v_cvt_pk_bf16_f32 v63, v64, v65
	global_store_dwordx2 v48, v[62:63], s[24:25] offset:0
	v_cvt_pk_bf16_f32 v70, v70, v71
	v_cvt_pk_bf16_f32 v71, v72, v73
	global_store_dwordx2 v48, v[70:71], s[24:25] offset:32
	v_cvt_pk_bf16_f32 v78, v78, v79
	v_cvt_pk_bf16_f32 v79, v80, v81
	global_store_dwordx2 v48, v[78:79], s[24:25] offset:64
	v_cvt_pk_bf16_f32 v86, v86, v87
	v_cvt_pk_bf16_f32 v87, v88, v89
	global_store_dwordx2 v48, v[86:87], s[24:25] offset:96
	v_add_u32_e32 v48, 0x8000, v48
	s_waitcnt vmcnt(8)
	v_lshlrev_b32_e32 v58, 16, v218
	v_and_b32_e32 v59, 0xffff0000, v218
	v_lshlrev_b32_e32 v66, 16, v222
	v_and_b32_e32 v67, 0xffff0000, v222
	v_lshlrev_b32_e32 v60, 16, v219
	v_and_b32_e32 v61, 0xffff0000, v219
	v_lshlrev_b32_e32 v68, 16, v223
	v_and_b32_e32 v69, 0xffff0000, v223
	v_lshlrev_b32_e32 v62, 16, v220
	v_and_b32_e32 v63, 0xffff0000, v220
	v_lshlrev_b32_e32 v70, 16, v224
	v_and_b32_e32 v71, 0xffff0000, v224
	v_lshlrev_b32_e32 v64, 16, v221
	v_and_b32_e32 v65, 0xffff0000, v221
	v_lshlrev_b32_e32 v72, 16, v225
	v_and_b32_e32 v73, 0xffff0000, v225
	v_mul_f32_e32 v74, v58, v58
	v_mul_f32_e32 v75, v59, v59
	v_fmac_f32_e32 v74, v60, v60
	v_fmac_f32_e32 v75, v61, v61
	v_fmac_f32_e32 v74, v62, v62
	v_fmac_f32_e32 v75, v63, v63
	v_fmac_f32_e32 v74, v64, v64
	v_fmac_f32_e32 v75, v65, v65
	v_fmac_f32_e32 v74, v66, v66
	v_fmac_f32_e32 v75, v67, v67
	v_fmac_f32_e32 v74, v68, v68
	v_fmac_f32_e32 v75, v69, v69
	v_fmac_f32_e32 v74, v70, v70
	v_fmac_f32_e32 v75, v71, v71
	v_fmac_f32_e32 v74, v72, v72
	v_fmac_f32_e32 v75, v73, v73
	v_add_f32_e32 v74, v74, v75
	v_mov_b32_e32 v166, v74
	s_nop 1
	v_permlane16_swap_b32_e32 v74, v166
	v_add_f32_e32 v74, v74, v166
	v_mov_b32_e32 v166, v74
	s_nop 1
	v_permlane32_swap_b32_e32 v74, v166
	v_add_f32_e32 v74, v74, v166
	v_fmamk_f32 v74, v74, 0x3c800000, v209
	v_rsq_f32_e32 v76, v74
	s_nop 0
	v_mul_f32_e32 v76, 0x3e000000, v76
	v_mul_f32_e32 v58, v58, v76
	v_mul_f32_e32 v66, v66, v76
	v_mul_f32_e32 v59, v59, v76
	v_mul_f32_e32 v67, v67, v76
	v_mul_f32_e32 v60, v60, v76
	v_mul_f32_e32 v68, v68, v76
	v_mul_f32_e32 v61, v61, v76
	v_mul_f32_e32 v69, v69, v76
	v_mul_f32_e32 v62, v62, v76
	v_mul_f32_e32 v70, v70, v76
	v_mul_f32_e32 v63, v63, v76
	v_mul_f32_e32 v71, v71, v76
	v_mul_f32_e32 v64, v64, v76
	v_mul_f32_e32 v72, v72, v76
	v_mul_f32_e32 v65, v65, v76
	v_mul_f32_e32 v73, v73, v76
	v_mul_f32_e32 v58, v58, v26
	v_mul_f32_e32 v66, v66, v34
	v_mul_f32_e32 v59, v59, v27
	v_mul_f32_e32 v67, v67, v35
	v_mul_f32_e32 v60, v60, v28
	v_mul_f32_e32 v68, v68, v36
	v_mul_f32_e32 v61, v61, v29
	v_mul_f32_e32 v69, v69, v37
	v_mul_f32_e32 v62, v62, v30
	v_mul_f32_e32 v70, v70, v38
	v_mul_f32_e32 v63, v63, v31
	v_mul_f32_e32 v71, v71, v39
	v_mul_f32_e32 v64, v64, v32
	v_mul_f32_e32 v72, v72, v40
	v_mul_f32_e32 v65, v65, v33
	v_mul_f32_e32 v73, v73, v41
	v_mul_f32_e32 v78, v66, v234
	v_mul_f32_e32 v86, v58, v234
	v_mul_f32_e32 v79, v67, v235
	v_mul_f32_e32 v87, v59, v235
	v_mul_f32_e32 v80, v68, v236
	v_mul_f32_e32 v88, v60, v236
	v_mul_f32_e32 v81, v69, v237
	v_mul_f32_e32 v89, v61, v237
	v_mul_f32_e32 v82, v70, v238
	v_mul_f32_e32 v90, v62, v238
	v_mul_f32_e32 v83, v71, v239
	v_mul_f32_e32 v91, v63, v239
	v_mul_f32_e32 v84, v72, v240
	v_mul_f32_e32 v92, v64, v240
	v_mul_f32_e32 v85, v73, v241
	v_mul_f32_e32 v93, v65, v241
	v_fma_f32 v78, v58, v226, -v78
	v_fmac_f32_e32 v86, v66, v226
	v_fma_f32 v79, v59, v227, -v79
	v_fmac_f32_e32 v87, v67, v227
	v_fma_f32 v80, v60, v228, -v80
	v_fmac_f32_e32 v88, v68, v228
	v_fma_f32 v81, v61, v229, -v81
	v_fmac_f32_e32 v89, v69, v229
	v_fma_f32 v82, v62, v230, -v82
	v_fmac_f32_e32 v90, v70, v230
	v_fma_f32 v83, v63, v231, -v83
	v_fmac_f32_e32 v91, v71, v231
	v_fma_f32 v84, v64, v232, -v84
	v_fmac_f32_e32 v92, v72, v232
	v_fma_f32 v85, v65, v233, -v85
	v_fmac_f32_e32 v93, v73, v233
	v_cvt_pk_bf16_f32 v50, v78, v79
	v_cvt_pk_bf16_f32 v54, v86, v87
	v_cvt_pk_bf16_f32 v51, v80, v81
	v_cvt_pk_bf16_f32 v55, v88, v89
	v_cvt_pk_bf16_f32 v52, v82, v83
	v_cvt_pk_bf16_f32 v56, v90, v91
	v_cvt_pk_bf16_f32 v53, v84, v85
	v_cvt_pk_bf16_f32 v57, v92, v93
	v_lshrrev_b32_e32 v242, 6, v204
	v_sub_u32_e32 v243, 11, v242
	v_cmp_lt_u32_e32 vcc, 3, v242
	v_and_b32_e32 v244, 15, v204
	s_nop 1
	v_cndmask_b32_e32 v242, v242, v243, vcc
	v_lshl_or_b32 v242, v242, 4, v244
	v_lshrrev_b32_e32 v243, 1, v204
	v_and_b32_e32 v243, 24, v243
	v_and_b32_e64 v244, s2, 3
	v_lshlrev_b32_e32 v244, 9, v244
	v_and_b32_e64 v245, s2, -4
	v_lshl_add_u32 v245, v245, 5, v242
	v_mul_u32_u24_e32 v245, 0x3c00, v245
	v_add3_u32 v245, v245, v244, v243
	v_lshlrev_b32_e32 v244, 1, v244
	v_lshl_add_u32 v244, v242, 2, v244
	global_load_dword v198, v244, s[22:23]
	global_load_dword v199, v244, s[22:23] offset:512
	global_load_dwordx2 v[218:219], v245, s[10:11] offset:3072
	global_load_dwordx2 v[220:221], v245, s[10:11] offset:3104
	global_load_dwordx2 v[222:223], v245, s[10:11] offset:3136
	global_load_dwordx2 v[224:225], v245, s[10:11] offset:3168
	global_load_dwordx2 v[226:227], v245, s[10:11] offset:3200
	global_load_dwordx2 v[228:229], v245, s[10:11] offset:3232
	global_load_dwordx2 v[230:231], v245, s[10:11] offset:3264
	global_load_dwordx2 v[232:233], v245, s[10:11] offset:3296
	global_load_dwordx2 v[234:235], v245, s[10:11] offset:3328
	global_load_dwordx2 v[236:237], v245, s[10:11] offset:3360
	global_load_dwordx2 v[238:239], v245, s[10:11] offset:3392
	global_load_dwordx2 v[240:241], v245, s[10:11] offset:3424
	global_load_dwordx2 v[242:243], v245, s[10:11] offset:3456
	global_load_dwordx2 v[200:201], v245, s[10:11] offset:3520
	global_load_dwordx2 v[202:203], v245, s[10:11] offset:3552
	global_load_dwordx2 v[244:245], v245, s[10:11] offset:3488
	s_nop 1
	s_waitcnt lgkmcnt(13)
; #define LAS __attribute__((address_space(3)))
; #define MFMA16(a, b, c) __builtin_amdgcn_mfma_f32_16x16x32_bf16((a), (b), (c), 0, 0, 0)
; __device__ __forceinline__ void p2_block(LAS unsigned char* lds, const bf16_t* __restrict__ PROJ, bf16_t* __restrict__ ATT, bf16_t* __restrict__ SGU, const float* __restrict__ qn, const float* __restrict__ kn, ...
;     ...
;         for (int t = 0; t < 10; ++t) { const bf16x8 k0 = *(const LAS bf16x8*)(kbase + t * 16 * KS_STRIDE), k1 = *(const LAS bf16x8*)(kbase + t * 16 * KS_STRIDE + 64);
;             f32x4 z = (f32x4){0.f, 0.f, 0.f, 0.f}; z = MFMA16(k0, qf0, z); sc_[t] = MFMA16(k1, qf1, z); }
;         float mx = -1e30f;
; #pragma unroll
;         for (int t = 0; t < 10; ++t)
; #pragma unroll
;             for (int e = 0; e < 4; ++e) { const int kx = 16 * (t0 + t) + 4 * fq + e, d = kx - irow; const bool ok = (d >= 1) && (d <= 128) && (n > 0 || kx >= 128);
;                 const float v = ok ? sc_[t][e] : -1e30f; sc_[t][e] = v; mx = fmaxf(mx, v); }
;         mx = fmaxf(mx, __shfl_xor(mx, 16)); mx = fmaxf(mx, __shfl_xor(mx, 32)); mx = fmaxf(mx, sink);
;         float sum = 0.f;
; #pragma unroll
;         for (int t = 0; t < 10; ++t)
; #pragma unroll
;             for (int e = 0; e < 4; ++e) { const float p = __builtin_amdgcn_exp2f((sc_[t][e] - mx) * LOG2E); sc_[t][e] = p; sum += p; }
	v_mfma_f32_16x16x32_bf16 v[58:61], v[98:101], v[50:53], 0
	s_waitcnt lgkmcnt(12)
	v_mfma_f32_16x16x32_bf16 v[58:61], v[102:105], v[54:57], v[58:61]
	ds_read_b128 v[154:157], v45 offset:23040
	ds_read_b128 v[158:161], v45 offset:23104
	s_waitcnt lgkmcnt(13)
	v_mfma_f32_16x16x32_bf16 v[62:65], v[106:109], v[50:53], 0
	s_waitcnt lgkmcnt(12)
	v_mfma_f32_16x16x32_bf16 v[62:65], v[110:113], v[54:57], v[62:65]
	ds_read_b128 v[162:165], v45 offset:25344
	ds_read_b128 v[182:185], v45 offset:25408
	s_waitcnt lgkmcnt(13)
	v_mfma_f32_16x16x32_bf16 v[66:69], v[114:117], v[50:53], 0
	s_waitcnt lgkmcnt(12)
	v_mfma_f32_16x16x32_bf16 v[66:69], v[118:121], v[54:57], v[66:69]
	s_waitcnt lgkmcnt(11)
	v_mfma_f32_16x16x32_bf16 v[70:73], v[122:125], v[50:53], 0
	s_waitcnt lgkmcnt(10)
	v_mfma_f32_16x16x32_bf16 v[70:73], v[126:129], v[54:57], v[70:73]
	s_waitcnt lgkmcnt(9)
	v_mfma_f32_16x16x32_bf16 v[74:77], v[130:133], v[50:53], 0
	s_waitcnt lgkmcnt(8)
	v_mfma_f32_16x16x32_bf16 v[74:77], v[134:137], v[54:57], v[74:77]
	s_waitcnt lgkmcnt(7)
	v_mfma_f32_16x16x32_bf16 v[78:81], v[138:141], v[50:53], 0
	s_waitcnt lgkmcnt(6)
	v_mfma_f32_16x16x32_bf16 v[78:81], v[142:145], v[54:57], v[78:81]
	s_waitcnt lgkmcnt(5)
	v_mfma_f32_16x16x32_bf16 v[82:85], v[146:149], v[50:53], 0
	s_waitcnt lgkmcnt(4)
	v_mfma_f32_16x16x32_bf16 v[82:85], v[150:153], v[54:57], v[82:85]
	s_waitcnt lgkmcnt(3)
	v_mfma_f32_16x16x32_bf16 v[86:89], v[154:157], v[50:53], 0
	s_waitcnt lgkmcnt(2)
	v_mfma_f32_16x16x32_bf16 v[86:89], v[158:161], v[54:57], v[86:89]
	s_waitcnt lgkmcnt(1)
	v_mfma_f32_16x16x32_bf16 v[90:93], v[162:165], v[50:53], 0
	s_waitcnt lgkmcnt(0)
	v_mfma_f32_16x16x32_bf16 v[90:93], v[182:185], v[54:57], v[90:93]
	ds_read2_b64 v[98:101], v194 offset0:12 offset1:16
	ds_read2_b64 v[102:105], v195 offset0:12 offset1:16
	ds_read2_b64 v[106:109], v196 offset0:12 offset1:16
	ds_read2_b64 v[110:113], v197 offset0:12 offset1:16
	ds_read2_b64 v[114:117], v194 offset0:20 offset1:24
	ds_read2_b64 v[118:121], v195 offset0:20 offset1:24
	ds_read2_b64 v[122:125], v196 offset0:20 offset1:24
	ds_read2_b64 v[126:129], v197 offset0:20 offset1:24
	ds_read2_b64 v[130:133], v194 offset0:28 offset1:32
	ds_read2_b64 v[134:137], v195 offset0:28 offset1:32
	ds_read2_b64 v[138:141], v196 offset0:28 offset1:32
	ds_read2_b64 v[142:145], v197 offset0:28 offset1:32
	ds_read2_b64 v[146:149], v194 offset0:36 offset1:40
	ds_read2_b64 v[150:153], v195 offset0:36 offset1:40
	ds_read2_b64 v[154:157], v196 offset0:36 offset1:40
	s_nop 4
	v_cndmask_b32_e64 v58, v49, v58, s[48:49]
	v_cndmask_b32_e64 v59, v49, v59, s[50:51]
	v_cndmask_b32_e64 v60, v49, v60, s[52:53]
	v_cndmask_b32_e64 v61, v49, v61, s[26:27]
	v_cndmask_b32_e64 v62, v49, v62, s[28:29]
	v_cndmask_b32_e64 v63, v49, v63, s[28:29]
	v_cndmask_b32_e64 v64, v49, v64, s[28:29]
	v_cndmask_b32_e64 v65, v49, v65, s[28:29]
	v_cndmask_b32_e64 v66, v49, v66, s[28:29]
	v_cndmask_b32_e64 v67, v49, v67, s[28:29]
	v_cndmask_b32_e64 v68, v49, v68, s[28:29]
	v_cndmask_b32_e64 v69, v49, v69, s[28:29]
	v_cndmask_b32_e64 v70, v49, v70, s[28:29]
	v_cndmask_b32_e64 v71, v49, v71, s[28:29]
	v_cndmask_b32_e64 v72, v49, v72, s[28:29]
	v_cndmask_b32_e64 v73, v49, v73, s[28:29]
	v_cndmask_b32_e64 v74, v49, v74, s[28:29]
	v_cndmask_b32_e64 v75, v49, v75, s[28:29]
	v_cndmask_b32_e64 v76, v49, v76, s[28:29]
	v_cndmask_b32_e64 v77, v49, v77, s[28:29]
	v_cndmask_b32_e64 v90, v90, v49, s[40:41]
	v_cndmask_b32_e64 v91, v91, v49, s[42:43]
	v_cndmask_b32_e64 v92, v92, v49, s[44:45]
	v_cndmask_b32_e64 v93, v93, v49, s[46:47]
	v_max_f32_e32 v167, v58, v59
	v_max_f32_e32 v94, v60, v61
	v_max3_f32 v167, v167, v62, v63
	v_max3_f32 v94, v94, v64, v65
	v_max3_f32 v167, v167, v66, v67
	v_max3_f32 v94, v94, v68, v69
	v_max3_f32 v167, v167, v70, v71
	v_max3_f32 v94, v94, v72, v73
	v_max3_f32 v167, v167, v74, v75
	v_max3_f32 v94, v94, v76, v77
	v_max3_f32 v167, v167, v78, v79
	v_max3_f32 v94, v94, v80, v81
	v_max3_f32 v167, v167, v82, v83
	v_max3_f32 v94, v94, v84, v85
	v_max3_f32 v167, v167, v86, v87
	v_max3_f32 v94, v94, v88, v89
	v_max3_f32 v167, v167, v90, v91
	v_max3_f32 v94, v94, v92, v93
	v_max_f32_e32 v167, v167, v94
	v_mov_b32_e32 v166, v167
	s_nop 1
	v_permlane16_swap_b32_e32 v167, v166
	v_max_f32_e32 v167, v167, v166
	v_mov_b32_e32 v166, v167
	s_nop 1
	v_permlane32_swap_b32_e32 v167, v166
	v_max_f32_e32 v167, v167, v166
	v_max_f32_e32 v167, v167, v42
	v_mul_f32_e32 v94, 0xbfb8aa3b, v167
	v_fmamk_f32 v58, v58, 0x3fb8aa3b, v94
	v_fmamk_f32 v59, v59, 0x3fb8aa3b, v94
	v_fmamk_f32 v60, v60, 0x3fb8aa3b, v94
	v_fmamk_f32 v61, v61, 0x3fb8aa3b, v94
	v_fmamk_f32 v62, v62, 0x3fb8aa3b, v94
	v_fmamk_f32 v63, v63, 0x3fb8aa3b, v94
	v_fmamk_f32 v64, v64, 0x3fb8aa3b, v94
	v_fmamk_f32 v65, v65, 0x3fb8aa3b, v94
	v_fmamk_f32 v66, v66, 0x3fb8aa3b, v94
	v_fmamk_f32 v67, v67, 0x3fb8aa3b, v94
	v_fmamk_f32 v68, v68, 0x3fb8aa3b, v94
	v_fmamk_f32 v69, v69, 0x3fb8aa3b, v94
	v_fmamk_f32 v70, v70, 0x3fb8aa3b, v94
	v_fmamk_f32 v71, v71, 0x3fb8aa3b, v94
	v_fmamk_f32 v72, v72, 0x3fb8aa3b, v94
	v_fmamk_f32 v73, v73, 0x3fb8aa3b, v94
	v_fmamk_f32 v74, v74, 0x3fb8aa3b, v94
	v_fmamk_f32 v75, v75, 0x3fb8aa3b, v94
	v_fmamk_f32 v76, v76, 0x3fb8aa3b, v94
	v_fmamk_f32 v77, v77, 0x3fb8aa3b, v94
	v_fmamk_f32 v78, v78, 0x3fb8aa3b, v94
	v_fmamk_f32 v79, v79, 0x3fb8aa3b, v94
	v_fmamk_f32 v80, v80, 0x3fb8aa3b, v94
	v_fmamk_f32 v81, v81, 0x3fb8aa3b, v94
	v_fmamk_f32 v82, v82, 0x3fb8aa3b, v94
	v_fmamk_f32 v83, v83, 0x3fb8aa3b, v94
	v_fmamk_f32 v84, v84, 0x3fb8aa3b, v94
	v_fmamk_f32 v85, v85, 0x3fb8aa3b, v94
	v_fmamk_f32 v86, v86, 0x3fb8aa3b, v94
	v_fmamk_f32 v87, v87, 0x3fb8aa3b, v94
	v_fmamk_f32 v88, v88, 0x3fb8aa3b, v94
	v_fmamk_f32 v89, v89, 0x3fb8aa3b, v94
; __device__ __forceinline__ unsigned cvt_pk_bf16(float lo, float hi) { unsigned r; asm volatile("v_cvt_pk_bf16_f32 %0, %1, %2" : "=v"(r) : "v"(lo), "v"(hi)); return r; }
; #define LAS __attribute__((address_space(3)))
; #define MFMA16(a, b, c) __builtin_amdgcn_mfma_f32_16x16x32_bf16((a), (b), (c), 0, 0, 0)
; __device__ __forceinline__ void p2_block(LAS unsigned char* lds, const bf16_t* __restrict__ PROJ, bf16_t* __restrict__ ATT, bf16_t* __restrict__ SGU, const float* __restrict__ qn, const float* __restrict__ kn, ...
;     ...
;             for (int e = 0; e < 4; ++e) { const float p = __builtin_amdgcn_exp2f((sc_[t][e] - mx) * LOG2E); sc_[t][e] = p; sum += p; }
;         sum += __shfl_xor(sum, 16); sum += __shfl_xor(sum, 32);
;         const float inv = 1.0f / (sum + __builtin_amdgcn_exp2f((sink - mx) * LOG2E));
;         f32x4 o[4];
; #pragma unroll
;         for (int dt = 0; dt < 4; ++dt) o[dt] = (f32x4){0.f, 0.f, 0.f, 0.f};
; #pragma unroll
;         for (int j = 0; j < 5; ++j) {
;             u32x4 pw; pw.x = cvt_pk_bf16(sc_[2 * j][0], sc_[2 * j][1]); pw.y = cvt_pk_bf16(sc_[2 * j][2], sc_[2 * j][3]); pw.z = cvt_pk_bf16(sc_[2 * j + 1][0], sc_[2 * j + 1][1]); pw.w = cvt_pk_bf16(sc_[2 * j + 1][2], sc_[2 * j + 1][3]);
;             const bf16x8 pf = __builtin_bit_cast(bf16x8, pw);
; #pragma unroll
;             for (int dt = 0; dt < 4; ++dt) { const LAS unsigned char* vb = VT + (16 * dt + fr) * VT_STRIDE + (16 * (t0 + 2 * j) + 4 * fq) * 2;
;                 const u32x2 va = *(const LAS u32x2*)vb, vc = *(const LAS u32x2*)(vb + 32); u32x4 vw; vw.x = va.x; vw.y = va.y; vw.z = vc.x; vw.w = vc.y;
;                 o[dt] = MFMA16(__builtin_bit_cast(bf16x8, vw), pf, o[dt]); }
;         }
;         bf16_t* op = ATT + grow * 1024 + hq * 64 + 4 * fq;
; #pragma unroll
;         for (int dt = 0; dt < 4; ++dt) { u32x2 ow; ow.x = cvt_pk_bf16(o[dt][0] * inv, o[dt][1] * inv); ow.y = cvt_pk_bf16(o[dt][2] * inv, o[dt][3] * inv); *(u32x2*)(op + 16 * dt) = ow; }
	v_fmamk_f32 v90, v90, 0x3fb8aa3b, v94
	v_fmamk_f32 v91, v91, 0x3fb8aa3b, v94
	v_fmamk_f32 v92, v92, 0x3fb8aa3b, v94
	v_fmamk_f32 v93, v93, 0x3fb8aa3b, v94
	v_exp_f32_e32 v58, v58
	v_exp_f32_e32 v59, v59
	v_exp_f32_e32 v60, v60
	v_exp_f32_e32 v61, v61
	v_exp_f32_e32 v62, v62
	v_exp_f32_e32 v63, v63
	v_exp_f32_e32 v64, v64
	v_exp_f32_e32 v65, v65
	v_exp_f32_e32 v66, v66
	v_exp_f32_e32 v67, v67
	v_exp_f32_e32 v68, v68
	v_exp_f32_e32 v69, v69
	v_exp_f32_e32 v70, v70
	v_exp_f32_e32 v71, v71
	v_exp_f32_e32 v72, v72
	v_exp_f32_e32 v73, v73
	v_exp_f32_e32 v74, v74
	v_exp_f32_e32 v75, v75
	v_exp_f32_e32 v76, v76
	v_exp_f32_e32 v77, v77
	v_exp_f32_e32 v78, v78
	v_exp_f32_e32 v79, v79
	v_exp_f32_e32 v80, v80
	v_exp_f32_e32 v81, v81
	v_exp_f32_e32 v82, v82
	v_exp_f32_e32 v83, v83
	v_exp_f32_e32 v84, v84
	v_exp_f32_e32 v85, v85
	v_exp_f32_e32 v86, v86
	v_exp_f32_e32 v87, v87
	v_exp_f32_e32 v88, v88
	v_exp_f32_e32 v89, v89
	v_exp_f32_e32 v90, v90
	v_exp_f32_e32 v91, v91
	v_exp_f32_e32 v92, v92
	v_exp_f32_e32 v93, v93
	v_fmamk_f32 v95, v42, 0x3fb8aa3b, v94
	v_exp_f32_e32 v95, v95
	v_add_f32_e32 v167, v58, v59
	v_add_f32_e32 v94, v60, v61
	v_add_f32_e32 v167, v167, v62
	v_add_f32_e32 v94, v94, v63
	v_add_f32_e32 v167, v167, v64
	v_add_f32_e32 v94, v94, v65
	v_add_f32_e32 v167, v167, v66
	v_add_f32_e32 v94, v94, v67
	v_add_f32_e32 v167, v167, v68
	v_add_f32_e32 v94, v94, v69
	v_add_f32_e32 v167, v167, v70
	v_add_f32_e32 v94, v94, v71
	v_add_f32_e32 v167, v167, v72
	v_add_f32_e32 v94, v94, v73
	v_add_f32_e32 v167, v167, v74
	v_add_f32_e32 v94, v94, v75
	v_add_f32_e32 v167, v167, v76
	v_add_f32_e32 v94, v94, v77
	v_add_f32_e32 v167, v167, v78
	v_add_f32_e32 v94, v94, v79
	v_add_f32_e32 v167, v167, v80
	v_add_f32_e32 v94, v94, v81
	v_add_f32_e32 v167, v167, v82
	v_add_f32_e32 v94, v94, v83
	v_add_f32_e32 v167, v167, v84
	v_add_f32_e32 v94, v94, v85
	v_add_f32_e32 v167, v167, v86
	v_add_f32_e32 v94, v94, v87
	v_add_f32_e32 v167, v167, v88
	v_add_f32_e32 v94, v94, v89
	v_add_f32_e32 v167, v167, v90
	v_add_f32_e32 v94, v94, v91
	v_add_f32_e32 v167, v167, v92
	v_add_f32_e32 v94, v94, v93
	v_add_f32_e32 v167, v167, v94
	v_mov_b32_e32 v166, v167
	s_nop 1
	v_permlane16_swap_b32_e32 v167, v166
	v_add_f32_e32 v167, v167, v166
	v_mov_b32_e32 v166, v167
	s_nop 1
	v_permlane32_swap_b32_e32 v167, v166
	v_add_f32_e32 v167, v167, v166
	v_add_f32_e32 v167, v167, v95
	v_rcp_f32_e32 v167, v167
	v_mov_b32_e32 v94, 0
	v_mov_b32_e32 v95, 0
	v_mov_b32_e32 v96, 0
	v_mov_b32_e32 v97, 0
	v_cvt_pk_bf16_f32 v58, v58, v59
	v_cvt_pk_bf16_f32 v59, v60, v61
	v_cvt_pk_bf16_f32 v60, v62, v63
	v_cvt_pk_bf16_f32 v61, v64, v65
	v_cvt_pk_bf16_f32 v66, v66, v67
	v_cvt_pk_bf16_f32 v67, v68, v69
	v_cvt_pk_bf16_f32 v68, v70, v71
	v_cvt_pk_bf16_f32 v69, v72, v73
	v_cvt_pk_bf16_f32 v74, v74, v75
	v_cvt_pk_bf16_f32 v75, v76, v77
	v_cvt_pk_bf16_f32 v76, v78, v79
	v_cvt_pk_bf16_f32 v77, v80, v81
	v_cvt_pk_bf16_f32 v82, v82, v83
	v_cvt_pk_bf16_f32 v83, v84, v85
	v_cvt_pk_bf16_f32 v84, v86, v87
	v_cvt_pk_bf16_f32 v85, v88, v89
	v_cvt_pk_bf16_f32 v90, v90, v91
	v_cvt_pk_bf16_f32 v91, v92, v93
	v_cvt_pk_bf16_f32 v92, v94, v95
	v_cvt_pk_bf16_f32 v93, v96, v97
	s_nop 1
	s_waitcnt lgkmcnt(14)
	v_mfma_f32_16x16x32_bf16 v[62:65], v[98:101], v[58:61], 0
	ds_read2_b64 v[158:161], v197 offset0:36 offset1:40
	s_waitcnt lgkmcnt(14)
	v_mfma_f32_16x16x32_bf16 v[70:73], v[102:105], v[58:61], 0
	ds_read2_b64 v[162:165], v194 offset0:44 offset1:48
	s_waitcnt lgkmcnt(14)
	v_mfma_f32_16x16x32_bf16 v[78:81], v[106:109], v[58:61], 0
	ds_read2_b64 v[182:185], v195 offset0:44 offset1:48
	s_waitcnt lgkmcnt(14)
	v_mfma_f32_16x16x32_bf16 v[86:89], v[110:113], v[58:61], 0
	ds_read2_b64 v[186:189], v196 offset0:44 offset1:48
	s_waitcnt lgkmcnt(14)
	v_mfma_f32_16x16x32_bf16 v[62:65], v[114:117], v[66:69], v[62:65]
	ds_read2_b64 v[190:193], v197 offset0:44 offset1:48
	s_waitcnt lgkmcnt(14)
	v_mfma_f32_16x16x32_bf16 v[70:73], v[118:121], v[66:69], v[70:73]
	s_waitcnt lgkmcnt(13)
	v_mfma_f32_16x16x32_bf16 v[78:81], v[122:125], v[66:69], v[78:81]
	s_waitcnt lgkmcnt(12)
	v_mfma_f32_16x16x32_bf16 v[86:89], v[126:129], v[66:69], v[86:89]
	s_waitcnt lgkmcnt(11)
	v_mfma_f32_16x16x32_bf16 v[62:65], v[130:133], v[74:77], v[62:65]
	s_waitcnt lgkmcnt(10)
	v_mfma_f32_16x16x32_bf16 v[70:73], v[134:137], v[74:77], v[70:73]
	s_waitcnt lgkmcnt(9)
	v_mfma_f32_16x16x32_bf16 v[78:81], v[138:141], v[74:77], v[78:81]
	s_waitcnt lgkmcnt(8)
	v_mfma_f32_16x16x32_bf16 v[86:89], v[142:145], v[74:77], v[86:89]
	s_waitcnt lgkmcnt(7)
	v_mfma_f32_16x16x32_bf16 v[62:65], v[146:149], v[82:85], v[62:65]
	s_waitcnt lgkmcnt(6)
	v_mfma_f32_16x16x32_bf16 v[70:73], v[150:153], v[82:85], v[70:73]
	s_waitcnt lgkmcnt(5)
	v_mfma_f32_16x16x32_bf16 v[78:81], v[154:157], v[82:85], v[78:81]
	s_waitcnt lgkmcnt(4)
	v_mfma_f32_16x16x32_bf16 v[86:89], v[158:161], v[82:85], v[86:89]
	s_waitcnt lgkmcnt(3)
	v_mfma_f32_16x16x32_bf16 v[62:65], v[162:165], v[90:93], v[62:65]
	s_waitcnt lgkmcnt(2)
	v_mfma_f32_16x16x32_bf16 v[70:73], v[182:185], v[90:93], v[70:73]
	s_waitcnt lgkmcnt(1)
	v_mfma_f32_16x16x32_bf16 v[78:81], v[186:189], v[90:93], v[78:81]
	s_waitcnt lgkmcnt(0)
	v_mfma_f32_16x16x32_bf16 v[86:89], v[190:193], v[90:93], v[86:89]
	s_nop 7
	v_mul_f32_e32 v62, v62, v167
	v_mul_f32_e32 v63, v63, v167
	v_mul_f32_e32 v64, v64, v167
	v_mul_f32_e32 v65, v65, v167
	v_mul_f32_e32 v70, v70, v167
	v_mul_f32_e32 v71, v71, v167
	v_mul_f32_e32 v72, v72, v167
	v_mul_f32_e32 v73, v73, v167
	v_mul_f32_e32 v78, v78, v167
	v_mul_f32_e32 v79, v79, v167
	v_mul_f32_e32 v80, v80, v167
	v_mul_f32_e32 v81, v81, v167
	v_mul_f32_e32 v86, v86, v167
	v_mul_f32_e32 v87, v87, v167
	v_mul_f32_e32 v88, v88, v167
	v_mul_f32_e32 v89, v89, v167
	v_cvt_pk_bf16_f32 v62, v62, v63
	v_cvt_pk_bf16_f32 v63, v64, v65
	global_store_dwordx2 v48, v[62:63], s[24:25] offset:0
	v_cvt_pk_bf16_f32 v70, v70, v71
	v_cvt_pk_bf16_f32 v71, v72, v73
	global_store_dwordx2 v48, v[70:71], s[24:25] offset:32
	v_cvt_pk_bf16_f32 v78, v78, v79
	v_cvt_pk_bf16_f32 v79, v80, v81
	global_store_dwordx2 v48, v[78:79], s[24:25] offset:64
	v_cvt_pk_bf16_f32 v86, v86, v87
	v_cvt_pk_bf16_f32 v87, v88, v89
	global_store_dwordx2 v48, v[86:87], s[24:25] offset:96
	v_add_u32_e32 v48, 0x8000, v48
	s_branch .Latt_done
; __device__ __forceinline__ unsigned cvt_pk_bf16(float lo, float hi) { unsigned r; asm volatile("v_cvt_pk_bf16_f32 %0, %1, %2" : "=v"(r) : "v"(lo), "v"(hi)); return r; }
; #define LAS __attribute__((address_space(3)))
; #define MFMA16(a, b, c) __builtin_amdgcn_mfma_f32_16x16x32_bf16((a), (b), (c), 0, 0, 0)
; __device__ __forceinline__ void p2_block(LAS unsigned char* lds, const bf16_t* __restrict__ PROJ, bf16_t* __restrict__ ATT, bf16_t* __restrict__ SGU, const float* __restrict__ qn, const float* __restrict__ kn, ...
;     ...
;         const int gg = 2 * kvh + gi, irow = 16 * w + fr, nks = (w >> 1) + 1;
;         const LAS unsigned char* VNT = lds + (gi ? VN_OFF1 : VN_OFF0);
;         f32x4 acc[8];
; #pragma unroll
;         for (int dt = 0; dt < 8; ++dt) acc[dt] = (f32x4){0.f, 0.f, 0.f, 0.f};
;         const float* wrow = wsp + (size_t)gg * 16384 + irow * 128 + 8 * fq;
; #pragma unroll
;         for (int ks = 0; ks < 4; ++ks) if (ks < nks) {
;             const f32x4 wa = *(const f32x4*)(wrow + 32 * ks), wb = *(const f32x4*)(wrow + 32 * ks + 4);
;             const int j0 = 32 * ks + 8 * fq; float wv[8];
; #pragma unroll
;             for (int e = 0; e < 4; ++e) { wv[e] = (j0 + e <= irow) ? wa[e] : 0.f; wv[4 + e] = (j0 + 4 + e <= irow) ? wb[e] : 0.f; }
;             u32x4 ww; ww.x = cvt_pk_bf16(wv[0], wv[1]); ww.y = cvt_pk_bf16(wv[2], wv[3]); ww.z = cvt_pk_bf16(wv[4], wv[5]); ww.w = cvt_pk_bf16(wv[6], wv[7]);
;             const bf16x8 wf = __builtin_bit_cast(bf16x8, ww);
; #pragma unroll
;             for (int dt = 0; dt < 8; ++dt) { const bf16x8 af = *(const LAS bf16x8*)(VNT + (16 * dt + fr) * VN_STRIDE + (32 * ks + 8 * fq) * 2); acc[dt] = MFMA16(af, wf, acc[dt]); }
;         }
;         const float bias = bsp[gg * 128 + irow];
;         const size_t grow = (size_t)b * pg8::SEQ + n * 128 + irow;
;         const bf16_t* up = PROJ + grow * pg8::IN_W + pg8::C_U + gg * 128 + 4 * fq; bf16_t* op = SGU + grow * 1024 + gg * 128 + 4 * fq;
.Latt_done:
	v_readfirstlane_b32 s16, v204
	v_and_b32_e32 v184, 15, v204
	v_bfe_u32 v185, v204, 4, 2
	s_and_b32 s24, s2, 3
	s_lshr_b32 s16, s16, 6
	s_sub_i32 s17, 11, s16
	s_cmp_gt_u32 s16, 3
	s_cselect_b32 s16, s17, s16
	s_lshl_b32 s4, s24, 17
	s_lshr_b32 s17, s16, 1
	v_lshl_add_u32 v191, s16, 4, v184
	v_lshlrev_b32_e32 v186, 9, v191
	v_lshl_add_u32 v186, v185, 5, v186
	v_add_u32_e32 v186, s4, v186
	v_add_u32_e32 v187, 0x10000, v186
	global_load_dwordx4 v[98:101], v186, s[20:21] offset:0
	global_load_dwordx4 v[102:105], v186, s[20:21] offset:16
	global_load_dwordx4 v[106:109], v186, s[20:21] offset:128
	global_load_dwordx4 v[110:113], v186, s[20:21] offset:144
	global_load_dwordx4 v[114:117], v186, s[20:21] offset:256
	global_load_dwordx4 v[118:121], v186, s[20:21] offset:272
	global_load_dwordx4 v[122:125], v186, s[20:21] offset:384
	global_load_dwordx4 v[126:129], v186, s[20:21] offset:400
	global_load_dwordx4 v[66:69], v187, s[20:21] offset:0
	global_load_dwordx4 v[70:73], v187, s[20:21] offset:16
	global_load_dwordx4 v[74:77], v187, s[20:21] offset:128
	global_load_dwordx4 v[78:81], v187, s[20:21] offset:144
	global_load_dwordx4 v[82:85], v187, s[20:21] offset:256
	global_load_dwordx4 v[86:89], v187, s[20:21] offset:272
	global_load_dwordx4 v[90:93], v187, s[20:21] offset:384
	global_load_dwordx4 v[94:97], v187, s[20:21] offset:400
	v_mul_u32_u24_e32 v194, 0x110, v184
	v_lshl_add_u32 v194, v185, 4, v194
	v_add_u32_e32 v194, 0x11800, v194
	v_lshlrev_b32_e32 v195, 3, v185
	v_sub_u32_e32 v195, v191, v195
	s_and_b32 s25, s2, -4
	s_lshl_b32 s25, s25, 5
	v_add_u32_e32 v192, s25, v191
	s_lshl_b32 s4, s24, 9
	v_lshl_add_u32 v193, v185, 3, s4
	v_lshl_add_u32 v182, v192, 11, v193
	s_cmp_eq_u32 s17, 0
	s_cbranch_scc1 .Lsgu_n1
	s_cmp_eq_u32 s17, 1
	s_cbranch_scc1 .Lsgu_n2
	s_cmp_eq_u32 s17, 2
	s_cbranch_scc1 .Lsgu_n3
	s_branch .Lsgu_n4

; __device__ __forceinline__ void tr_item(const float* __restrict__ W, int K, int N, bf16_t* WT, const float* __restrict__ kscale, int rowmode, int item, int lane) {
;     const int nblk = N >> 5, kb = item / nblk, nb = item - kb * nblk;
;     const int c = lane >> 3, q = lane & 7, k0 = kb * 64 + c * 8, n0 = nb * 32 + q * 4;
;     f32x4 v[8];
; #pragma unroll
;     for (int i = 0; i < 8; ++i) v[i] = __builtin_nontemporal_load((const f32x4*)(W + (size_t)(k0 + i) * N + n0));
;     if (kscale) { const f32x4 s0 = *(const f32x4*)(kscale + k0), s1 = *(const f32x4*)(kscale + k0 + 4);
; #pragma unroll
;         for (int i = 0; i < 4; ++i) { v[i] = v[i] * s0[i]; v[4 + i] = v[4 + i] * s1[i]; } }
;     int drow;
;     if (rowmode == 0) drow = n0;
;     else if (rowmode == 3) { const int g = n0 - pg8::C_GA; drow = g < 0 ? n0 : pg8::C_GA + (((g & 2047) >> 7) << 8) + ((g >> 11) << 7) + (g & 127); }
;     else drow = ((n0 >> 7) << 8) + (n0 & 127) + (rowmode == 2 ? 128 : 0);
; #pragma unroll
;     for (int e = 0; e < 4; ++e) { u32x4 o; o.x = cvt_pk_bf16(v[0][e], v[1][e]); o.y = cvt_pk_bf16(v[2][e], v[3][e]); o.z = cvt_pk_bf16(v[4][e], v[5][e]); o.w = cvt_pk_bf16(v[6][e], v[7][e]);
;         pg8::st16_wt(WT + (size_t)(drow + e) * K + k0, o); }
;     ...
;     for (int mi = 0; mi < 7 * DEPTH; ++mi) {
;         if (!((mask >> mi) & 1u)) continue;
;         const int l = mi / 7, kind = mi - 7 * l;
;         const float* W; const float* ks = nullptr; bf16_t* WT; int K, N, rm = 0;
;         if (kind == 0)      { W = a.in[2] + (size_t)l * 2048 * 7680;  K = 2048; N = 7680; WT = (bf16_t*)(ws + WS_WIN + l * SZ_WIN); ks = a.in[1] + l * 2048; rm = 3; }
;         else if (kind == 1) { W = a.in[10] + (size_t)l * 1024 * 2048; K = 1024; N = 2048; WT = (bf16_t*)(ws + WS_WA + l * SZ_WA); }
;         else if (kind == 2) { W = a.in[11] + (size_t)l * 1024 * 2048; K = 1024; N = 2048; WT = (bf16_t*)(ws + WS_WB + l * SZ_WB); }
;         else if (kind == 3) { W = a.in[12] + (size_t)l * 2048 * 2048; K = 2048; N = 2048; WT = (bf16_t*)(ws + WS_WO + l * SZ_WO); }
;         else if (kind == 4) { W = a.in[14] + (size_t)l * 2048 * 5632; K = 2048; N = 5632; WT = (bf16_t*)(ws + WS_WGU + l * SZ_WGU); ks = a.in[13] + l * 2048; rm = 1; }
;         else if (kind == 5) { W = a.in[15] + (size_t)l * 2048 * 5632; K = 2048; N = 5632; WT = (bf16_t*)(ws + WS_WGU + l * SZ_WGU); ks = a.in[13] + l * 2048; rm = 2; }
.LBB0_400:
	s_or_b64 exec, exec, s[0:1]
	s_cmpk_lg_u32 s3, 0x100
	s_cbranch_scc1 .Lcv_skip_2
	v_readfirstlane_b32 vcc_lo, v204
	s_nop 3
	s_lshr_b32 vcc_lo, vcc_lo, 6
	s_cmp_eq_u32 vcc_lo, 0
	s_cbranch_scc1 .Lcv_skip_2
	s_lshr_b32 m0, s85, 5
	v_subrev_u32_e32 v106, 64, v204
	v_mov_b32_e32 v107, m0
	v_lshlrev_b32_e32 v107, 8, v107
	v_mov_b32_e32 v108, v106
	v_lshrrev_b32_e32 v109, 3, v108
	v_add_u32_e32 v109, v109, v107
	v_mul_u32_u24_e32 v109, 0x800, v109
	v_and_b32_e32 v108, 7, v108
	v_lshl_add_u32 v109, v108, 6, v109
	v_add_u32_e32 v108, 448, v106
	v_lshrrev_b32_e32 v110, 3, v108
	v_add_u32_e32 v110, v110, v107
	v_mul_u32_u24_e32 v110, 0x800, v110
	v_and_b32_e32 v108, 7, v108
	v_lshl_add_u32 v110, v108, 6, v110
	v_add_u32_e32 v108, 896, v106
	v_lshrrev_b32_e32 v111, 3, v108
	v_add_u32_e32 v111, v111, v107
	v_mul_u32_u24_e32 v111, 0x800, v111
	v_and_b32_e32 v108, 7, v108
	v_lshl_add_u32 v111, v108, 6, v111
	v_add_u32_e32 v108, 1344, v106
	v_lshrrev_b32_e32 v112, 3, v108
	v_add_u32_e32 v112, v112, v107
	v_mul_u32_u24_e32 v112, 0x800, v112
	v_and_b32_e32 v108, 7, v108
	v_lshl_add_u32 v112, v108, 6, v112
	v_add_u32_e32 v108, 1792, v106
	v_and_b32_e32 v108, 0x7ff, v108
	v_lshrrev_b32_e32 v113, 3, v108
	v_add_u32_e32 v113, v113, v107
	v_mul_u32_u24_e32 v113, 0x800, v113
	v_and_b32_e32 v108, 7, v108
	v_lshl_add_u32 v113, v108, 6, v113
	v_readlane_b32 vcc_lo, v250, 36
	v_readlane_b32 vcc_hi, v250, 37
	s_nop 3
	s_add_u32 vcc_lo, vcc_lo, 0x3dc0000
	s_addc_u32 vcc_hi, vcc_hi, 0
	s_cmp_lg_u32 s64, 0
	s_cselect_b32 m0, 0x400000, 0
	s_add_u32 vcc_lo, vcc_lo, m0
	s_addc_u32 vcc_hi, vcc_hi, 0
	global_load_dword v120, v109, vcc
	global_load_dword v121, v110, vcc
	global_load_dword v122, v111, vcc
	global_load_dword v123, v112, vcc
	global_load_dword v124, v113, vcc
	s_cmp_lg_u32 s64, 0
	s_cbranch_scc1 .Lcv_pfwait_2
	v_and_b32_e32 v106, 63, v204
	v_lshrrev_b32_e32 v107, 3, v106
	v_and_b32_e32 v108, 7, v106
	v_readfirstlane_b32 vcc_lo, v204
	s_nop 3
	s_lshr_b32 vcc_lo, vcc_lo, 6
	s_mul_i32 vcc_hi, s85, 7
	s_add_i32 vcc_lo, vcc_lo, vcc_hi
	s_add_i32 vcc_lo, vcc_lo, -1
	s_add_i32 vcc_lo, vcc_lo, 1792
	s_cmp_ge_u32 vcc_lo, 3520
	s_cbranch_scc1 .Lcv_2_0_n0
	s_sub_u32 vcc_lo, vcc_lo, 0
	v_mov_b32_e32 v113, vcc_lo
	v_mul_u32_u24_e32 v109, 0x5d18, v113
	v_lshrrev_b32_e32 v109, 22, v109
	v_mul_u32_u24_e32 v110, 0xb0, v109
	v_sub_u32_e32 v110, v113, v110
	v_lshlrev_b32_e32 v109, 6, v109
	v_lshl_add_u32 v109, v107, 3, v109
	v_lshlrev_b32_e32 v110, 5, v110
	v_lshl_add_u32 v110, v108, 2, v110
	v_mul_u32_u24_e32 v111, 0x5800, v109
	v_lshl_add_u32 v111, v110, 2, v111
	v_lshrrev_b32_e32 v112, 7, v110
	v_lshlrev_b32_e32 v112, 8, v112
	v_and_b32_e32 v113, 0x7f, v110
	v_add_u32_e32 v112, v112, v113
	v_lshlrev_b32_e32 v112, 12, v112
	v_lshl_add_u32 v112, v109, 1, v112
	v_lshlrev_b32_e32 v113, 2, v109
	v_readlane_b32 vcc_lo, v250, 28
	v_readlane_b32 vcc_hi, v250, 29
	s_nop 4
	global_load_dwordx4 v[98:101], v113, vcc
	global_load_dwordx4 v[102:105], v113, vcc offset:16
	v_readlane_b32 vcc_lo, v250, 30
	v_readlane_b32 vcc_hi, v250, 31
	s_nop 4
	global_load_dwordx4 v[66:69], v111, vcc nt
	v_add_u32_e32 v111, 0x5800, v111
	global_load_dwordx4 v[70:73], v111, vcc nt
	v_add_u32_e32 v111, 0x5800, v111
	global_load_dwordx4 v[74:77], v111, vcc nt
	v_add_u32_e32 v111, 0x5800, v111
	global_load_dwordx4 v[78:81], v111, vcc nt
	v_add_u32_e32 v111, 0x5800, v111
	global_load_dwordx4 v[82:85], v111, vcc nt
	v_add_u32_e32 v111, 0x5800, v111
	global_load_dwordx4 v[86:89], v111, vcc nt
	v_add_u32_e32 v111, 0x5800, v111
	global_load_dwordx4 v[90:93], v111, vcc nt
	v_add_u32_e32 v111, 0x5800, v111
	global_load_dwordx4 v[94:97], v111, vcc nt
	v_readlane_b32 vcc_lo, v250, 36
	v_readlane_b32 vcc_hi, v250, 37
	s_nop 3
	s_add_u32 vcc_lo, vcc_lo, 0x5dc0000
	s_addc_u32 vcc_hi, vcc_hi, 0
	s_waitcnt vmcnt(0)
	v_mul_f32_e32 v66, v66, v98
	v_mul_f32_e32 v67, v67, v98
	v_mul_f32_e32 v68, v68, v98
	v_mul_f32_e32 v69, v69, v98
	v_mul_f32_e32 v70, v70, v99
	v_mul_f32_e32 v71, v71, v99
	v_mul_f32_e32 v72, v72, v99
	v_mul_f32_e32 v73, v73, v99
	v_mul_f32_e32 v74, v74, v100
	v_mul_f32_e32 v75, v75, v100
	v_mul_f32_e32 v76, v76, v100
	v_mul_f32_e32 v77, v77, v100
	v_mul_f32_e32 v78, v78, v101
	v_mul_f32_e32 v79, v79, v101
	v_mul_f32_e32 v80, v80, v101
	v_mul_f32_e32 v81, v81, v101
	v_mul_f32_e32 v82, v82, v102
	v_mul_f32_e32 v83, v83, v102
	v_mul_f32_e32 v84, v84, v102
	v_mul_f32_e32 v85, v85, v102
	v_mul_f32_e32 v86, v86, v103
	v_mul_f32_e32 v87, v87, v103
	v_mul_f32_e32 v88, v88, v103
	v_mul_f32_e32 v89, v89, v103
	v_mul_f32_e32 v90, v90, v104
	v_mul_f32_e32 v91, v91, v104
	v_mul_f32_e32 v92, v92, v104
	v_mul_f32_e32 v93, v93, v104
	v_mul_f32_e32 v94, v94, v105
	v_mul_f32_e32 v95, v95, v105
	v_mul_f32_e32 v96, v96, v105
	v_mul_f32_e32 v97, v97, v105
	v_cvt_pk_bf16_f32 v114, v66, v70
	v_cvt_pk_bf16_f32 v115, v74, v78
	v_cvt_pk_bf16_f32 v116, v82, v86
	v_cvt_pk_bf16_f32 v117, v90, v94
	v_cvt_pk_bf16_f32 v118, v67, v71
	v_cvt_pk_bf16_f32 v119, v75, v79
	v_cvt_pk_bf16_f32 v120, v83, v87
	v_cvt_pk_bf16_f32 v121, v91, v95
	v_cvt_pk_bf16_f32 v122, v68, v72
	v_cvt_pk_bf16_f32 v123, v76, v80
	v_cvt_pk_bf16_f32 v124, v84, v88
	v_cvt_pk_bf16_f32 v125, v92, v96
	v_cvt_pk_bf16_f32 v126, v69, v73
	v_cvt_pk_bf16_f32 v127, v77, v81
	v_cvt_pk_bf16_f32 v128, v85, v89
	v_cvt_pk_bf16_f32 v129, v93, v97
	global_store_dwordx4 v112, v[114:117], vcc sc1
	v_add_u32_e32 v112, 0x1000, v112
	global_store_dwordx4 v112, v[118:121], vcc sc1
	v_add_u32_e32 v112, 0x1000, v112
	global_store_dwordx4 v112, v[122:125], vcc sc1
	v_add_u32_e32 v112, 0x1000, v112
	global_store_dwordx4 v112, v[126:129], vcc sc1
	s_branch .Lcv_done_2_0

; __device__ __forceinline__ void tr_item(const float* __restrict__ W, int K, int N, bf16_t* WT, const float* __restrict__ kscale, int rowmode, int item, int lane) {
;     const int nblk = N >> 5, kb = item / nblk, nb = item - kb * nblk;
;     const int c = lane >> 3, q = lane & 7, k0 = kb * 64 + c * 8, n0 = nb * 32 + q * 4;
;     f32x4 v[8];
; #pragma unroll
;     for (int i = 0; i < 8; ++i) v[i] = __builtin_nontemporal_load((const f32x4*)(W + (size_t)(k0 + i) * N + n0));
;     if (kscale) { const f32x4 s0 = *(const f32x4*)(kscale + k0), s1 = *(const f32x4*)(kscale + k0 + 4);
; #pragma unroll
;         for (int i = 0; i < 4; ++i) { v[i] = v[i] * s0[i]; v[4 + i] = v[4 + i] * s1[i]; } }
;     int drow;
;     if (rowmode == 0) drow = n0;
;     else if (rowmode == 3) { const int g = n0 - pg8::C_GA; drow = g < 0 ? n0 : pg8::C_GA + (((g & 2047) >> 7) << 8) + ((g >> 11) << 7) + (g & 127); }
;     else drow = ((n0 >> 7) << 8) + (n0 & 127) + (rowmode == 2 ? 128 : 0);
; #pragma unroll
;     for (int e = 0; e < 4; ++e) { u32x4 o; o.x = cvt_pk_bf16(v[0][e], v[1][e]); o.y = cvt_pk_bf16(v[2][e], v[3][e]); o.z = cvt_pk_bf16(v[4][e], v[5][e]); o.w = cvt_pk_bf16(v[6][e], v[7][e]);
;         pg8::st16_wt(WT + (size_t)(drow + e) * K + k0, o); }
;     ...
;     for (int mi = 0; mi < 7 * DEPTH; ++mi) {
;         if (!((mask >> mi) & 1u)) continue;
;         const int l = mi / 7, kind = mi - 7 * l;
;         const float* W; const float* ks = nullptr; bf16_t* WT; int K, N, rm = 0;
;         if (kind == 0)      { W = a.in[2] + (size_t)l * 2048 * 7680;  K = 2048; N = 7680; WT = (bf16_t*)(ws + WS_WIN + l * SZ_WIN); ks = a.in[1] + l * 2048; rm = 3; }
;         else if (kind == 1) { W = a.in[10] + (size_t)l * 1024 * 2048; K = 1024; N = 2048; WT = (bf16_t*)(ws + WS_WA + l * SZ_WA); }
;         else if (kind == 2) { W = a.in[11] + (size_t)l * 1024 * 2048; K = 1024; N = 2048; WT = (bf16_t*)(ws + WS_WB + l * SZ_WB); }
;         else if (kind == 3) { W = a.in[12] + (size_t)l * 2048 * 2048; K = 2048; N = 2048; WT = (bf16_t*)(ws + WS_WO + l * SZ_WO); }
;         else if (kind == 4) { W = a.in[14] + (size_t)l * 2048 * 5632; K = 2048; N = 5632; WT = (bf16_t*)(ws + WS_WGU + l * SZ_WGU); ks = a.in[13] + l * 2048; rm = 1; }
;         else if (kind == 5) { W = a.in[15] + (size_t)l * 2048 * 5632; K = 2048; N = 5632; WT = (bf16_t*)(ws + WS_WGU + l * SZ_WGU); ks = a.in[13] + l * 2048; rm = 2; }
.LBB0_524:
	s_or_b64 exec, exec, s[0:1]
	s_cmpk_lg_u32 s3, 0x100
	s_cbranch_scc1 .Lcv_skip_3
	v_readfirstlane_b32 vcc_lo, v204
	s_nop 3
	s_lshr_b32 vcc_lo, vcc_lo, 6
	s_cmp_eq_u32 vcc_lo, 0
	s_cbranch_scc1 .Lcv_skip_3
	s_lshr_b32 m0, s85, 5
	v_subrev_u32_e32 v106, 64, v204
	v_mov_b32_e32 v107, m0
	v_lshlrev_b32_e32 v107, 8, v107
	v_mov_b32_e32 v108, v106
	v_lshrrev_b32_e32 v109, 3, v108
	v_add_u32_e32 v109, v109, v107
	v_mul_u32_u24_e32 v109, 0x1000, v109
	v_and_b32_e32 v108, 7, v108
	v_lshl_add_u32 v109, v108, 6, v109
	v_add_u32_e32 v108, 448, v106
	v_lshrrev_b32_e32 v110, 3, v108
	v_add_u32_e32 v110, v110, v107
	v_mul_u32_u24_e32 v110, 0x1000, v110
	v_and_b32_e32 v108, 7, v108
	v_lshl_add_u32 v110, v108, 6, v110
	v_add_u32_e32 v108, 896, v106
	v_lshrrev_b32_e32 v111, 3, v108
	v_add_u32_e32 v111, v111, v107
	v_mul_u32_u24_e32 v111, 0x1000, v111
	v_and_b32_e32 v108, 7, v108
	v_lshl_add_u32 v111, v108, 6, v111
	v_add_u32_e32 v108, 1344, v106
	v_lshrrev_b32_e32 v112, 3, v108
	v_add_u32_e32 v112, v112, v107
	v_mul_u32_u24_e32 v112, 0x1000, v112
	v_and_b32_e32 v108, 7, v108
	v_lshl_add_u32 v112, v108, 6, v112
	v_add_u32_e32 v108, 1792, v106
	v_and_b32_e32 v108, 0x7ff, v108
	v_lshrrev_b32_e32 v113, 3, v108
	v_add_u32_e32 v113, v113, v107
	v_mul_u32_u24_e32 v113, 0x1000, v113
	v_and_b32_e32 v108, 7, v108
	v_lshl_add_u32 v113, v108, 6, v113
	v_readlane_b32 vcc_lo, v250, 36
	v_readlane_b32 vcc_hi, v250, 37
	s_nop 3
	s_add_u32 vcc_lo, vcc_lo, 0x4dc0000
	s_addc_u32 vcc_hi, vcc_hi, 0
	s_cmp_lg_u32 s64, 0
	s_cselect_b32 m0, 0x800000, 0
	s_add_u32 vcc_lo, vcc_lo, m0
	s_addc_u32 vcc_hi, vcc_hi, 0
	global_load_dword v120, v109, vcc
	global_load_dword v121, v110, vcc
	global_load_dword v122, v111, vcc
	global_load_dword v123, v112, vcc
	global_load_dword v124, v113, vcc
	s_cmp_lg_u32 s64, 0
	s_cbranch_scc1 .Lcv_pfwait_3
	v_and_b32_e32 v106, 63, v204
	v_lshrrev_b32_e32 v107, 3, v106
	v_and_b32_e32 v108, 7, v106
	v_readfirstlane_b32 vcc_lo, v204
	s_nop 3
	s_lshr_b32 vcc_lo, vcc_lo, 6
	s_mul_i32 vcc_hi, s85, 7
	s_add_i32 vcc_lo, vcc_lo, vcc_hi
	s_add_i32 vcc_lo, vcc_lo, -1
	s_add_i32 vcc_lo, vcc_lo, 3584
	s_sub_u32 vcc_lo, vcc_lo, 3520
	v_mov_b32_e32 v113, vcc_lo
	v_mul_u32_u24_e32 v109, 0x5d18, v113
	v_lshrrev_b32_e32 v109, 22, v109
	v_mul_u32_u24_e32 v110, 0xb0, v109
	v_sub_u32_e32 v110, v113, v110
	v_lshlrev_b32_e32 v109, 6, v109
	v_lshl_add_u32 v109, v107, 3, v109
	v_lshlrev_b32_e32 v110, 5, v110
	v_lshl_add_u32 v110, v108, 2, v110
	v_mul_u32_u24_e32 v111, 0x5800, v109
	v_lshl_add_u32 v111, v110, 2, v111
	v_add_u32_e32 v111, 0x2c00000, v111
	v_lshrrev_b32_e32 v112, 7, v110
	v_lshlrev_b32_e32 v112, 8, v112
	v_and_b32_e32 v113, 0x7f, v110
	v_add_u32_e32 v112, v112, v113
	v_lshlrev_b32_e32 v112, 12, v112
	v_lshl_add_u32 v112, v109, 1, v112
	v_lshlrev_b32_e32 v113, 2, v109
	v_add_u32_e32 v113, 0x2000, v113
	v_readlane_b32 vcc_lo, v250, 28
	v_readlane_b32 vcc_hi, v250, 29
	s_nop 4
	global_load_dwordx4 v[98:101], v113, vcc
	global_load_dwordx4 v[102:105], v113, vcc offset:16
	v_readlane_b32 vcc_lo, v250, 30
	v_readlane_b32 vcc_hi, v250, 31
	s_nop 4
	global_load_dwordx4 v[66:69], v111, vcc nt
	v_add_u32_e32 v111, 0x5800, v111
	global_load_dwordx4 v[70:73], v111, vcc nt
	v_add_u32_e32 v111, 0x5800, v111
	global_load_dwordx4 v[74:77], v111, vcc nt
	v_add_u32_e32 v111, 0x5800, v111
	global_load_dwordx4 v[78:81], v111, vcc nt
	v_add_u32_e32 v111, 0x5800, v111
	global_load_dwordx4 v[82:85], v111, vcc nt
	v_add_u32_e32 v111, 0x5800, v111
	global_load_dwordx4 v[86:89], v111, vcc nt
	v_add_u32_e32 v111, 0x5800, v111
	global_load_dwordx4 v[90:93], v111, vcc nt
	v_add_u32_e32 v111, 0x5800, v111
	global_load_dwordx4 v[94:97], v111, vcc nt
	v_readlane_b32 vcc_lo, v250, 36
	v_readlane_b32 vcc_hi, v250, 37
	s_nop 3
	s_add_u32 vcc_lo, vcc_lo, 0x89c0000
	s_addc_u32 vcc_hi, vcc_hi, 0
	s_waitcnt vmcnt(0)
	v_mul_f32_e32 v66, v66, v98
	v_mul_f32_e32 v67, v67, v98
	v_mul_f32_e32 v68, v68, v98
	v_mul_f32_e32 v69, v69, v98
	v_mul_f32_e32 v70, v70, v99
	v_mul_f32_e32 v71, v71, v99
	v_mul_f32_e32 v72, v72, v99
	v_mul_f32_e32 v73, v73, v99
	v_mul_f32_e32 v74, v74, v100
	v_mul_f32_e32 v75, v75, v100
	v_mul_f32_e32 v76, v76, v100
	v_mul_f32_e32 v77, v77, v100
	v_mul_f32_e32 v78, v78, v101
	v_mul_f32_e32 v79, v79, v101
	v_mul_f32_e32 v80, v80, v101
	v_mul_f32_e32 v81, v81, v101
	v_mul_f32_e32 v82, v82, v102
	v_mul_f32_e32 v83, v83, v102
	v_mul_f32_e32 v84, v84, v102
	v_mul_f32_e32 v85, v85, v102
	v_mul_f32_e32 v86, v86, v103
	v_mul_f32_e32 v87, v87, v103
	v_mul_f32_e32 v88, v88, v103
	v_mul_f32_e32 v89, v89, v103
	v_mul_f32_e32 v90, v90, v104
	v_mul_f32_e32 v91, v91, v104
	v_mul_f32_e32 v92, v92, v104
	v_mul_f32_e32 v93, v93, v104
	v_mul_f32_e32 v94, v94, v105
	v_mul_f32_e32 v95, v95, v105
	v_mul_f32_e32 v96, v96, v105
	v_mul_f32_e32 v97, v97, v105
	v_cvt_pk_bf16_f32 v114, v66, v70
	v_cvt_pk_bf16_f32 v115, v74, v78
	v_cvt_pk_bf16_f32 v116, v82, v86
	v_cvt_pk_bf16_f32 v117, v90, v94
	v_cvt_pk_bf16_f32 v118, v67, v71
	v_cvt_pk_bf16_f32 v119, v75, v79
	v_cvt_pk_bf16_f32 v120, v83, v87
	v_cvt_pk_bf16_f32 v121, v91, v95
	v_cvt_pk_bf16_f32 v122, v68, v72
	v_cvt_pk_bf16_f32 v123, v76, v80
	v_cvt_pk_bf16_f32 v124, v84, v88
	v_cvt_pk_bf16_f32 v125, v92, v96
	v_cvt_pk_bf16_f32 v126, v69, v73
	v_cvt_pk_bf16_f32 v127, v77, v81
	v_cvt_pk_bf16_f32 v128, v85, v89
	v_cvt_pk_bf16_f32 v129, v93, v97
	global_store_dwordx4 v112, v[114:117], vcc sc1
	v_add_u32_e32 v112, 0x1000, v112
	global_store_dwordx4 v112, v[118:121], vcc sc1
	v_add_u32_e32 v112, 0x1000, v112
	global_store_dwordx4 v112, v[122:125], vcc sc1
	v_add_u32_e32 v112, 0x1000, v112
	global_store_dwordx4 v112, v[126:129], vcc sc1

; __device__ __forceinline__ void tr_item(const float* __restrict__ W, int K, int N, bf16_t* WT, const float* __restrict__ kscale, int rowmode, int item, int lane) {
;     const int nblk = N >> 5, kb = item / nblk, nb = item - kb * nblk;
;     const int c = lane >> 3, q = lane & 7, k0 = kb * 64 + c * 8, n0 = nb * 32 + q * 4;
;     f32x4 v[8];
; #pragma unroll
;     for (int i = 0; i < 8; ++i) v[i] = __builtin_nontemporal_load((const f32x4*)(W + (size_t)(k0 + i) * N + n0));
;     if (kscale) { const f32x4 s0 = *(const f32x4*)(kscale + k0), s1 = *(const f32x4*)(kscale + k0 + 4);
; #pragma unroll
;         for (int i = 0; i < 4; ++i) { v[i] = v[i] * s0[i]; v[4 + i] = v[4 + i] * s1[i]; } }
;     int drow;
;     if (rowmode == 0) drow = n0;
;     else if (rowmode == 3) { const int g = n0 - pg8::C_GA; drow = g < 0 ? n0 : pg8::C_GA + (((g & 2047) >> 7) << 8) + ((g >> 11) << 7) + (g & 127); }
;     else drow = ((n0 >> 7) << 8) + (n0 & 127) + (rowmode == 2 ? 128 : 0);
; #pragma unroll
;     for (int e = 0; e < 4; ++e) { u32x4 o; o.x = cvt_pk_bf16(v[0][e], v[1][e]); o.y = cvt_pk_bf16(v[2][e], v[3][e]); o.z = cvt_pk_bf16(v[4][e], v[5][e]); o.w = cvt_pk_bf16(v[6][e], v[7][e]);
;         pg8::st16_wt(WT + (size_t)(drow + e) * K + k0, o); }
;     ...
;     for (int mi = 0; mi < 7 * DEPTH; ++mi) {
;         if (!((mask >> mi) & 1u)) continue;
;         const int l = mi / 7, kind = mi - 7 * l;
;         const float* W; const float* ks = nullptr; bf16_t* WT; int K, N, rm = 0;
;         if (kind == 0)      { W = a.in[2] + (size_t)l * 2048 * 7680;  K = 2048; N = 7680; WT = (bf16_t*)(ws + WS_WIN + l * SZ_WIN); ks = a.in[1] + l * 2048; rm = 3; }
;         else if (kind == 1) { W = a.in[10] + (size_t)l * 1024 * 2048; K = 1024; N = 2048; WT = (bf16_t*)(ws + WS_WA + l * SZ_WA); }
;         else if (kind == 2) { W = a.in[11] + (size_t)l * 1024 * 2048; K = 1024; N = 2048; WT = (bf16_t*)(ws + WS_WB + l * SZ_WB); }
;         else if (kind == 3) { W = a.in[12] + (size_t)l * 2048 * 2048; K = 2048; N = 2048; WT = (bf16_t*)(ws + WS_WO + l * SZ_WO); }
;         else if (kind == 4) { W = a.in[14] + (size_t)l * 2048 * 5632; K = 2048; N = 5632; WT = (bf16_t*)(ws + WS_WGU + l * SZ_WGU); ks = a.in[13] + l * 2048; rm = 1; }
;         else if (kind == 5) { W = a.in[15] + (size_t)l * 2048 * 5632; K = 2048; N = 5632; WT = (bf16_t*)(ws + WS_WGU + l * SZ_WGU); ks = a.in[13] + l * 2048; rm = 2; }
.LBB0_632:
	s_or_b64 exec, exec, s[0:1]
	s_cmpk_lg_u32 s3, 0x100
	s_cbranch_scc1 .Lcv_skip_4
	v_readfirstlane_b32 vcc_lo, v204
	s_nop 3
	s_lshr_b32 vcc_lo, vcc_lo, 6
	s_cmp_eq_u32 vcc_lo, 0
	s_cbranch_scc1 .Lcv_skip_4
	s_lshr_b32 m0, s85, 5
	v_subrev_u32_e32 v106, 64, v204
	v_mov_b32_e32 v107, m0
	v_lshlrev_b32_e32 v107, 8, v107
	v_mov_b32_e32 v108, v106
	v_lshrrev_b32_e32 v109, 3, v108
	v_add_u32_e32 v109, v109, v107
	v_mul_u32_u24_e32 v109, 0x1000, v109
	v_and_b32_e32 v108, 7, v108
	v_lshl_add_u32 v109, v108, 6, v109
	v_add_u32_e32 v108, 448, v106
	v_lshrrev_b32_e32 v110, 3, v108
	v_add_u32_e32 v110, v110, v107
	v_mul_u32_u24_e32 v110, 0x1000, v110
	v_and_b32_e32 v108, 7, v108
	v_lshl_add_u32 v110, v108, 6, v110
	v_add_u32_e32 v108, 896, v106
	v_lshrrev_b32_e32 v111, 3, v108
	v_add_u32_e32 v111, v111, v107
	v_mul_u32_u24_e32 v111, 0x1000, v111
	v_and_b32_e32 v108, 7, v108
	v_lshl_add_u32 v111, v108, 6, v111
	v_add_u32_e32 v108, 1344, v106
	v_lshrrev_b32_e32 v112, 3, v108
	v_add_u32_e32 v112, v112, v107
	v_mul_u32_u24_e32 v112, 0x1000, v112
	v_and_b32_e32 v108, 7, v108
	v_lshl_add_u32 v112, v108, 6, v112
	v_add_u32_e32 v108, 1792, v106
	v_and_b32_e32 v108, 0x7ff, v108
	v_lshrrev_b32_e32 v113, 3, v108
	v_add_u32_e32 v113, v113, v107
	v_mul_u32_u24_e32 v113, 0x1000, v113
	v_and_b32_e32 v108, 7, v108
	v_lshl_add_u32 v113, v108, 6, v113
	v_readlane_b32 vcc_lo, v250, 36
	v_readlane_b32 vcc_hi, v250, 37
	s_nop 3
	s_add_u32 vcc_lo, vcc_lo, 0x5dc0000
	s_addc_u32 vcc_hi, vcc_hi, 0
	s_cmp_lg_u32 s64, 0
	s_cselect_b32 m0, 0x2c00000, 0
	s_add_u32 vcc_lo, vcc_lo, m0
	s_addc_u32 vcc_hi, vcc_hi, 0
	global_load_dword v120, v109, vcc
	global_load_dword v121, v110, vcc
	global_load_dword v122, v111, vcc
	global_load_dword v123, v112, vcc
	global_load_dword v124, v113, vcc
	s_cmp_lg_u32 s64, 0
	s_cbranch_scc1 .Lcv_pfwait_4
	v_and_b32_e32 v106, 63, v204
	v_lshrrev_b32_e32 v107, 3, v106
	v_and_b32_e32 v108, 7, v106
	v_readfirstlane_b32 vcc_lo, v204
	s_nop 3
	s_lshr_b32 vcc_lo, vcc_lo, 6
	s_mul_i32 vcc_hi, s85, 7
	s_add_i32 vcc_lo, vcc_lo, vcc_hi
	s_add_i32 vcc_lo, vcc_lo, -1
	s_cmp_ge_u32 vcc_lo, 1664
	s_cbranch_scc1 .Lcv_pfwait_4
	s_add_i32 vcc_lo, vcc_lo, 5376
	s_sub_u32 vcc_lo, vcc_lo, 3520
	v_mov_b32_e32 v113, vcc_lo
	v_mul_u32_u24_e32 v109, 0x5d18, v113
	v_lshrrev_b32_e32 v109, 22, v109
	v_mul_u32_u24_e32 v110, 0xb0, v109
	v_sub_u32_e32 v110, v113, v110
	v_lshlrev_b32_e32 v109, 6, v109
	v_lshl_add_u32 v109, v107, 3, v109
	v_lshlrev_b32_e32 v110, 5, v110
	v_lshl_add_u32 v110, v108, 2, v110
	v_mul_u32_u24_e32 v111, 0x5800, v109
	v_lshl_add_u32 v111, v110, 2, v111
	v_add_u32_e32 v111, 0x2c00000, v111
	v_lshrrev_b32_e32 v112, 7, v110
	v_lshlrev_b32_e32 v112, 8, v112
	v_and_b32_e32 v113, 0x7f, v110
	v_add_u32_e32 v112, v112, v113
	v_lshlrev_b32_e32 v112, 12, v112
	v_lshl_add_u32 v112, v109, 1, v112
	v_lshlrev_b32_e32 v113, 2, v109
	v_add_u32_e32 v113, 0x2000, v113
	v_readlane_b32 vcc_lo, v250, 28
	v_readlane_b32 vcc_hi, v250, 29
	s_nop 4
	global_load_dwordx4 v[98:101], v113, vcc
	global_load_dwordx4 v[102:105], v113, vcc offset:16
	v_readlane_b32 vcc_lo, v250, 30
	v_readlane_b32 vcc_hi, v250, 31
	s_nop 4
	global_load_dwordx4 v[66:69], v111, vcc nt
	v_add_u32_e32 v111, 0x5800, v111
	global_load_dwordx4 v[70:73], v111, vcc nt
	v_add_u32_e32 v111, 0x5800, v111
	global_load_dwordx4 v[74:77], v111, vcc nt
	v_add_u32_e32 v111, 0x5800, v111
	global_load_dwordx4 v[78:81], v111, vcc nt
	v_add_u32_e32 v111, 0x5800, v111
	global_load_dwordx4 v[82:85], v111, vcc nt
	v_add_u32_e32 v111, 0x5800, v111
	global_load_dwordx4 v[86:89], v111, vcc nt
	v_add_u32_e32 v111, 0x5800, v111
	global_load_dwordx4 v[90:93], v111, vcc nt
	v_add_u32_e32 v111, 0x5800, v111
	global_load_dwordx4 v[94:97], v111, vcc nt
	v_readlane_b32 vcc_lo, v250, 36
	v_readlane_b32 vcc_hi, v250, 37
	s_nop 3
	s_add_u32 vcc_lo, vcc_lo, 0x89c0000
	s_addc_u32 vcc_hi, vcc_hi, 0
	s_waitcnt vmcnt(0)
	v_mul_f32_e32 v66, v66, v98
	v_mul_f32_e32 v67, v67, v98
	v_mul_f32_e32 v68, v68, v98
	v_mul_f32_e32 v69, v69, v98
	v_mul_f32_e32 v70, v70, v99
	v_mul_f32_e32 v71, v71, v99
	v_mul_f32_e32 v72, v72, v99
	v_mul_f32_e32 v73, v73, v99
	v_mul_f32_e32 v74, v74, v100
	v_mul_f32_e32 v75, v75, v100
	v_mul_f32_e32 v76, v76, v100
	v_mul_f32_e32 v77, v77, v100
	v_mul_f32_e32 v78, v78, v101
	v_mul_f32_e32 v79, v79, v101
	v_mul_f32_e32 v80, v80, v101
	v_mul_f32_e32 v81, v81, v101
	v_mul_f32_e32 v82, v82, v102
	v_mul_f32_e32 v83, v83, v102
	v_mul_f32_e32 v84, v84, v102
	v_mul_f32_e32 v85, v85, v102
	v_mul_f32_e32 v86, v86, v103
	v_mul_f32_e32 v87, v87, v103
	v_mul_f32_e32 v88, v88, v103
	v_mul_f32_e32 v89, v89, v103
	v_mul_f32_e32 v90, v90, v104
	v_mul_f32_e32 v91, v91, v104
	v_mul_f32_e32 v92, v92, v104
	v_mul_f32_e32 v93, v93, v104
	v_mul_f32_e32 v94, v94, v105
	v_mul_f32_e32 v95, v95, v105
	v_mul_f32_e32 v96, v96, v105
	v_mul_f32_e32 v97, v97, v105
	v_cvt_pk_bf16_f32 v114, v66, v70
	v_cvt_pk_bf16_f32 v115, v74, v78
	v_cvt_pk_bf16_f32 v116, v82, v86
	v_cvt_pk_bf16_f32 v117, v90, v94
	v_cvt_pk_bf16_f32 v118, v67, v71
	v_cvt_pk_bf16_f32 v119, v75, v79
	v_cvt_pk_bf16_f32 v120, v83, v87
	v_cvt_pk_bf16_f32 v121, v91, v95
	v_cvt_pk_bf16_f32 v122, v68, v72
	v_cvt_pk_bf16_f32 v123, v76, v80
	v_cvt_pk_bf16_f32 v124, v84, v88
	v_cvt_pk_bf16_f32 v125, v92, v96
	v_cvt_pk_bf16_f32 v126, v69, v73
	v_cvt_pk_bf16_f32 v127, v77, v81
	v_cvt_pk_bf16_f32 v128, v85, v89
	v_cvt_pk_bf16_f32 v129, v93, v97
	global_store_dwordx4 v112, v[114:117], vcc sc1
	v_add_u32_e32 v112, 0x1000, v112
	global_store_dwordx4 v112, v[118:121], vcc sc1
	v_add_u32_e32 v112, 0x1000, v112
	global_store_dwordx4 v112, v[122:125], vcc sc1
	v_add_u32_e32 v112, 0x1000, v112
	global_store_dwordx4 v112, v[126:129], vcc sc1

; #define SEAM(k) do { if (IN(k) && IN((k) + 1)) { if (hi > 4096) cg::this_grid().sync(); else xcd_barrier(bar); } } while (0)
; __global__ void __launch_bounds__(NTHREADS, 2) mk_fwd(Args args) {
;     ...
;             { int thr = S.nwg - ((S.nwg + G - 1) / G - 1) * G; if (thr >= G) thr = 0;
;                 if (blk >= thr) p0_prologue(args, (blk - thr) * NWAVES + wave, (G - thr) * NWAVES, lane, l == 0 ? 0x07C0u : 0x2000u, false); }
;         }
;         SEAM(pb + 4);
;         if (KON(6) && IN(pb + 5)) {
;             pg8::Gemm g{ACT, WD, ACT, WD, pg8::MROWS, 2048, pg8::D_FF}; pg8::StaticOrder S; S.init(pg8::MROWS, 2048, G, blk, 0);
;             pg8::EpiRes E{args.out, XB, SSQ + (size_t)((2 * l + 2) & 3) * 8 * pg8::MROWS, l + 1 < DEPTH ? 1 : 0, RED};
;             pg8::gemm_phase<pg8::EpiRes, pg8::StaticOrder, true, true>(lds, g, S, E);
.LBB0_770:
	s_or_b64 exec, exec, s[0:1]
	s_cmpk_lg_u32 s3, 0x100
	s_cbranch_scc1 .Lcv_skip_5
	v_readfirstlane_b32 vcc_lo, v204
	s_nop 3
	s_lshr_b32 vcc_lo, vcc_lo, 6
	s_cmp_eq_u32 vcc_lo, 0
	s_cbranch_scc1 .Lcv_skip_5
	s_lshr_b32 m0, s85, 5
	v_subrev_u32_e32 v106, 64, v204
	v_mov_b32_e32 v107, m0
	v_lshlrev_b32_e32 v107, 8, v107
	v_mov_b32_e32 v108, v106
	v_lshrrev_b32_e32 v109, 3, v108
	v_add_u32_e32 v109, v109, v107
	v_mul_u32_u24_e32 v109, 0x2c00, v109
	v_and_b32_e32 v108, 7, v108
	v_lshl_add_u32 v109, v108, 6, v109
	v_add_u32_e32 v108, 448, v106
	v_lshrrev_b32_e32 v110, 3, v108
	v_add_u32_e32 v110, v110, v107
	v_mul_u32_u24_e32 v110, 0x2c00, v110
	v_and_b32_e32 v108, 7, v108
	v_lshl_add_u32 v110, v108, 6, v110
	v_add_u32_e32 v108, 896, v106
	v_lshrrev_b32_e32 v111, 3, v108
	v_add_u32_e32 v111, v111, v107
	v_mul_u32_u24_e32 v111, 0x2c00, v111
	v_and_b32_e32 v108, 7, v108
	v_lshl_add_u32 v111, v108, 6, v111
	v_add_u32_e32 v108, 1344, v106
	v_lshrrev_b32_e32 v112, 3, v108
	v_add_u32_e32 v112, v112, v107
	v_mul_u32_u24_e32 v112, 0x2c00, v112
	v_and_b32_e32 v108, 7, v108
	v_lshl_add_u32 v112, v108, 6, v112
	v_add_u32_e32 v108, 1792, v106
	v_and_b32_e32 v108, 0x7ff, v108
	v_lshrrev_b32_e32 v113, 3, v108
	v_add_u32_e32 v113, v113, v107
	v_mul_u32_u24_e32 v113, 0x2c00, v113
	v_and_b32_e32 v108, 7, v108
	v_lshl_add_u32 v113, v108, 6, v113
	v_readlane_b32 vcc_lo, v250, 36
	v_readlane_b32 vcc_hi, v250, 37
	s_nop 3
	s_add_u32 vcc_lo, vcc_lo, 0xb5c0000
	s_addc_u32 vcc_hi, vcc_hi, 0
	s_cmp_lg_u32 s64, 0
	s_cselect_b32 m0, 0x1600000, 0
	s_add_u32 vcc_lo, vcc_lo, m0
	s_addc_u32 vcc_hi, vcc_hi, 0
	global_load_dword v120, v109, vcc
	global_load_dword v121, v110, vcc
	global_load_dword v122, v111, vcc
	global_load_dword v123, v112, vcc
	global_load_dword v124, v113, vcc

; #define SEAM(k) do { if (IN(k) && IN((k) + 1)) { if (hi > 4096) cg::this_grid().sync(); else xcd_barrier(bar); } } while (0)
; __global__ void __launch_bounds__(NTHREADS, 2) mk_fwd(Args args) {
;     ...
;         if (KON(6) && IN(pb + 5)) {
;             pg8::Gemm g{ACT, WD, ACT, WD, pg8::MROWS, 2048, pg8::D_FF}; pg8::StaticOrder S; S.init(pg8::MROWS, 2048, G, blk, 0);
;             pg8::EpiRes E{args.out, XB, SSQ + (size_t)((2 * l + 2) & 3) * 8 * pg8::MROWS, l + 1 < DEPTH ? 1 : 0, RED};
;             pg8::gemm_phase<pg8::EpiRes, pg8::StaticOrder, true, true>(lds, g, S, E);
;         }
;         SEAM(pb + 5);
.LBB0_961:
	s_or_b64 exec, exec, s[0:1]
	s_cmpk_lg_u32 s3, 0x100
	s_cbranch_scc1 .Lcv_skip_6
	v_readfirstlane_b32 vcc_lo, v204
	s_nop 3
	s_lshr_b32 vcc_lo, vcc_lo, 6
	s_cmp_eq_u32 vcc_lo, 0
	s_cbranch_scc1 .Lcv_skip_6
	s_cmp_lg_u32 s64, 0
	s_cbranch_scc1 .Lcv_skip_6
	s_lshr_b32 m0, s85, 5
	v_subrev_u32_e32 v106, 64, v204
	v_mov_b32_e32 v107, m0
	v_lshlrev_b32_e32 v107, 8, v107
	v_mov_b32_e32 v108, v106
	v_lshrrev_b32_e32 v109, 3, v108
	v_add_u32_e32 v109, v109, v107
	v_mul_u32_u24_e32 v109, 0x1000, v109
	v_and_b32_e32 v108, 7, v108
	v_lshl_add_u32 v109, v108, 6, v109
	v_add_u32_e32 v108, 448, v106
	v_lshrrev_b32_e32 v110, 3, v108
	v_add_u32_e32 v110, v110, v107
	v_mul_u32_u24_e32 v110, 0x1000, v110
	v_and_b32_e32 v108, 7, v108
	v_lshl_add_u32 v110, v108, 6, v110
	v_add_u32_e32 v108, 896, v106
	v_lshrrev_b32_e32 v111, 3, v108
	v_add_u32_e32 v111, v111, v107
	v_mul_u32_u24_e32 v111, 0x1000, v111
	v_and_b32_e32 v108, 7, v108
	v_lshl_add_u32 v111, v108, 6, v111
	v_add_u32_e32 v108, 1344, v106
	v_lshrrev_b32_e32 v112, 3, v108
	v_add_u32_e32 v112, v112, v107
	v_mul_u32_u24_e32 v112, 0x1000, v112
	v_and_b32_e32 v108, 7, v108
	v_lshl_add_u32 v112, v108, 6, v112
	v_add_u32_e32 v108, 1792, v106
	v_and_b32_e32 v108, 0x7ff, v108
	v_lshrrev_b32_e32 v113, 3, v108
	v_add_u32_e32 v113, v113, v107
	v_mul_u32_u24_e32 v113, 0x1000, v113
	v_and_b32_e32 v108, 7, v108
	v_lshl_add_u32 v113, v108, 6, v113
	v_readlane_b32 vcc_lo, v250, 36
	v_readlane_b32 vcc_hi, v250, 37
	s_nop 3
	s_add_u32 vcc_lo, vcc_lo, 0x1fc0000
	s_addc_u32 vcc_hi, vcc_hi, 0
	global_load_dword v120, v109, vcc
	global_load_dword v121, v110, vcc
	global_load_dword v122, v111, vcc
	global_load_dword v123, v112, vcc
	global_load_dword v124, v113, vcc
